# up-projection epilogues: removed dead zero-initialisers of full-row DPP rotates (hazard distances re-checked)
# speedup vs baseline: 1.0287x; 1.0096x over previous
; __device__ __forceinline__ float dpp_ror1(float v) { return __int_as_float(__builtin_amdgcn_update_dpp(0, __float_as_int(v), 0x121, 0xf, 0xf, false)); }
; __device__ __forceinline__ float dpp_ror2(float v) { return __int_as_float(__builtin_amdgcn_update_dpp(0, __float_as_int(v), 0x122, 0xf, 0xf, false)); }
;   __device__ __forceinline__ void operator()(const AccT& acc, const Unit& u, int wr, int wc, int fr, int fq) const {
;     ...
;         for (int m = 0; m < 4; ++m) {
;           f32x4 res;
; #pragma unroll
;           for (int r = 0; r < 4; ++r) {
;             const float g_cur = xg[m][r], v_cur = xv[m][r];
;             const f32x4 xgp = xg[m > 0 ? m - 1 : 0], xvp = xv[m > 0 ? m - 1 : 0];
;             const float g_pm = (m > 0) ? xgp[r] : 0.f, v_pm = (m > 0) ? xvp[r] : 0.f;
;             const float g1 = dpp_ror1((fr == 15) ? g_pm : g_cur), g2 = dpp_ror2((fr >= 14) ? g_pm : g_cur);
;             const float v1 = dpp_ror1((fr == 15) ? v_pm : v_cur), v2 = dpp_ror2((fr >= 14) ? v_pm : v_cur);
;             const float cg_ = bg[r] + g2 * wg0[r] + g1 * wg1[r] + g_cur * wg2[r];
;             const float cv_ = bv[r] + v2 * wv0[r] + v1 * wv1[r] + v_cur * wv2[r];
;             res[r] = cg_ * __builtin_amdgcn_rcpf(1.f + __builtin_amdgcn_exp2f(-1.4426950408889634f * cg_)) * cv_;
;           }
.LBB0_477:
	s_or_b64 exec, exec, s[38:39]
	v_mov_b32_e32 v123, v122
	v_mov_b32_e32 v127, v126
	v_mov_b32_e32 v84, v126
	v_mov_b32_e32 v85, v126
	v_pk_mul_f32 v[82:83], v[20:21], v[126:127]
	v_pk_mul_f32 v[20:21], v[30:31], v[84:85]
	v_mov_b32_e32 v30, v122
	v_mov_b32_e32 v31, v122
	v_pk_mul_f32 v[24:25], v[24:25], v[122:123]
	v_pk_mul_f32 v[18:19], v[18:19], v[30:31]
	v_pk_mul_f32 v[26:27], v[26:27], v[30:31]
	v_cndmask_b32_e64 v31, v24, v44, s[8:9]

; __device__ __forceinline__ float dpp_ror1(float v) { return __int_as_float(__builtin_amdgcn_update_dpp(0, __float_as_int(v), 0x121, 0xf, 0xf, false)); }
; __device__ __forceinline__ float dpp_ror2(float v) { return __int_as_float(__builtin_amdgcn_update_dpp(0, __float_as_int(v), 0x122, 0xf, 0xf, false)); }
;   __device__ __forceinline__ void operator()(const AccT& acc, const Unit& u, int wr, int wc, int fr, int fq) const {
;     ...
;           for (int r = 0; r < 4; ++r) {
;             const float g_cur = xg[m][r], v_cur = xv[m][r];
;             const f32x4 xgp = xg[m > 0 ? m - 1 : 0], xvp = xv[m > 0 ? m - 1 : 0];
;             const float g_pm = (m > 0) ? xgp[r] : 0.f, v_pm = (m > 0) ? xvp[r] : 0.f;
;             const float g1 = dpp_ror1((fr == 15) ? g_pm : g_cur), g2 = dpp_ror2((fr >= 14) ? g_pm : g_cur);
;             const float v1 = dpp_ror1((fr == 15) ? v_pm : v_cur), v2 = dpp_ror2((fr >= 14) ? v_pm : v_cur);
	v_pk_mul_f32 v[16:17], v[16:17], v[122:123]
	v_pk_mul_f32 v[22:23], v[22:23], v[84:85]
	v_mov_b32_dpp v30, v31 row_ror:1 row_mask:0xf bank_mask:0xf
	v_cndmask_b32_e64 v31, v24, v44, s[6:7]
	s_nop 0

; __device__ __forceinline__ float dpp_ror1(float v) { return __int_as_float(__builtin_amdgcn_update_dpp(0, __float_as_int(v), 0x121, 0xf, 0xf, false)); }
; __device__ __forceinline__ float dpp_ror2(float v) { return __int_as_float(__builtin_amdgcn_update_dpp(0, __float_as_int(v), 0x122, 0xf, 0xf, false)); }
;   __device__ __forceinline__ void operator()(const AccT& acc, const Unit& u, int wr, int wc, int fr, int fq) const {
;     ...
;           for (int r = 0; r < 4; ++r) {
;             const float g_cur = xg[m][r], v_cur = xv[m][r];
;             const f32x4 xgp = xg[m > 0 ? m - 1 : 0], xvp = xv[m > 0 ? m - 1 : 0];
;             const float g_pm = (m > 0) ? xgp[r] : 0.f, v_pm = (m > 0) ? xvp[r] : 0.f;
;             const float g1 = dpp_ror1((fr == 15) ? g_pm : g_cur), g2 = dpp_ror2((fr >= 14) ? g_pm : g_cur);
;             const float v1 = dpp_ror1((fr == 15) ? v_pm : v_cur), v2 = dpp_ror2((fr >= 14) ? v_pm : v_cur);
	v_cndmask_b32_e64 v85, v25, v45, s[8:9]
	v_mov_b32_dpp v44, v31 row_ror:2 row_mask:0xf bank_mask:0xf
	v_cndmask_b32_e64 v31, v16, v40, s[8:9]
	v_cndmask_b32_e64 v86, v17, v41, s[8:9]
	v_cndmask_b32_e64 v87, v26, v46, s[8:9]
	v_mov_b32_dpp v84, v31 row_ror:1 row_mask:0xf bank_mask:0xf
	v_cndmask_b32_e64 v31, v16, v40, s[6:7]

; __device__ __forceinline__ float dpp_ror1(float v) { return __int_as_float(__builtin_amdgcn_update_dpp(0, __float_as_int(v), 0x121, 0xf, 0xf, false)); }
; __device__ __forceinline__ float dpp_ror2(float v) { return __int_as_float(__builtin_amdgcn_update_dpp(0, __float_as_int(v), 0x122, 0xf, 0xf, false)); }
;   __device__ __forceinline__ void operator()(const AccT& acc, const Unit& u, int wr, int wc, int fr, int fq) const {
;     ...
;           for (int r = 0; r < 4; ++r) {
;             const float g_cur = xg[m][r], v_cur = xv[m][r];
;             const f32x4 xgp = xg[m > 0 ? m - 1 : 0], xvp = xv[m > 0 ? m - 1 : 0];
;             const float g_pm = (m > 0) ? xgp[r] : 0.f, v_pm = (m > 0) ? xvp[r] : 0.f;
;             const float g1 = dpp_ror1((fr == 15) ? g_pm : g_cur), g2 = dpp_ror2((fr >= 14) ? g_pm : g_cur);
;             const float v1 = dpp_ror1((fr == 15) ? v_pm : v_cur), v2 = dpp_ror2((fr >= 14) ? v_pm : v_cur);
	v_mov_b32_e32 v88, 0
	v_cndmask_b32_e64 v89, v27, v47, s[8:9]
	v_mov_b32_dpp v40, v31 row_ror:2 row_mask:0xf bank_mask:0xf

; __device__ __forceinline__ float dpp_ror1(float v) { return __int_as_float(__builtin_amdgcn_update_dpp(0, __float_as_int(v), 0x121, 0xf, 0xf, false)); }
; __device__ __forceinline__ float dpp_ror2(float v) { return __int_as_float(__builtin_amdgcn_update_dpp(0, __float_as_int(v), 0x122, 0xf, 0xf, false)); }
;   __device__ __forceinline__ void operator()(const AccT& acc, const Unit& u, int wr, int wc, int fr, int fq) const {
;     ...
;           for (int r = 0; r < 4; ++r) {
;             const float g_cur = xg[m][r], v_cur = xv[m][r];
;             const f32x4 xgp = xg[m > 0 ? m - 1 : 0], xvp = xv[m > 0 ? m - 1 : 0];
;             const float g_pm = (m > 0) ? xgp[r] : 0.f, v_pm = (m > 0) ? xvp[r] : 0.f;
;             const float g1 = dpp_ror1((fr == 15) ? g_pm : g_cur), g2 = dpp_ror2((fr >= 14) ? g_pm : g_cur);
;             const float v1 = dpp_ror1((fr == 15) ? v_pm : v_cur), v2 = dpp_ror2((fr >= 14) ? v_pm : v_cur);
;             const float cg_ = bg[r] + g2 * wg0[r] + g1 * wg1[r] + g_cur * wg2[r];
;             const float cv_ = bv[r] + v2 * wv0[r] + v1 * wv1[r] + v_cur * wv2[r];
	v_cndmask_b32_e64 v90, v19, v43, s[8:9]
	v_pk_mul_f32 v[28:29], v[28:29], v[126:127]
	v_mov_b32_dpp v31, v85 row_ror:1 row_mask:0xf bank_mask:0xf
	v_cndmask_b32_e64 v85, v25, v45, s[6:7]
	v_mov_b32_e32 v45, 0
	s_and_b64 vcc, exec, s[10:11]
	s_mov_b32 s40, s46
	v_mov_b32_dpp v45, v85 row_ror:2 row_mask:0xf bank_mask:0xf
	s_waitcnt vmcnt(0)
	v_pk_fma_f32 v[44:45], v[64:65], v[44:45], v[76:77]

; __device__ __forceinline__ float dpp_ror1(float v) { return __int_as_float(__builtin_amdgcn_update_dpp(0, __float_as_int(v), 0x121, 0xf, 0xf, false)); }
; __device__ __forceinline__ float dpp_ror2(float v) { return __int_as_float(__builtin_amdgcn_update_dpp(0, __float_as_int(v), 0x122, 0xf, 0xf, false)); }
;   __device__ __forceinline__ void operator()(const AccT& acc, const Unit& u, int wr, int wc, int fr, int fq) const {
;     ...
;           for (int r = 0; r < 4; ++r) {
;             const float g_cur = xg[m][r], v_cur = xv[m][r];
;             const f32x4 xgp = xg[m > 0 ? m - 1 : 0], xvp = xv[m > 0 ? m - 1 : 0];
;             const float g_pm = (m > 0) ? xgp[r] : 0.f, v_pm = (m > 0) ? xvp[r] : 0.f;
;             const float g1 = dpp_ror1((fr == 15) ? g_pm : g_cur), g2 = dpp_ror2((fr >= 14) ? g_pm : g_cur);
;             const float v1 = dpp_ror1((fr == 15) ? v_pm : v_cur), v2 = dpp_ror2((fr >= 14) ? v_pm : v_cur);
;             const float cg_ = bg[r] + g2 * wg0[r] + g1 * wg1[r] + g_cur * wg2[r];
;             const float cv_ = bv[r] + v2 * wv0[r] + v1 * wv1[r] + v_cur * wv2[r];
;             res[r] = cg_ * __builtin_amdgcn_rcpf(1.f + __builtin_amdgcn_exp2f(-1.4426950408889634f * cg_)) * cv_;
	v_pk_fma_f32 v[30:31], v[68:69], v[30:31], v[44:45]
	s_mov_b32 s38, s48
	v_pk_fma_f32 v[30:31], v[24:25], v[60:61], v[30:31]
	v_mov_b32_dpp v85, v86 row_ror:1 row_mask:0xf bank_mask:0xf
	v_mul_f32_e32 v44, 0xbfb8aa3b, v30
	v_mul_f32_e32 v45, 0xbfb8aa3b, v31
	v_exp_f32_e32 v44, v44
	v_exp_f32_e32 v45, v45
	v_cndmask_b32_e64 v86, v17, v41, s[6:7]

; __device__ __forceinline__ float dpp_ror1(float v) { return __int_as_float(__builtin_amdgcn_update_dpp(0, __float_as_int(v), 0x121, 0xf, 0xf, false)); }
; __device__ __forceinline__ float dpp_ror2(float v) { return __int_as_float(__builtin_amdgcn_update_dpp(0, __float_as_int(v), 0x122, 0xf, 0xf, false)); }
;   __device__ __forceinline__ void operator()(const AccT& acc, const Unit& u, int wr, int wc, int fr, int fq) const {
;     ...
;           for (int r = 0; r < 4; ++r) {
;             const float g_cur = xg[m][r], v_cur = xv[m][r];
;             const f32x4 xgp = xg[m > 0 ? m - 1 : 0], xvp = xv[m > 0 ? m - 1 : 0];
;             const float g_pm = (m > 0) ? xgp[r] : 0.f, v_pm = (m > 0) ? xvp[r] : 0.f;
;             const float g1 = dpp_ror1((fr == 15) ? g_pm : g_cur), g2 = dpp_ror2((fr >= 14) ? g_pm : g_cur);
;             const float v1 = dpp_ror1((fr == 15) ? v_pm : v_cur), v2 = dpp_ror2((fr >= 14) ? v_pm : v_cur);
;             const float cg_ = bg[r] + g2 * wg0[r] + g1 * wg1[r] + g_cur * wg2[r];
;             const float cv_ = bv[r] + v2 * wv0[r] + v1 * wv1[r] + v_cur * wv2[r];
;             res[r] = cg_ * __builtin_amdgcn_rcpf(1.f + __builtin_amdgcn_exp2f(-1.4426950408889634f * cg_)) * cv_;
	v_add_f32_e32 v44, 1.0, v44
	v_add_f32_e32 v45, 1.0, v45
	v_mov_b32_dpp v41, v86 row_ror:2 row_mask:0xf bank_mask:0xf

; __device__ __forceinline__ float dpp_ror1(float v) { return __int_as_float(__builtin_amdgcn_update_dpp(0, __float_as_int(v), 0x121, 0xf, 0xf, false)); }
; __device__ __forceinline__ float dpp_ror2(float v) { return __int_as_float(__builtin_amdgcn_update_dpp(0, __float_as_int(v), 0x122, 0xf, 0xf, false)); }
;   __device__ __forceinline__ void operator()(const AccT& acc, const Unit& u, int wr, int wc, int fr, int fq) const {
;     ...
;           for (int r = 0; r < 4; ++r) {
;             const float g_cur = xg[m][r], v_cur = xv[m][r];
;             const f32x4 xgp = xg[m > 0 ? m - 1 : 0], xvp = xv[m > 0 ? m - 1 : 0];
;             const float g_pm = (m > 0) ? xgp[r] : 0.f, v_pm = (m > 0) ? xvp[r] : 0.f;
;             const float g1 = dpp_ror1((fr == 15) ? g_pm : g_cur), g2 = dpp_ror2((fr >= 14) ? g_pm : g_cur);
;             const float v1 = dpp_ror1((fr == 15) ? v_pm : v_cur), v2 = dpp_ror2((fr >= 14) ? v_pm : v_cur);
;             const float cg_ = bg[r] + g2 * wg0[r] + g1 * wg1[r] + g_cur * wg2[r];
;             const float cv_ = bv[r] + v2 * wv0[r] + v1 * wv1[r] + v_cur * wv2[r];
;             res[r] = cg_ * __builtin_amdgcn_rcpf(1.f + __builtin_amdgcn_exp2f(-1.4426950408889634f * cg_)) * cv_;
	v_rcp_f32_e32 v44, v44
	v_rcp_f32_e32 v45, v45
	v_mov_b32_dpp v86, v87 row_ror:1 row_mask:0xf bank_mask:0xf
	v_cndmask_b32_e64 v87, v26, v46, s[6:7]

; __device__ __forceinline__ float dpp_ror1(float v) { return __int_as_float(__builtin_amdgcn_update_dpp(0, __float_as_int(v), 0x121, 0xf, 0xf, false)); }
; __device__ __forceinline__ float dpp_ror2(float v) { return __int_as_float(__builtin_amdgcn_update_dpp(0, __float_as_int(v), 0x122, 0xf, 0xf, false)); }
;   __device__ __forceinline__ void operator()(const AccT& acc, const Unit& u, int wr, int wc, int fr, int fq) const {
;     ...
;           for (int r = 0; r < 4; ++r) {
;             const float g_cur = xg[m][r], v_cur = xv[m][r];
;             const f32x4 xgp = xg[m > 0 ? m - 1 : 0], xvp = xv[m > 0 ? m - 1 : 0];
;             const float g_pm = (m > 0) ? xgp[r] : 0.f, v_pm = (m > 0) ? xvp[r] : 0.f;
;             const float g1 = dpp_ror1((fr == 15) ? g_pm : g_cur), g2 = dpp_ror2((fr >= 14) ? g_pm : g_cur);
;             const float v1 = dpp_ror1((fr == 15) ? v_pm : v_cur), v2 = dpp_ror2((fr >= 14) ? v_pm : v_cur);
;             const float cg_ = bg[r] + g2 * wg0[r] + g1 * wg1[r] + g_cur * wg2[r];
;             const float cv_ = bv[r] + v2 * wv0[r] + v1 * wv1[r] + v_cur * wv2[r];
	v_pk_fma_f32 v[40:41], v[52:53], v[40:41], v[72:73]
	v_pk_mul_f32 v[30:31], v[30:31], v[44:45]
	v_mov_b32_dpp v46, v87 row_ror:2 row_mask:0xf bank_mask:0xf
	v_cndmask_b32_e64 v87, v18, v42, s[8:9]
	v_pk_fma_f32 v[40:41], v[56:57], v[84:85], v[40:41]
	s_mov_b64 s[66:67], s[58:59]
	v_mov_b32_dpp v88, v87 row_ror:1 row_mask:0xf bank_mask:0xf
	v_cndmask_b32_e64 v87, v18, v42, s[6:7]

; __device__ __forceinline__ float dpp_ror1(float v) { return __int_as_float(__builtin_amdgcn_update_dpp(0, __float_as_int(v), 0x121, 0xf, 0xf, false)); }
; __device__ __forceinline__ float dpp_ror2(float v) { return __int_as_float(__builtin_amdgcn_update_dpp(0, __float_as_int(v), 0x122, 0xf, 0xf, false)); }
;   __device__ __forceinline__ void operator()(const AccT& acc, const Unit& u, int wr, int wc, int fr, int fq) const {
;     ...
;           for (int r = 0; r < 4; ++r) {
;             const float g_cur = xg[m][r], v_cur = xv[m][r];
;             const f32x4 xgp = xg[m > 0 ? m - 1 : 0], xvp = xv[m > 0 ? m - 1 : 0];
;             const float g_pm = (m > 0) ? xgp[r] : 0.f, v_pm = (m > 0) ? xvp[r] : 0.f;
;             const float g1 = dpp_ror1((fr == 15) ? g_pm : g_cur), g2 = dpp_ror2((fr >= 14) ? g_pm : g_cur);
;             const float v1 = dpp_ror1((fr == 15) ? v_pm : v_cur), v2 = dpp_ror2((fr >= 14) ? v_pm : v_cur);
;             const float cg_ = bg[r] + g2 * wg0[r] + g1 * wg1[r] + g_cur * wg2[r];
;             const float cv_ = bv[r] + v2 * wv0[r] + v1 * wv1[r] + v_cur * wv2[r];
	v_pk_fma_f32 v[40:41], v[16:17], v[48:49], v[40:41]
	s_mov_b64 s[60:61], s[50:51]
	v_mov_b32_dpp v42, v87 row_ror:2 row_mask:0xf bank_mask:0xf

; __device__ __forceinline__ float dpp_ror1(float v) { return __int_as_float(__builtin_amdgcn_update_dpp(0, __float_as_int(v), 0x121, 0xf, 0xf, false)); }
; __device__ __forceinline__ float dpp_ror2(float v) { return __int_as_float(__builtin_amdgcn_update_dpp(0, __float_as_int(v), 0x122, 0xf, 0xf, false)); }
;   __device__ __forceinline__ void operator()(const AccT& acc, const Unit& u, int wr, int wc, int fr, int fq) const {
;     ...
;           for (int r = 0; r < 4; ++r) {
;             const float g_cur = xg[m][r], v_cur = xv[m][r];
;             const f32x4 xgp = xg[m > 0 ? m - 1 : 0], xvp = xv[m > 0 ? m - 1 : 0];
;             const float g_pm = (m > 0) ? xgp[r] : 0.f, v_pm = (m > 0) ? xvp[r] : 0.f;
;             const float g1 = dpp_ror1((fr == 15) ? g_pm : g_cur), g2 = dpp_ror2((fr >= 14) ? g_pm : g_cur);
;             const float v1 = dpp_ror1((fr == 15) ? v_pm : v_cur), v2 = dpp_ror2((fr >= 14) ? v_pm : v_cur);
;             const float cg_ = bg[r] + g2 * wg0[r] + g1 * wg1[r] + g_cur * wg2[r];
;             const float cv_ = bv[r] + v2 * wv0[r] + v1 * wv1[r] + v_cur * wv2[r];
;             res[r] = cg_ * __builtin_amdgcn_rcpf(1.f + __builtin_amdgcn_exp2f(-1.4426950408889634f * cg_)) * cv_;
	v_pk_mul_f32 v[30:31], v[40:41], v[30:31]
	s_nop 0
	v_mov_b32_dpp v87, v89 row_ror:1 row_mask:0xf bank_mask:0xf
	v_cndmask_b32_e64 v89, v27, v47, s[6:7]

; __device__ __forceinline__ float dpp_ror1(float v) { return __int_as_float(__builtin_amdgcn_update_dpp(0, __float_as_int(v), 0x121, 0xf, 0xf, false)); }
; __device__ __forceinline__ float dpp_ror2(float v) { return __int_as_float(__builtin_amdgcn_update_dpp(0, __float_as_int(v), 0x122, 0xf, 0xf, false)); }
;   __device__ __forceinline__ void operator()(const AccT& acc, const Unit& u, int wr, int wc, int fr, int fq) const {
;     ...
;           for (int r = 0; r < 4; ++r) {
;             const float g_cur = xg[m][r], v_cur = xv[m][r];
;             const f32x4 xgp = xg[m > 0 ? m - 1 : 0], xvp = xv[m > 0 ? m - 1 : 0];
;             const float g_pm = (m > 0) ? xgp[r] : 0.f, v_pm = (m > 0) ? xvp[r] : 0.f;
;             const float g1 = dpp_ror1((fr == 15) ? g_pm : g_cur), g2 = dpp_ror2((fr >= 14) ? g_pm : g_cur);
;             const float v1 = dpp_ror1((fr == 15) ? v_pm : v_cur), v2 = dpp_ror2((fr >= 14) ? v_pm : v_cur);
;             const float cg_ = bg[r] + g2 * wg0[r] + g1 * wg1[r] + g_cur * wg2[r];
;             const float cv_ = bv[r] + v2 * wv0[r] + v1 * wv1[r] + v_cur * wv2[r];
;             res[r] = cg_ * __builtin_amdgcn_rcpf(1.f + __builtin_amdgcn_exp2f(-1.4426950408889634f * cg_)) * cv_;
	v_cvt_pk_bf16_f32 v30, v30, v31
	s_nop 0
	v_mov_b32_dpp v47, v89 row_ror:2 row_mask:0xf bank_mask:0xf
	v_pk_fma_f32 v[40:41], v[66:67], v[46:47], v[78:79]

; __device__ __forceinline__ float dpp_ror1(float v) { return __int_as_float(__builtin_amdgcn_update_dpp(0, __float_as_int(v), 0x121, 0xf, 0xf, false)); }
; __device__ __forceinline__ float dpp_ror2(float v) { return __int_as_float(__builtin_amdgcn_update_dpp(0, __float_as_int(v), 0x122, 0xf, 0xf, false)); }
;   __device__ __forceinline__ void operator()(const AccT& acc, const Unit& u, int wr, int wc, int fr, int fq) const {
;     ...
;           for (int r = 0; r < 4; ++r) {
;             const float g_cur = xg[m][r], v_cur = xv[m][r];
;             const f32x4 xgp = xg[m > 0 ? m - 1 : 0], xvp = xv[m > 0 ? m - 1 : 0];
;             const float g_pm = (m > 0) ? xgp[r] : 0.f, v_pm = (m > 0) ? xvp[r] : 0.f;
;             const float g1 = dpp_ror1((fr == 15) ? g_pm : g_cur), g2 = dpp_ror2((fr >= 14) ? g_pm : g_cur);
;             const float v1 = dpp_ror1((fr == 15) ? v_pm : v_cur), v2 = dpp_ror2((fr >= 14) ? v_pm : v_cur);
;             const float cg_ = bg[r] + g2 * wg0[r] + g1 * wg1[r] + g_cur * wg2[r];
;             const float cv_ = bv[r] + v2 * wv0[r] + v1 * wv1[r] + v_cur * wv2[r];
;             res[r] = cg_ * __builtin_amdgcn_rcpf(1.f + __builtin_amdgcn_exp2f(-1.4426950408889634f * cg_)) * cv_;
	v_pk_fma_f32 v[40:41], v[70:71], v[86:87], v[40:41]
	v_cndmask_b32_e64 v46, v23, v19, s[8:9]
	v_pk_fma_f32 v[40:41], v[26:27], v[62:63], v[40:41]
	v_mov_b32_dpp v89, v90 row_ror:1 row_mask:0xf bank_mask:0xf
	v_mul_f32_e32 v44, 0xbfb8aa3b, v40
	v_mul_f32_e32 v45, 0xbfb8aa3b, v41
	v_exp_f32_e32 v44, v44
	v_exp_f32_e32 v45, v45
	v_cndmask_b32_e64 v90, v19, v43, s[6:7]

; __device__ __forceinline__ float dpp_ror1(float v) { return __int_as_float(__builtin_amdgcn_update_dpp(0, __float_as_int(v), 0x121, 0xf, 0xf, false)); }
; __device__ __forceinline__ float dpp_ror2(float v) { return __int_as_float(__builtin_amdgcn_update_dpp(0, __float_as_int(v), 0x122, 0xf, 0xf, false)); }
;   __device__ __forceinline__ void operator()(const AccT& acc, const Unit& u, int wr, int wc, int fr, int fq) const {
;     ...
;           for (int r = 0; r < 4; ++r) {
;             const float g_cur = xg[m][r], v_cur = xv[m][r];
;             const f32x4 xgp = xg[m > 0 ? m - 1 : 0], xvp = xv[m > 0 ? m - 1 : 0];
;             const float g_pm = (m > 0) ? xgp[r] : 0.f, v_pm = (m > 0) ? xvp[r] : 0.f;
;             const float g1 = dpp_ror1((fr == 15) ? g_pm : g_cur), g2 = dpp_ror2((fr >= 14) ? g_pm : g_cur);
;             const float v1 = dpp_ror1((fr == 15) ? v_pm : v_cur), v2 = dpp_ror2((fr >= 14) ? v_pm : v_cur);
;             const float cg_ = bg[r] + g2 * wg0[r] + g1 * wg1[r] + g_cur * wg2[r];
;             const float cv_ = bv[r] + v2 * wv0[r] + v1 * wv1[r] + v_cur * wv2[r];
;             res[r] = cg_ * __builtin_amdgcn_rcpf(1.f + __builtin_amdgcn_exp2f(-1.4426950408889634f * cg_)) * cv_;
;           }
	v_add_f32_e32 v44, 1.0, v44
	v_add_f32_e32 v45, 1.0, v45
	v_rcp_f32_e32 v44, v44
	v_rcp_f32_e32 v45, v45
	v_mov_b32_dpp v43, v90 row_ror:2 row_mask:0xf bank_mask:0xf
	v_pk_fma_f32 v[42:43], v[54:55], v[42:43], v[74:75]
	v_pk_mul_f32 v[40:41], v[40:41], v[44:45]
	v_pk_fma_f32 v[42:43], v[58:59], v[88:89], v[42:43]

; __device__ __forceinline__ uint2 pack4(f32x4 v) { return make_uint2(pack2(v[0], v[1]), pack2(v[2], v[3])); }
; __device__ __forceinline__ float dpp_ror1(float v) { return __int_as_float(__builtin_amdgcn_update_dpp(0, __float_as_int(v), 0x121, 0xf, 0xf, false)); }
; __device__ __forceinline__ float dpp_ror2(float v) { return __int_as_float(__builtin_amdgcn_update_dpp(0, __float_as_int(v), 0x122, 0xf, 0xf, false)); }
;   __device__ __forceinline__ void operator()(const AccT& acc, const Unit& u, int wr, int wc, int fr, int fq) const {
;     ...
;           for (int r = 0; r < 4; ++r) {
;             const float g_cur = xg[m][r], v_cur = xv[m][r];
;             const f32x4 xgp = xg[m > 0 ? m - 1 : 0], xvp = xv[m > 0 ? m - 1 : 0];
;             const float g_pm = (m > 0) ? xgp[r] : 0.f, v_pm = (m > 0) ? xvp[r] : 0.f;
;             const float g1 = dpp_ror1((fr == 15) ? g_pm : g_cur), g2 = dpp_ror2((fr >= 14) ? g_pm : g_cur);
;             const float v1 = dpp_ror1((fr == 15) ? v_pm : v_cur), v2 = dpp_ror2((fr >= 14) ? v_pm : v_cur);
;             const float cg_ = bg[r] + g2 * wg0[r] + g1 * wg1[r] + g_cur * wg2[r];
;             const float cv_ = bv[r] + v2 * wv0[r] + v1 * wv1[r] + v_cur * wv2[r];
;             res[r] = cg_ * __builtin_amdgcn_rcpf(1.f + __builtin_amdgcn_exp2f(-1.4426950408889634f * cg_)) * cv_;
;           }
;           if (m > 0 || fr >= 2)
;             *(uint2*)(act + (size_t)EPI_ROW(u, ai, m) * DFF + f0) = pack4(res);
	v_pk_fma_f32 v[42:43], v[18:19], v[50:51], v[42:43]
	v_cndmask_b32_e64 v45, v21, v27, s[8:9]
	v_pk_mul_f32 v[40:41], v[42:43], v[40:41]
	v_cndmask_b32_e64 v42, v83, v17, s[8:9]
	v_cvt_pk_bf16_f32 v31, v40, v41
	global_store_dwordx2 v[130:131], v[30:31], off offset:32
	v_cndmask_b32_e64 v31, v28, v24, s[8:9]
	s_nop 0

; __device__ __forceinline__ float dpp_ror1(float v) { return __int_as_float(__builtin_amdgcn_update_dpp(0, __float_as_int(v), 0x121, 0xf, 0xf, false)); }
; __device__ __forceinline__ float dpp_ror2(float v) { return __int_as_float(__builtin_amdgcn_update_dpp(0, __float_as_int(v), 0x122, 0xf, 0xf, false)); }
;   __device__ __forceinline__ void operator()(const AccT& acc, const Unit& u, int wr, int wc, int fr, int fq) const {
;     ...
;           for (int r = 0; r < 4; ++r) {
;             const float g_cur = xg[m][r], v_cur = xv[m][r];
;             const f32x4 xgp = xg[m > 0 ? m - 1 : 0], xvp = xv[m > 0 ? m - 1 : 0];
;             const float g_pm = (m > 0) ? xgp[r] : 0.f, v_pm = (m > 0) ? xvp[r] : 0.f;
;             const float g1 = dpp_ror1((fr == 15) ? g_pm : g_cur), g2 = dpp_ror2((fr >= 14) ? g_pm : g_cur);
;             const float v1 = dpp_ror1((fr == 15) ? v_pm : v_cur), v2 = dpp_ror2((fr >= 14) ? v_pm : v_cur);
	v_cndmask_b32_e64 v41, v29, v25, s[8:9]
	v_mov_b32_dpp v30, v31 row_ror:1 row_mask:0xf bank_mask:0xf
	v_cndmask_b32_e64 v31, v28, v24, s[6:7]

; __device__ __forceinline__ float dpp_ror1(float v) { return __int_as_float(__builtin_amdgcn_update_dpp(0, __float_as_int(v), 0x121, 0xf, 0xf, false)); }
; __device__ __forceinline__ float dpp_ror2(float v) { return __int_as_float(__builtin_amdgcn_update_dpp(0, __float_as_int(v), 0x122, 0xf, 0xf, false)); }
;   __device__ __forceinline__ void operator()(const AccT& acc, const Unit& u, int wr, int wc, int fr, int fq) const {
;     ...
;           for (int r = 0; r < 4; ++r) {
;             const float g_cur = xg[m][r], v_cur = xv[m][r];
;             const f32x4 xgp = xg[m > 0 ? m - 1 : 0], xvp = xv[m > 0 ? m - 1 : 0];
;             const float g_pm = (m > 0) ? xgp[r] : 0.f, v_pm = (m > 0) ? xvp[r] : 0.f;
;             const float g1 = dpp_ror1((fr == 15) ? g_pm : g_cur), g2 = dpp_ror2((fr >= 14) ? g_pm : g_cur);
;             const float v1 = dpp_ror1((fr == 15) ? v_pm : v_cur), v2 = dpp_ror2((fr >= 14) ? v_pm : v_cur);
	v_cndmask_b32_e64 v43, v20, v26, s[8:9]
	s_nop 0
	v_mov_b32_dpp v24, v31 row_ror:2 row_mask:0xf bank_mask:0xf
	v_cndmask_b32_e64 v31, v82, v16, s[8:9]
	s_nop 1
	v_mov_b32_dpp v40, v31 row_ror:1 row_mask:0xf bank_mask:0xf
	v_cndmask_b32_e64 v31, v82, v16, s[6:7]

; __device__ __forceinline__ float dpp_ror1(float v) { return __int_as_float(__builtin_amdgcn_update_dpp(0, __float_as_int(v), 0x121, 0xf, 0xf, false)); }
; __device__ __forceinline__ float dpp_ror2(float v) { return __int_as_float(__builtin_amdgcn_update_dpp(0, __float_as_int(v), 0x122, 0xf, 0xf, false)); }
;   __device__ __forceinline__ void operator()(const AccT& acc, const Unit& u, int wr, int wc, int fr, int fq) const {
;     ...
;           for (int r = 0; r < 4; ++r) {
;             const float g_cur = xg[m][r], v_cur = xv[m][r];
;             const f32x4 xgp = xg[m > 0 ? m - 1 : 0], xvp = xv[m > 0 ? m - 1 : 0];
;             const float g_pm = (m > 0) ? xgp[r] : 0.f, v_pm = (m > 0) ? xvp[r] : 0.f;
;             const float g1 = dpp_ror1((fr == 15) ? g_pm : g_cur), g2 = dpp_ror2((fr >= 14) ? g_pm : g_cur);
;             const float v1 = dpp_ror1((fr == 15) ? v_pm : v_cur), v2 = dpp_ror2((fr >= 14) ? v_pm : v_cur);
	s_nop 1
	v_mov_b32_dpp v16, v31 row_ror:2 row_mask:0xf bank_mask:0xf

; __device__ __forceinline__ float dpp_ror1(float v) { return __int_as_float(__builtin_amdgcn_update_dpp(0, __float_as_int(v), 0x121, 0xf, 0xf, false)); }
; __device__ __forceinline__ float dpp_ror2(float v) { return __int_as_float(__builtin_amdgcn_update_dpp(0, __float_as_int(v), 0x122, 0xf, 0xf, false)); }
;   __device__ __forceinline__ void operator()(const AccT& acc, const Unit& u, int wr, int wc, int fr, int fq) const {
;     ...
;           for (int r = 0; r < 4; ++r) {
;             const float g_cur = xg[m][r], v_cur = xv[m][r];
;             const f32x4 xgp = xg[m > 0 ? m - 1 : 0], xvp = xv[m > 0 ? m - 1 : 0];
;             const float g_pm = (m > 0) ? xgp[r] : 0.f, v_pm = (m > 0) ? xvp[r] : 0.f;
;             const float g1 = dpp_ror1((fr == 15) ? g_pm : g_cur), g2 = dpp_ror2((fr >= 14) ? g_pm : g_cur);
;             const float v1 = dpp_ror1((fr == 15) ? v_pm : v_cur), v2 = dpp_ror2((fr >= 14) ? v_pm : v_cur);
	s_nop 1
	v_mov_b32_dpp v31, v41 row_ror:1 row_mask:0xf bank_mask:0xf
	v_cndmask_b32_e64 v41, v29, v25, s[6:7]

; __device__ __forceinline__ float dpp_ror1(float v) { return __int_as_float(__builtin_amdgcn_update_dpp(0, __float_as_int(v), 0x121, 0xf, 0xf, false)); }
; __device__ __forceinline__ float dpp_ror2(float v) { return __int_as_float(__builtin_amdgcn_update_dpp(0, __float_as_int(v), 0x122, 0xf, 0xf, false)); }
;   __device__ __forceinline__ void operator()(const AccT& acc, const Unit& u, int wr, int wc, int fr, int fq) const {
;     ...
;           for (int r = 0; r < 4; ++r) {
;             const float g_cur = xg[m][r], v_cur = xv[m][r];
;             const f32x4 xgp = xg[m > 0 ? m - 1 : 0], xvp = xv[m > 0 ? m - 1 : 0];
;             const float g_pm = (m > 0) ? xgp[r] : 0.f, v_pm = (m > 0) ? xvp[r] : 0.f;
;             const float g1 = dpp_ror1((fr == 15) ? g_pm : g_cur), g2 = dpp_ror2((fr >= 14) ? g_pm : g_cur);
;             const float v1 = dpp_ror1((fr == 15) ? v_pm : v_cur), v2 = dpp_ror2((fr >= 14) ? v_pm : v_cur);
;             const float cg_ = bg[r] + g2 * wg0[r] + g1 * wg1[r] + g_cur * wg2[r];
;             const float cv_ = bv[r] + v2 * wv0[r] + v1 * wv1[r] + v_cur * wv2[r];
	s_nop 1
	v_mov_b32_dpp v25, v41 row_ror:2 row_mask:0xf bank_mask:0xf
	v_pk_fma_f32 v[24:25], v[64:65], v[24:25], v[76:77]

; __device__ __forceinline__ float dpp_ror1(float v) { return __int_as_float(__builtin_amdgcn_update_dpp(0, __float_as_int(v), 0x121, 0xf, 0xf, false)); }
; __device__ __forceinline__ float dpp_ror2(float v) { return __int_as_float(__builtin_amdgcn_update_dpp(0, __float_as_int(v), 0x122, 0xf, 0xf, false)); }
;   __device__ __forceinline__ void operator()(const AccT& acc, const Unit& u, int wr, int wc, int fr, int fq) const {
;     ...
;           for (int r = 0; r < 4; ++r) {
;             const float g_cur = xg[m][r], v_cur = xv[m][r];
;             const f32x4 xgp = xg[m > 0 ? m - 1 : 0], xvp = xv[m > 0 ? m - 1 : 0];
;             const float g_pm = (m > 0) ? xgp[r] : 0.f, v_pm = (m > 0) ? xvp[r] : 0.f;
;             const float g1 = dpp_ror1((fr == 15) ? g_pm : g_cur), g2 = dpp_ror2((fr >= 14) ? g_pm : g_cur);
;             const float v1 = dpp_ror1((fr == 15) ? v_pm : v_cur), v2 = dpp_ror2((fr >= 14) ? v_pm : v_cur);
;             const float cg_ = bg[r] + g2 * wg0[r] + g1 * wg1[r] + g_cur * wg2[r];
;             const float cv_ = bv[r] + v2 * wv0[r] + v1 * wv1[r] + v_cur * wv2[r];
;             res[r] = cg_ * __builtin_amdgcn_rcpf(1.f + __builtin_amdgcn_exp2f(-1.4426950408889634f * cg_)) * cv_;
	v_pk_fma_f32 v[24:25], v[68:69], v[30:31], v[24:25]
	s_nop 0
	v_pk_fma_f32 v[24:25], v[28:29], v[60:61], v[24:25]
	v_mov_b32_dpp v41, v42 row_ror:1 row_mask:0xf bank_mask:0xf
	v_mul_f32_e32 v30, 0xbfb8aa3b, v24
	v_mul_f32_e32 v31, 0xbfb8aa3b, v25
	v_exp_f32_e32 v30, v30
	v_exp_f32_e32 v31, v31
	v_cndmask_b32_e64 v42, v83, v17, s[6:7]

; __device__ __forceinline__ float dpp_ror1(float v) { return __int_as_float(__builtin_amdgcn_update_dpp(0, __float_as_int(v), 0x121, 0xf, 0xf, false)); }
; __device__ __forceinline__ float dpp_ror2(float v) { return __int_as_float(__builtin_amdgcn_update_dpp(0, __float_as_int(v), 0x122, 0xf, 0xf, false)); }
;   __device__ __forceinline__ void operator()(const AccT& acc, const Unit& u, int wr, int wc, int fr, int fq) const {
;     ...
;         for (int m = 0; m < 4; ++m) {
;           f32x4 res;
; #pragma unroll
;           for (int r = 0; r < 4; ++r) {
;             const float g_cur = xg[m][r], v_cur = xv[m][r];
;             const f32x4 xgp = xg[m > 0 ? m - 1 : 0], xvp = xv[m > 0 ? m - 1 : 0];
;             const float g_pm = (m > 0) ? xgp[r] : 0.f, v_pm = (m > 0) ? xvp[r] : 0.f;
;             const float g1 = dpp_ror1((fr == 15) ? g_pm : g_cur), g2 = dpp_ror2((fr >= 14) ? g_pm : g_cur);
;             const float v1 = dpp_ror1((fr == 15) ? v_pm : v_cur), v2 = dpp_ror2((fr >= 14) ? v_pm : v_cur);
;             const float cg_ = bg[r] + g2 * wg0[r] + g1 * wg1[r] + g_cur * wg2[r];
;             const float cv_ = bv[r] + v2 * wv0[r] + v1 * wv1[r] + v_cur * wv2[r];
;             res[r] = cg_ * __builtin_amdgcn_rcpf(1.f + __builtin_amdgcn_exp2f(-1.4426950408889634f * cg_)) * cv_;
;           }
	v_add_f32_e32 v30, 1.0, v30
	v_add_f32_e32 v31, 1.0, v31
	v_mov_b32_dpp v17, v42 row_ror:2 row_mask:0xf bank_mask:0xf

; __device__ __forceinline__ float dpp_ror1(float v) { return __int_as_float(__builtin_amdgcn_update_dpp(0, __float_as_int(v), 0x121, 0xf, 0xf, false)); }
; __device__ __forceinline__ float dpp_ror2(float v) { return __int_as_float(__builtin_amdgcn_update_dpp(0, __float_as_int(v), 0x122, 0xf, 0xf, false)); }
;   __device__ __forceinline__ void operator()(const AccT& acc, const Unit& u, int wr, int wc, int fr, int fq) const {
;     ...
;         for (int m = 0; m < 4; ++m) {
;           f32x4 res;
; #pragma unroll
;           for (int r = 0; r < 4; ++r) {
;             const float g_cur = xg[m][r], v_cur = xv[m][r];
;             const f32x4 xgp = xg[m > 0 ? m - 1 : 0], xvp = xv[m > 0 ? m - 1 : 0];
;             const float g_pm = (m > 0) ? xgp[r] : 0.f, v_pm = (m > 0) ? xvp[r] : 0.f;
;             const float g1 = dpp_ror1((fr == 15) ? g_pm : g_cur), g2 = dpp_ror2((fr >= 14) ? g_pm : g_cur);
;             const float v1 = dpp_ror1((fr == 15) ? v_pm : v_cur), v2 = dpp_ror2((fr >= 14) ? v_pm : v_cur);
;             const float cg_ = bg[r] + g2 * wg0[r] + g1 * wg1[r] + g_cur * wg2[r];
;             const float cv_ = bv[r] + v2 * wv0[r] + v1 * wv1[r] + v_cur * wv2[r];
;             res[r] = cg_ * __builtin_amdgcn_rcpf(1.f + __builtin_amdgcn_exp2f(-1.4426950408889634f * cg_)) * cv_;
;           }
	v_rcp_f32_e32 v30, v30
	v_rcp_f32_e32 v31, v31
	v_mov_b32_dpp v42, v43 row_ror:1 row_mask:0xf bank_mask:0xf
	v_cndmask_b32_e64 v43, v20, v26, s[6:7]

; __device__ __forceinline__ float dpp_ror1(float v) { return __int_as_float(__builtin_amdgcn_update_dpp(0, __float_as_int(v), 0x121, 0xf, 0xf, false)); }
; __device__ __forceinline__ float dpp_ror2(float v) { return __int_as_float(__builtin_amdgcn_update_dpp(0, __float_as_int(v), 0x122, 0xf, 0xf, false)); }
;   __device__ __forceinline__ void operator()(const AccT& acc, const Unit& u, int wr, int wc, int fr, int fq) const {
;     ...
;         for (int m = 0; m < 4; ++m) {
;           f32x4 res;
; #pragma unroll
;           for (int r = 0; r < 4; ++r) {
;             const float g_cur = xg[m][r], v_cur = xv[m][r];
;             const f32x4 xgp = xg[m > 0 ? m - 1 : 0], xvp = xv[m > 0 ? m - 1 : 0];
;             const float g_pm = (m > 0) ? xgp[r] : 0.f, v_pm = (m > 0) ? xvp[r] : 0.f;
;             const float g1 = dpp_ror1((fr == 15) ? g_pm : g_cur), g2 = dpp_ror2((fr >= 14) ? g_pm : g_cur);
;             const float v1 = dpp_ror1((fr == 15) ? v_pm : v_cur), v2 = dpp_ror2((fr >= 14) ? v_pm : v_cur);
;             const float cg_ = bg[r] + g2 * wg0[r] + g1 * wg1[r] + g_cur * wg2[r];
;             const float cv_ = bv[r] + v2 * wv0[r] + v1 * wv1[r] + v_cur * wv2[r];
;             res[r] = cg_ * __builtin_amdgcn_rcpf(1.f + __builtin_amdgcn_exp2f(-1.4426950408889634f * cg_)) * cv_;
;           }
	v_pk_fma_f32 v[16:17], v[52:53], v[16:17], v[72:73]
	v_pk_mul_f32 v[24:25], v[24:25], v[30:31]
	v_mov_b32_dpp v26, v43 row_ror:2 row_mask:0xf bank_mask:0xf
	v_cndmask_b32_e64 v43, v22, v18, s[8:9]
	v_pk_fma_f32 v[16:17], v[56:57], v[40:41], v[16:17]
	s_nop 0
	v_mov_b32_dpp v44, v43 row_ror:1 row_mask:0xf bank_mask:0xf
	v_cndmask_b32_e64 v43, v22, v18, s[6:7]

; __device__ __forceinline__ float dpp_ror1(float v) { return __int_as_float(__builtin_amdgcn_update_dpp(0, __float_as_int(v), 0x121, 0xf, 0xf, false)); }
; __device__ __forceinline__ float dpp_ror2(float v) { return __int_as_float(__builtin_amdgcn_update_dpp(0, __float_as_int(v), 0x122, 0xf, 0xf, false)); }
;   __device__ __forceinline__ void operator()(const AccT& acc, const Unit& u, int wr, int wc, int fr, int fq) const {
;     ...
;         for (int m = 0; m < 4; ++m) {
;           f32x4 res;
; #pragma unroll
;           for (int r = 0; r < 4; ++r) {
;             const float g_cur = xg[m][r], v_cur = xv[m][r];
;             const f32x4 xgp = xg[m > 0 ? m - 1 : 0], xvp = xv[m > 0 ? m - 1 : 0];
;             const float g_pm = (m > 0) ? xgp[r] : 0.f, v_pm = (m > 0) ? xvp[r] : 0.f;
;             const float g1 = dpp_ror1((fr == 15) ? g_pm : g_cur), g2 = dpp_ror2((fr >= 14) ? g_pm : g_cur);
;             const float v1 = dpp_ror1((fr == 15) ? v_pm : v_cur), v2 = dpp_ror2((fr >= 14) ? v_pm : v_cur);
;             const float cg_ = bg[r] + g2 * wg0[r] + g1 * wg1[r] + g_cur * wg2[r];
;             const float cv_ = bv[r] + v2 * wv0[r] + v1 * wv1[r] + v_cur * wv2[r];
;             res[r] = cg_ * __builtin_amdgcn_rcpf(1.f + __builtin_amdgcn_exp2f(-1.4426950408889634f * cg_)) * cv_;
;           }
	v_pk_fma_f32 v[16:17], v[82:83], v[48:49], v[16:17]
	v_cndmask_b32_e64 v31, v39, v21, s[8:9]
	v_mov_b32_dpp v18, v43 row_ror:2 row_mask:0xf bank_mask:0xf

; __device__ __forceinline__ float dpp_ror1(float v) { return __int_as_float(__builtin_amdgcn_update_dpp(0, __float_as_int(v), 0x121, 0xf, 0xf, false)); }
; __device__ __forceinline__ float dpp_ror2(float v) { return __int_as_float(__builtin_amdgcn_update_dpp(0, __float_as_int(v), 0x122, 0xf, 0xf, false)); }
;   __device__ __forceinline__ void operator()(const AccT& acc, const Unit& u, int wr, int wc, int fr, int fq) const {
;     ...
;         for (int m = 0; m < 4; ++m) {
;           f32x4 res;
; #pragma unroll
;           for (int r = 0; r < 4; ++r) {
;             const float g_cur = xg[m][r], v_cur = xv[m][r];
;             const f32x4 xgp = xg[m > 0 ? m - 1 : 0], xvp = xv[m > 0 ? m - 1 : 0];
;             const float g_pm = (m > 0) ? xgp[r] : 0.f, v_pm = (m > 0) ? xvp[r] : 0.f;
;             const float g1 = dpp_ror1((fr == 15) ? g_pm : g_cur), g2 = dpp_ror2((fr >= 14) ? g_pm : g_cur);
;             const float v1 = dpp_ror1((fr == 15) ? v_pm : v_cur), v2 = dpp_ror2((fr >= 14) ? v_pm : v_cur);
;             const float cg_ = bg[r] + g2 * wg0[r] + g1 * wg1[r] + g_cur * wg2[r];
;             const float cv_ = bv[r] + v2 * wv0[r] + v1 * wv1[r] + v_cur * wv2[r];
;             res[r] = cg_ * __builtin_amdgcn_rcpf(1.f + __builtin_amdgcn_exp2f(-1.4426950408889634f * cg_)) * cv_;
;           }
	v_pk_mul_f32 v[16:17], v[16:17], v[24:25]
	v_cndmask_b32_e64 v40, v35, v23, s[8:9]
	v_mov_b32_dpp v43, v45 row_ror:1 row_mask:0xf bank_mask:0xf
	v_cndmask_b32_e64 v45, v21, v27, s[6:7]

; __device__ __forceinline__ float dpp_ror1(float v) { return __int_as_float(__builtin_amdgcn_update_dpp(0, __float_as_int(v), 0x121, 0xf, 0xf, false)); }
; __device__ __forceinline__ float dpp_ror2(float v) { return __int_as_float(__builtin_amdgcn_update_dpp(0, __float_as_int(v), 0x122, 0xf, 0xf, false)); }
;   __device__ __forceinline__ void operator()(const AccT& acc, const Unit& u, int wr, int wc, int fr, int fq) const {
;     ...
;         for (int m = 0; m < 4; ++m) {
;           f32x4 res;
; #pragma unroll
;           for (int r = 0; r < 4; ++r) {
;             const float g_cur = xg[m][r], v_cur = xv[m][r];
;             const f32x4 xgp = xg[m > 0 ? m - 1 : 0], xvp = xv[m > 0 ? m - 1 : 0];
;             const float g_pm = (m > 0) ? xgp[r] : 0.f, v_pm = (m > 0) ? xvp[r] : 0.f;
;             const float g1 = dpp_ror1((fr == 15) ? g_pm : g_cur), g2 = dpp_ror2((fr >= 14) ? g_pm : g_cur);
;             const float v1 = dpp_ror1((fr == 15) ? v_pm : v_cur), v2 = dpp_ror2((fr >= 14) ? v_pm : v_cur);
;             const float cg_ = bg[r] + g2 * wg0[r] + g1 * wg1[r] + g_cur * wg2[r];
;             const float cv_ = bv[r] + v2 * wv0[r] + v1 * wv1[r] + v_cur * wv2[r];
;             res[r] = cg_ * __builtin_amdgcn_rcpf(1.f + __builtin_amdgcn_exp2f(-1.4426950408889634f * cg_)) * cv_;
;           }
	v_cvt_pk_bf16_f32 v16, v16, v17
	s_nop 0
	v_mov_b32_dpp v27, v45 row_ror:2 row_mask:0xf bank_mask:0xf
	v_pk_fma_f32 v[24:25], v[66:67], v[26:27], v[78:79]

; __device__ __forceinline__ float dpp_ror1(float v) { return __int_as_float(__builtin_amdgcn_update_dpp(0, __float_as_int(v), 0x121, 0xf, 0xf, false)); }
; __device__ __forceinline__ float dpp_ror2(float v) { return __int_as_float(__builtin_amdgcn_update_dpp(0, __float_as_int(v), 0x122, 0xf, 0xf, false)); }
;   __device__ __forceinline__ void operator()(const AccT& acc, const Unit& u, int wr, int wc, int fr, int fq) const {
;     ...
;         for (int m = 0; m < 4; ++m) {
;           f32x4 res;
; #pragma unroll
;           for (int r = 0; r < 4; ++r) {
;             const float g_cur = xg[m][r], v_cur = xv[m][r];
;             const f32x4 xgp = xg[m > 0 ? m - 1 : 0], xvp = xv[m > 0 ? m - 1 : 0];
;             const float g_pm = (m > 0) ? xgp[r] : 0.f, v_pm = (m > 0) ? xvp[r] : 0.f;
;             const float g1 = dpp_ror1((fr == 15) ? g_pm : g_cur), g2 = dpp_ror2((fr >= 14) ? g_pm : g_cur);
;             const float v1 = dpp_ror1((fr == 15) ? v_pm : v_cur), v2 = dpp_ror2((fr >= 14) ? v_pm : v_cur);
;             const float cg_ = bg[r] + g2 * wg0[r] + g1 * wg1[r] + g_cur * wg2[r];
;             const float cv_ = bv[r] + v2 * wv0[r] + v1 * wv1[r] + v_cur * wv2[r];
;             res[r] = cg_ * __builtin_amdgcn_rcpf(1.f + __builtin_amdgcn_exp2f(-1.4426950408889634f * cg_)) * cv_;
;           }
	v_pk_fma_f32 v[24:25], v[70:71], v[42:43], v[24:25]
	s_nop 0
	v_pk_fma_f32 v[24:25], v[20:21], v[62:63], v[24:25]
	v_mov_b32_dpp v45, v46 row_ror:1 row_mask:0xf bank_mask:0xf
	v_mul_f32_e32 v26, 0xbfb8aa3b, v24
	v_mul_f32_e32 v27, 0xbfb8aa3b, v25
	v_exp_f32_e32 v26, v26
	v_exp_f32_e32 v27, v27
	v_cndmask_b32_e64 v46, v23, v19, s[6:7]

; __device__ __forceinline__ float dpp_ror1(float v) { return __int_as_float(__builtin_amdgcn_update_dpp(0, __float_as_int(v), 0x121, 0xf, 0xf, false)); }
; __device__ __forceinline__ float dpp_ror2(float v) { return __int_as_float(__builtin_amdgcn_update_dpp(0, __float_as_int(v), 0x122, 0xf, 0xf, false)); }
;   __device__ __forceinline__ void operator()(const AccT& acc, const Unit& u, int wr, int wc, int fr, int fq) const {
;     ...
;         for (int m = 0; m < 4; ++m) {
;           f32x4 res;
; #pragma unroll
;           for (int r = 0; r < 4; ++r) {
;             const float g_cur = xg[m][r], v_cur = xv[m][r];
;             const f32x4 xgp = xg[m > 0 ? m - 1 : 0], xvp = xv[m > 0 ? m - 1 : 0];
;             const float g_pm = (m > 0) ? xgp[r] : 0.f, v_pm = (m > 0) ? xvp[r] : 0.f;
;             const float g1 = dpp_ror1((fr == 15) ? g_pm : g_cur), g2 = dpp_ror2((fr >= 14) ? g_pm : g_cur);
;             const float v1 = dpp_ror1((fr == 15) ? v_pm : v_cur), v2 = dpp_ror2((fr >= 14) ? v_pm : v_cur);
;             const float cg_ = bg[r] + g2 * wg0[r] + g1 * wg1[r] + g_cur * wg2[r];
;             const float cv_ = bv[r] + v2 * wv0[r] + v1 * wv1[r] + v_cur * wv2[r];
;             res[r] = cg_ * __builtin_amdgcn_rcpf(1.f + __builtin_amdgcn_exp2f(-1.4426950408889634f * cg_)) * cv_;
;           }
	v_add_f32_e32 v26, 1.0, v26
	v_add_f32_e32 v27, 1.0, v27
	v_rcp_f32_e32 v26, v26
	v_rcp_f32_e32 v27, v27
	v_mov_b32_dpp v19, v46 row_ror:2 row_mask:0xf bank_mask:0xf
	v_pk_fma_f32 v[18:19], v[54:55], v[18:19], v[74:75]
	v_pk_mul_f32 v[24:25], v[24:25], v[26:27]
	v_pk_fma_f32 v[18:19], v[58:59], v[44:45], v[18:19]

; __device__ __forceinline__ float dpp_ror1(float v) { return __int_as_float(__builtin_amdgcn_update_dpp(0, __float_as_int(v), 0x121, 0xf, 0xf, false)); }
; __device__ __forceinline__ float dpp_ror2(float v) { return __int_as_float(__builtin_amdgcn_update_dpp(0, __float_as_int(v), 0x122, 0xf, 0xf, false)); }
;   __device__ __forceinline__ void operator()(const AccT& acc, const Unit& u, int wr, int wc, int fr, int fq) const {
;     ...
;         for (int m = 0; m < 4; ++m) {
;           f32x4 res;
; #pragma unroll
;           for (int r = 0; r < 4; ++r) {
;             const float g_cur = xg[m][r], v_cur = xv[m][r];
;             const f32x4 xgp = xg[m > 0 ? m - 1 : 0], xvp = xv[m > 0 ? m - 1 : 0];
;             const float g_pm = (m > 0) ? xgp[r] : 0.f, v_pm = (m > 0) ? xvp[r] : 0.f;
;             const float g1 = dpp_ror1((fr == 15) ? g_pm : g_cur), g2 = dpp_ror2((fr >= 14) ? g_pm : g_cur);
;             const float v1 = dpp_ror1((fr == 15) ? v_pm : v_cur), v2 = dpp_ror2((fr >= 14) ? v_pm : v_cur);
;             const float cg_ = bg[r] + g2 * wg0[r] + g1 * wg1[r] + g_cur * wg2[r];
;             const float cv_ = bv[r] + v2 * wv0[r] + v1 * wv1[r] + v_cur * wv2[r];
;             res[r] = cg_ * __builtin_amdgcn_rcpf(1.f + __builtin_amdgcn_exp2f(-1.4426950408889634f * cg_)) * cv_;
;           }
	v_pk_fma_f32 v[18:19], v[22:23], v[50:51], v[18:19]
	v_cndmask_b32_e64 v27, v33, v83, s[8:9]
	v_pk_mul_f32 v[18:19], v[18:19], v[24:25]

; __device__ __forceinline__ uint2 pack4(f32x4 v) { return make_uint2(pack2(v[0], v[1]), pack2(v[2], v[3])); }
; __device__ __forceinline__ float dpp_ror1(float v) { return __int_as_float(__builtin_amdgcn_update_dpp(0, __float_as_int(v), 0x121, 0xf, 0xf, false)); }
; __device__ __forceinline__ float dpp_ror2(float v) { return __int_as_float(__builtin_amdgcn_update_dpp(0, __float_as_int(v), 0x122, 0xf, 0xf, false)); }
;   __device__ __forceinline__ void operator()(const AccT& acc, const Unit& u, int wr, int wc, int fr, int fq) const {
;     ...
;         for (int m = 0; m < 4; ++m) {
;           f32x4 res;
; #pragma unroll
;           for (int r = 0; r < 4; ++r) {
;             const float g_cur = xg[m][r], v_cur = xv[m][r];
;             const f32x4 xgp = xg[m > 0 ? m - 1 : 0], xvp = xv[m > 0 ? m - 1 : 0];
;             const float g_pm = (m > 0) ? xgp[r] : 0.f, v_pm = (m > 0) ? xvp[r] : 0.f;
;             const float g1 = dpp_ror1((fr == 15) ? g_pm : g_cur), g2 = dpp_ror2((fr >= 14) ? g_pm : g_cur);
;             const float v1 = dpp_ror1((fr == 15) ? v_pm : v_cur), v2 = dpp_ror2((fr >= 14) ? v_pm : v_cur);
;             const float cg_ = bg[r] + g2 * wg0[r] + g1 * wg1[r] + g_cur * wg2[r];
;             const float cv_ = bv[r] + v2 * wv0[r] + v1 * wv1[r] + v_cur * wv2[r];
;             res[r] = cg_ * __builtin_amdgcn_rcpf(1.f + __builtin_amdgcn_exp2f(-1.4426950408889634f * cg_)) * cv_;
;           }
;           if (m > 0 || fr >= 2)
;             *(uint2*)(act + (size_t)EPI_ROW(u, ai, m) * DFF + f0) = pack4(res);
	v_cvt_pk_bf16_f32 v17, v18, v19
	global_store_dwordx2 v[128:129], v[16:17], off offset:32
	v_cndmask_b32_e64 v17, v36, v28, s[8:9]
	s_nop 0

; __device__ __forceinline__ float dpp_ror1(float v) { return __int_as_float(__builtin_amdgcn_update_dpp(0, __float_as_int(v), 0x121, 0xf, 0xf, false)); }
; __device__ __forceinline__ float dpp_ror2(float v) { return __int_as_float(__builtin_amdgcn_update_dpp(0, __float_as_int(v), 0x122, 0xf, 0xf, false)); }
;   __device__ __forceinline__ void operator()(const AccT& acc, const Unit& u, int wr, int wc, int fr, int fq) const {
;     ...
;             const f32x4 xgp = xg[m > 0 ? m - 1 : 0], xvp = xv[m > 0 ? m - 1 : 0];
;             const float g_pm = (m > 0) ? xgp[r] : 0.f, v_pm = (m > 0) ? xvp[r] : 0.f;
;             const float g1 = dpp_ror1((fr == 15) ? g_pm : g_cur), g2 = dpp_ror2((fr >= 14) ? g_pm : g_cur);
;             const float v1 = dpp_ror1((fr == 15) ? v_pm : v_cur), v2 = dpp_ror2((fr >= 14) ? v_pm : v_cur);
	v_cndmask_b32_e64 v19, v37, v29, s[8:9]
	v_mov_b32_dpp v16, v17 row_ror:1 row_mask:0xf bank_mask:0xf
	v_cndmask_b32_e64 v17, v36, v28, s[6:7]
	v_cndmask_b32_e64 v25, v37, v29, s[6:7]
	v_cndmask_b32_e64 v28, v33, v83, s[6:7]
	v_mov_b32_dpp v18, v17 row_ror:2 row_mask:0xf bank_mask:0xf
	v_cndmask_b32_e64 v17, v32, v82, s[8:9]
	v_cndmask_b32_e64 v29, v38, v20, s[8:9]
	s_nop 0
	v_mov_b32_dpp v24, v17 row_ror:1 row_mask:0xf bank_mask:0xf
	v_cndmask_b32_e64 v17, v32, v82, s[6:7]
	s_nop 1
	v_mov_b32_dpp v26, v17 row_ror:2 row_mask:0xf bank_mask:0xf

; __device__ __forceinline__ float dpp_ror1(float v) { return __int_as_float(__builtin_amdgcn_update_dpp(0, __float_as_int(v), 0x121, 0xf, 0xf, false)); }
; __device__ __forceinline__ float dpp_ror2(float v) { return __int_as_float(__builtin_amdgcn_update_dpp(0, __float_as_int(v), 0x122, 0xf, 0xf, false)); }
;   __device__ __forceinline__ void operator()(const AccT& acc, const Unit& u, int wr, int wc, int fr, int fq) const {
;     ...
;             const f32x4 xgp = xg[m > 0 ? m - 1 : 0], xvp = xv[m > 0 ? m - 1 : 0];
;             const float g_pm = (m > 0) ? xgp[r] : 0.f, v_pm = (m > 0) ? xvp[r] : 0.f;
;             const float g1 = dpp_ror1((fr == 15) ? g_pm : g_cur), g2 = dpp_ror2((fr >= 14) ? g_pm : g_cur);
;             const float v1 = dpp_ror1((fr == 15) ? v_pm : v_cur), v2 = dpp_ror2((fr >= 14) ? v_pm : v_cur);
	s_nop 1
	v_mov_b32_dpp v17, v19 row_ror:1 row_mask:0xf bank_mask:0xf

; __device__ __forceinline__ float dpp_ror1(float v) { return __int_as_float(__builtin_amdgcn_update_dpp(0, __float_as_int(v), 0x121, 0xf, 0xf, false)); }
; __device__ __forceinline__ float dpp_ror2(float v) { return __int_as_float(__builtin_amdgcn_update_dpp(0, __float_as_int(v), 0x122, 0xf, 0xf, false)); }
;   __device__ __forceinline__ void operator()(const AccT& acc, const Unit& u, int wr, int wc, int fr, int fq) const {
;     ...
;             const f32x4 xgp = xg[m > 0 ? m - 1 : 0], xvp = xv[m > 0 ? m - 1 : 0];
;             const float g_pm = (m > 0) ? xgp[r] : 0.f, v_pm = (m > 0) ? xvp[r] : 0.f;
;             const float g1 = dpp_ror1((fr == 15) ? g_pm : g_cur), g2 = dpp_ror2((fr >= 14) ? g_pm : g_cur);
;             const float v1 = dpp_ror1((fr == 15) ? v_pm : v_cur), v2 = dpp_ror2((fr >= 14) ? v_pm : v_cur);
;             const float cg_ = bg[r] + g2 * wg0[r] + g1 * wg1[r] + g_cur * wg2[r];
;             const float cv_ = bv[r] + v2 * wv0[r] + v1 * wv1[r] + v_cur * wv2[r];
;             res[r] = cg_ * __builtin_amdgcn_rcpf(1.f + __builtin_amdgcn_exp2f(-1.4426950408889634f * cg_)) * cv_;
;           }
	s_nop 1
	v_mov_b32_dpp v19, v25 row_ror:2 row_mask:0xf bank_mask:0xf
	v_pk_fma_f32 v[18:19], v[64:65], v[18:19], v[76:77]

;   __device__ __forceinline__ void operator()(const AccT& acc, const Unit& u, int wr, int wc, int fr, int fq) const {
;     ...
;             const float cg_ = bg[r] + g2 * wg0[r] + g1 * wg1[r] + g_cur * wg2[r];
;             const float cv_ = bv[r] + v2 * wv0[r] + v1 * wv1[r] + v_cur * wv2[r];
;             res[r] = cg_ * __builtin_amdgcn_rcpf(1.f + __builtin_amdgcn_exp2f(-1.4426950408889634f * cg_)) * cv_;
	v_pk_fma_f32 v[16:17], v[68:69], v[16:17], v[18:19]
	s_nop 0
	v_pk_fma_f32 v[16:17], v[36:37], v[60:61], v[16:17]
	v_mov_b32_dpp v25, v27 row_ror:1 row_mask:0xf bank_mask:0xf
	v_mul_f32_e32 v18, 0xbfb8aa3b, v16
	v_mul_f32_e32 v19, 0xbfb8aa3b, v17
	v_exp_f32_e32 v18, v18
	v_exp_f32_e32 v19, v19

; __device__ __forceinline__ float dpp_ror1(float v) { return __int_as_float(__builtin_amdgcn_update_dpp(0, __float_as_int(v), 0x121, 0xf, 0xf, false)); }
; __device__ __forceinline__ float dpp_ror2(float v) { return __int_as_float(__builtin_amdgcn_update_dpp(0, __float_as_int(v), 0x122, 0xf, 0xf, false)); }
;   __device__ __forceinline__ void operator()(const AccT& acc, const Unit& u, int wr, int wc, int fr, int fq) const {
;     ...
;             const float g1 = dpp_ror1((fr == 15) ? g_pm : g_cur), g2 = dpp_ror2((fr >= 14) ? g_pm : g_cur);
;             const float v1 = dpp_ror1((fr == 15) ? v_pm : v_cur), v2 = dpp_ror2((fr >= 14) ? v_pm : v_cur);
;             const float cg_ = bg[r] + g2 * wg0[r] + g1 * wg1[r] + g_cur * wg2[r];
;             const float cv_ = bv[r] + v2 * wv0[r] + v1 * wv1[r] + v_cur * wv2[r];
;             res[r] = cg_ * __builtin_amdgcn_rcpf(1.f + __builtin_amdgcn_exp2f(-1.4426950408889634f * cg_)) * cv_;
	v_add_f32_e32 v18, 1.0, v18
	s_nop 0
	v_mov_b32_dpp v27, v28 row_ror:2 row_mask:0xf bank_mask:0xf

; __device__ __forceinline__ float dpp_ror1(float v) { return __int_as_float(__builtin_amdgcn_update_dpp(0, __float_as_int(v), 0x121, 0xf, 0xf, false)); }
; __device__ __forceinline__ float dpp_ror2(float v) { return __int_as_float(__builtin_amdgcn_update_dpp(0, __float_as_int(v), 0x122, 0xf, 0xf, false)); }
;   __device__ __forceinline__ void operator()(const AccT& acc, const Unit& u, int wr, int wc, int fr, int fq) const {
;     ...
;             const float g1 = dpp_ror1((fr == 15) ? g_pm : g_cur), g2 = dpp_ror2((fr >= 14) ? g_pm : g_cur);
;             const float v1 = dpp_ror1((fr == 15) ? v_pm : v_cur), v2 = dpp_ror2((fr >= 14) ? v_pm : v_cur);
;             const float cg_ = bg[r] + g2 * wg0[r] + g1 * wg1[r] + g_cur * wg2[r];
;             const float cv_ = bv[r] + v2 * wv0[r] + v1 * wv1[r] + v_cur * wv2[r];
;             res[r] = cg_ * __builtin_amdgcn_rcpf(1.f + __builtin_amdgcn_exp2f(-1.4426950408889634f * cg_)) * cv_;
	v_add_f32_e32 v19, 1.0, v19
	v_rcp_f32_e32 v18, v18
	v_mov_b32_dpp v28, v29 row_ror:1 row_mask:0xf bank_mask:0xf
	v_cndmask_b32_e64 v29, v38, v20, s[6:7]

; __device__ __forceinline__ float dpp_ror1(float v) { return __int_as_float(__builtin_amdgcn_update_dpp(0, __float_as_int(v), 0x121, 0xf, 0xf, false)); }
; __device__ __forceinline__ float dpp_ror2(float v) { return __int_as_float(__builtin_amdgcn_update_dpp(0, __float_as_int(v), 0x122, 0xf, 0xf, false)); }
;   __device__ __forceinline__ void operator()(const AccT& acc, const Unit& u, int wr, int wc, int fr, int fq) const {
;     ...
;             const float g1 = dpp_ror1((fr == 15) ? g_pm : g_cur), g2 = dpp_ror2((fr >= 14) ? g_pm : g_cur);
;             const float v1 = dpp_ror1((fr == 15) ? v_pm : v_cur), v2 = dpp_ror2((fr >= 14) ? v_pm : v_cur);
;             const float cg_ = bg[r] + g2 * wg0[r] + g1 * wg1[r] + g_cur * wg2[r];
;             const float cv_ = bv[r] + v2 * wv0[r] + v1 * wv1[r] + v_cur * wv2[r];
;             res[r] = cg_ * __builtin_amdgcn_rcpf(1.f + __builtin_amdgcn_exp2f(-1.4426950408889634f * cg_)) * cv_;
	v_rcp_f32_e32 v19, v19
	v_pk_fma_f32 v[26:27], v[52:53], v[26:27], v[72:73]
	v_mov_b32_dpp v20, v29 row_ror:2 row_mask:0xf bank_mask:0xf
	v_cndmask_b32_e64 v29, v34, v22, s[8:9]
	v_pk_mul_f32 v[16:17], v[16:17], v[18:19]
	v_pk_fma_f32 v[24:25], v[56:57], v[24:25], v[26:27]
	v_mov_b32_dpp v30, v29 row_ror:1 row_mask:0xf bank_mask:0xf
	v_cndmask_b32_e64 v29, v34, v22, s[6:7]

; __device__ __forceinline__ float dpp_ror1(float v) { return __int_as_float(__builtin_amdgcn_update_dpp(0, __float_as_int(v), 0x121, 0xf, 0xf, false)); }
; __device__ __forceinline__ float dpp_ror2(float v) { return __int_as_float(__builtin_amdgcn_update_dpp(0, __float_as_int(v), 0x122, 0xf, 0xf, false)); }
;   __device__ __forceinline__ void operator()(const AccT& acc, const Unit& u, int wr, int wc, int fr, int fq) const {
;     ...
;             const float g1 = dpp_ror1((fr == 15) ? g_pm : g_cur), g2 = dpp_ror2((fr >= 14) ? g_pm : g_cur);
;             const float v1 = dpp_ror1((fr == 15) ? v_pm : v_cur), v2 = dpp_ror2((fr >= 14) ? v_pm : v_cur);
;             const float cg_ = bg[r] + g2 * wg0[r] + g1 * wg1[r] + g_cur * wg2[r];
;             const float cv_ = bv[r] + v2 * wv0[r] + v1 * wv1[r] + v_cur * wv2[r];
	v_pk_fma_f32 v[24:25], v[32:33], v[48:49], v[24:25]
	s_nop 0
	v_mov_b32_dpp v22, v29 row_ror:2 row_mask:0xf bank_mask:0xf

; __device__ __forceinline__ float dpp_ror1(float v) { return __int_as_float(__builtin_amdgcn_update_dpp(0, __float_as_int(v), 0x121, 0xf, 0xf, false)); }
; __device__ __forceinline__ float dpp_ror2(float v) { return __int_as_float(__builtin_amdgcn_update_dpp(0, __float_as_int(v), 0x122, 0xf, 0xf, false)); }
;   __device__ __forceinline__ void operator()(const AccT& acc, const Unit& u, int wr, int wc, int fr, int fq) const {
;     ...
;             const float g1 = dpp_ror1((fr == 15) ? g_pm : g_cur), g2 = dpp_ror2((fr >= 14) ? g_pm : g_cur);
;             const float v1 = dpp_ror1((fr == 15) ? v_pm : v_cur), v2 = dpp_ror2((fr >= 14) ? v_pm : v_cur);
;             const float cg_ = bg[r] + g2 * wg0[r] + g1 * wg1[r] + g_cur * wg2[r];
;             const float cv_ = bv[r] + v2 * wv0[r] + v1 * wv1[r] + v_cur * wv2[r];
;             res[r] = cg_ * __builtin_amdgcn_rcpf(1.f + __builtin_amdgcn_exp2f(-1.4426950408889634f * cg_)) * cv_;
	v_pk_mul_f32 v[16:17], v[24:25], v[16:17]
	s_nop 0
	v_mov_b32_dpp v29, v31 row_ror:1 row_mask:0xf bank_mask:0xf
	v_cndmask_b32_e64 v31, v39, v21, s[6:7]

; __device__ __forceinline__ uint2 pack4(f32x4 v) { return make_uint2(pack2(v[0], v[1]), pack2(v[2], v[3])); }
; __device__ __forceinline__ float dpp_ror1(float v) { return __int_as_float(__builtin_amdgcn_update_dpp(0, __float_as_int(v), 0x121, 0xf, 0xf, false)); }
; __device__ __forceinline__ float dpp_ror2(float v) { return __int_as_float(__builtin_amdgcn_update_dpp(0, __float_as_int(v), 0x122, 0xf, 0xf, false)); }
;   __device__ __forceinline__ void operator()(const AccT& acc, const Unit& u, int wr, int wc, int fr, int fq) const {
;     ...
;             const float g1 = dpp_ror1((fr == 15) ? g_pm : g_cur), g2 = dpp_ror2((fr >= 14) ? g_pm : g_cur);
;             const float v1 = dpp_ror1((fr == 15) ? v_pm : v_cur), v2 = dpp_ror2((fr >= 14) ? v_pm : v_cur);
;             const float cg_ = bg[r] + g2 * wg0[r] + g1 * wg1[r] + g_cur * wg2[r];
;             const float cv_ = bv[r] + v2 * wv0[r] + v1 * wv1[r] + v_cur * wv2[r];
;             res[r] = cg_ * __builtin_amdgcn_rcpf(1.f + __builtin_amdgcn_exp2f(-1.4426950408889634f * cg_)) * cv_;
;           }
;           if (m > 0 || fr >= 2)
;             *(uint2*)(act + (size_t)EPI_ROW(u, ai, m) * DFF + f0) = pack4(res);
	v_cvt_pk_bf16_f32 v16, v16, v17
	s_nop 0
	v_mov_b32_dpp v21, v31 row_ror:2 row_mask:0xf bank_mask:0xf
	v_pk_fma_f32 v[18:19], v[66:67], v[20:21], v[78:79]

;   __device__ __forceinline__ void operator()(const AccT& acc, const Unit& u, int wr, int wc, int fr, int fq) const {
;     ...
;             const float cg_ = bg[r] + g2 * wg0[r] + g1 * wg1[r] + g_cur * wg2[r];
;             const float cv_ = bv[r] + v2 * wv0[r] + v1 * wv1[r] + v_cur * wv2[r];
;             res[r] = cg_ * __builtin_amdgcn_rcpf(1.f + __builtin_amdgcn_exp2f(-1.4426950408889634f * cg_)) * cv_;
	v_pk_fma_f32 v[18:19], v[70:71], v[28:29], v[18:19]
	s_nop 0
	v_pk_fma_f32 v[18:19], v[38:39], v[62:63], v[18:19]
	v_mov_b32_dpp v31, v40 row_ror:1 row_mask:0xf bank_mask:0xf
	v_mul_f32_e32 v20, 0xbfb8aa3b, v18
	v_mul_f32_e32 v21, 0xbfb8aa3b, v19
	v_exp_f32_e32 v20, v20
	v_exp_f32_e32 v21, v21
	v_cndmask_b32_e64 v40, v35, v23, s[6:7]

; __device__ __forceinline__ uint2 pack4(f32x4 v) { return make_uint2(pack2(v[0], v[1]), pack2(v[2], v[3])); }
;   __device__ __forceinline__ void operator()(const AccT& acc, const Unit& u, int wr, int wc, int fr, int fq) const {
;     ...
;             const float cg_ = bg[r] + g2 * wg0[r] + g1 * wg1[r] + g_cur * wg2[r];
;             const float cv_ = bv[r] + v2 * wv0[r] + v1 * wv1[r] + v_cur * wv2[r];
;             res[r] = cg_ * __builtin_amdgcn_rcpf(1.f + __builtin_amdgcn_exp2f(-1.4426950408889634f * cg_)) * cv_;
;           }
;           if (m > 0 || fr >= 2)
;             *(uint2*)(act + (size_t)EPI_ROW(u, ai, m) * DFF + f0) = pack4(res);
	v_add_f32_e32 v20, 1.0, v20
	v_add_f32_e32 v21, 1.0, v21
	v_rcp_f32_e32 v20, v20
	v_rcp_f32_e32 v21, v21
	v_mov_b32_dpp v23, v40 row_ror:2 row_mask:0xf bank_mask:0xf
	v_pk_fma_f32 v[22:23], v[54:55], v[22:23], v[74:75]
	v_pk_mul_f32 v[18:19], v[18:19], v[20:21]
	v_pk_fma_f32 v[22:23], v[58:59], v[30:31], v[22:23]
	s_nop 0
	v_pk_fma_f32 v[22:23], v[34:35], v[50:51], v[22:23]
	s_nop 0
	v_pk_mul_f32 v[18:19], v[22:23], v[18:19]
	s_nop 0
	v_cvt_pk_bf16_f32 v17, v18, v19
	global_store_dwordx2 v[80:81], v[16:17], off offset:32
	s_cbranch_vccnz .LBB0_514

; __device__ __forceinline__ float dpp_ror1(float v) { return __int_as_float(__builtin_amdgcn_update_dpp(0, __float_as_int(v), 0x121, 0xf, 0xf, false)); }
; __device__ __forceinline__ float dpp_ror2(float v) { return __int_as_float(__builtin_amdgcn_update_dpp(0, __float_as_int(v), 0x122, 0xf, 0xf, false)); }
;   __device__ __forceinline__ void operator()(const AccT& acc, const Unit& u, int wr, int wc, int fr, int fq) const {
;     ...
;             const f32x4 xgp = xg[m > 0 ? m - 1 : 0], xvp = xv[m > 0 ? m - 1 : 0];
;             const float g_pm = (m > 0) ? xgp[r] : 0.f, v_pm = (m > 0) ? xvp[r] : 0.f;
;             const float g1 = dpp_ror1((fr == 15) ? g_pm : g_cur), g2 = dpp_ror2((fr >= 14) ? g_pm : g_cur);
;             const float v1 = dpp_ror1((fr == 15) ? v_pm : v_cur), v2 = dpp_ror2((fr >= 14) ? v_pm : v_cur);
.LBB0_486:
	s_or_b64 exec, exec, s[38:39]
	v_cndmask_b32_e64 v232, v172, 0, s[8:9]
	s_nop 0
	s_nop 0

; __device__ __forceinline__ float dpp_ror1(float v) { return __int_as_float(__builtin_amdgcn_update_dpp(0, __float_as_int(v), 0x121, 0xf, 0xf, false)); }
; __device__ __forceinline__ float dpp_ror2(float v) { return __int_as_float(__builtin_amdgcn_update_dpp(0, __float_as_int(v), 0x122, 0xf, 0xf, false)); }
;   __device__ __forceinline__ void operator()(const AccT& acc, const Unit& u, int wr, int wc, int fr, int fq) const {
;     ...
;             const f32x4 xgp = xg[m > 0 ? m - 1 : 0], xvp = xv[m > 0 ? m - 1 : 0];
;             const float g_pm = (m > 0) ? xgp[r] : 0.f, v_pm = (m > 0) ? xvp[r] : 0.f;
;             const float g1 = dpp_ror1((fr == 15) ? g_pm : g_cur), g2 = dpp_ror2((fr >= 14) ? g_pm : g_cur);
;             const float v1 = dpp_ror1((fr == 15) ? v_pm : v_cur), v2 = dpp_ror2((fr >= 14) ? v_pm : v_cur);
	v_mov_b32_dpp v242, v232 row_ror:1 row_mask:0xf bank_mask:0xf
	v_mov_b32_dpp v244, v231 row_ror:2 row_mask:0xf bank_mask:0xf
	v_cndmask_b32_e64 v231, v168, 0, s[8:9]

; __device__ __forceinline__ float dpp_ror1(float v) { return __int_as_float(__builtin_amdgcn_update_dpp(0, __float_as_int(v), 0x121, 0xf, 0xf, false)); }
; __device__ __forceinline__ float dpp_ror2(float v) { return __int_as_float(__builtin_amdgcn_update_dpp(0, __float_as_int(v), 0x122, 0xf, 0xf, false)); }
;   __device__ __forceinline__ void operator()(const AccT& acc, const Unit& u, int wr, int wc, int fr, int fq) const {
;     ...
;             const f32x4 xgp = xg[m > 0 ? m - 1 : 0], xvp = xv[m > 0 ? m - 1 : 0];
;             const float g_pm = (m > 0) ? xgp[r] : 0.f, v_pm = (m > 0) ? xvp[r] : 0.f;
;             const float g1 = dpp_ror1((fr == 15) ? g_pm : g_cur), g2 = dpp_ror2((fr >= 14) ? g_pm : g_cur);
;             const float v1 = dpp_ror1((fr == 15) ? v_pm : v_cur), v2 = dpp_ror2((fr >= 14) ? v_pm : v_cur);
	v_mov_b32_dpp v240, v230 row_ror:2 row_mask:0xf bank_mask:0xf
	v_cndmask_b32_e64 v230, v173, 0, s[8:9]
	s_nop 0


; __device__ __forceinline__ float dpp_ror1(float v) { return __int_as_float(__builtin_amdgcn_update_dpp(0, __float_as_int(v), 0x121, 0xf, 0xf, false)); }
; __device__ __forceinline__ float dpp_ror2(float v) { return __int_as_float(__builtin_amdgcn_update_dpp(0, __float_as_int(v), 0x122, 0xf, 0xf, false)); }
;   __device__ __forceinline__ void operator()(const AccT& acc, const Unit& u, int wr, int wc, int fr, int fq) const {
;     ...
;             const f32x4 xgp = xg[m > 0 ? m - 1 : 0], xvp = xv[m > 0 ? m - 1 : 0];
;             const float g_pm = (m > 0) ? xgp[r] : 0.f, v_pm = (m > 0) ? xvp[r] : 0.f;
;             const float g1 = dpp_ror1((fr == 15) ? g_pm : g_cur), g2 = dpp_ror2((fr >= 14) ? g_pm : g_cur);
;             const float v1 = dpp_ror1((fr == 15) ? v_pm : v_cur), v2 = dpp_ror2((fr >= 14) ? v_pm : v_cur);
	v_mov_b32_dpp v236, v231 row_ror:1 row_mask:0xf bank_mask:0xf
	v_mov_b32_dpp v243, v230 row_ror:1 row_mask:0xf bank_mask:0xf
	v_mov_b32_dpp v245, v229 row_ror:2 row_mask:0xf bank_mask:0xf
	v_cndmask_b32_e64 v229, v169, 0, s[8:9]

; __device__ __forceinline__ float dpp_ror1(float v) { return __int_as_float(__builtin_amdgcn_update_dpp(0, __float_as_int(v), 0x121, 0xf, 0xf, false)); }
; __device__ __forceinline__ float dpp_ror2(float v) { return __int_as_float(__builtin_amdgcn_update_dpp(0, __float_as_int(v), 0x122, 0xf, 0xf, false)); }
;   __device__ __forceinline__ void operator()(const AccT& acc, const Unit& u, int wr, int wc, int fr, int fq) const {
;     ...
;             const f32x4 xgp = xg[m > 0 ? m - 1 : 0], xvp = xv[m > 0 ? m - 1 : 0];
;             const float g_pm = (m > 0) ? xgp[r] : 0.f, v_pm = (m > 0) ? xvp[r] : 0.f;
;             const float g1 = dpp_ror1((fr == 15) ? g_pm : g_cur), g2 = dpp_ror2((fr >= 14) ? g_pm : g_cur);
;             const float v1 = dpp_ror1((fr == 15) ? v_pm : v_cur), v2 = dpp_ror2((fr >= 14) ? v_pm : v_cur);
	v_mov_b32_dpp v241, v223 row_ror:2 row_mask:0xf bank_mask:0xf
	v_cndmask_b32_e64 v223, v174, 0, s[8:9]

; __device__ __forceinline__ float dpp_ror1(float v) { return __int_as_float(__builtin_amdgcn_update_dpp(0, __float_as_int(v), 0x121, 0xf, 0xf, false)); }
; __device__ __forceinline__ float dpp_ror2(float v) { return __int_as_float(__builtin_amdgcn_update_dpp(0, __float_as_int(v), 0x122, 0xf, 0xf, false)); }
;   __device__ __forceinline__ void operator()(const AccT& acc, const Unit& u, int wr, int wc, int fr, int fq) const {
;     ...
;             const f32x4 xgp = xg[m > 0 ? m - 1 : 0], xvp = xv[m > 0 ? m - 1 : 0];
;             const float g_pm = (m > 0) ? xgp[r] : 0.f, v_pm = (m > 0) ? xvp[r] : 0.f;
;             const float g1 = dpp_ror1((fr == 15) ? g_pm : g_cur), g2 = dpp_ror2((fr >= 14) ? g_pm : g_cur);
;             const float v1 = dpp_ror1((fr == 15) ? v_pm : v_cur), v2 = dpp_ror2((fr >= 14) ? v_pm : v_cur);
	v_mov_b32_dpp v238, v219 row_ror:2 row_mask:0xf bank_mask:0xf
	v_cndmask_b32_e64 v219, v170, 0, s[8:9]

; __device__ __forceinline__ float dpp_ror1(float v) { return __int_as_float(__builtin_amdgcn_update_dpp(0, __float_as_int(v), 0x121, 0xf, 0xf, false)); }
; __device__ __forceinline__ float dpp_ror2(float v) { return __int_as_float(__builtin_amdgcn_update_dpp(0, __float_as_int(v), 0x122, 0xf, 0xf, false)); }
;   __device__ __forceinline__ void operator()(const AccT& acc, const Unit& u, int wr, int wc, int fr, int fq) const {
;     ...
;             const f32x4 xgp = xg[m > 0 ? m - 1 : 0], xvp = xv[m > 0 ? m - 1 : 0];
;             const float g_pm = (m > 0) ? xgp[r] : 0.f, v_pm = (m > 0) ? xvp[r] : 0.f;
;             const float g1 = dpp_ror1((fr == 15) ? g_pm : g_cur), g2 = dpp_ror2((fr >= 14) ? g_pm : g_cur);
;             const float v1 = dpp_ror1((fr == 15) ? v_pm : v_cur), v2 = dpp_ror2((fr >= 14) ? v_pm : v_cur);
	v_mov_b32_dpp v232, v215 row_ror:2 row_mask:0xf bank_mask:0xf
	v_cndmask_b32_e64 v215, v175, 0, s[8:9]

; __device__ __forceinline__ float dpp_ror1(float v) { return __int_as_float(__builtin_amdgcn_update_dpp(0, __float_as_int(v), 0x121, 0xf, 0xf, false)); }
; __device__ __forceinline__ float dpp_ror2(float v) { return __int_as_float(__builtin_amdgcn_update_dpp(0, __float_as_int(v), 0x122, 0xf, 0xf, false)); }
;   __device__ __forceinline__ void operator()(const AccT& acc, const Unit& u, int wr, int wc, int fr, int fq) const {
;     ...
;             const f32x4 xgp = xg[m > 0 ? m - 1 : 0], xvp = xv[m > 0 ? m - 1 : 0];
;             const float g_pm = (m > 0) ? xgp[r] : 0.f, v_pm = (m > 0) ? xvp[r] : 0.f;
;             const float g1 = dpp_ror1((fr == 15) ? g_pm : g_cur), g2 = dpp_ror2((fr >= 14) ? g_pm : g_cur);
;             const float v1 = dpp_ror1((fr == 15) ? v_pm : v_cur), v2 = dpp_ror2((fr >= 14) ? v_pm : v_cur);
	v_mov_b32_dpp v239, v213 row_ror:2 row_mask:0xf bank_mask:0xf
	v_cndmask_b32_e64 v213, v171, 0, s[8:9]


; __device__ __forceinline__ uint2 pack4(f32x4 v) { return make_uint2(pack2(v[0], v[1]), pack2(v[2], v[3])); }
; __device__ __forceinline__ float dpp_ror1(float v) { return __int_as_float(__builtin_amdgcn_update_dpp(0, __float_as_int(v), 0x121, 0xf, 0xf, false)); }
; __device__ __forceinline__ float dpp_ror2(float v) { return __int_as_float(__builtin_amdgcn_update_dpp(0, __float_as_int(v), 0x122, 0xf, 0xf, false)); }
; __device__ __forceinline__ float rstd_of(const unsigned long long* rowss, int row) {
;   return rsqrtf((float)rowss[row] * (1.f / (SS_FIX * DM)) + 1e-6f);
;   __device__ __forceinline__ void operator()(const AccT& acc, const Unit& u, int wr, int wc, int fr, int fq) const {
;     ...
;             const f32x4 xgp = xg[m > 0 ? m - 1 : 0], xvp = xv[m > 0 ? m - 1 : 0];
;             const float g_pm = (m > 0) ? xgp[r] : 0.f, v_pm = (m > 0) ? xvp[r] : 0.f;
;             const float g1 = dpp_ror1((fr == 15) ? g_pm : g_cur), g2 = dpp_ror2((fr >= 14) ? g_pm : g_cur);
;             const float v1 = dpp_ror1((fr == 15) ? v_pm : v_cur), v2 = dpp_ror2((fr >= 14) ? v_pm : v_cur);
;             const float cg_ = bg[r] + g2 * wg0[r] + g1 * wg1[r] + g_cur * wg2[r];
;             const float cv_ = bv[r] + v2 * wv0[r] + v1 * wv1[r] + v_cur * wv2[r];
;             res[r] = cg_ * __builtin_amdgcn_rcpf(1.f + __builtin_amdgcn_exp2f(-1.4426950408889634f * cg_)) * cv_;
;           }
;           if (m > 0 || fr >= 2)
;             *(uint2*)(act + (size_t)EPI_ROW(u, ai, m) * DFF + f0) = pack4(res);
	v_mov_b32_dpp v237, v229 row_ror:1 row_mask:0xf bank_mask:0xf
	v_mov_b32_dpp v234, v223 row_ror:1 row_mask:0xf bank_mask:0xf
	v_mov_b32_dpp v230, v219 row_ror:1 row_mask:0xf bank_mask:0xf
	v_mov_b32_dpp v235, v215 row_ror:1 row_mask:0xf bank_mask:0xf
	v_mov_b32_dpp v231, v213 row_ror:1 row_mask:0xf bank_mask:0xf
	v_mov_b32_dpp v233, v199 row_ror:2 row_mask:0xf bank_mask:0xf
	s_and_saveexec_b64 s[34:35], s[4:5]
	s_xor_b64 s[38:39], exec, s[34:35]
	s_andn2_saveexec_b64 s[38:39], s[38:39]
	s_cbranch_execz .LBB0_490
	v_pk_fma_f32 v[244:245], v[128:129], v[244:245], v[156:157]
	v_pk_fma_f32 v[238:239], v[130:131], v[238:239], v[158:159]
	v_pk_fma_f32 v[242:243], v[132:133], v[242:243], v[244:245]
	v_pk_fma_f32 v[234:235], v[134:135], v[234:235], v[238:239]
	v_pk_fma_f32 v[242:243], v[136:137], v[172:173], v[242:243]
	v_pk_fma_f32 v[234:235], v[138:139], v[174:175], v[234:235]
	v_mul_f32_e32 v199, 0xbfb8aa3b, v242
	v_exp_f32_e32 v199, v199
	v_mul_f32_e32 v213, 0xbfb8aa3b, v243
	v_exp_f32_e32 v213, v213
	v_pk_fma_f32 v[232:233], v[142:143], v[232:233], v[154:155]
	v_add_f32_e32 v199, 1.0, v199
	v_rcp_f32_e32 v244, v199
	v_add_f32_e32 v213, 1.0, v213
	v_mul_f32_e32 v199, 0xbfb8aa3b, v234
	v_rcp_f32_e32 v245, v213
	v_exp_f32_e32 v199, v199
	v_mul_f32_e32 v213, 0xbfb8aa3b, v235
	v_exp_f32_e32 v213, v213
	v_pk_fma_f32 v[230:231], v[146:147], v[230:231], v[232:233]
	v_add_f32_e32 v199, 1.0, v199
	v_rcp_f32_e32 v238, v199
	v_add_f32_e32 v199, 1.0, v213
	v_rcp_f32_e32 v239, v199
	v_pk_fma_f32 v[240:241], v[140:141], v[240:241], v[152:153]
	v_pk_fma_f32 v[230:231], v[150:151], v[170:171], v[230:231]
	v_pk_fma_f32 v[236:237], v[144:145], v[236:237], v[240:241]
	v_pk_mul_f32 v[232:233], v[234:235], v[238:239]
	v_pk_fma_f32 v[236:237], v[148:149], v[168:169], v[236:237]
	v_pk_mul_f32 v[230:231], v[230:231], v[232:233]
	v_pk_mul_f32 v[240:241], v[242:243], v[244:245]
	v_cvt_pk_bf16_f32 v233, v230, v231
	v_mov_b64_e32 v[230:231], s[52:53]
	v_pk_mul_f32 v[236:237], v[236:237], v[240:241]
	v_mad_i64_i32 v[230:231], s[34:35], v198, s0, v[230:231]
	v_cvt_pk_bf16_f32 v232, v236, v237
	v_lshl_add_u64 v[230:231], v[188:189], 1, v[230:231]
	global_store_dwordx2 v[230:231], v[232:233], off
.LBB0_490:
	s_or_b64 exec, exec, s[38:39]
	v_ffbh_u32_e32 v199, v225
	v_min_u32_e32 v199, 32, v199
	v_lshlrev_b64 v[224:225], v199, v[224:225]
	v_min_u32_e32 v215, 1, v224
	v_or_b32_e32 v215, v225, v215
	v_cvt_f32_u32_e32 v215, v215
	v_sub_u32_e32 v199, 32, v199


; __device__ __forceinline__ float rstd_of(const unsigned long long* rowss, int row) {
;   return rsqrtf((float)rowss[row] * (1.f / (SS_FIX * DM)) + 1e-6f);
	v_ldexp_f32 v199, v215, v199
	v_fmamk_f32 v199, v199, 0x2e800000, v252
	v_cmp_gt_f32_e32 vcc, s96, v199
	v_mul_f32_e32 v215, 0x4b800000, v199
	s_nop 0
	v_cndmask_b32_e32 v199, v199, v215, vcc
	v_rsq_f32_e32 v199, v199


; __device__ __forceinline__ float dpp_ror1(float v) { return __int_as_float(__builtin_amdgcn_update_dpp(0, __float_as_int(v), 0x121, 0xf, 0xf, false)); }
; __device__ __forceinline__ float rstd_of(const unsigned long long* rowss, int row) {
;   return rsqrtf((float)rowss[row] * (1.f / (SS_FIX * DM)) + 1e-6f);
;   __device__ __forceinline__ void operator()(const AccT& acc, const Unit& u, int wr, int wc, int fr, int fq) const {
;     ...
;       for (int m = 0; m < 4; ++m) rs[m] = rstd_of(rowss, EPI_ROW(u, ai, m));
;       const int chunk = 4 * u.pm + 2 * ai + wr;
; #pragma unroll
;       for (int n = 0; n < 2; ++n) {
;         const int f0 = 128 * u.pn + 32 * wc + 16 * n + 4 * fq;
;         const int gc = u.pn * 256 + 32 * wc + 16 * n + 4 * fq;
;         const f32x4 wg0 = *(const f32x4*)(cw + f0), wg1 = *(const f32x4*)(cw + NUP + f0), wg2 = *(const f32x4*)(cw + 2 * NUP + f0);
;         const f32x4 wv0 = *(const f32x4*)(cw + DFF + f0), wv1 = *(const f32x4*)(cw + NUP + DFF + f0), wv2 = *(const f32x4*)(cw + 2 * NUP + DFF + f0);
;         const f32x4 bg = *(const f32x4*)(cb + f0), bv = *(const f32x4*)(cb + DFF + f0);
;         f32x4 xg[4], xv[4];
; #pragma unroll
;         for (int m = 0; m < 4; ++m) { xg[m] = acc[ai][0][m][n] * rs[m]; xv[m] = acc[ai][1][m][n] * rs[m]; }
;         if (fr < 2) {
;           float* d = ub + ((size_t)(chunk * 4 + fr) * NUP + gc);
;           *(float4*)d = make_float4(xg[0][0], xg[0][1], xg[0][2], xg[0][3]);
;           *(float4*)(d + 128) = make_float4(xv[0][0], xv[0][1], xv[0][2], xv[0][3]);
;         }
;         if (fr >= 14) {
;           float* d = ub + ((size_t)(chunk * 4 + 2 + (fr - 14)) * NUP + gc);
;           *(float4*)d = make_float4(xg[3][0], xg[3][1], xg[3][2], xg[3][3]);
;           *(float4*)(d + 128) = make_float4(xv[3][0], xv[3][1], xv[3][2], xv[3][3]);
;         }
; #pragma unroll
;         for (int m = 0; m < 4; ++m) {
;           f32x4 res;
; #pragma unroll
;           for (int r = 0; r < 4; ++r) {
;             const float g_cur = xg[m][r], v_cur = xv[m][r];
;             const f32x4 xgp = xg[m > 0 ? m - 1 : 0], xvp = xv[m > 0 ? m - 1 : 0];
;             const float g_pm = (m > 0) ? xgp[r] : 0.f, v_pm = (m > 0) ? xvp[r] : 0.f;
;             const float g1 = dpp_ror1((fr == 15) ? g_pm : g_cur), g2 = dpp_ror2((fr >= 14) ? g_pm : g_cur);
	v_mov_b32_e32 v213, v212
	v_mul_f32_e32 v215, 0x45800000, v199
	v_cndmask_b32_e32 v224, v199, v215, vcc
	v_ffbh_u32_e32 v199, v227
	v_min_u32_e32 v199, 32, v199
	v_lshlrev_b64 v[226:227], v199, v[226:227]
	v_min_u32_e32 v215, 1, v226
	v_or_b32_e32 v215, v227, v215
	v_cvt_f32_u32_e32 v215, v215
	v_sub_u32_e32 v199, 32, v199
	v_pk_mul_f32 v[230:231], v[124:125], v[224:225] op_sel_hi:[1,0]
	v_pk_mul_f32 v[124:125], v[118:119], v[224:225] op_sel_hi:[1,0]
	v_ldexp_f32 v199, v215, v199
	v_fmamk_f32 v199, v199, 0x2e800000, v252
	v_cmp_gt_f32_e32 vcc, s96, v199
	v_mul_f32_e32 v215, 0x4b800000, v199
	v_pk_mul_f32 v[232:233], v[116:117], v[224:225] op_sel_hi:[1,0]
	v_cndmask_b32_e32 v199, v199, v215, vcc
	v_rsq_f32_e32 v199, v199
	v_pk_mul_f32 v[126:127], v[126:127], v[224:225] op_sel_hi:[1,0]
	v_pk_mul_f32 v[108:109], v[108:109], v[212:213]
	v_pk_mul_f32 v[104:105], v[104:105], v[212:213]
	v_mul_f32_e32 v215, 0x45800000, v199
	v_cndmask_b32_e32 v226, v199, v215, vcc
	v_pk_mul_f32 v[118:119], v[120:121], v[226:227] op_sel_hi:[1,0]
	v_cndmask_b32_e64 v121, v230, v172, s[8:9]
	s_nop 0
	v_pk_mul_f32 v[116:117], v[122:123], v[226:227] op_sel_hi:[1,0]

; __device__ __forceinline__ float dpp_ror1(float v) { return __int_as_float(__builtin_amdgcn_update_dpp(0, __float_as_int(v), 0x121, 0xf, 0xf, false)); }
; __device__ __forceinline__ float dpp_ror2(float v) { return __int_as_float(__builtin_amdgcn_update_dpp(0, __float_as_int(v), 0x122, 0xf, 0xf, false)); }
;   __device__ __forceinline__ void operator()(const AccT& acc, const Unit& u, int wr, int wc, int fr, int fq) const {
;     ...
;             const f32x4 xgp = xg[m > 0 ? m - 1 : 0], xvp = xv[m > 0 ? m - 1 : 0];
;             const float g_pm = (m > 0) ? xgp[r] : 0.f, v_pm = (m > 0) ? xvp[r] : 0.f;
;             const float g1 = dpp_ror1((fr == 15) ? g_pm : g_cur), g2 = dpp_ror2((fr >= 14) ? g_pm : g_cur);
;             const float v1 = dpp_ror1((fr == 15) ? v_pm : v_cur), v2 = dpp_ror2((fr >= 14) ? v_pm : v_cur);
	v_mov_b32_dpp v120, v121 row_ror:1 row_mask:0xf bank_mask:0xf
	v_cndmask_b32_e64 v121, v230, v172, s[6:7]
	s_nop 0
	v_cndmask_b32_e64 v123, v231, v173, s[8:9]
	v_mov_b32_dpp v122, v121 row_ror:2 row_mask:0xf bank_mask:0xf
	v_cndmask_b32_e64 v121, v232, v168, s[8:9]
	v_cndmask_b32_e64 v173, v231, v173, s[6:7]
	v_cndmask_b32_e64 v199, v233, v169, s[8:9]
	v_mov_b32_dpp v172, v121 row_ror:1 row_mask:0xf bank_mask:0xf
	v_cndmask_b32_e64 v121, v232, v168, s[6:7]

; __device__ __forceinline__ float dpp_ror1(float v) { return __int_as_float(__builtin_amdgcn_update_dpp(0, __float_as_int(v), 0x121, 0xf, 0xf, false)); }
; __device__ __forceinline__ float dpp_ror2(float v) { return __int_as_float(__builtin_amdgcn_update_dpp(0, __float_as_int(v), 0x122, 0xf, 0xf, false)); }
;   __device__ __forceinline__ void operator()(const AccT& acc, const Unit& u, int wr, int wc, int fr, int fq) const {
;     ...
;         for (int m = 0; m < 4; ++m) { xg[m] = acc[ai][0][m][n] * rs[m]; xv[m] = acc[ai][1][m][n] * rs[m]; }
;     ...
;             const float g1 = dpp_ror1((fr == 15) ? g_pm : g_cur), g2 = dpp_ror2((fr >= 14) ? g_pm : g_cur);
;             const float v1 = dpp_ror1((fr == 15) ? v_pm : v_cur), v2 = dpp_ror2((fr >= 14) ? v_pm : v_cur);
	v_pk_mul_f32 v[112:113], v[112:113], v[226:227] op_sel_hi:[1,0]
	v_pk_mul_f32 v[114:115], v[114:115], v[226:227] op_sel_hi:[1,0]
	v_mov_b32_dpp v168, v121 row_ror:2 row_mask:0xf bank_mask:0xf

; __device__ __forceinline__ float dpp_ror1(float v) { return __int_as_float(__builtin_amdgcn_update_dpp(0, __float_as_int(v), 0x121, 0xf, 0xf, false)); }
; __device__ __forceinline__ float dpp_ror2(float v) { return __int_as_float(__builtin_amdgcn_update_dpp(0, __float_as_int(v), 0x122, 0xf, 0xf, false)); }
;   __device__ __forceinline__ void operator()(const AccT& acc, const Unit& u, int wr, int wc, int fr, int fq) const {
;     ...
;             const float g1 = dpp_ror1((fr == 15) ? g_pm : g_cur), g2 = dpp_ror2((fr >= 14) ? g_pm : g_cur);
;             const float v1 = dpp_ror1((fr == 15) ? v_pm : v_cur), v2 = dpp_ror2((fr >= 14) ? v_pm : v_cur);
	s_nop 1
	v_mov_b32_dpp v121, v123 row_ror:1 row_mask:0xf bank_mask:0xf

; __device__ __forceinline__ float dpp_ror1(float v) { return __int_as_float(__builtin_amdgcn_update_dpp(0, __float_as_int(v), 0x121, 0xf, 0xf, false)); }
; __device__ __forceinline__ float dpp_ror2(float v) { return __int_as_float(__builtin_amdgcn_update_dpp(0, __float_as_int(v), 0x122, 0xf, 0xf, false)); }
;   __device__ __forceinline__ void operator()(const AccT& acc, const Unit& u, int wr, int wc, int fr, int fq) const {
;     ...
;             const float g1 = dpp_ror1((fr == 15) ? g_pm : g_cur), g2 = dpp_ror2((fr >= 14) ? g_pm : g_cur);
;             const float v1 = dpp_ror1((fr == 15) ? v_pm : v_cur), v2 = dpp_ror2((fr >= 14) ? v_pm : v_cur);
;             const float cg_ = bg[r] + g2 * wg0[r] + g1 * wg1[r] + g_cur * wg2[r];
	s_nop 1
	v_mov_b32_dpp v123, v173 row_ror:2 row_mask:0xf bank_mask:0xf
	v_pk_fma_f32 v[122:123], v[128:129], v[122:123], v[156:157]

;   __device__ __forceinline__ void operator()(const AccT& acc, const Unit& u, int wr, int wc, int fr, int fq) const {
;     ...
;             const float cg_ = bg[r] + g2 * wg0[r] + g1 * wg1[r] + g_cur * wg2[r];
;             const float cv_ = bv[r] + v2 * wv0[r] + v1 * wv1[r] + v_cur * wv2[r];
;             res[r] = cg_ * __builtin_amdgcn_rcpf(1.f + __builtin_amdgcn_exp2f(-1.4426950408889634f * cg_)) * cv_;
	v_pk_fma_f32 v[120:121], v[132:133], v[120:121], v[122:123]
	s_nop 0
	v_pk_fma_f32 v[120:121], v[136:137], v[230:231], v[120:121]
	v_mov_b32_dpp v173, v199 row_ror:1 row_mask:0xf bank_mask:0xf
	v_mul_f32_e32 v122, 0xbfb8aa3b, v120
	v_mul_f32_e32 v123, 0xbfb8aa3b, v121
	v_exp_f32_e32 v122, v122
	v_exp_f32_e32 v123, v123
	v_cndmask_b32_e64 v199, v233, v169, s[6:7]

; __device__ __forceinline__ float dpp_ror1(float v) { return __int_as_float(__builtin_amdgcn_update_dpp(0, __float_as_int(v), 0x121, 0xf, 0xf, false)); }
; __device__ __forceinline__ float dpp_ror2(float v) { return __int_as_float(__builtin_amdgcn_update_dpp(0, __float_as_int(v), 0x122, 0xf, 0xf, false)); }
;   __device__ __forceinline__ void operator()(const AccT& acc, const Unit& u, int wr, int wc, int fr, int fq) const {
;     ...
;             const float g1 = dpp_ror1((fr == 15) ? g_pm : g_cur), g2 = dpp_ror2((fr >= 14) ? g_pm : g_cur);
;             const float v1 = dpp_ror1((fr == 15) ? v_pm : v_cur), v2 = dpp_ror2((fr >= 14) ? v_pm : v_cur);
;             const float cg_ = bg[r] + g2 * wg0[r] + g1 * wg1[r] + g_cur * wg2[r];
;             const float cv_ = bv[r] + v2 * wv0[r] + v1 * wv1[r] + v_cur * wv2[r];
;             res[r] = cg_ * __builtin_amdgcn_rcpf(1.f + __builtin_amdgcn_exp2f(-1.4426950408889634f * cg_)) * cv_;
	v_add_f32_e32 v122, 1.0, v122
	v_add_f32_e32 v123, 1.0, v123
	v_mov_b32_dpp v169, v199 row_ror:2 row_mask:0xf bank_mask:0xf
	v_cndmask_b32_e64 v199, v126, v174, s[8:9]
	v_rcp_f32_e32 v122, v122
	v_rcp_f32_e32 v123, v123
	v_mov_b32_dpp v234, v199 row_ror:1 row_mask:0xf bank_mask:0xf
	v_cndmask_b32_e64 v199, v126, v174, s[6:7]

; __device__ __forceinline__ float dpp_ror1(float v) { return __int_as_float(__builtin_amdgcn_update_dpp(0, __float_as_int(v), 0x121, 0xf, 0xf, false)); }
; __device__ __forceinline__ float dpp_ror2(float v) { return __int_as_float(__builtin_amdgcn_update_dpp(0, __float_as_int(v), 0x122, 0xf, 0xf, false)); }
;   __device__ __forceinline__ void operator()(const AccT& acc, const Unit& u, int wr, int wc, int fr, int fq) const {
;     ...
;             const float g1 = dpp_ror1((fr == 15) ? g_pm : g_cur), g2 = dpp_ror2((fr >= 14) ? g_pm : g_cur);
;             const float v1 = dpp_ror1((fr == 15) ? v_pm : v_cur), v2 = dpp_ror2((fr >= 14) ? v_pm : v_cur);
;             const float cg_ = bg[r] + g2 * wg0[r] + g1 * wg1[r] + g_cur * wg2[r];
;             const float cv_ = bv[r] + v2 * wv0[r] + v1 * wv1[r] + v_cur * wv2[r];
	v_pk_fma_f32 v[168:169], v[140:141], v[168:169], v[152:153]
	v_pk_mul_f32 v[120:121], v[120:121], v[122:123]
	v_mov_b32_dpp v174, v199 row_ror:2 row_mask:0xf bank_mask:0xf
	v_cndmask_b32_e64 v199, v124, v170, s[8:9]
	v_pk_fma_f32 v[168:169], v[144:145], v[172:173], v[168:169]
	s_nop 0
	v_mov_b32_dpp v236, v199 row_ror:1 row_mask:0xf bank_mask:0xf
	v_cndmask_b32_e64 v199, v124, v170, s[6:7]

; __device__ __forceinline__ float dpp_ror1(float v) { return __int_as_float(__builtin_amdgcn_update_dpp(0, __float_as_int(v), 0x121, 0xf, 0xf, false)); }
; __device__ __forceinline__ float dpp_ror2(float v) { return __int_as_float(__builtin_amdgcn_update_dpp(0, __float_as_int(v), 0x122, 0xf, 0xf, false)); }
;   __device__ __forceinline__ void operator()(const AccT& acc, const Unit& u, int wr, int wc, int fr, int fq) const {
;     ...
;             const float g1 = dpp_ror1((fr == 15) ? g_pm : g_cur), g2 = dpp_ror2((fr >= 14) ? g_pm : g_cur);
;             const float v1 = dpp_ror1((fr == 15) ? v_pm : v_cur), v2 = dpp_ror2((fr >= 14) ? v_pm : v_cur);
;             const float cg_ = bg[r] + g2 * wg0[r] + g1 * wg1[r] + g_cur * wg2[r];
;             const float cv_ = bv[r] + v2 * wv0[r] + v1 * wv1[r] + v_cur * wv2[r];
;             res[r] = cg_ * __builtin_amdgcn_rcpf(1.f + __builtin_amdgcn_exp2f(-1.4426950408889634f * cg_)) * cv_;
	v_pk_fma_f32 v[168:169], v[148:149], v[232:233], v[168:169]
	s_nop 0
	v_mov_b32_dpp v170, v199 row_ror:2 row_mask:0xf bank_mask:0xf
	v_cndmask_b32_e64 v199, v127, v175, s[8:9]
	v_pk_mul_f32 v[120:121], v[168:169], v[120:121]
	s_nop 0
	v_mov_b32_dpp v235, v199 row_ror:1 row_mask:0xf bank_mask:0xf
	v_cndmask_b32_e64 v199, v127, v175, s[6:7]

; __device__ __forceinline__ uint2 pack4(f32x4 v) { return make_uint2(pack2(v[0], v[1]), pack2(v[2], v[3])); }
; __device__ __forceinline__ float dpp_ror1(float v) { return __int_as_float(__builtin_amdgcn_update_dpp(0, __float_as_int(v), 0x121, 0xf, 0xf, false)); }
; __device__ __forceinline__ float dpp_ror2(float v) { return __int_as_float(__builtin_amdgcn_update_dpp(0, __float_as_int(v), 0x122, 0xf, 0xf, false)); }
;   __device__ __forceinline__ void operator()(const AccT& acc, const Unit& u, int wr, int wc, int fr, int fq) const {
;     ...
;             const float g1 = dpp_ror1((fr == 15) ? g_pm : g_cur), g2 = dpp_ror2((fr >= 14) ? g_pm : g_cur);
;             const float v1 = dpp_ror1((fr == 15) ? v_pm : v_cur), v2 = dpp_ror2((fr >= 14) ? v_pm : v_cur);
;             const float cg_ = bg[r] + g2 * wg0[r] + g1 * wg1[r] + g_cur * wg2[r];
;             const float cv_ = bv[r] + v2 * wv0[r] + v1 * wv1[r] + v_cur * wv2[r];
;             res[r] = cg_ * __builtin_amdgcn_rcpf(1.f + __builtin_amdgcn_exp2f(-1.4426950408889634f * cg_)) * cv_;
;           }
;           if (m > 0 || fr >= 2)
;             *(uint2*)(act + (size_t)EPI_ROW(u, ai, m) * DFF + f0) = pack4(res);
	v_cvt_pk_bf16_f32 v172, v120, v121
	v_mov_b64_e32 v[120:121], s[52:53]
	v_mov_b32_dpp v175, v199 row_ror:2 row_mask:0xf bank_mask:0xf
	v_pk_fma_f32 v[122:123], v[130:131], v[174:175], v[158:159]
	v_cndmask_b32_e64 v199, v125, v171, s[8:9]
	v_pk_fma_f32 v[122:123], v[134:135], v[234:235], v[122:123]

;   __device__ __forceinline__ void operator()(const AccT& acc, const Unit& u, int wr, int wc, int fr, int fq) const {
;     ...
;             const float cg_ = bg[r] + g2 * wg0[r] + g1 * wg1[r] + g_cur * wg2[r];
;             const float cv_ = bv[r] + v2 * wv0[r] + v1 * wv1[r] + v_cur * wv2[r];
;             res[r] = cg_ * __builtin_amdgcn_rcpf(1.f + __builtin_amdgcn_exp2f(-1.4426950408889634f * cg_)) * cv_;
	v_pk_fma_f32 v[122:123], v[138:139], v[126:127], v[122:123]
	v_mov_b32_dpp v237, v199 row_ror:1 row_mask:0xf bank_mask:0xf
	v_mul_f32_e32 v168, 0xbfb8aa3b, v122
	v_mul_f32_e32 v169, 0xbfb8aa3b, v123
	v_exp_f32_e32 v168, v168
	v_exp_f32_e32 v169, v169
	v_cndmask_b32_e64 v199, v125, v171, s[6:7]

; __device__ __forceinline__ uint2 pack4(f32x4 v) { return make_uint2(pack2(v[0], v[1]), pack2(v[2], v[3])); }
;   __device__ __forceinline__ void operator()(const AccT& acc, const Unit& u, int wr, int wc, int fr, int fq) const {
;     ...
;             const float cg_ = bg[r] + g2 * wg0[r] + g1 * wg1[r] + g_cur * wg2[r];
;             const float cv_ = bv[r] + v2 * wv0[r] + v1 * wv1[r] + v_cur * wv2[r];
;             res[r] = cg_ * __builtin_amdgcn_rcpf(1.f + __builtin_amdgcn_exp2f(-1.4426950408889634f * cg_)) * cv_;
;           }
;           if (m > 0 || fr >= 2)
;             *(uint2*)(act + (size_t)EPI_ROW(u, ai, m) * DFF + f0) = pack4(res);
	v_add_f32_e32 v168, 1.0, v168
	v_add_f32_e32 v169, 1.0, v169
	v_rcp_f32_e32 v168, v168
	v_rcp_f32_e32 v169, v169
	v_mov_b32_dpp v171, v199 row_ror:2 row_mask:0xf bank_mask:0xf
	v_pk_fma_f32 v[170:171], v[142:143], v[170:171], v[154:155]
	v_cndmask_b32_e64 v175, v119, v231, s[6:7]
	v_pk_fma_f32 v[170:171], v[146:147], v[236:237], v[170:171]
	v_pk_mul_f32 v[122:123], v[122:123], v[168:169]
	v_pk_fma_f32 v[170:171], v[150:151], v[124:125], v[170:171]
	v_lshlrev_b64 v[168:169], 1, v[188:189]
	v_pk_mul_f32 v[122:123], v[170:171], v[122:123]
	v_cndmask_b32_e64 v199, v113, v233, s[8:9]
	v_cvt_pk_bf16_f32 v173, v122, v123
	v_mad_i64_i32 v[122:123], s[34:35], v228, s0, v[120:121]
	v_lshl_add_u64 v[170:171], v[122:123], 0, v[168:169]
	v_cndmask_b32_e64 v123, v118, v230, s[8:9]
	s_nop 0
	global_store_dwordx2 v[170:171], v[172:173], off

; __device__ __forceinline__ float dpp_ror1(float v) { return __int_as_float(__builtin_amdgcn_update_dpp(0, __float_as_int(v), 0x121, 0xf, 0xf, false)); }
; __device__ __forceinline__ float dpp_ror2(float v) { return __int_as_float(__builtin_amdgcn_update_dpp(0, __float_as_int(v), 0x122, 0xf, 0xf, false)); }
;   __device__ __forceinline__ void operator()(const AccT& acc, const Unit& u, int wr, int wc, int fr, int fq) const {
;     ...
;             const f32x4 xgp = xg[m > 0 ? m - 1 : 0], xvp = xv[m > 0 ? m - 1 : 0];
;             const float g_pm = (m > 0) ? xgp[r] : 0.f, v_pm = (m > 0) ? xvp[r] : 0.f;
;             const float g1 = dpp_ror1((fr == 15) ? g_pm : g_cur), g2 = dpp_ror2((fr >= 14) ? g_pm : g_cur);
;             const float v1 = dpp_ror1((fr == 15) ? v_pm : v_cur), v2 = dpp_ror2((fr >= 14) ? v_pm : v_cur);
	v_mov_b32_dpp v122, v123 row_ror:1 row_mask:0xf bank_mask:0xf
	v_cndmask_b32_e64 v123, v118, v230, s[6:7]
	s_nop 0
	v_cndmask_b32_e64 v173, v119, v231, s[8:9]
	v_mov_b32_dpp v172, v123 row_ror:2 row_mask:0xf bank_mask:0xf
	v_cndmask_b32_e64 v123, v112, v232, s[8:9]
	s_nop 0
	s_nop 0
	v_mov_b32_dpp v174, v123 row_ror:1 row_mask:0xf bank_mask:0xf
	v_cndmask_b32_e64 v123, v112, v232, s[6:7]
	s_nop 0
	s_nop 0
	v_mov_b32_dpp v228, v123 row_ror:2 row_mask:0xf bank_mask:0xf

; __device__ __forceinline__ float dpp_ror1(float v) { return __int_as_float(__builtin_amdgcn_update_dpp(0, __float_as_int(v), 0x121, 0xf, 0xf, false)); }
; __device__ __forceinline__ float dpp_ror2(float v) { return __int_as_float(__builtin_amdgcn_update_dpp(0, __float_as_int(v), 0x122, 0xf, 0xf, false)); }
;   __device__ __forceinline__ void operator()(const AccT& acc, const Unit& u, int wr, int wc, int fr, int fq) const {
;     ...
;             const float g1 = dpp_ror1((fr == 15) ? g_pm : g_cur), g2 = dpp_ror2((fr >= 14) ? g_pm : g_cur);
;             const float v1 = dpp_ror1((fr == 15) ? v_pm : v_cur), v2 = dpp_ror2((fr >= 14) ? v_pm : v_cur);
	s_nop 1
	v_mov_b32_dpp v123, v173 row_ror:1 row_mask:0xf bank_mask:0xf

; __device__ __forceinline__ float dpp_ror1(float v) { return __int_as_float(__builtin_amdgcn_update_dpp(0, __float_as_int(v), 0x121, 0xf, 0xf, false)); }
; __device__ __forceinline__ float dpp_ror2(float v) { return __int_as_float(__builtin_amdgcn_update_dpp(0, __float_as_int(v), 0x122, 0xf, 0xf, false)); }
;   __device__ __forceinline__ void operator()(const AccT& acc, const Unit& u, int wr, int wc, int fr, int fq) const {
;     ...
;             const float g1 = dpp_ror1((fr == 15) ? g_pm : g_cur), g2 = dpp_ror2((fr >= 14) ? g_pm : g_cur);
;             const float v1 = dpp_ror1((fr == 15) ? v_pm : v_cur), v2 = dpp_ror2((fr >= 14) ? v_pm : v_cur);
;             const float cg_ = bg[r] + g2 * wg0[r] + g1 * wg1[r] + g_cur * wg2[r];
	s_nop 1
	v_mov_b32_dpp v173, v175 row_ror:2 row_mask:0xf bank_mask:0xf
	v_pk_fma_f32 v[172:173], v[128:129], v[172:173], v[156:157]

; __device__ __forceinline__ float dpp_ror1(float v) { return __int_as_float(__builtin_amdgcn_update_dpp(0, __float_as_int(v), 0x121, 0xf, 0xf, false)); }
; __device__ __forceinline__ float dpp_ror2(float v) { return __int_as_float(__builtin_amdgcn_update_dpp(0, __float_as_int(v), 0x122, 0xf, 0xf, false)); }
;   __device__ __forceinline__ void operator()(const AccT& acc, const Unit& u, int wr, int wc, int fr, int fq) const {
;     ...
;             const float g1 = dpp_ror1((fr == 15) ? g_pm : g_cur), g2 = dpp_ror2((fr >= 14) ? g_pm : g_cur);
;             const float v1 = dpp_ror1((fr == 15) ? v_pm : v_cur), v2 = dpp_ror2((fr >= 14) ? v_pm : v_cur);
;             const float cg_ = bg[r] + g2 * wg0[r] + g1 * wg1[r] + g_cur * wg2[r];
;             const float cv_ = bv[r] + v2 * wv0[r] + v1 * wv1[r] + v_cur * wv2[r];
;             res[r] = cg_ * __builtin_amdgcn_rcpf(1.f + __builtin_amdgcn_exp2f(-1.4426950408889634f * cg_)) * cv_;
	v_pk_fma_f32 v[122:123], v[132:133], v[122:123], v[172:173]
	s_nop 0
	v_mov_b32_dpp v175, v199 row_ror:1 row_mask:0xf bank_mask:0xf
	v_cndmask_b32_e64 v199, v113, v233, s[6:7]
	v_pk_fma_f32 v[122:123], v[136:137], v[118:119], v[122:123]
	s_nop 0
	v_mov_b32_dpp v229, v199 row_ror:2 row_mask:0xf bank_mask:0xf
	v_cndmask_b32_e64 v199, v116, v126, s[8:9]
	v_mul_f32_e32 v172, 0xbfb8aa3b, v122
	v_mul_f32_e32 v173, 0xbfb8aa3b, v123
	v_mov_b32_dpp v230, v199 row_ror:1 row_mask:0xf bank_mask:0xf
	v_cndmask_b32_e64 v199, v116, v126, s[6:7]

; __device__ __forceinline__ float dpp_ror1(float v) { return __int_as_float(__builtin_amdgcn_update_dpp(0, __float_as_int(v), 0x121, 0xf, 0xf, false)); }
; __device__ __forceinline__ float dpp_ror2(float v) { return __int_as_float(__builtin_amdgcn_update_dpp(0, __float_as_int(v), 0x122, 0xf, 0xf, false)); }
;   __device__ __forceinline__ void operator()(const AccT& acc, const Unit& u, int wr, int wc, int fr, int fq) const {
;     ...
;             const float g1 = dpp_ror1((fr == 15) ? g_pm : g_cur), g2 = dpp_ror2((fr >= 14) ? g_pm : g_cur);
;             const float v1 = dpp_ror1((fr == 15) ? v_pm : v_cur), v2 = dpp_ror2((fr >= 14) ? v_pm : v_cur);
;             const float cg_ = bg[r] + g2 * wg0[r] + g1 * wg1[r] + g_cur * wg2[r];
;             const float cv_ = bv[r] + v2 * wv0[r] + v1 * wv1[r] + v_cur * wv2[r];
;             res[r] = cg_ * __builtin_amdgcn_rcpf(1.f + __builtin_amdgcn_exp2f(-1.4426950408889634f * cg_)) * cv_;
	v_exp_f32_e32 v172, v172
	v_exp_f32_e32 v173, v173
	v_mov_b32_dpp v126, v199 row_ror:2 row_mask:0xf bank_mask:0xf
	v_cndmask_b32_e64 v199, v114, v124, s[8:9]
	v_add_f32_e32 v172, 1.0, v172
	v_add_f32_e32 v173, 1.0, v173
	v_mov_b32_dpp v232, v199 row_ror:1 row_mask:0xf bank_mask:0xf
	v_cndmask_b32_e64 v199, v114, v124, s[6:7]

; __device__ __forceinline__ float dpp_ror1(float v) { return __int_as_float(__builtin_amdgcn_update_dpp(0, __float_as_int(v), 0x121, 0xf, 0xf, false)); }
; __device__ __forceinline__ float dpp_ror2(float v) { return __int_as_float(__builtin_amdgcn_update_dpp(0, __float_as_int(v), 0x122, 0xf, 0xf, false)); }
;   __device__ __forceinline__ void operator()(const AccT& acc, const Unit& u, int wr, int wc, int fr, int fq) const {
;     ...
;             const float g1 = dpp_ror1((fr == 15) ? g_pm : g_cur), g2 = dpp_ror2((fr >= 14) ? g_pm : g_cur);
;             const float v1 = dpp_ror1((fr == 15) ? v_pm : v_cur), v2 = dpp_ror2((fr >= 14) ? v_pm : v_cur);
;             const float cg_ = bg[r] + g2 * wg0[r] + g1 * wg1[r] + g_cur * wg2[r];
;             const float cv_ = bv[r] + v2 * wv0[r] + v1 * wv1[r] + v_cur * wv2[r];
;             res[r] = cg_ * __builtin_amdgcn_rcpf(1.f + __builtin_amdgcn_exp2f(-1.4426950408889634f * cg_)) * cv_;
	v_rcp_f32_e32 v172, v172
	v_rcp_f32_e32 v173, v173
	v_mov_b32_dpp v124, v199 row_ror:2 row_mask:0xf bank_mask:0xf
	v_cndmask_b32_e64 v199, v117, v127, s[8:9]
	v_pk_fma_f32 v[228:229], v[140:141], v[228:229], v[152:153]
	v_pk_mul_f32 v[122:123], v[122:123], v[172:173]
	v_mov_b32_dpp v231, v199 row_ror:1 row_mask:0xf bank_mask:0xf
	v_cndmask_b32_e64 v199, v117, v127, s[6:7]

; __device__ __forceinline__ float dpp_ror1(float v) { return __int_as_float(__builtin_amdgcn_update_dpp(0, __float_as_int(v), 0x121, 0xf, 0xf, false)); }
; __device__ __forceinline__ float dpp_ror2(float v) { return __int_as_float(__builtin_amdgcn_update_dpp(0, __float_as_int(v), 0x122, 0xf, 0xf, false)); }
;   __device__ __forceinline__ void operator()(const AccT& acc, const Unit& u, int wr, int wc, int fr, int fq) const {
;     ...
;             const float g1 = dpp_ror1((fr == 15) ? g_pm : g_cur), g2 = dpp_ror2((fr >= 14) ? g_pm : g_cur);
;             const float v1 = dpp_ror1((fr == 15) ? v_pm : v_cur), v2 = dpp_ror2((fr >= 14) ? v_pm : v_cur);
;             const float cg_ = bg[r] + g2 * wg0[r] + g1 * wg1[r] + g_cur * wg2[r];
;             const float cv_ = bv[r] + v2 * wv0[r] + v1 * wv1[r] + v_cur * wv2[r];
;             res[r] = cg_ * __builtin_amdgcn_rcpf(1.f + __builtin_amdgcn_exp2f(-1.4426950408889634f * cg_)) * cv_;
	v_pk_fma_f32 v[174:175], v[144:145], v[174:175], v[228:229]
	s_nop 0
	v_mov_b32_dpp v127, v199 row_ror:2 row_mask:0xf bank_mask:0xf
	v_pk_fma_f32 v[126:127], v[130:131], v[126:127], v[158:159]
	v_cndmask_b32_e64 v199, v115, v125, s[8:9]
	v_pk_fma_f32 v[126:127], v[134:135], v[230:231], v[126:127]
	v_pk_fma_f32 v[174:175], v[148:149], v[112:113], v[174:175]
	v_pk_fma_f32 v[126:127], v[138:139], v[116:117], v[126:127]
	v_mov_b32_dpp v233, v199 row_ror:1 row_mask:0xf bank_mask:0xf
	v_mul_f32_e32 v172, 0xbfb8aa3b, v126
	v_mul_f32_e32 v173, 0xbfb8aa3b, v127
	v_exp_f32_e32 v172, v172
	v_exp_f32_e32 v173, v173
	v_cndmask_b32_e64 v199, v115, v125, s[6:7]

; __device__ __forceinline__ uint2 pack4(f32x4 v) { return make_uint2(pack2(v[0], v[1]), pack2(v[2], v[3])); }
; __device__ __forceinline__ float dpp_ror1(float v) { return __int_as_float(__builtin_amdgcn_update_dpp(0, __float_as_int(v), 0x121, 0xf, 0xf, false)); }
; __device__ __forceinline__ float dpp_ror2(float v) { return __int_as_float(__builtin_amdgcn_update_dpp(0, __float_as_int(v), 0x122, 0xf, 0xf, false)); }
;   __device__ __forceinline__ void operator()(const AccT& acc, const Unit& u, int wr, int wc, int fr, int fq) const {
;     ...
;             const float g1 = dpp_ror1((fr == 15) ? g_pm : g_cur), g2 = dpp_ror2((fr >= 14) ? g_pm : g_cur);
;             const float v1 = dpp_ror1((fr == 15) ? v_pm : v_cur), v2 = dpp_ror2((fr >= 14) ? v_pm : v_cur);
;             const float cg_ = bg[r] + g2 * wg0[r] + g1 * wg1[r] + g_cur * wg2[r];
;             const float cv_ = bv[r] + v2 * wv0[r] + v1 * wv1[r] + v_cur * wv2[r];
;             res[r] = cg_ * __builtin_amdgcn_rcpf(1.f + __builtin_amdgcn_exp2f(-1.4426950408889634f * cg_)) * cv_;
;           }
;           if (m > 0 || fr >= 2)
;             *(uint2*)(act + (size_t)EPI_ROW(u, ai, m) * DFF + f0) = pack4(res);
	v_add_f32_e32 v172, 1.0, v172
	v_add_f32_e32 v173, 1.0, v173
	v_rcp_f32_e32 v172, v172
	v_rcp_f32_e32 v173, v173
	v_mov_b32_dpp v125, v199 row_ror:2 row_mask:0xf bank_mask:0xf
	v_pk_fma_f32 v[124:125], v[142:143], v[124:125], v[154:155]
	v_pk_mul_f32 v[122:123], v[174:175], v[122:123]
	v_pk_fma_f32 v[124:125], v[146:147], v[232:233], v[124:125]
	v_pk_mul_f32 v[126:127], v[126:127], v[172:173]
	v_pk_fma_f32 v[124:125], v[150:151], v[114:115], v[124:125]
	v_cvt_pk_bf16_f32 v122, v122, v123
	v_pk_mul_f32 v[124:125], v[124:125], v[126:127]
	v_cndmask_b32_e64 v126, v161, v113, s[8:9]
	v_cvt_pk_bf16_f32 v123, v124, v125
	v_mad_i64_i32 v[124:125], s[34:35], v222, s0, v[120:121]
	v_lshl_add_u64 v[172:173], v[124:125], 0, v[168:169]
	global_store_dwordx2 v[172:173], v[122:123], off
	v_cndmask_b32_e64 v123, v164, v118, s[8:9]
	s_nop 0

; __device__ __forceinline__ float dpp_ror1(float v) { return __int_as_float(__builtin_amdgcn_update_dpp(0, __float_as_int(v), 0x121, 0xf, 0xf, false)); }
; __device__ __forceinline__ float dpp_ror2(float v) { return __int_as_float(__builtin_amdgcn_update_dpp(0, __float_as_int(v), 0x122, 0xf, 0xf, false)); }
;   __device__ __forceinline__ void operator()(const AccT& acc, const Unit& u, int wr, int wc, int fr, int fq) const {
;     ...
;             const f32x4 xgp = xg[m > 0 ? m - 1 : 0], xvp = xv[m > 0 ? m - 1 : 0];
;             const float g_pm = (m > 0) ? xgp[r] : 0.f, v_pm = (m > 0) ? xvp[r] : 0.f;
;             const float g1 = dpp_ror1((fr == 15) ? g_pm : g_cur), g2 = dpp_ror2((fr >= 14) ? g_pm : g_cur);
;             const float v1 = dpp_ror1((fr == 15) ? v_pm : v_cur), v2 = dpp_ror2((fr >= 14) ? v_pm : v_cur);
	v_cndmask_b32_e64 v125, v165, v119, s[8:9]
	v_mov_b32_dpp v122, v123 row_ror:1 row_mask:0xf bank_mask:0xf
	v_cndmask_b32_e64 v123, v164, v118, s[6:7]
	s_nop 0
	v_cndmask_b32_e64 v127, v166, v116, s[8:9]

; __device__ __forceinline__ float dpp_ror1(float v) { return __int_as_float(__builtin_amdgcn_update_dpp(0, __float_as_int(v), 0x121, 0xf, 0xf, false)); }
; __device__ __forceinline__ float dpp_ror2(float v) { return __int_as_float(__builtin_amdgcn_update_dpp(0, __float_as_int(v), 0x122, 0xf, 0xf, false)); }
;   __device__ __forceinline__ void operator()(const AccT& acc, const Unit& u, int wr, int wc, int fr, int fq) const {
;     ...
;             const f32x4 xgp = xg[m > 0 ? m - 1 : 0], xvp = xv[m > 0 ? m - 1 : 0];
;             const float g_pm = (m > 0) ? xgp[r] : 0.f, v_pm = (m > 0) ? xvp[r] : 0.f;
;             const float g1 = dpp_ror1((fr == 15) ? g_pm : g_cur), g2 = dpp_ror2((fr >= 14) ? g_pm : g_cur);
;             const float v1 = dpp_ror1((fr == 15) ? v_pm : v_cur), v2 = dpp_ror2((fr >= 14) ? v_pm : v_cur);
	v_mov_b32_dpp v118, v123 row_ror:2 row_mask:0xf bank_mask:0xf
	v_cndmask_b32_e64 v123, v160, v112, s[8:9]
	v_cndmask_b32_e64 v175, v167, v117, s[8:9]
	v_cndmask_b32_e64 v199, v163, v115, s[8:9]
	v_mov_b32_dpp v124, v123 row_ror:1 row_mask:0xf bank_mask:0xf
	v_cndmask_b32_e64 v123, v160, v112, s[6:7]

; __device__ __forceinline__ float dpp_ror1(float v) { return __int_as_float(__builtin_amdgcn_update_dpp(0, __float_as_int(v), 0x121, 0xf, 0xf, false)); }
; __device__ __forceinline__ float dpp_ror2(float v) { return __int_as_float(__builtin_amdgcn_update_dpp(0, __float_as_int(v), 0x122, 0xf, 0xf, false)); }
;   __device__ __forceinline__ void operator()(const AccT& acc, const Unit& u, int wr, int wc, int fr, int fq) const {
;     ...
;             const float g1 = dpp_ror1((fr == 15) ? g_pm : g_cur), g2 = dpp_ror2((fr >= 14) ? g_pm : g_cur);
;             const float v1 = dpp_ror1((fr == 15) ? v_pm : v_cur), v2 = dpp_ror2((fr >= 14) ? v_pm : v_cur);
	s_nop 1
	v_mov_b32_dpp v112, v123 row_ror:2 row_mask:0xf bank_mask:0xf

; __device__ __forceinline__ float dpp_ror1(float v) { return __int_as_float(__builtin_amdgcn_update_dpp(0, __float_as_int(v), 0x121, 0xf, 0xf, false)); }
; __device__ __forceinline__ float dpp_ror2(float v) { return __int_as_float(__builtin_amdgcn_update_dpp(0, __float_as_int(v), 0x122, 0xf, 0xf, false)); }
;   __device__ __forceinline__ void operator()(const AccT& acc, const Unit& u, int wr, int wc, int fr, int fq) const {
;     ...
;             const float g1 = dpp_ror1((fr == 15) ? g_pm : g_cur), g2 = dpp_ror2((fr >= 14) ? g_pm : g_cur);
;             const float v1 = dpp_ror1((fr == 15) ? v_pm : v_cur), v2 = dpp_ror2((fr >= 14) ? v_pm : v_cur);
	s_nop 1
	v_mov_b32_dpp v123, v125 row_ror:1 row_mask:0xf bank_mask:0xf
	v_cndmask_b32_e64 v125, v165, v119, s[6:7]

; __device__ __forceinline__ float dpp_ror1(float v) { return __int_as_float(__builtin_amdgcn_update_dpp(0, __float_as_int(v), 0x121, 0xf, 0xf, false)); }
; __device__ __forceinline__ float dpp_ror2(float v) { return __int_as_float(__builtin_amdgcn_update_dpp(0, __float_as_int(v), 0x122, 0xf, 0xf, false)); }
;   __device__ __forceinline__ void operator()(const AccT& acc, const Unit& u, int wr, int wc, int fr, int fq) const {
;     ...
;             const float g1 = dpp_ror1((fr == 15) ? g_pm : g_cur), g2 = dpp_ror2((fr >= 14) ? g_pm : g_cur);
;             const float v1 = dpp_ror1((fr == 15) ? v_pm : v_cur), v2 = dpp_ror2((fr >= 14) ? v_pm : v_cur);
;             const float cg_ = bg[r] + g2 * wg0[r] + g1 * wg1[r] + g_cur * wg2[r];
	s_nop 1
	v_mov_b32_dpp v119, v125 row_ror:2 row_mask:0xf bank_mask:0xf
	v_pk_fma_f32 v[118:119], v[128:129], v[118:119], v[156:157]

; __device__ __forceinline__ float dpp_ror1(float v) { return __int_as_float(__builtin_amdgcn_update_dpp(0, __float_as_int(v), 0x121, 0xf, 0xf, false)); }
; __device__ __forceinline__ float dpp_ror2(float v) { return __int_as_float(__builtin_amdgcn_update_dpp(0, __float_as_int(v), 0x122, 0xf, 0xf, false)); }
;   __device__ __forceinline__ void operator()(const AccT& acc, const Unit& u, int wr, int wc, int fr, int fq) const {
;     ...
;             const float g1 = dpp_ror1((fr == 15) ? g_pm : g_cur), g2 = dpp_ror2((fr >= 14) ? g_pm : g_cur);
;             const float v1 = dpp_ror1((fr == 15) ? v_pm : v_cur), v2 = dpp_ror2((fr >= 14) ? v_pm : v_cur);
;             const float cg_ = bg[r] + g2 * wg0[r] + g1 * wg1[r] + g_cur * wg2[r];
	v_pk_fma_f32 v[118:119], v[132:133], v[122:123], v[118:119]
	s_nop 0
	v_pk_fma_f32 v[118:119], v[136:137], v[164:165], v[118:119]
	v_mov_b32_dpp v125, v126 row_ror:1 row_mask:0xf bank_mask:0xf
	v_cndmask_b32_e64 v126, v161, v113, s[6:7]

; __device__ __forceinline__ float dpp_ror1(float v) { return __int_as_float(__builtin_amdgcn_update_dpp(0, __float_as_int(v), 0x121, 0xf, 0xf, false)); }
; __device__ __forceinline__ float dpp_ror2(float v) { return __int_as_float(__builtin_amdgcn_update_dpp(0, __float_as_int(v), 0x122, 0xf, 0xf, false)); }
;   __device__ __forceinline__ void operator()(const AccT& acc, const Unit& u, int wr, int wc, int fr, int fq) const {
;     ...
;             const float g1 = dpp_ror1((fr == 15) ? g_pm : g_cur), g2 = dpp_ror2((fr >= 14) ? g_pm : g_cur);
;             const float v1 = dpp_ror1((fr == 15) ? v_pm : v_cur), v2 = dpp_ror2((fr >= 14) ? v_pm : v_cur);
;             const float cg_ = bg[r] + g2 * wg0[r] + g1 * wg1[r] + g_cur * wg2[r];
;             const float cv_ = bv[r] + v2 * wv0[r] + v1 * wv1[r] + v_cur * wv2[r];
;             res[r] = cg_ * __builtin_amdgcn_rcpf(1.f + __builtin_amdgcn_exp2f(-1.4426950408889634f * cg_)) * cv_;
	v_mul_f32_e32 v122, 0xbfb8aa3b, v118
	v_mul_f32_e32 v123, 0xbfb8aa3b, v119
	v_mov_b32_dpp v113, v126 row_ror:2 row_mask:0xf bank_mask:0xf

; __device__ __forceinline__ float dpp_ror1(float v) { return __int_as_float(__builtin_amdgcn_update_dpp(0, __float_as_int(v), 0x121, 0xf, 0xf, false)); }
; __device__ __forceinline__ float dpp_ror2(float v) { return __int_as_float(__builtin_amdgcn_update_dpp(0, __float_as_int(v), 0x122, 0xf, 0xf, false)); }
;   __device__ __forceinline__ void operator()(const AccT& acc, const Unit& u, int wr, int wc, int fr, int fq) const {
;     ...
;             const float g1 = dpp_ror1((fr == 15) ? g_pm : g_cur), g2 = dpp_ror2((fr >= 14) ? g_pm : g_cur);
;             const float v1 = dpp_ror1((fr == 15) ? v_pm : v_cur), v2 = dpp_ror2((fr >= 14) ? v_pm : v_cur);
;             const float cg_ = bg[r] + g2 * wg0[r] + g1 * wg1[r] + g_cur * wg2[r];
;             const float cv_ = bv[r] + v2 * wv0[r] + v1 * wv1[r] + v_cur * wv2[r];
;             res[r] = cg_ * __builtin_amdgcn_rcpf(1.f + __builtin_amdgcn_exp2f(-1.4426950408889634f * cg_)) * cv_;
	v_exp_f32_e32 v122, v122
	v_exp_f32_e32 v123, v123
	v_mov_b32_dpp v126, v127 row_ror:1 row_mask:0xf bank_mask:0xf
	v_cndmask_b32_e64 v127, v166, v116, s[6:7]

; __device__ __forceinline__ float dpp_ror1(float v) { return __int_as_float(__builtin_amdgcn_update_dpp(0, __float_as_int(v), 0x121, 0xf, 0xf, false)); }
; __device__ __forceinline__ float dpp_ror2(float v) { return __int_as_float(__builtin_amdgcn_update_dpp(0, __float_as_int(v), 0x122, 0xf, 0xf, false)); }
;   __device__ __forceinline__ void operator()(const AccT& acc, const Unit& u, int wr, int wc, int fr, int fq) const {
;     ...
;         for (int m = 0; m < 4; ++m) {
;           f32x4 res;
; #pragma unroll
;           for (int r = 0; r < 4; ++r) {
;             const float g_cur = xg[m][r], v_cur = xv[m][r];
;             const f32x4 xgp = xg[m > 0 ? m - 1 : 0], xvp = xv[m > 0 ? m - 1 : 0];
;             const float g_pm = (m > 0) ? xgp[r] : 0.f, v_pm = (m > 0) ? xvp[r] : 0.f;
;             const float g1 = dpp_ror1((fr == 15) ? g_pm : g_cur), g2 = dpp_ror2((fr >= 14) ? g_pm : g_cur);
;             const float v1 = dpp_ror1((fr == 15) ? v_pm : v_cur), v2 = dpp_ror2((fr >= 14) ? v_pm : v_cur);
;             const float cg_ = bg[r] + g2 * wg0[r] + g1 * wg1[r] + g_cur * wg2[r];
;             const float cv_ = bv[r] + v2 * wv0[r] + v1 * wv1[r] + v_cur * wv2[r];
;             res[r] = cg_ * __builtin_amdgcn_rcpf(1.f + __builtin_amdgcn_exp2f(-1.4426950408889634f * cg_)) * cv_;
	v_add_f32_e32 v122, 1.0, v122
	v_add_f32_e32 v123, 1.0, v123
	v_mov_b32_dpp v116, v127 row_ror:2 row_mask:0xf bank_mask:0xf
	v_cndmask_b32_e64 v127, v162, v114, s[8:9]
	v_rcp_f32_e32 v122, v122
	v_rcp_f32_e32 v123, v123
	v_mov_b32_dpp v174, v127 row_ror:1 row_mask:0xf bank_mask:0xf
	v_cndmask_b32_e64 v127, v162, v114, s[6:7]

; __device__ __forceinline__ float dpp_ror1(float v) { return __int_as_float(__builtin_amdgcn_update_dpp(0, __float_as_int(v), 0x121, 0xf, 0xf, false)); }
; __device__ __forceinline__ float dpp_ror2(float v) { return __int_as_float(__builtin_amdgcn_update_dpp(0, __float_as_int(v), 0x122, 0xf, 0xf, false)); }
;   __device__ __forceinline__ void operator()(const AccT& acc, const Unit& u, int wr, int wc, int fr, int fq) const {
;     ...
;         for (int m = 0; m < 4; ++m) {
;           f32x4 res;
; #pragma unroll
;           for (int r = 0; r < 4; ++r) {
;             const float g_cur = xg[m][r], v_cur = xv[m][r];
;             const f32x4 xgp = xg[m > 0 ? m - 1 : 0], xvp = xv[m > 0 ? m - 1 : 0];
;             const float g_pm = (m > 0) ? xgp[r] : 0.f, v_pm = (m > 0) ? xvp[r] : 0.f;
;             const float g1 = dpp_ror1((fr == 15) ? g_pm : g_cur), g2 = dpp_ror2((fr >= 14) ? g_pm : g_cur);
;             const float v1 = dpp_ror1((fr == 15) ? v_pm : v_cur), v2 = dpp_ror2((fr >= 14) ? v_pm : v_cur);
;             const float cg_ = bg[r] + g2 * wg0[r] + g1 * wg1[r] + g_cur * wg2[r];
;             const float cv_ = bv[r] + v2 * wv0[r] + v1 * wv1[r] + v_cur * wv2[r];
;             res[r] = cg_ * __builtin_amdgcn_rcpf(1.f + __builtin_amdgcn_exp2f(-1.4426950408889634f * cg_)) * cv_;
	v_pk_fma_f32 v[112:113], v[140:141], v[112:113], v[152:153]
	v_pk_mul_f32 v[118:119], v[118:119], v[122:123]
	v_mov_b32_dpp v114, v127 row_ror:2 row_mask:0xf bank_mask:0xf

; __device__ __forceinline__ float dpp_ror1(float v) { return __int_as_float(__builtin_amdgcn_update_dpp(0, __float_as_int(v), 0x121, 0xf, 0xf, false)); }
; __device__ __forceinline__ float dpp_ror2(float v) { return __int_as_float(__builtin_amdgcn_update_dpp(0, __float_as_int(v), 0x122, 0xf, 0xf, false)); }
;   __device__ __forceinline__ void operator()(const AccT& acc, const Unit& u, int wr, int wc, int fr, int fq) const {
;     ...
;         for (int m = 0; m < 4; ++m) {
;           f32x4 res;
; #pragma unroll
;           for (int r = 0; r < 4; ++r) {
;             const float g_cur = xg[m][r], v_cur = xv[m][r];
;             const f32x4 xgp = xg[m > 0 ? m - 1 : 0], xvp = xv[m > 0 ? m - 1 : 0];
;             const float g_pm = (m > 0) ? xgp[r] : 0.f, v_pm = (m > 0) ? xvp[r] : 0.f;
;             const float g1 = dpp_ror1((fr == 15) ? g_pm : g_cur), g2 = dpp_ror2((fr >= 14) ? g_pm : g_cur);
;             const float v1 = dpp_ror1((fr == 15) ? v_pm : v_cur), v2 = dpp_ror2((fr >= 14) ? v_pm : v_cur);
;             const float cg_ = bg[r] + g2 * wg0[r] + g1 * wg1[r] + g_cur * wg2[r];
;             const float cv_ = bv[r] + v2 * wv0[r] + v1 * wv1[r] + v_cur * wv2[r];
;             res[r] = cg_ * __builtin_amdgcn_rcpf(1.f + __builtin_amdgcn_exp2f(-1.4426950408889634f * cg_)) * cv_;
	v_pk_fma_f32 v[112:113], v[144:145], v[124:125], v[112:113]
	s_nop 0
	v_mov_b32_dpp v127, v175 row_ror:1 row_mask:0xf bank_mask:0xf
	v_cndmask_b32_e64 v175, v167, v117, s[6:7]

; __device__ __forceinline__ float dpp_ror1(float v) { return __int_as_float(__builtin_amdgcn_update_dpp(0, __float_as_int(v), 0x121, 0xf, 0xf, false)); }
; __device__ __forceinline__ float dpp_ror2(float v) { return __int_as_float(__builtin_amdgcn_update_dpp(0, __float_as_int(v), 0x122, 0xf, 0xf, false)); }
;   __device__ __forceinline__ void operator()(const AccT& acc, const Unit& u, int wr, int wc, int fr, int fq) const {
;     ...
;         for (int m = 0; m < 4; ++m) {
;           f32x4 res;
; #pragma unroll
;           for (int r = 0; r < 4; ++r) {
;             const float g_cur = xg[m][r], v_cur = xv[m][r];
;             const f32x4 xgp = xg[m > 0 ? m - 1 : 0], xvp = xv[m > 0 ? m - 1 : 0];
;             const float g_pm = (m > 0) ? xgp[r] : 0.f, v_pm = (m > 0) ? xvp[r] : 0.f;
;             const float g1 = dpp_ror1((fr == 15) ? g_pm : g_cur), g2 = dpp_ror2((fr >= 14) ? g_pm : g_cur);
;             const float v1 = dpp_ror1((fr == 15) ? v_pm : v_cur), v2 = dpp_ror2((fr >= 14) ? v_pm : v_cur);
;             const float cg_ = bg[r] + g2 * wg0[r] + g1 * wg1[r] + g_cur * wg2[r];
;             const float cv_ = bv[r] + v2 * wv0[r] + v1 * wv1[r] + v_cur * wv2[r];
;             res[r] = cg_ * __builtin_amdgcn_rcpf(1.f + __builtin_amdgcn_exp2f(-1.4426950408889634f * cg_)) * cv_;
	v_pk_fma_f32 v[112:113], v[148:149], v[160:161], v[112:113]
	s_nop 0
	v_mov_b32_dpp v117, v175 row_ror:2 row_mask:0xf bank_mask:0xf
	v_pk_fma_f32 v[116:117], v[130:131], v[116:117], v[158:159]
	v_pk_mul_f32 v[112:113], v[112:113], v[118:119]
	v_pk_fma_f32 v[116:117], v[134:135], v[126:127], v[116:117]

; __device__ __forceinline__ float dpp_ror1(float v) { return __int_as_float(__builtin_amdgcn_update_dpp(0, __float_as_int(v), 0x121, 0xf, 0xf, false)); }
; __device__ __forceinline__ float dpp_ror2(float v) { return __int_as_float(__builtin_amdgcn_update_dpp(0, __float_as_int(v), 0x122, 0xf, 0xf, false)); }
;   __device__ __forceinline__ void operator()(const AccT& acc, const Unit& u, int wr, int wc, int fr, int fq) const {
;     ...
;         for (int m = 0; m < 4; ++m) {
;           f32x4 res;
; #pragma unroll
;           for (int r = 0; r < 4; ++r) {
;             const float g_cur = xg[m][r], v_cur = xv[m][r];
;             const f32x4 xgp = xg[m > 0 ? m - 1 : 0], xvp = xv[m > 0 ? m - 1 : 0];
;             const float g_pm = (m > 0) ? xgp[r] : 0.f, v_pm = (m > 0) ? xvp[r] : 0.f;
;             const float g1 = dpp_ror1((fr == 15) ? g_pm : g_cur), g2 = dpp_ror2((fr >= 14) ? g_pm : g_cur);
;             const float v1 = dpp_ror1((fr == 15) ? v_pm : v_cur), v2 = dpp_ror2((fr >= 14) ? v_pm : v_cur);
;             const float cg_ = bg[r] + g2 * wg0[r] + g1 * wg1[r] + g_cur * wg2[r];
;             const float cv_ = bv[r] + v2 * wv0[r] + v1 * wv1[r] + v_cur * wv2[r];
;             res[r] = cg_ * __builtin_amdgcn_rcpf(1.f + __builtin_amdgcn_exp2f(-1.4426950408889634f * cg_)) * cv_;
	v_pk_fma_f32 v[116:117], v[138:139], v[166:167], v[116:117]
	v_cvt_pk_bf16_f32 v112, v112, v113
	v_mul_f32_e32 v118, 0xbfb8aa3b, v116
	v_mul_f32_e32 v119, 0xbfb8aa3b, v117
	v_exp_f32_e32 v118, v118
	v_exp_f32_e32 v119, v119
	v_mov_b32_dpp v175, v199 row_ror:1 row_mask:0xf bank_mask:0xf
	v_cndmask_b32_e64 v199, v163, v115, s[6:7]
	v_add_f32_e32 v118, 1.0, v118
	v_add_f32_e32 v119, 1.0, v119

;   __device__ __forceinline__ void operator()(const AccT& acc, const Unit& u, int wr, int wc, int fr, int fq) const {
;     ...
;         const int f0 = 128 * u.pn + 32 * wc + 16 * n + 4 * fq;
;         const int gc = u.pn * 256 + 32 * wc + 16 * n + 4 * fq;
;         const f32x4 wg0 = *(const f32x4*)(cw + f0), wg1 = *(const f32x4*)(cw + NUP + f0), wg2 = *(const f32x4*)(cw + 2 * NUP + f0);
;         const f32x4 wv0 = *(const f32x4*)(cw + DFF + f0), wv1 = *(const f32x4*)(cw + NUP + DFF + f0), wv2 = *(const f32x4*)(cw + 2 * NUP + DFF + f0);
;         const f32x4 bg = *(const f32x4*)(cb + f0), bv = *(const f32x4*)(cb + DFF + f0);
;         f32x4 xg[4], xv[4];
; #pragma unroll
;         for (int m = 0; m < 4; ++m) { xg[m] = acc[ai][0][m][n] * rs[m]; xv[m] = acc[ai][1][m][n] * rs[m]; }
;         if (fr < 2) {
;           float* d = ub + ((size_t)(chunk * 4 + fr) * NUP + gc);
;           *(float4*)d = make_float4(xg[0][0], xg[0][1], xg[0][2], xg[0][3]);
;           *(float4*)(d + 128) = make_float4(xv[0][0], xv[0][1], xv[0][2], xv[0][3]);
;         }
;         if (fr >= 14) {
;           float* d = ub + ((size_t)(chunk * 4 + 2 + (fr - 14)) * NUP + gc);
;           *(float4*)d = make_float4(xg[3][0], xg[3][1], xg[3][2], xg[3][3]);
;           *(float4*)(d + 128) = make_float4(xv[3][0], xv[3][1], xv[3][2], xv[3][3]);
;         }
; #pragma unroll
;         for (int m = 0; m < 4; ++m) {
;           f32x4 res;
; #pragma unroll
;           for (int r = 0; r < 4; ++r) {
;             const float g_cur = xg[m][r], v_cur = xv[m][r];
;             const f32x4 xgp = xg[m > 0 ? m - 1 : 0], xvp = xv[m > 0 ? m - 1 : 0];
;             const float g_pm = (m > 0) ? xgp[r] : 0.f, v_pm = (m > 0) ? xvp[r] : 0.f;
;             const float g1 = dpp_ror1((fr == 15) ? g_pm : g_cur), g2 = dpp_ror2((fr >= 14) ? g_pm : g_cur);
;             const float v1 = dpp_ror1((fr == 15) ? v_pm : v_cur), v2 = dpp_ror2((fr >= 14) ? v_pm : v_cur);
;             const float cg_ = bg[r] + g2 * wg0[r] + g1 * wg1[r] + g_cur * wg2[r];
;             const float cv_ = bv[r] + v2 * wv0[r] + v1 * wv1[r] + v_cur * wv2[r];
;             res[r] = cg_ * __builtin_amdgcn_rcpf(1.f + __builtin_amdgcn_exp2f(-1.4426950408889634f * cg_)) * cv_;
;           }
;           if (m > 0 || fr >= 2)
;             *(uint2*)(act + (size_t)EPI_ROW(u, ai, m) * DFF + f0) = pack4(res);
	v_rcp_f32_e32 v118, v118
	v_rcp_f32_e32 v119, v119
	v_mov_b32_dpp v115, v199 row_ror:2 row_mask:0xf bank_mask:0xf
	v_pk_fma_f32 v[114:115], v[142:143], v[114:115], v[154:155]
	v_mov_b32_e32 v158, v212
	v_pk_fma_f32 v[114:115], v[146:147], v[174:175], v[114:115]
	v_pk_mul_f32 v[116:117], v[116:117], v[118:119]
	v_pk_fma_f32 v[114:115], v[150:151], v[162:163], v[114:115]
	v_mov_b32_e32 v159, v212
	v_pk_mul_f32 v[114:115], v[114:115], v[116:117]
	v_or_b32_e32 v116, 16, v188
	v_cvt_pk_bf16_f32 v113, v114, v115
	v_mad_i64_i32 v[114:115], s[34:35], v214, s0, v[120:121]
	v_ashrrev_i32_e32 v117, 31, v116
	v_lshl_add_u64 v[156:157], v[114:115], 0, v[168:169]
	v_lshlrev_b64 v[136:137], 2, v[116:117]
	global_store_dwordx2 v[156:157], v[112:113], off
	v_lshl_add_u64 v[144:145], s[70:71], 0, v[136:137]
	v_lshl_add_u64 v[146:147], s[44:45], 0, v[136:137]
	v_lshl_add_u64 v[148:149], s[82:83], 0, v[136:137]
	v_lshl_add_u64 v[150:151], s[42:43], 0, v[136:137]
	v_lshl_add_u64 v[152:153], s[84:85], 0, v[136:137]
	v_lshl_add_u64 v[154:155], s[64:65], 0, v[136:137]
	global_load_dwordx4 v[112:115], v[194:195], off offset:64
	global_load_dwordx4 v[116:119], v[144:145], off
	global_load_dwordx4 v[124:127], v[146:147], off
	global_load_dwordx4 v[120:123], v[148:149], off
	global_load_dwordx4 v[128:131], v[150:151], off
	global_load_dwordx4 v[132:135], v[152:153], off
	global_load_dwordx4 v[140:143], v[196:197], off offset:64
	global_load_dwordx4 v[136:139], v[154:155], off
	v_pk_mul_f32 v[110:111], v[110:111], v[158:159]
	v_pk_mul_f32 v[106:107], v[106:107], v[158:159]
	s_and_saveexec_b64 s[38:39], s[4:5]
	s_cbranch_execz .LBB0_492
	v_lshl_add_u64 v[158:159], v[190:191], 2, v[216:217]
	global_store_dwordx4 v[158:159], v[108:111], off offset:64
	global_store_dwordx4 v[158:159], v[104:107], off offset:576

; __device__ __forceinline__ float dpp_ror1(float v) { return __int_as_float(__builtin_amdgcn_update_dpp(0, __float_as_int(v), 0x121, 0xf, 0xf, false)); }
; __device__ __forceinline__ float dpp_ror2(float v) { return __int_as_float(__builtin_amdgcn_update_dpp(0, __float_as_int(v), 0x122, 0xf, 0xf, false)); }
;   __device__ __forceinline__ void operator()(const AccT& acc, const Unit& u, int wr, int wc, int fr, int fq) const {
;     ...
;         for (int m = 0; m < 4; ++m) {
;           f32x4 res;
; #pragma unroll
;           for (int r = 0; r < 4; ++r) {
;             const float g_cur = xg[m][r], v_cur = xv[m][r];
;             const f32x4 xgp = xg[m > 0 ? m - 1 : 0], xvp = xv[m > 0 ? m - 1 : 0];
;             const float g_pm = (m > 0) ? xgp[r] : 0.f, v_pm = (m > 0) ? xvp[r] : 0.f;
;             const float g1 = dpp_ror1((fr == 15) ? g_pm : g_cur), g2 = dpp_ror2((fr >= 14) ? g_pm : g_cur);
;             const float v1 = dpp_ror1((fr == 15) ? v_pm : v_cur), v2 = dpp_ror2((fr >= 14) ? v_pm : v_cur);
.LBB0_494:
	s_or_b64 exec, exec, s[38:39]
	v_cndmask_b32_e64 v165, v108, 0, s[8:9]
	s_nop 0
	s_nop 0

; __device__ __forceinline__ float dpp_ror1(float v) { return __int_as_float(__builtin_amdgcn_update_dpp(0, __float_as_int(v), 0x121, 0xf, 0xf, false)); }
; __device__ __forceinline__ float dpp_ror2(float v) { return __int_as_float(__builtin_amdgcn_update_dpp(0, __float_as_int(v), 0x122, 0xf, 0xf, false)); }
;   __device__ __forceinline__ void operator()(const AccT& acc, const Unit& u, int wr, int wc, int fr, int fq) const {
;     ...
;         for (int m = 0; m < 4; ++m) {
;           f32x4 res;
; #pragma unroll
;           for (int r = 0; r < 4; ++r) {
;             const float g_cur = xg[m][r], v_cur = xv[m][r];
;             const f32x4 xgp = xg[m > 0 ? m - 1 : 0], xvp = xv[m > 0 ? m - 1 : 0];
;             const float g_pm = (m > 0) ? xgp[r] : 0.f, v_pm = (m > 0) ? xvp[r] : 0.f;
;             const float g1 = dpp_ror1((fr == 15) ? g_pm : g_cur), g2 = dpp_ror2((fr >= 14) ? g_pm : g_cur);
;             const float v1 = dpp_ror1((fr == 15) ? v_pm : v_cur), v2 = dpp_ror2((fr >= 14) ? v_pm : v_cur);
	v_mov_b32_dpp v212, v165 row_ror:1 row_mask:0xf bank_mask:0xf
	v_mov_b32_dpp v214, v164 row_ror:2 row_mask:0xf bank_mask:0xf
	v_cndmask_b32_e64 v165, v104, 0, s[8:9]

; __device__ __forceinline__ float dpp_ror1(float v) { return __int_as_float(__builtin_amdgcn_update_dpp(0, __float_as_int(v), 0x121, 0xf, 0xf, false)); }
; __device__ __forceinline__ float dpp_ror2(float v) { return __int_as_float(__builtin_amdgcn_update_dpp(0, __float_as_int(v), 0x122, 0xf, 0xf, false)); }
;   __device__ __forceinline__ void operator()(const AccT& acc, const Unit& u, int wr, int wc, int fr, int fq) const {
;     ...
;         for (int m = 0; m < 4; ++m) {
;           f32x4 res;
; #pragma unroll
;           for (int r = 0; r < 4; ++r) {
;             const float g_cur = xg[m][r], v_cur = xv[m][r];
;             const f32x4 xgp = xg[m > 0 ? m - 1 : 0], xvp = xv[m > 0 ? m - 1 : 0];
;             const float g_pm = (m > 0) ? xgp[r] : 0.f, v_pm = (m > 0) ? xvp[r] : 0.f;
;             const float g1 = dpp_ror1((fr == 15) ? g_pm : g_cur), g2 = dpp_ror2((fr >= 14) ? g_pm : g_cur);
;             const float v1 = dpp_ror1((fr == 15) ? v_pm : v_cur), v2 = dpp_ror2((fr >= 14) ? v_pm : v_cur);
	v_mov_b32_dpp v215, v162 row_ror:2 row_mask:0xf bank_mask:0xf
	v_cndmask_b32_e64 v162, v105, 0, s[8:9]
	v_mov_b32_dpp v164, v165 row_ror:1 row_mask:0xf bank_mask:0xf
	s_nop 0


; __device__ __forceinline__ float dpp_ror1(float v) { return __int_as_float(__builtin_amdgcn_update_dpp(0, __float_as_int(v), 0x121, 0xf, 0xf, false)); }
; __device__ __forceinline__ float dpp_ror2(float v) { return __int_as_float(__builtin_amdgcn_update_dpp(0, __float_as_int(v), 0x122, 0xf, 0xf, false)); }
;   __device__ __forceinline__ void operator()(const AccT& acc, const Unit& u, int wr, int wc, int fr, int fq) const {
;     ...
;         for (int m = 0; m < 4; ++m) {
;           f32x4 res;
; #pragma unroll
;           for (int r = 0; r < 4; ++r) {
;             const float g_cur = xg[m][r], v_cur = xv[m][r];
;             const f32x4 xgp = xg[m > 0 ? m - 1 : 0], xvp = xv[m > 0 ? m - 1 : 0];
;             const float g_pm = (m > 0) ? xgp[r] : 0.f, v_pm = (m > 0) ? xvp[r] : 0.f;
;             const float g1 = dpp_ror1((fr == 15) ? g_pm : g_cur), g2 = dpp_ror2((fr >= 14) ? g_pm : g_cur);
;             const float v1 = dpp_ror1((fr == 15) ? v_pm : v_cur), v2 = dpp_ror2((fr >= 14) ? v_pm : v_cur);
	v_mov_b32_dpp v165, v162 row_ror:1 row_mask:0xf bank_mask:0xf
	v_mov_b32_dpp v175, v160 row_ror:2 row_mask:0xf bank_mask:0xf
	v_cndmask_b32_e64 v160, v110, 0, s[8:9]
	s_nop 0

; __device__ __forceinline__ float dpp_ror1(float v) { return __int_as_float(__builtin_amdgcn_update_dpp(0, __float_as_int(v), 0x121, 0xf, 0xf, false)); }
; __device__ __forceinline__ float dpp_ror2(float v) { return __int_as_float(__builtin_amdgcn_update_dpp(0, __float_as_int(v), 0x122, 0xf, 0xf, false)); }
;   __device__ __forceinline__ void operator()(const AccT& acc, const Unit& u, int wr, int wc, int fr, int fq) const {
;     ...
;         for (int m = 0; m < 4; ++m) {
;           f32x4 res;
; #pragma unroll
;           for (int r = 0; r < 4; ++r) {
;             const float g_cur = xg[m][r], v_cur = xv[m][r];
;             const f32x4 xgp = xg[m > 0 ? m - 1 : 0], xvp = xv[m > 0 ? m - 1 : 0];
;             const float g_pm = (m > 0) ? xgp[r] : 0.f, v_pm = (m > 0) ? xvp[r] : 0.f;
;             const float g1 = dpp_ror1((fr == 15) ? g_pm : g_cur), g2 = dpp_ror2((fr >= 14) ? g_pm : g_cur);
;             const float v1 = dpp_ror1((fr == 15) ? v_pm : v_cur), v2 = dpp_ror2((fr >= 14) ? v_pm : v_cur);
	v_mov_b32_dpp v166, v158 row_ror:2 row_mask:0xf bank_mask:0xf
	v_mov_b32_dpp v162, v160 row_ror:1 row_mask:0xf bank_mask:0xf
	v_cndmask_b32_e64 v160, v106, 0, s[8:9]

; __device__ __forceinline__ float dpp_ror1(float v) { return __int_as_float(__builtin_amdgcn_update_dpp(0, __float_as_int(v), 0x121, 0xf, 0xf, false)); }
; __device__ __forceinline__ float dpp_ror2(float v) { return __int_as_float(__builtin_amdgcn_update_dpp(0, __float_as_int(v), 0x122, 0xf, 0xf, false)); }
;   __device__ __forceinline__ void operator()(const AccT& acc, const Unit& u, int wr, int wc, int fr, int fq) const {
;     ...
;         for (int m = 0; m < 4; ++m) {
;           f32x4 res;
; #pragma unroll
;           for (int r = 0; r < 4; ++r) {
;             const float g_cur = xg[m][r], v_cur = xv[m][r];
;             const f32x4 xgp = xg[m > 0 ? m - 1 : 0], xvp = xv[m > 0 ? m - 1 : 0];
;             const float g_pm = (m > 0) ? xgp[r] : 0.f, v_pm = (m > 0) ? xvp[r] : 0.f;
;             const float g1 = dpp_ror1((fr == 15) ? g_pm : g_cur), g2 = dpp_ror2((fr >= 14) ? g_pm : g_cur);
;             const float v1 = dpp_ror1((fr == 15) ? v_pm : v_cur), v2 = dpp_ror2((fr >= 14) ? v_pm : v_cur);
	v_mov_b32_dpp v174, v163 row_ror:2 row_mask:0xf bank_mask:0xf
	v_cndmask_b32_e64 v163, v109, 0, s[8:9]
	s_nop 0
	v_mov_b32_dpp v158, v160 row_ror:1 row_mask:0xf bank_mask:0xf

; __device__ __forceinline__ float dpp_ror1(float v) { return __int_as_float(__builtin_amdgcn_update_dpp(0, __float_as_int(v), 0x121, 0xf, 0xf, false)); }
; __device__ __forceinline__ float dpp_ror2(float v) { return __int_as_float(__builtin_amdgcn_update_dpp(0, __float_as_int(v), 0x122, 0xf, 0xf, false)); }
;   __device__ __forceinline__ void operator()(const AccT& acc, const Unit& u, int wr, int wc, int fr, int fq) const {
;     ...
;         for (int m = 0; m < 4; ++m) {
;           f32x4 res;
; #pragma unroll
;           for (int r = 0; r < 4; ++r) {
;             const float g_cur = xg[m][r], v_cur = xv[m][r];
;             const f32x4 xgp = xg[m > 0 ? m - 1 : 0], xvp = xv[m > 0 ? m - 1 : 0];
;             const float g_pm = (m > 0) ? xgp[r] : 0.f, v_pm = (m > 0) ? xvp[r] : 0.f;
;             const float g1 = dpp_ror1((fr == 15) ? g_pm : g_cur), g2 = dpp_ror2((fr >= 14) ? g_pm : g_cur);
;             const float v1 = dpp_ror1((fr == 15) ? v_pm : v_cur), v2 = dpp_ror2((fr >= 14) ? v_pm : v_cur);
	v_mov_b32_dpp v213, v163 row_ror:1 row_mask:0xf bank_mask:0xf

; __device__ __forceinline__ float dpp_ror1(float v) { return __int_as_float(__builtin_amdgcn_update_dpp(0, __float_as_int(v), 0x121, 0xf, 0xf, false)); }
; __device__ __forceinline__ float dpp_ror2(float v) { return __int_as_float(__builtin_amdgcn_update_dpp(0, __float_as_int(v), 0x122, 0xf, 0xf, false)); }
;   __device__ __forceinline__ void operator()(const AccT& acc, const Unit& u, int wr, int wc, int fr, int fq) const {
;     ...
;         for (int m = 0; m < 4; ++m) {
;           f32x4 res;
; #pragma unroll
;           for (int r = 0; r < 4; ++r) {
;             const float g_cur = xg[m][r], v_cur = xv[m][r];
;             const f32x4 xgp = xg[m > 0 ? m - 1 : 0], xvp = xv[m > 0 ? m - 1 : 0];
;             const float g_pm = (m > 0) ? xgp[r] : 0.f, v_pm = (m > 0) ? xvp[r] : 0.f;
;             const float g1 = dpp_ror1((fr == 15) ? g_pm : g_cur), g2 = dpp_ror2((fr >= 14) ? g_pm : g_cur);
;             const float v1 = dpp_ror1((fr == 15) ? v_pm : v_cur), v2 = dpp_ror2((fr >= 14) ? v_pm : v_cur);
	v_mov_b32_dpp v160, v161 row_ror:2 row_mask:0xf bank_mask:0xf
	v_cndmask_b32_e64 v161, v111, 0, s[8:9]
	s_nop 0
	s_nop 0
	v_mov_b32_dpp v163, v161 row_ror:1 row_mask:0xf bank_mask:0xf
	v_mov_b32_dpp v167, v159 row_ror:2 row_mask:0xf bank_mask:0xf
	v_cndmask_b32_e64 v161, v107, 0, s[8:9]

; __device__ __forceinline__ float dpp_ror1(float v) { return __int_as_float(__builtin_amdgcn_update_dpp(0, __float_as_int(v), 0x121, 0xf, 0xf, false)); }
; __device__ __forceinline__ float dpp_ror2(float v) { return __int_as_float(__builtin_amdgcn_update_dpp(0, __float_as_int(v), 0x122, 0xf, 0xf, false)); }
;   __device__ __forceinline__ void operator()(const AccT& acc, const Unit& u, int wr, int wc, int fr, int fq) const {
;     ...
;         for (int m = 0; m < 4; ++m) {
;           f32x4 res;
; #pragma unroll
;           for (int r = 0; r < 4; ++r) {
;             const float g_cur = xg[m][r], v_cur = xv[m][r];
;             const f32x4 xgp = xg[m > 0 ? m - 1 : 0], xvp = xv[m > 0 ? m - 1 : 0];
;             const float g_pm = (m > 0) ? xgp[r] : 0.f, v_pm = (m > 0) ? xvp[r] : 0.f;
;             const float g1 = dpp_ror1((fr == 15) ? g_pm : g_cur), g2 = dpp_ror2((fr >= 14) ? g_pm : g_cur);
;             const float v1 = dpp_ror1((fr == 15) ? v_pm : v_cur), v2 = dpp_ror2((fr >= 14) ? v_pm : v_cur);
	s_nop 1
	v_mov_b32_dpp v159, v161 row_ror:1 row_mask:0xf bank_mask:0xf

; __device__ __forceinline__ uint2 pack4(f32x4 v) { return make_uint2(pack2(v[0], v[1]), pack2(v[2], v[3])); }
; __device__ __forceinline__ float dpp_ror1(float v) { return __int_as_float(__builtin_amdgcn_update_dpp(0, __float_as_int(v), 0x121, 0xf, 0xf, false)); }
; __device__ __forceinline__ float dpp_ror2(float v) { return __int_as_float(__builtin_amdgcn_update_dpp(0, __float_as_int(v), 0x122, 0xf, 0xf, false)); }
;   __device__ __forceinline__ void operator()(const AccT& acc, const Unit& u, int wr, int wc, int fr, int fq) const {
;     ...
;         f32x4 xg[4], xv[4];
; #pragma unroll
;         for (int m = 0; m < 4; ++m) { xg[m] = acc[ai][0][m][n] * rs[m]; xv[m] = acc[ai][1][m][n] * rs[m]; }
;     ...
;         for (int m = 0; m < 4; ++m) {
;           f32x4 res;
; #pragma unroll
;           for (int r = 0; r < 4; ++r) {
;             const float g_cur = xg[m][r], v_cur = xv[m][r];
;             const f32x4 xgp = xg[m > 0 ? m - 1 : 0], xvp = xv[m > 0 ? m - 1 : 0];
;             const float g_pm = (m > 0) ? xgp[r] : 0.f, v_pm = (m > 0) ? xvp[r] : 0.f;
;             const float g1 = dpp_ror1((fr == 15) ? g_pm : g_cur), g2 = dpp_ror2((fr >= 14) ? g_pm : g_cur);
;             const float v1 = dpp_ror1((fr == 15) ? v_pm : v_cur), v2 = dpp_ror2((fr >= 14) ? v_pm : v_cur);
;             const float cg_ = bg[r] + g2 * wg0[r] + g1 * wg1[r] + g_cur * wg2[r];
;             const float cv_ = bv[r] + v2 * wv0[r] + v1 * wv1[r] + v_cur * wv2[r];
;             res[r] = cg_ * __builtin_amdgcn_rcpf(1.f + __builtin_amdgcn_exp2f(-1.4426950408889634f * cg_)) * cv_;
;           }
;           if (m > 0 || fr >= 2)
;             *(uint2*)(act + (size_t)EPI_ROW(u, ai, m) * DFF + f0) = pack4(res);
	s_nop 1
	v_mov_b32_dpp v161, v199 row_ror:2 row_mask:0xf bank_mask:0xf
	s_and_saveexec_b64 s[34:35], s[4:5]
	s_xor_b64 s[38:39], exec, s[34:35]
	s_andn2_saveexec_b64 s[38:39], s[38:39]
	s_cbranch_execz .LBB0_498
	s_waitcnt vmcnt(0)
	v_pk_fma_f32 v[166:167], v[114:115], v[166:167], v[142:143]
	v_pk_fma_f32 v[214:215], v[112:113], v[214:215], v[140:141]
	v_pk_fma_f32 v[162:163], v[118:119], v[162:163], v[166:167]
	v_pk_fma_f32 v[212:213], v[116:117], v[212:213], v[214:215]
	v_pk_fma_f32 v[162:163], v[110:111], v[126:127], v[162:163]
	v_pk_fma_f32 v[212:213], v[108:109], v[124:125], v[212:213]
	v_mul_f32_e32 v166, 0xbfb8aa3b, v162
	v_mul_f32_e32 v167, 0xbfb8aa3b, v163
	v_exp_f32_e32 v166, v166
	v_exp_f32_e32 v167, v167
	v_mul_f32_e32 v199, 0xbfb8aa3b, v212
	v_mul_f32_e32 v214, 0xbfb8aa3b, v213
	v_exp_f32_e32 v199, v199
	v_exp_f32_e32 v214, v214
	v_add_f32_e32 v166, 1.0, v166
	v_add_f32_e32 v167, 1.0, v167
	v_rcp_f32_e32 v166, v166
	v_rcp_f32_e32 v167, v167
	v_add_f32_e32 v199, 1.0, v199
	v_add_f32_e32 v215, 1.0, v214
	v_rcp_f32_e32 v214, v199
	v_rcp_f32_e32 v215, v215
	v_pk_fma_f32 v[160:161], v[122:123], v[160:161], v[138:139]
	v_pk_fma_f32 v[174:175], v[120:121], v[174:175], v[136:137]
	v_pk_fma_f32 v[158:159], v[130:131], v[158:159], v[160:161]
	v_pk_mul_f32 v[160:161], v[162:163], v[166:167]
	v_pk_fma_f32 v[158:159], v[106:107], v[134:135], v[158:159]
	v_pk_fma_f32 v[164:165], v[128:129], v[164:165], v[174:175]
	v_pk_mul_f32 v[158:159], v[158:159], v[160:161]
	v_pk_fma_f32 v[164:165], v[104:105], v[132:133], v[164:165]
	v_pk_mul_f32 v[174:175], v[212:213], v[214:215]
	v_cvt_pk_bf16_f32 v161, v158, v159
	v_mov_b64_e32 v[158:159], s[52:53]
	v_pk_mul_f32 v[164:165], v[164:165], v[174:175]
	v_mad_i64_i32 v[158:159], s[34:35], v198, s0, v[158:159]
	v_cvt_pk_bf16_f32 v160, v164, v165
	v_lshl_add_u64 v[158:159], v[188:189], 1, v[158:159]
	global_store_dwordx2 v[158:159], v[160:161], off offset:32
.LBB0_498:
	s_or_b64 exec, exec, s[38:39]
	v_mov_b32_e32 v225, v224
	v_mov_b32_e32 v227, v226
	v_mov_b32_e32 v158, v224
	v_mov_b32_e32 v159, v224
	v_pk_mul_f32 v[160:161], v[92:93], v[224:225]
	v_pk_mul_f32 v[92:93], v[86:87], v[158:159]
	v_mov_b32_e32 v162, v226
	v_mov_b32_e32 v163, v226
	v_pk_mul_f32 v[86:87], v[88:89], v[226:227]
	v_cndmask_b32_e64 v89, v160, v108, s[8:9]

; __device__ __forceinline__ float dpp_ror1(float v) { return __int_as_float(__builtin_amdgcn_update_dpp(0, __float_as_int(v), 0x121, 0xf, 0xf, false)); }
; __device__ __forceinline__ float dpp_ror2(float v) { return __int_as_float(__builtin_amdgcn_update_dpp(0, __float_as_int(v), 0x122, 0xf, 0xf, false)); }
;   __device__ __forceinline__ void operator()(const AccT& acc, const Unit& u, int wr, int wc, int fr, int fq) const {
;     ...
;         for (int m = 0; m < 4; ++m) { xg[m] = acc[ai][0][m][n] * rs[m]; xv[m] = acc[ai][1][m][n] * rs[m]; }
;         if (fr < 2) {
;           float* d = ub + ((size_t)(chunk * 4 + fr) * NUP + gc);
;           *(float4*)d = make_float4(xg[0][0], xg[0][1], xg[0][2], xg[0][3]);
;           *(float4*)(d + 128) = make_float4(xv[0][0], xv[0][1], xv[0][2], xv[0][3]);
;         }
;         if (fr >= 14) {
;           float* d = ub + ((size_t)(chunk * 4 + 2 + (fr - 14)) * NUP + gc);
;           *(float4*)d = make_float4(xg[3][0], xg[3][1], xg[3][2], xg[3][3]);
;           *(float4*)(d + 128) = make_float4(xv[3][0], xv[3][1], xv[3][2], xv[3][3]);
;         }
; #pragma unroll
;         for (int m = 0; m < 4; ++m) {
;           f32x4 res;
; #pragma unroll
;           for (int r = 0; r < 4; ++r) {
;             const float g_cur = xg[m][r], v_cur = xv[m][r];
;             const f32x4 xgp = xg[m > 0 ? m - 1 : 0], xvp = xv[m > 0 ? m - 1 : 0];
;             const float g_pm = (m > 0) ? xgp[r] : 0.f, v_pm = (m > 0) ? xvp[r] : 0.f;
;             const float g1 = dpp_ror1((fr == 15) ? g_pm : g_cur), g2 = dpp_ror2((fr >= 14) ? g_pm : g_cur);
;             const float v1 = dpp_ror1((fr == 15) ? v_pm : v_cur), v2 = dpp_ror2((fr >= 14) ? v_pm : v_cur);
	v_pk_mul_f32 v[94:95], v[94:95], v[158:159]
	v_pk_mul_f32 v[158:159], v[84:85], v[224:225]
	v_pk_mul_f32 v[84:85], v[90:91], v[162:163]
	v_mov_b32_dpp v88, v89 row_ror:1 row_mask:0xf bank_mask:0xf
	v_cndmask_b32_e64 v89, v160, v108, s[6:7]
	s_nop 0

; __device__ __forceinline__ float dpp_ror1(float v) { return __int_as_float(__builtin_amdgcn_update_dpp(0, __float_as_int(v), 0x121, 0xf, 0xf, false)); }
; __device__ __forceinline__ float dpp_ror2(float v) { return __int_as_float(__builtin_amdgcn_update_dpp(0, __float_as_int(v), 0x122, 0xf, 0xf, false)); }
;   __device__ __forceinline__ void operator()(const AccT& acc, const Unit& u, int wr, int wc, int fr, int fq) const {
;     ...
;         for (int m = 0; m < 4; ++m) {
;           f32x4 res;
; #pragma unroll
;           for (int r = 0; r < 4; ++r) {
;             const float g_cur = xg[m][r], v_cur = xv[m][r];
;             const f32x4 xgp = xg[m > 0 ? m - 1 : 0], xvp = xv[m > 0 ? m - 1 : 0];
;             const float g_pm = (m > 0) ? xgp[r] : 0.f, v_pm = (m > 0) ? xvp[r] : 0.f;
;             const float g1 = dpp_ror1((fr == 15) ? g_pm : g_cur), g2 = dpp_ror2((fr >= 14) ? g_pm : g_cur);
;             const float v1 = dpp_ror1((fr == 15) ? v_pm : v_cur), v2 = dpp_ror2((fr >= 14) ? v_pm : v_cur);
	v_cndmask_b32_e64 v91, v161, v109, s[8:9]
	v_mov_b32_dpp v90, v89 row_ror:2 row_mask:0xf bank_mask:0xf
	v_cndmask_b32_e64 v89, v158, v104, s[8:9]
	v_cndmask_b32_e64 v109, v161, v109, s[6:7]
	v_pk_mul_f32 v[82:83], v[82:83], v[162:163]
	v_mov_b32_dpp v108, v89 row_ror:1 row_mask:0xf bank_mask:0xf
	v_cndmask_b32_e64 v89, v158, v104, s[6:7]

; __device__ __forceinline__ float dpp_ror1(float v) { return __int_as_float(__builtin_amdgcn_update_dpp(0, __float_as_int(v), 0x121, 0xf, 0xf, false)); }
; __device__ __forceinline__ float dpp_ror2(float v) { return __int_as_float(__builtin_amdgcn_update_dpp(0, __float_as_int(v), 0x122, 0xf, 0xf, false)); }
;   __device__ __forceinline__ void operator()(const AccT& acc, const Unit& u, int wr, int wc, int fr, int fq) const {
;     ...
;         for (int m = 0; m < 4; ++m) {
;           f32x4 res;
; #pragma unroll
;           for (int r = 0; r < 4; ++r) {
;             const float g_cur = xg[m][r], v_cur = xv[m][r];
;             const f32x4 xgp = xg[m > 0 ? m - 1 : 0], xvp = xv[m > 0 ? m - 1 : 0];
;             const float g_pm = (m > 0) ? xgp[r] : 0.f, v_pm = (m > 0) ? xvp[r] : 0.f;
;             const float g1 = dpp_ror1((fr == 15) ? g_pm : g_cur), g2 = dpp_ror2((fr >= 14) ? g_pm : g_cur);
;             const float v1 = dpp_ror1((fr == 15) ? v_pm : v_cur), v2 = dpp_ror2((fr >= 14) ? v_pm : v_cur);
	v_cndmask_b32_e64 v162, v159, v105, s[8:9]
	v_cndmask_b32_e64 v163, v94, v110, s[8:9]
	v_mov_b32_dpp v104, v89 row_ror:2 row_mask:0xf bank_mask:0xf


; __device__ __forceinline__ float dpp_ror1(float v) { return __int_as_float(__builtin_amdgcn_update_dpp(0, __float_as_int(v), 0x121, 0xf, 0xf, false)); }
; __device__ __forceinline__ float dpp_ror2(float v) { return __int_as_float(__builtin_amdgcn_update_dpp(0, __float_as_int(v), 0x122, 0xf, 0xf, false)); }
;   __device__ __forceinline__ void operator()(const AccT& acc, const Unit& u, int wr, int wc, int fr, int fq) const {
;     ...
;         for (int m = 0; m < 4; ++m) {
;           f32x4 res;
; #pragma unroll
;           for (int r = 0; r < 4; ++r) {
;             const float g_cur = xg[m][r], v_cur = xv[m][r];
;             const f32x4 xgp = xg[m > 0 ? m - 1 : 0], xvp = xv[m > 0 ? m - 1 : 0];
;             const float g_pm = (m > 0) ? xgp[r] : 0.f, v_pm = (m > 0) ? xvp[r] : 0.f;
;             const float g1 = dpp_ror1((fr == 15) ? g_pm : g_cur), g2 = dpp_ror2((fr >= 14) ? g_pm : g_cur);
;             const float v1 = dpp_ror1((fr == 15) ? v_pm : v_cur), v2 = dpp_ror2((fr >= 14) ? v_pm : v_cur);
	v_cndmask_b32_e64 v165, v95, v111, s[8:9]
	v_mov_b32_dpp v89, v91 row_ror:1 row_mask:0xf bank_mask:0xf

; __device__ __forceinline__ float dpp_ror1(float v) { return __int_as_float(__builtin_amdgcn_update_dpp(0, __float_as_int(v), 0x121, 0xf, 0xf, false)); }
; __device__ __forceinline__ float dpp_ror2(float v) { return __int_as_float(__builtin_amdgcn_update_dpp(0, __float_as_int(v), 0x122, 0xf, 0xf, false)); }
;   __device__ __forceinline__ void operator()(const AccT& acc, const Unit& u, int wr, int wc, int fr, int fq) const {
;     ...
;         for (int m = 0; m < 4; ++m) {
;           f32x4 res;
; #pragma unroll
;           for (int r = 0; r < 4; ++r) {
;             const float g_cur = xg[m][r], v_cur = xv[m][r];
;             const f32x4 xgp = xg[m > 0 ? m - 1 : 0], xvp = xv[m > 0 ? m - 1 : 0];
;             const float g_pm = (m > 0) ? xgp[r] : 0.f, v_pm = (m > 0) ? xvp[r] : 0.f;
;             const float g1 = dpp_ror1((fr == 15) ? g_pm : g_cur), g2 = dpp_ror2((fr >= 14) ? g_pm : g_cur);
;             const float v1 = dpp_ror1((fr == 15) ? v_pm : v_cur), v2 = dpp_ror2((fr >= 14) ? v_pm : v_cur);
;             const float cg_ = bg[r] + g2 * wg0[r] + g1 * wg1[r] + g_cur * wg2[r];
	v_cndmask_b32_e64 v166, v93, v107, s[8:9]
	v_pk_mul_f32 v[80:81], v[80:81], v[226:227]
	v_mov_b32_dpp v91, v109 row_ror:2 row_mask:0xf bank_mask:0xf
	s_waitcnt vmcnt(0)
	v_pk_fma_f32 v[90:91], v[112:113], v[90:91], v[140:141]

; __device__ __forceinline__ float dpp_ror1(float v) { return __int_as_float(__builtin_amdgcn_update_dpp(0, __float_as_int(v), 0x121, 0xf, 0xf, false)); }
; __device__ __forceinline__ float dpp_ror2(float v) { return __int_as_float(__builtin_amdgcn_update_dpp(0, __float_as_int(v), 0x122, 0xf, 0xf, false)); }
;   __device__ __forceinline__ void operator()(const AccT& acc, const Unit& u, int wr, int wc, int fr, int fq) const {
;     ...
;         for (int m = 0; m < 4; ++m) {
;           f32x4 res;
; #pragma unroll
;           for (int r = 0; r < 4; ++r) {
;             const float g_cur = xg[m][r], v_cur = xv[m][r];
;             const f32x4 xgp = xg[m > 0 ? m - 1 : 0], xvp = xv[m > 0 ? m - 1 : 0];
;             const float g_pm = (m > 0) ? xgp[r] : 0.f, v_pm = (m > 0) ? xvp[r] : 0.f;
;             const float g1 = dpp_ror1((fr == 15) ? g_pm : g_cur), g2 = dpp_ror2((fr >= 14) ? g_pm : g_cur);
;             const float v1 = dpp_ror1((fr == 15) ? v_pm : v_cur), v2 = dpp_ror2((fr >= 14) ? v_pm : v_cur);
;             const float cg_ = bg[r] + g2 * wg0[r] + g1 * wg1[r] + g_cur * wg2[r];
;             const float cv_ = bv[r] + v2 * wv0[r] + v1 * wv1[r] + v_cur * wv2[r];
;             res[r] = cg_ * __builtin_amdgcn_rcpf(1.f + __builtin_amdgcn_exp2f(-1.4426950408889634f * cg_)) * cv_;
	v_pk_fma_f32 v[88:89], v[116:117], v[88:89], v[90:91]
	s_add_i32 s40, s40, 8
	v_pk_fma_f32 v[88:89], v[160:161], v[124:125], v[88:89]
	v_mov_b32_dpp v109, v162 row_ror:1 row_mask:0xf bank_mask:0xf
	v_mul_f32_e32 v90, 0xbfb8aa3b, v88
	v_mul_f32_e32 v91, 0xbfb8aa3b, v89
	v_exp_f32_e32 v90, v90
	v_exp_f32_e32 v91, v91
	v_cndmask_b32_e64 v162, v159, v105, s[6:7]

; __device__ __forceinline__ float dpp_ror1(float v) { return __int_as_float(__builtin_amdgcn_update_dpp(0, __float_as_int(v), 0x121, 0xf, 0xf, false)); }
; __device__ __forceinline__ float dpp_ror2(float v) { return __int_as_float(__builtin_amdgcn_update_dpp(0, __float_as_int(v), 0x122, 0xf, 0xf, false)); }
;   __device__ __forceinline__ void operator()(const AccT& acc, const Unit& u, int wr, int wc, int fr, int fq) const {
;     ...
;         for (int m = 0; m < 4; ++m) {
;           f32x4 res;
; #pragma unroll
;           for (int r = 0; r < 4; ++r) {
;             const float g_cur = xg[m][r], v_cur = xv[m][r];
;             const f32x4 xgp = xg[m > 0 ? m - 1 : 0], xvp = xv[m > 0 ? m - 1 : 0];
;             const float g_pm = (m > 0) ? xgp[r] : 0.f, v_pm = (m > 0) ? xvp[r] : 0.f;
;             const float g1 = dpp_ror1((fr == 15) ? g_pm : g_cur), g2 = dpp_ror2((fr >= 14) ? g_pm : g_cur);
;             const float v1 = dpp_ror1((fr == 15) ? v_pm : v_cur), v2 = dpp_ror2((fr >= 14) ? v_pm : v_cur);
;             const float cg_ = bg[r] + g2 * wg0[r] + g1 * wg1[r] + g_cur * wg2[r];
;             const float cv_ = bv[r] + v2 * wv0[r] + v1 * wv1[r] + v_cur * wv2[r];
;             res[r] = cg_ * __builtin_amdgcn_rcpf(1.f + __builtin_amdgcn_exp2f(-1.4426950408889634f * cg_)) * cv_;
	v_add_f32_e32 v90, 1.0, v90
	v_add_f32_e32 v91, 1.0, v91
	v_mov_b32_dpp v105, v162 row_ror:2 row_mask:0xf bank_mask:0xf

; __device__ __forceinline__ float dpp_ror1(float v) { return __int_as_float(__builtin_amdgcn_update_dpp(0, __float_as_int(v), 0x121, 0xf, 0xf, false)); }
; __device__ __forceinline__ float dpp_ror2(float v) { return __int_as_float(__builtin_amdgcn_update_dpp(0, __float_as_int(v), 0x122, 0xf, 0xf, false)); }
;   __device__ __forceinline__ void operator()(const AccT& acc, const Unit& u, int wr, int wc, int fr, int fq) const {
;     ...
;         for (int m = 0; m < 4; ++m) {
;           f32x4 res;
; #pragma unroll
;           for (int r = 0; r < 4; ++r) {
;             const float g_cur = xg[m][r], v_cur = xv[m][r];
;             const f32x4 xgp = xg[m > 0 ? m - 1 : 0], xvp = xv[m > 0 ? m - 1 : 0];
;             const float g_pm = (m > 0) ? xgp[r] : 0.f, v_pm = (m > 0) ? xvp[r] : 0.f;
;             const float g1 = dpp_ror1((fr == 15) ? g_pm : g_cur), g2 = dpp_ror2((fr >= 14) ? g_pm : g_cur);
;             const float v1 = dpp_ror1((fr == 15) ? v_pm : v_cur), v2 = dpp_ror2((fr >= 14) ? v_pm : v_cur);
;             const float cg_ = bg[r] + g2 * wg0[r] + g1 * wg1[r] + g_cur * wg2[r];
;             const float cv_ = bv[r] + v2 * wv0[r] + v1 * wv1[r] + v_cur * wv2[r];
;             res[r] = cg_ * __builtin_amdgcn_rcpf(1.f + __builtin_amdgcn_exp2f(-1.4426950408889634f * cg_)) * cv_;
	v_rcp_f32_e32 v90, v90
	v_rcp_f32_e32 v91, v91
	v_mov_b32_dpp v162, v163 row_ror:1 row_mask:0xf bank_mask:0xf
	v_cndmask_b32_e64 v163, v94, v110, s[6:7]

; __device__ __forceinline__ float dpp_ror1(float v) { return __int_as_float(__builtin_amdgcn_update_dpp(0, __float_as_int(v), 0x121, 0xf, 0xf, false)); }
; __device__ __forceinline__ float dpp_ror2(float v) { return __int_as_float(__builtin_amdgcn_update_dpp(0, __float_as_int(v), 0x122, 0xf, 0xf, false)); }
;   __device__ __forceinline__ void operator()(const AccT& acc, const Unit& u, int wr, int wc, int fr, int fq) const {
;     ...
;         for (int m = 0; m < 4; ++m) {
;           f32x4 res;
; #pragma unroll
;           for (int r = 0; r < 4; ++r) {
;             const float g_cur = xg[m][r], v_cur = xv[m][r];
;             const f32x4 xgp = xg[m > 0 ? m - 1 : 0], xvp = xv[m > 0 ? m - 1 : 0];
;             const float g_pm = (m > 0) ? xgp[r] : 0.f, v_pm = (m > 0) ? xvp[r] : 0.f;
;             const float g1 = dpp_ror1((fr == 15) ? g_pm : g_cur), g2 = dpp_ror2((fr >= 14) ? g_pm : g_cur);
;             const float v1 = dpp_ror1((fr == 15) ? v_pm : v_cur), v2 = dpp_ror2((fr >= 14) ? v_pm : v_cur);
;             const float cg_ = bg[r] + g2 * wg0[r] + g1 * wg1[r] + g_cur * wg2[r];
;             const float cv_ = bv[r] + v2 * wv0[r] + v1 * wv1[r] + v_cur * wv2[r];
;             res[r] = cg_ * __builtin_amdgcn_rcpf(1.f + __builtin_amdgcn_exp2f(-1.4426950408889634f * cg_)) * cv_;
	v_pk_fma_f32 v[104:105], v[120:121], v[104:105], v[136:137]
	v_pk_mul_f32 v[88:89], v[88:89], v[90:91]
	v_mov_b32_dpp v110, v163 row_ror:2 row_mask:0xf bank_mask:0xf
	v_cndmask_b32_e64 v163, v92, v106, s[8:9]
	v_pk_fma_f32 v[104:105], v[128:129], v[108:109], v[104:105]
	v_cndmask_b32_e64 v108, v81, v159, s[6:7]
	v_mov_b32_dpp v164, v163 row_ror:1 row_mask:0xf bank_mask:0xf
	v_cndmask_b32_e64 v163, v92, v106, s[6:7]

; __device__ __forceinline__ float dpp_ror1(float v) { return __int_as_float(__builtin_amdgcn_update_dpp(0, __float_as_int(v), 0x121, 0xf, 0xf, false)); }
; __device__ __forceinline__ float dpp_ror2(float v) { return __int_as_float(__builtin_amdgcn_update_dpp(0, __float_as_int(v), 0x122, 0xf, 0xf, false)); }
;   __device__ __forceinline__ void operator()(const AccT& acc, const Unit& u, int wr, int wc, int fr, int fq) const {
;     ...
;         for (int m = 0; m < 4; ++m) {
;           f32x4 res;
; #pragma unroll
;           for (int r = 0; r < 4; ++r) {
;             const float g_cur = xg[m][r], v_cur = xv[m][r];
;             const f32x4 xgp = xg[m > 0 ? m - 1 : 0], xvp = xv[m > 0 ? m - 1 : 0];
;             const float g_pm = (m > 0) ? xgp[r] : 0.f, v_pm = (m > 0) ? xvp[r] : 0.f;
;             const float g1 = dpp_ror1((fr == 15) ? g_pm : g_cur), g2 = dpp_ror2((fr >= 14) ? g_pm : g_cur);
;             const float v1 = dpp_ror1((fr == 15) ? v_pm : v_cur), v2 = dpp_ror2((fr >= 14) ? v_pm : v_cur);
;             const float cg_ = bg[r] + g2 * wg0[r] + g1 * wg1[r] + g_cur * wg2[r];
;             const float cv_ = bv[r] + v2 * wv0[r] + v1 * wv1[r] + v_cur * wv2[r];
;             res[r] = cg_ * __builtin_amdgcn_rcpf(1.f + __builtin_amdgcn_exp2f(-1.4426950408889634f * cg_)) * cv_;
	v_pk_fma_f32 v[104:105], v[158:159], v[132:133], v[104:105]
	v_cndmask_b32_e64 v109, v84, v94, s[8:9]
	v_mov_b32_dpp v106, v163 row_ror:2 row_mask:0xf bank_mask:0xf

; __device__ __forceinline__ float dpp_ror1(float v) { return __int_as_float(__builtin_amdgcn_update_dpp(0, __float_as_int(v), 0x121, 0xf, 0xf, false)); }
; __device__ __forceinline__ float dpp_ror2(float v) { return __int_as_float(__builtin_amdgcn_update_dpp(0, __float_as_int(v), 0x122, 0xf, 0xf, false)); }
;   __device__ __forceinline__ void operator()(const AccT& acc, const Unit& u, int wr, int wc, int fr, int fq) const {
;     ...
;         for (int m = 0; m < 4; ++m) {
;           f32x4 res;
; #pragma unroll
;           for (int r = 0; r < 4; ++r) {
;             const float g_cur = xg[m][r], v_cur = xv[m][r];
;             const f32x4 xgp = xg[m > 0 ? m - 1 : 0], xvp = xv[m > 0 ? m - 1 : 0];
;             const float g_pm = (m > 0) ? xgp[r] : 0.f, v_pm = (m > 0) ? xvp[r] : 0.f;
;             const float g1 = dpp_ror1((fr == 15) ? g_pm : g_cur), g2 = dpp_ror2((fr >= 14) ? g_pm : g_cur);
;             const float v1 = dpp_ror1((fr == 15) ? v_pm : v_cur), v2 = dpp_ror2((fr >= 14) ? v_pm : v_cur);
;             const float cg_ = bg[r] + g2 * wg0[r] + g1 * wg1[r] + g_cur * wg2[r];
;             const float cv_ = bv[r] + v2 * wv0[r] + v1 * wv1[r] + v_cur * wv2[r];
;             res[r] = cg_ * __builtin_amdgcn_rcpf(1.f + __builtin_amdgcn_exp2f(-1.4426950408889634f * cg_)) * cv_;
	v_pk_mul_f32 v[88:89], v[104:105], v[88:89]
	s_nop 0
	v_mov_b32_dpp v163, v165 row_ror:1 row_mask:0xf bank_mask:0xf
	v_cndmask_b32_e64 v165, v95, v111, s[6:7]

; __device__ __forceinline__ uint2 pack4(f32x4 v) { return make_uint2(pack2(v[0], v[1]), pack2(v[2], v[3])); }
; __device__ __forceinline__ float dpp_ror1(float v) { return __int_as_float(__builtin_amdgcn_update_dpp(0, __float_as_int(v), 0x121, 0xf, 0xf, false)); }
; __device__ __forceinline__ float dpp_ror2(float v) { return __int_as_float(__builtin_amdgcn_update_dpp(0, __float_as_int(v), 0x122, 0xf, 0xf, false)); }
;   __device__ __forceinline__ void operator()(const AccT& acc, const Unit& u, int wr, int wc, int fr, int fq) const {
;     ...
;         for (int m = 0; m < 4; ++m) {
;           f32x4 res;
; #pragma unroll
;           for (int r = 0; r < 4; ++r) {
;             const float g_cur = xg[m][r], v_cur = xv[m][r];
;             const f32x4 xgp = xg[m > 0 ? m - 1 : 0], xvp = xv[m > 0 ? m - 1 : 0];
;             const float g_pm = (m > 0) ? xgp[r] : 0.f, v_pm = (m > 0) ? xvp[r] : 0.f;
;             const float g1 = dpp_ror1((fr == 15) ? g_pm : g_cur), g2 = dpp_ror2((fr >= 14) ? g_pm : g_cur);
;             const float v1 = dpp_ror1((fr == 15) ? v_pm : v_cur), v2 = dpp_ror2((fr >= 14) ? v_pm : v_cur);
;             const float cg_ = bg[r] + g2 * wg0[r] + g1 * wg1[r] + g_cur * wg2[r];
;             const float cv_ = bv[r] + v2 * wv0[r] + v1 * wv1[r] + v_cur * wv2[r];
;             res[r] = cg_ * __builtin_amdgcn_rcpf(1.f + __builtin_amdgcn_exp2f(-1.4426950408889634f * cg_)) * cv_;
;           }
;           if (m > 0 || fr >= 2)
;             *(uint2*)(act + (size_t)EPI_ROW(u, ai, m) * DFF + f0) = pack4(res);
	v_cvt_pk_bf16_f32 v88, v88, v89
	s_nop 0
	v_mov_b32_dpp v111, v165 row_ror:2 row_mask:0xf bank_mask:0xf
	v_pk_fma_f32 v[90:91], v[114:115], v[110:111], v[142:143]

; __device__ __forceinline__ float dpp_ror1(float v) { return __int_as_float(__builtin_amdgcn_update_dpp(0, __float_as_int(v), 0x121, 0xf, 0xf, false)); }
; __device__ __forceinline__ float dpp_ror2(float v) { return __int_as_float(__builtin_amdgcn_update_dpp(0, __float_as_int(v), 0x122, 0xf, 0xf, false)); }
;   __device__ __forceinline__ void operator()(const AccT& acc, const Unit& u, int wr, int wc, int fr, int fq) const {
;     ...
;         for (int m = 0; m < 4; ++m) {
;           f32x4 res;
; #pragma unroll
;           for (int r = 0; r < 4; ++r) {
;             const float g_cur = xg[m][r], v_cur = xv[m][r];
;             const f32x4 xgp = xg[m > 0 ? m - 1 : 0], xvp = xv[m > 0 ? m - 1 : 0];
;             const float g_pm = (m > 0) ? xgp[r] : 0.f, v_pm = (m > 0) ? xvp[r] : 0.f;
;             const float g1 = dpp_ror1((fr == 15) ? g_pm : g_cur), g2 = dpp_ror2((fr >= 14) ? g_pm : g_cur);
;             const float v1 = dpp_ror1((fr == 15) ? v_pm : v_cur), v2 = dpp_ror2((fr >= 14) ? v_pm : v_cur);
;             const float cg_ = bg[r] + g2 * wg0[r] + g1 * wg1[r] + g_cur * wg2[r];
;             const float cv_ = bv[r] + v2 * wv0[r] + v1 * wv1[r] + v_cur * wv2[r];
;             res[r] = cg_ * __builtin_amdgcn_rcpf(1.f + __builtin_amdgcn_exp2f(-1.4426950408889634f * cg_)) * cv_;
	v_pk_fma_f32 v[90:91], v[118:119], v[162:163], v[90:91]

; __device__ __forceinline__ float dpp_ror1(float v) { return __int_as_float(__builtin_amdgcn_update_dpp(0, __float_as_int(v), 0x121, 0xf, 0xf, false)); }
; __device__ __forceinline__ float dpp_ror2(float v) { return __int_as_float(__builtin_amdgcn_update_dpp(0, __float_as_int(v), 0x122, 0xf, 0xf, false)); }
;   __device__ __forceinline__ void operator()(const AccT& acc, const Unit& u, int wr, int wc, int fr, int fq) const {
;     ...
;         for (int m = 0; m < 4; ++m) {
;           f32x4 res;
; #pragma unroll
;           for (int r = 0; r < 4; ++r) {
;             const float g_cur = xg[m][r], v_cur = xv[m][r];
;             const f32x4 xgp = xg[m > 0 ? m - 1 : 0], xvp = xv[m > 0 ? m - 1 : 0];
;             const float g_pm = (m > 0) ? xgp[r] : 0.f, v_pm = (m > 0) ? xvp[r] : 0.f;
;             const float g1 = dpp_ror1((fr == 15) ? g_pm : g_cur), g2 = dpp_ror2((fr >= 14) ? g_pm : g_cur);
;             const float v1 = dpp_ror1((fr == 15) ? v_pm : v_cur), v2 = dpp_ror2((fr >= 14) ? v_pm : v_cur);
;             const float cg_ = bg[r] + g2 * wg0[r] + g1 * wg1[r] + g_cur * wg2[r];
;             const float cv_ = bv[r] + v2 * wv0[r] + v1 * wv1[r] + v_cur * wv2[r];
;             res[r] = cg_ * __builtin_amdgcn_rcpf(1.f + __builtin_amdgcn_exp2f(-1.4426950408889634f * cg_)) * cv_;
	v_pk_fma_f32 v[90:91], v[94:95], v[126:127], v[90:91]
	v_mov_b32_dpp v165, v166 row_ror:1 row_mask:0xf bank_mask:0xf
	v_mul_f32_e32 v104, 0xbfb8aa3b, v90
	v_mul_f32_e32 v105, 0xbfb8aa3b, v91
	v_exp_f32_e32 v104, v104
	v_exp_f32_e32 v105, v105
	v_cndmask_b32_e64 v166, v93, v107, s[6:7]

; __device__ __forceinline__ float dpp_ror1(float v) { return __int_as_float(__builtin_amdgcn_update_dpp(0, __float_as_int(v), 0x121, 0xf, 0xf, false)); }
; __device__ __forceinline__ float dpp_ror2(float v) { return __int_as_float(__builtin_amdgcn_update_dpp(0, __float_as_int(v), 0x122, 0xf, 0xf, false)); }
;   __device__ __forceinline__ void operator()(const AccT& acc, const Unit& u, int wr, int wc, int fr, int fq) const {
;     ...
;         for (int m = 0; m < 4; ++m) {
;           f32x4 res;
; #pragma unroll
;           for (int r = 0; r < 4; ++r) {
;             const float g_cur = xg[m][r], v_cur = xv[m][r];
;             const f32x4 xgp = xg[m > 0 ? m - 1 : 0], xvp = xv[m > 0 ? m - 1 : 0];
;             const float g_pm = (m > 0) ? xgp[r] : 0.f, v_pm = (m > 0) ? xvp[r] : 0.f;
;             const float g1 = dpp_ror1((fr == 15) ? g_pm : g_cur), g2 = dpp_ror2((fr >= 14) ? g_pm : g_cur);
;             const float v1 = dpp_ror1((fr == 15) ? v_pm : v_cur), v2 = dpp_ror2((fr >= 14) ? v_pm : v_cur);
;             const float cg_ = bg[r] + g2 * wg0[r] + g1 * wg1[r] + g_cur * wg2[r];
;             const float cv_ = bv[r] + v2 * wv0[r] + v1 * wv1[r] + v_cur * wv2[r];
;             res[r] = cg_ * __builtin_amdgcn_rcpf(1.f + __builtin_amdgcn_exp2f(-1.4426950408889634f * cg_)) * cv_;
	v_add_f32_e32 v104, 1.0, v104
	v_add_f32_e32 v105, 1.0, v105
	v_rcp_f32_e32 v104, v104
	v_rcp_f32_e32 v105, v105
	v_mov_b32_dpp v107, v166 row_ror:2 row_mask:0xf bank_mask:0xf
	v_pk_fma_f32 v[106:107], v[122:123], v[106:107], v[138:139]
	v_cndmask_b32_e64 v111, v85, v95, s[8:9]
	v_pk_fma_f32 v[106:107], v[130:131], v[164:165], v[106:107]
	v_pk_mul_f32 v[90:91], v[90:91], v[104:105]
	v_pk_fma_f32 v[106:107], v[92:93], v[134:135], v[106:107]

; __device__ __forceinline__ float dpp_ror1(float v) { return __int_as_float(__builtin_amdgcn_update_dpp(0, __float_as_int(v), 0x121, 0xf, 0xf, false)); }
; __device__ __forceinline__ float dpp_ror2(float v) { return __int_as_float(__builtin_amdgcn_update_dpp(0, __float_as_int(v), 0x122, 0xf, 0xf, false)); }
;   __device__ __forceinline__ void operator()(const AccT& acc, const Unit& u, int wr, int wc, int fr, int fq) const {
;     ...
;         for (int m = 0; m < 4; ++m) {
;           f32x4 res;
; #pragma unroll
;           for (int r = 0; r < 4; ++r) {
;             const float g_cur = xg[m][r], v_cur = xv[m][r];
;             const f32x4 xgp = xg[m > 0 ? m - 1 : 0], xvp = xv[m > 0 ? m - 1 : 0];
;             const float g_pm = (m > 0) ? xgp[r] : 0.f, v_pm = (m > 0) ? xvp[r] : 0.f;
;             const float g1 = dpp_ror1((fr == 15) ? g_pm : g_cur), g2 = dpp_ror2((fr >= 14) ? g_pm : g_cur);
;             const float v1 = dpp_ror1((fr == 15) ? v_pm : v_cur), v2 = dpp_ror2((fr >= 14) ? v_pm : v_cur);
;             const float cg_ = bg[r] + g2 * wg0[r] + g1 * wg1[r] + g_cur * wg2[r];
;             const float cv_ = bv[r] + v2 * wv0[r] + v1 * wv1[r] + v_cur * wv2[r];
;             res[r] = cg_ * __builtin_amdgcn_rcpf(1.f + __builtin_amdgcn_exp2f(-1.4426950408889634f * cg_)) * cv_;
	v_pk_mul_f32 v[90:91], v[106:107], v[90:91]

; __device__ __forceinline__ uint2 pack4(f32x4 v) { return make_uint2(pack2(v[0], v[1]), pack2(v[2], v[3])); }
; __device__ __forceinline__ float dpp_ror1(float v) { return __int_as_float(__builtin_amdgcn_update_dpp(0, __float_as_int(v), 0x121, 0xf, 0xf, false)); }
; __device__ __forceinline__ float dpp_ror2(float v) { return __int_as_float(__builtin_amdgcn_update_dpp(0, __float_as_int(v), 0x122, 0xf, 0xf, false)); }
;   __device__ __forceinline__ void operator()(const AccT& acc, const Unit& u, int wr, int wc, int fr, int fq) const {
;     ...
;         for (int m = 0; m < 4; ++m) {
;           f32x4 res;
; #pragma unroll
;           for (int r = 0; r < 4; ++r) {
;             const float g_cur = xg[m][r], v_cur = xv[m][r];
;             const f32x4 xgp = xg[m > 0 ? m - 1 : 0], xvp = xv[m > 0 ? m - 1 : 0];
;             const float g_pm = (m > 0) ? xgp[r] : 0.f, v_pm = (m > 0) ? xvp[r] : 0.f;
;             const float g1 = dpp_ror1((fr == 15) ? g_pm : g_cur), g2 = dpp_ror2((fr >= 14) ? g_pm : g_cur);
;             const float v1 = dpp_ror1((fr == 15) ? v_pm : v_cur), v2 = dpp_ror2((fr >= 14) ? v_pm : v_cur);
;             const float cg_ = bg[r] + g2 * wg0[r] + g1 * wg1[r] + g_cur * wg2[r];
;             const float cv_ = bv[r] + v2 * wv0[r] + v1 * wv1[r] + v_cur * wv2[r];
;             res[r] = cg_ * __builtin_amdgcn_rcpf(1.f + __builtin_amdgcn_exp2f(-1.4426950408889634f * cg_)) * cv_;
;           }
;           if (m > 0 || fr >= 2)
;             *(uint2*)(act + (size_t)EPI_ROW(u, ai, m) * DFF + f0) = pack4(res);
	v_cvt_pk_bf16_f32 v89, v90, v91
	global_store_dwordx2 v[170:171], v[88:89], off offset:32
	v_cndmask_b32_e64 v89, v86, v160, s[8:9]
	s_nop 0

; __device__ __forceinline__ float dpp_ror1(float v) { return __int_as_float(__builtin_amdgcn_update_dpp(0, __float_as_int(v), 0x121, 0xf, 0xf, false)); }
; __device__ __forceinline__ float dpp_ror2(float v) { return __int_as_float(__builtin_amdgcn_update_dpp(0, __float_as_int(v), 0x122, 0xf, 0xf, false)); }
;   __device__ __forceinline__ void operator()(const AccT& acc, const Unit& u, int wr, int wc, int fr, int fq) const {
;     ...
;         for (int m = 0; m < 4; ++m) {
;           f32x4 res;
; #pragma unroll
;           for (int r = 0; r < 4; ++r) {
;             const float g_cur = xg[m][r], v_cur = xv[m][r];
;             const f32x4 xgp = xg[m > 0 ? m - 1 : 0], xvp = xv[m > 0 ? m - 1 : 0];
;             const float g_pm = (m > 0) ? xgp[r] : 0.f, v_pm = (m > 0) ? xvp[r] : 0.f;
;             const float g1 = dpp_ror1((fr == 15) ? g_pm : g_cur), g2 = dpp_ror2((fr >= 14) ? g_pm : g_cur);
;             const float v1 = dpp_ror1((fr == 15) ? v_pm : v_cur), v2 = dpp_ror2((fr >= 14) ? v_pm : v_cur);
	v_cndmask_b32_e64 v91, v87, v161, s[8:9]
	v_mov_b32_dpp v88, v89 row_ror:1 row_mask:0xf bank_mask:0xf
	v_cndmask_b32_e64 v89, v86, v160, s[6:7]
	v_cndmask_b32_e64 v105, v87, v161, s[6:7]
	v_cndmask_b32_e64 v107, v81, v159, s[8:9]
	v_mov_b32_dpp v90, v89 row_ror:2 row_mask:0xf bank_mask:0xf
	v_cndmask_b32_e64 v89, v80, v158, s[8:9]
	s_nop 1
	v_mov_b32_dpp v104, v89 row_ror:1 row_mask:0xf bank_mask:0xf
	v_cndmask_b32_e64 v89, v80, v158, s[6:7]
	v_cndmask_b32_e64 v158, v83, v93, s[8:9]
	s_nop 0
	v_mov_b32_dpp v106, v89 row_ror:2 row_mask:0xf bank_mask:0xf

; __device__ __forceinline__ float dpp_ror1(float v) { return __int_as_float(__builtin_amdgcn_update_dpp(0, __float_as_int(v), 0x121, 0xf, 0xf, false)); }
; __device__ __forceinline__ float dpp_ror2(float v) { return __int_as_float(__builtin_amdgcn_update_dpp(0, __float_as_int(v), 0x122, 0xf, 0xf, false)); }
;   __device__ __forceinline__ void operator()(const AccT& acc, const Unit& u, int wr, int wc, int fr, int fq) const {
;     ...
;         for (int m = 0; m < 4; ++m) {
;           f32x4 res;
; #pragma unroll
;           for (int r = 0; r < 4; ++r) {
;             const float g_cur = xg[m][r], v_cur = xv[m][r];
;             const f32x4 xgp = xg[m > 0 ? m - 1 : 0], xvp = xv[m > 0 ? m - 1 : 0];
;             const float g_pm = (m > 0) ? xgp[r] : 0.f, v_pm = (m > 0) ? xvp[r] : 0.f;
;             const float g1 = dpp_ror1((fr == 15) ? g_pm : g_cur), g2 = dpp_ror2((fr >= 14) ? g_pm : g_cur);
;             const float v1 = dpp_ror1((fr == 15) ? v_pm : v_cur), v2 = dpp_ror2((fr >= 14) ? v_pm : v_cur);
	s_nop 1
	v_mov_b32_dpp v89, v91 row_ror:1 row_mask:0xf bank_mask:0xf

; __device__ __forceinline__ float dpp_ror1(float v) { return __int_as_float(__builtin_amdgcn_update_dpp(0, __float_as_int(v), 0x121, 0xf, 0xf, false)); }
; __device__ __forceinline__ float dpp_ror2(float v) { return __int_as_float(__builtin_amdgcn_update_dpp(0, __float_as_int(v), 0x122, 0xf, 0xf, false)); }
;   __device__ __forceinline__ void operator()(const AccT& acc, const Unit& u, int wr, int wc, int fr, int fq) const {
;     ...
;         for (int m = 0; m < 4; ++m) {
;           f32x4 res;
; #pragma unroll
;           for (int r = 0; r < 4; ++r) {
;             const float g_cur = xg[m][r], v_cur = xv[m][r];
;             const f32x4 xgp = xg[m > 0 ? m - 1 : 0], xvp = xv[m > 0 ? m - 1 : 0];
;             const float g_pm = (m > 0) ? xgp[r] : 0.f, v_pm = (m > 0) ? xvp[r] : 0.f;
;             const float g1 = dpp_ror1((fr == 15) ? g_pm : g_cur), g2 = dpp_ror2((fr >= 14) ? g_pm : g_cur);
;             const float v1 = dpp_ror1((fr == 15) ? v_pm : v_cur), v2 = dpp_ror2((fr >= 14) ? v_pm : v_cur);
;             const float cg_ = bg[r] + g2 * wg0[r] + g1 * wg1[r] + g_cur * wg2[r];
	s_nop 1
	v_mov_b32_dpp v91, v105 row_ror:2 row_mask:0xf bank_mask:0xf
	v_pk_fma_f32 v[90:91], v[112:113], v[90:91], v[140:141]

; __device__ __forceinline__ float dpp_ror1(float v) { return __int_as_float(__builtin_amdgcn_update_dpp(0, __float_as_int(v), 0x121, 0xf, 0xf, false)); }
; __device__ __forceinline__ float dpp_ror2(float v) { return __int_as_float(__builtin_amdgcn_update_dpp(0, __float_as_int(v), 0x122, 0xf, 0xf, false)); }
;   __device__ __forceinline__ void operator()(const AccT& acc, const Unit& u, int wr, int wc, int fr, int fq) const {
;     ...
;         for (int m = 0; m < 4; ++m) {
;           f32x4 res;
; #pragma unroll
;           for (int r = 0; r < 4; ++r) {
;             const float g_cur = xg[m][r], v_cur = xv[m][r];
;             const f32x4 xgp = xg[m > 0 ? m - 1 : 0], xvp = xv[m > 0 ? m - 1 : 0];
;             const float g_pm = (m > 0) ? xgp[r] : 0.f, v_pm = (m > 0) ? xvp[r] : 0.f;
;             const float g1 = dpp_ror1((fr == 15) ? g_pm : g_cur), g2 = dpp_ror2((fr >= 14) ? g_pm : g_cur);
;             const float v1 = dpp_ror1((fr == 15) ? v_pm : v_cur), v2 = dpp_ror2((fr >= 14) ? v_pm : v_cur);
;             const float cg_ = bg[r] + g2 * wg0[r] + g1 * wg1[r] + g_cur * wg2[r];
;             const float cv_ = bv[r] + v2 * wv0[r] + v1 * wv1[r] + v_cur * wv2[r];
;             res[r] = cg_ * __builtin_amdgcn_rcpf(1.f + __builtin_amdgcn_exp2f(-1.4426950408889634f * cg_)) * cv_;
	v_pk_fma_f32 v[88:89], v[116:117], v[88:89], v[90:91]
	s_nop 0
	v_pk_fma_f32 v[88:89], v[86:87], v[124:125], v[88:89]
	v_mov_b32_dpp v105, v107 row_ror:1 row_mask:0xf bank_mask:0xf
	v_mul_f32_e32 v90, 0xbfb8aa3b, v88
	v_mul_f32_e32 v91, 0xbfb8aa3b, v89
	v_exp_f32_e32 v90, v90
	v_exp_f32_e32 v91, v91

; __device__ __forceinline__ float dpp_ror1(float v) { return __int_as_float(__builtin_amdgcn_update_dpp(0, __float_as_int(v), 0x121, 0xf, 0xf, false)); }
; __device__ __forceinline__ float dpp_ror2(float v) { return __int_as_float(__builtin_amdgcn_update_dpp(0, __float_as_int(v), 0x122, 0xf, 0xf, false)); }
;   __device__ __forceinline__ void operator()(const AccT& acc, const Unit& u, int wr, int wc, int fr, int fq) const {
;     ...
;         for (int m = 0; m < 4; ++m) {
;           f32x4 res;
; #pragma unroll
;           for (int r = 0; r < 4; ++r) {
;             const float g_cur = xg[m][r], v_cur = xv[m][r];
;             const f32x4 xgp = xg[m > 0 ? m - 1 : 0], xvp = xv[m > 0 ? m - 1 : 0];
;             const float g_pm = (m > 0) ? xgp[r] : 0.f, v_pm = (m > 0) ? xvp[r] : 0.f;
;             const float g1 = dpp_ror1((fr == 15) ? g_pm : g_cur), g2 = dpp_ror2((fr >= 14) ? g_pm : g_cur);
;             const float v1 = dpp_ror1((fr == 15) ? v_pm : v_cur), v2 = dpp_ror2((fr >= 14) ? v_pm : v_cur);
;             const float cg_ = bg[r] + g2 * wg0[r] + g1 * wg1[r] + g_cur * wg2[r];
;             const float cv_ = bv[r] + v2 * wv0[r] + v1 * wv1[r] + v_cur * wv2[r];
;             res[r] = cg_ * __builtin_amdgcn_rcpf(1.f + __builtin_amdgcn_exp2f(-1.4426950408889634f * cg_)) * cv_;
	v_add_f32_e32 v90, 1.0, v90
	s_nop 0
	v_mov_b32_dpp v107, v108 row_ror:2 row_mask:0xf bank_mask:0xf

; __device__ __forceinline__ float dpp_ror1(float v) { return __int_as_float(__builtin_amdgcn_update_dpp(0, __float_as_int(v), 0x121, 0xf, 0xf, false)); }
; __device__ __forceinline__ float dpp_ror2(float v) { return __int_as_float(__builtin_amdgcn_update_dpp(0, __float_as_int(v), 0x122, 0xf, 0xf, false)); }
;   __device__ __forceinline__ void operator()(const AccT& acc, const Unit& u, int wr, int wc, int fr, int fq) const {
;     ...
;         for (int m = 0; m < 4; ++m) {
;           f32x4 res;
; #pragma unroll
;           for (int r = 0; r < 4; ++r) {
;             const float g_cur = xg[m][r], v_cur = xv[m][r];
;             const f32x4 xgp = xg[m > 0 ? m - 1 : 0], xvp = xv[m > 0 ? m - 1 : 0];
;             const float g_pm = (m > 0) ? xgp[r] : 0.f, v_pm = (m > 0) ? xvp[r] : 0.f;
;             const float g1 = dpp_ror1((fr == 15) ? g_pm : g_cur), g2 = dpp_ror2((fr >= 14) ? g_pm : g_cur);
;             const float v1 = dpp_ror1((fr == 15) ? v_pm : v_cur), v2 = dpp_ror2((fr >= 14) ? v_pm : v_cur);
;             const float cg_ = bg[r] + g2 * wg0[r] + g1 * wg1[r] + g_cur * wg2[r];
;             const float cv_ = bv[r] + v2 * wv0[r] + v1 * wv1[r] + v_cur * wv2[r];
;             res[r] = cg_ * __builtin_amdgcn_rcpf(1.f + __builtin_amdgcn_exp2f(-1.4426950408889634f * cg_)) * cv_;
	v_add_f32_e32 v91, 1.0, v91
	v_rcp_f32_e32 v90, v90
	v_mov_b32_dpp v108, v109 row_ror:1 row_mask:0xf bank_mask:0xf
	v_cndmask_b32_e64 v109, v84, v94, s[6:7]

; __device__ __forceinline__ float dpp_ror1(float v) { return __int_as_float(__builtin_amdgcn_update_dpp(0, __float_as_int(v), 0x121, 0xf, 0xf, false)); }
; __device__ __forceinline__ float dpp_ror2(float v) { return __int_as_float(__builtin_amdgcn_update_dpp(0, __float_as_int(v), 0x122, 0xf, 0xf, false)); }
;   __device__ __forceinline__ void operator()(const AccT& acc, const Unit& u, int wr, int wc, int fr, int fq) const {
;     ...
;         for (int m = 0; m < 4; ++m) {
;           f32x4 res;
; #pragma unroll
;           for (int r = 0; r < 4; ++r) {
;             const float g_cur = xg[m][r], v_cur = xv[m][r];
;             const f32x4 xgp = xg[m > 0 ? m - 1 : 0], xvp = xv[m > 0 ? m - 1 : 0];
;             const float g_pm = (m > 0) ? xgp[r] : 0.f, v_pm = (m > 0) ? xvp[r] : 0.f;
;             const float g1 = dpp_ror1((fr == 15) ? g_pm : g_cur), g2 = dpp_ror2((fr >= 14) ? g_pm : g_cur);
;             const float v1 = dpp_ror1((fr == 15) ? v_pm : v_cur), v2 = dpp_ror2((fr >= 14) ? v_pm : v_cur);
;             const float cg_ = bg[r] + g2 * wg0[r] + g1 * wg1[r] + g_cur * wg2[r];
;             const float cv_ = bv[r] + v2 * wv0[r] + v1 * wv1[r] + v_cur * wv2[r];
;             res[r] = cg_ * __builtin_amdgcn_rcpf(1.f + __builtin_amdgcn_exp2f(-1.4426950408889634f * cg_)) * cv_;
	v_rcp_f32_e32 v91, v91
	v_pk_fma_f32 v[106:107], v[120:121], v[106:107], v[136:137]
	v_mov_b32_dpp v94, v109 row_ror:2 row_mask:0xf bank_mask:0xf
	v_cndmask_b32_e64 v109, v82, v92, s[8:9]
	v_pk_mul_f32 v[88:89], v[88:89], v[90:91]
	v_pk_fma_f32 v[104:105], v[128:129], v[104:105], v[106:107]
	v_mov_b32_dpp v110, v109 row_ror:1 row_mask:0xf bank_mask:0xf
	v_cndmask_b32_e64 v109, v82, v92, s[6:7]

; __device__ __forceinline__ float dpp_ror1(float v) { return __int_as_float(__builtin_amdgcn_update_dpp(0, __float_as_int(v), 0x121, 0xf, 0xf, false)); }
; __device__ __forceinline__ float dpp_ror2(float v) { return __int_as_float(__builtin_amdgcn_update_dpp(0, __float_as_int(v), 0x122, 0xf, 0xf, false)); }
;   __device__ __forceinline__ void operator()(const AccT& acc, const Unit& u, int wr, int wc, int fr, int fq) const {
;     ...
;         for (int m = 0; m < 4; ++m) {
;           f32x4 res;
; #pragma unroll
;           for (int r = 0; r < 4; ++r) {
;             const float g_cur = xg[m][r], v_cur = xv[m][r];
;             const f32x4 xgp = xg[m > 0 ? m - 1 : 0], xvp = xv[m > 0 ? m - 1 : 0];
;             const float g_pm = (m > 0) ? xgp[r] : 0.f, v_pm = (m > 0) ? xvp[r] : 0.f;
;             const float g1 = dpp_ror1((fr == 15) ? g_pm : g_cur), g2 = dpp_ror2((fr >= 14) ? g_pm : g_cur);
;             const float v1 = dpp_ror1((fr == 15) ? v_pm : v_cur), v2 = dpp_ror2((fr >= 14) ? v_pm : v_cur);
;             const float cg_ = bg[r] + g2 * wg0[r] + g1 * wg1[r] + g_cur * wg2[r];
;             const float cv_ = bv[r] + v2 * wv0[r] + v1 * wv1[r] + v_cur * wv2[r];
;             res[r] = cg_ * __builtin_amdgcn_rcpf(1.f + __builtin_amdgcn_exp2f(-1.4426950408889634f * cg_)) * cv_;
	v_pk_fma_f32 v[104:105], v[80:81], v[132:133], v[104:105]
	s_nop 0
	v_mov_b32_dpp v92, v109 row_ror:2 row_mask:0xf bank_mask:0xf

; __device__ __forceinline__ float dpp_ror1(float v) { return __int_as_float(__builtin_amdgcn_update_dpp(0, __float_as_int(v), 0x121, 0xf, 0xf, false)); }
; __device__ __forceinline__ float dpp_ror2(float v) { return __int_as_float(__builtin_amdgcn_update_dpp(0, __float_as_int(v), 0x122, 0xf, 0xf, false)); }
;   __device__ __forceinline__ void operator()(const AccT& acc, const Unit& u, int wr, int wc, int fr, int fq) const {
;     ...
;         for (int m = 0; m < 4; ++m) {
;           f32x4 res;
; #pragma unroll
;           for (int r = 0; r < 4; ++r) {
;             const float g_cur = xg[m][r], v_cur = xv[m][r];
;             const f32x4 xgp = xg[m > 0 ? m - 1 : 0], xvp = xv[m > 0 ? m - 1 : 0];
;             const float g_pm = (m > 0) ? xgp[r] : 0.f, v_pm = (m > 0) ? xvp[r] : 0.f;
;             const float g1 = dpp_ror1((fr == 15) ? g_pm : g_cur), g2 = dpp_ror2((fr >= 14) ? g_pm : g_cur);
;             const float v1 = dpp_ror1((fr == 15) ? v_pm : v_cur), v2 = dpp_ror2((fr >= 14) ? v_pm : v_cur);
;             const float cg_ = bg[r] + g2 * wg0[r] + g1 * wg1[r] + g_cur * wg2[r];
;             const float cv_ = bv[r] + v2 * wv0[r] + v1 * wv1[r] + v_cur * wv2[r];
;             res[r] = cg_ * __builtin_amdgcn_rcpf(1.f + __builtin_amdgcn_exp2f(-1.4426950408889634f * cg_)) * cv_;
	v_pk_mul_f32 v[88:89], v[104:105], v[88:89]
	v_cndmask_b32_e64 v104, v99, v83, s[8:9]
	v_mov_b32_dpp v109, v111 row_ror:1 row_mask:0xf bank_mask:0xf
	v_cndmask_b32_e64 v111, v85, v95, s[6:7]

; __device__ __forceinline__ uint2 pack4(f32x4 v) { return make_uint2(pack2(v[0], v[1]), pack2(v[2], v[3])); }
; __device__ __forceinline__ float dpp_ror1(float v) { return __int_as_float(__builtin_amdgcn_update_dpp(0, __float_as_int(v), 0x121, 0xf, 0xf, false)); }
; __device__ __forceinline__ float dpp_ror2(float v) { return __int_as_float(__builtin_amdgcn_update_dpp(0, __float_as_int(v), 0x122, 0xf, 0xf, false)); }
;   __device__ __forceinline__ void operator()(const AccT& acc, const Unit& u, int wr, int wc, int fr, int fq) const {
;     ...
;         for (int m = 0; m < 4; ++m) {
;           f32x4 res;
; #pragma unroll
;           for (int r = 0; r < 4; ++r) {
;             const float g_cur = xg[m][r], v_cur = xv[m][r];
;             const f32x4 xgp = xg[m > 0 ? m - 1 : 0], xvp = xv[m > 0 ? m - 1 : 0];
;             const float g_pm = (m > 0) ? xgp[r] : 0.f, v_pm = (m > 0) ? xvp[r] : 0.f;
;             const float g1 = dpp_ror1((fr == 15) ? g_pm : g_cur), g2 = dpp_ror2((fr >= 14) ? g_pm : g_cur);
;             const float v1 = dpp_ror1((fr == 15) ? v_pm : v_cur), v2 = dpp_ror2((fr >= 14) ? v_pm : v_cur);
;             const float cg_ = bg[r] + g2 * wg0[r] + g1 * wg1[r] + g_cur * wg2[r];
;             const float cv_ = bv[r] + v2 * wv0[r] + v1 * wv1[r] + v_cur * wv2[r];
;             res[r] = cg_ * __builtin_amdgcn_rcpf(1.f + __builtin_amdgcn_exp2f(-1.4426950408889634f * cg_)) * cv_;
;           }
;           if (m > 0 || fr >= 2)
;             *(uint2*)(act + (size_t)EPI_ROW(u, ai, m) * DFF + f0) = pack4(res);
	v_cvt_pk_bf16_f32 v88, v88, v89
	s_nop 0
	v_mov_b32_dpp v95, v111 row_ror:2 row_mask:0xf bank_mask:0xf
	v_pk_fma_f32 v[90:91], v[114:115], v[94:95], v[142:143]

; __device__ __forceinline__ float dpp_ror1(float v) { return __int_as_float(__builtin_amdgcn_update_dpp(0, __float_as_int(v), 0x121, 0xf, 0xf, false)); }
; __device__ __forceinline__ float dpp_ror2(float v) { return __int_as_float(__builtin_amdgcn_update_dpp(0, __float_as_int(v), 0x122, 0xf, 0xf, false)); }
;   __device__ __forceinline__ void operator()(const AccT& acc, const Unit& u, int wr, int wc, int fr, int fq) const {
;     ...
;         for (int m = 0; m < 4; ++m) {
;           f32x4 res;
; #pragma unroll
;           for (int r = 0; r < 4; ++r) {
;             const float g_cur = xg[m][r], v_cur = xv[m][r];
;             const f32x4 xgp = xg[m > 0 ? m - 1 : 0], xvp = xv[m > 0 ? m - 1 : 0];
;             const float g_pm = (m > 0) ? xgp[r] : 0.f, v_pm = (m > 0) ? xvp[r] : 0.f;
;             const float g1 = dpp_ror1((fr == 15) ? g_pm : g_cur), g2 = dpp_ror2((fr >= 14) ? g_pm : g_cur);
;             const float v1 = dpp_ror1((fr == 15) ? v_pm : v_cur), v2 = dpp_ror2((fr >= 14) ? v_pm : v_cur);
;             const float cg_ = bg[r] + g2 * wg0[r] + g1 * wg1[r] + g_cur * wg2[r];
;             const float cv_ = bv[r] + v2 * wv0[r] + v1 * wv1[r] + v_cur * wv2[r];
;             res[r] = cg_ * __builtin_amdgcn_rcpf(1.f + __builtin_amdgcn_exp2f(-1.4426950408889634f * cg_)) * cv_;
	v_pk_fma_f32 v[90:91], v[118:119], v[108:109], v[90:91]
	s_nop 0
	v_pk_fma_f32 v[90:91], v[84:85], v[126:127], v[90:91]
	v_mov_b32_dpp v111, v158 row_ror:1 row_mask:0xf bank_mask:0xf
	v_mul_f32_e32 v94, 0xbfb8aa3b, v90
	v_mul_f32_e32 v95, 0xbfb8aa3b, v91
	v_exp_f32_e32 v94, v94
	v_exp_f32_e32 v95, v95
	v_cndmask_b32_e64 v158, v83, v93, s[6:7]

; __device__ __forceinline__ float dpp_ror1(float v) { return __int_as_float(__builtin_amdgcn_update_dpp(0, __float_as_int(v), 0x121, 0xf, 0xf, false)); }
; __device__ __forceinline__ float dpp_ror2(float v) { return __int_as_float(__builtin_amdgcn_update_dpp(0, __float_as_int(v), 0x122, 0xf, 0xf, false)); }
;   __device__ __forceinline__ void operator()(const AccT& acc, const Unit& u, int wr, int wc, int fr, int fq) const {
;     ...
;         for (int m = 0; m < 4; ++m) {
;           f32x4 res;
; #pragma unroll
;           for (int r = 0; r < 4; ++r) {
;             const float g_cur = xg[m][r], v_cur = xv[m][r];
;             const f32x4 xgp = xg[m > 0 ? m - 1 : 0], xvp = xv[m > 0 ? m - 1 : 0];
;             const float g_pm = (m > 0) ? xgp[r] : 0.f, v_pm = (m > 0) ? xvp[r] : 0.f;
;             const float g1 = dpp_ror1((fr == 15) ? g_pm : g_cur), g2 = dpp_ror2((fr >= 14) ? g_pm : g_cur);
;             const float v1 = dpp_ror1((fr == 15) ? v_pm : v_cur), v2 = dpp_ror2((fr >= 14) ? v_pm : v_cur);
;             const float cg_ = bg[r] + g2 * wg0[r] + g1 * wg1[r] + g_cur * wg2[r];
;             const float cv_ = bv[r] + v2 * wv0[r] + v1 * wv1[r] + v_cur * wv2[r];
;             res[r] = cg_ * __builtin_amdgcn_rcpf(1.f + __builtin_amdgcn_exp2f(-1.4426950408889634f * cg_)) * cv_;
	v_add_f32_e32 v94, 1.0, v94
	v_add_f32_e32 v95, 1.0, v95
	v_rcp_f32_e32 v94, v94
	v_rcp_f32_e32 v95, v95
	v_mov_b32_dpp v93, v158 row_ror:2 row_mask:0xf bank_mask:0xf
	v_pk_fma_f32 v[92:93], v[122:123], v[92:93], v[138:139]
	v_pk_mul_f32 v[90:91], v[90:91], v[94:95]
	v_pk_fma_f32 v[92:93], v[130:131], v[110:111], v[92:93]

; __device__ __forceinline__ uint2 pack4(f32x4 v) { return make_uint2(pack2(v[0], v[1]), pack2(v[2], v[3])); }
; __device__ __forceinline__ float dpp_ror1(float v) { return __int_as_float(__builtin_amdgcn_update_dpp(0, __float_as_int(v), 0x121, 0xf, 0xf, false)); }
; __device__ __forceinline__ float dpp_ror2(float v) { return __int_as_float(__builtin_amdgcn_update_dpp(0, __float_as_int(v), 0x122, 0xf, 0xf, false)); }
;   __device__ __forceinline__ void operator()(const AccT& acc, const Unit& u, int wr, int wc, int fr, int fq) const {
;     ...
;         for (int m = 0; m < 4; ++m) {
;           f32x4 res;
; #pragma unroll
;           for (int r = 0; r < 4; ++r) {
;             const float g_cur = xg[m][r], v_cur = xv[m][r];
;             const f32x4 xgp = xg[m > 0 ? m - 1 : 0], xvp = xv[m > 0 ? m - 1 : 0];
;             const float g_pm = (m > 0) ? xgp[r] : 0.f, v_pm = (m > 0) ? xvp[r] : 0.f;
;             const float g1 = dpp_ror1((fr == 15) ? g_pm : g_cur), g2 = dpp_ror2((fr >= 14) ? g_pm : g_cur);
;             const float v1 = dpp_ror1((fr == 15) ? v_pm : v_cur), v2 = dpp_ror2((fr >= 14) ? v_pm : v_cur);
;             const float cg_ = bg[r] + g2 * wg0[r] + g1 * wg1[r] + g_cur * wg2[r];
;             const float cv_ = bv[r] + v2 * wv0[r] + v1 * wv1[r] + v_cur * wv2[r];
;             res[r] = cg_ * __builtin_amdgcn_rcpf(1.f + __builtin_amdgcn_exp2f(-1.4426950408889634f * cg_)) * cv_;
;           }
;           if (m > 0 || fr >= 2)
;             *(uint2*)(act + (size_t)EPI_ROW(u, ai, m) * DFF + f0) = pack4(res);
	v_pk_fma_f32 v[92:93], v[82:83], v[134:135], v[92:93]
	v_cndmask_b32_e64 v95, v103, v85, s[8:9]
	v_pk_mul_f32 v[90:91], v[92:93], v[90:91]
	v_cndmask_b32_e64 v92, v97, v81, s[8:9]
	v_cvt_pk_bf16_f32 v89, v90, v91
	global_store_dwordx2 v[172:173], v[88:89], off offset:32
	v_cndmask_b32_e64 v89, v100, v86, s[8:9]
	s_nop 0

; __device__ __forceinline__ float dpp_ror1(float v) { return __int_as_float(__builtin_amdgcn_update_dpp(0, __float_as_int(v), 0x121, 0xf, 0xf, false)); }
; __device__ __forceinline__ float dpp_ror2(float v) { return __int_as_float(__builtin_amdgcn_update_dpp(0, __float_as_int(v), 0x122, 0xf, 0xf, false)); }
;   __device__ __forceinline__ void operator()(const AccT& acc, const Unit& u, int wr, int wc, int fr, int fq) const {
;     ...
;         for (int m = 0; m < 4; ++m) {
;           f32x4 res;
; #pragma unroll
;           for (int r = 0; r < 4; ++r) {
;             const float g_cur = xg[m][r], v_cur = xv[m][r];
;             const f32x4 xgp = xg[m > 0 ? m - 1 : 0], xvp = xv[m > 0 ? m - 1 : 0];
;             const float g_pm = (m > 0) ? xgp[r] : 0.f, v_pm = (m > 0) ? xvp[r] : 0.f;
;             const float g1 = dpp_ror1((fr == 15) ? g_pm : g_cur), g2 = dpp_ror2((fr >= 14) ? g_pm : g_cur);
;             const float v1 = dpp_ror1((fr == 15) ? v_pm : v_cur), v2 = dpp_ror2((fr >= 14) ? v_pm : v_cur);
	v_cndmask_b32_e64 v91, v101, v87, s[8:9]
	v_mov_b32_dpp v88, v89 row_ror:1 row_mask:0xf bank_mask:0xf
	v_cndmask_b32_e64 v89, v100, v86, s[6:7]

; __device__ __forceinline__ float dpp_ror1(float v) { return __int_as_float(__builtin_amdgcn_update_dpp(0, __float_as_int(v), 0x121, 0xf, 0xf, false)); }
; __device__ __forceinline__ float dpp_ror2(float v) { return __int_as_float(__builtin_amdgcn_update_dpp(0, __float_as_int(v), 0x122, 0xf, 0xf, false)); }
;   __device__ __forceinline__ void operator()(const AccT& acc, const Unit& u, int wr, int wc, int fr, int fq) const {
;     ...
;         for (int m = 0; m < 4; ++m) {
;           f32x4 res;
; #pragma unroll
;           for (int r = 0; r < 4; ++r) {
;             const float g_cur = xg[m][r], v_cur = xv[m][r];
;             const f32x4 xgp = xg[m > 0 ? m - 1 : 0], xvp = xv[m > 0 ? m - 1 : 0];
;             const float g_pm = (m > 0) ? xgp[r] : 0.f, v_pm = (m > 0) ? xvp[r] : 0.f;
;             const float g1 = dpp_ror1((fr == 15) ? g_pm : g_cur), g2 = dpp_ror2((fr >= 14) ? g_pm : g_cur);
;             const float v1 = dpp_ror1((fr == 15) ? v_pm : v_cur), v2 = dpp_ror2((fr >= 14) ? v_pm : v_cur);
	v_cndmask_b32_e64 v93, v102, v84, s[8:9]
	s_nop 0
	v_mov_b32_dpp v86, v89 row_ror:2 row_mask:0xf bank_mask:0xf
	v_cndmask_b32_e64 v89, v96, v80, s[8:9]
	s_nop 1
	v_mov_b32_dpp v90, v89 row_ror:1 row_mask:0xf bank_mask:0xf
	v_cndmask_b32_e64 v89, v96, v80, s[6:7]

; __device__ __forceinline__ float dpp_ror1(float v) { return __int_as_float(__builtin_amdgcn_update_dpp(0, __float_as_int(v), 0x121, 0xf, 0xf, false)); }
; __device__ __forceinline__ float dpp_ror2(float v) { return __int_as_float(__builtin_amdgcn_update_dpp(0, __float_as_int(v), 0x122, 0xf, 0xf, false)); }
;   __device__ __forceinline__ void operator()(const AccT& acc, const Unit& u, int wr, int wc, int fr, int fq) const {
;     ...
;         for (int m = 0; m < 4; ++m) {
;           f32x4 res;
; #pragma unroll
;           for (int r = 0; r < 4; ++r) {
;             const float g_cur = xg[m][r], v_cur = xv[m][r];
;             const f32x4 xgp = xg[m > 0 ? m - 1 : 0], xvp = xv[m > 0 ? m - 1 : 0];
;             const float g_pm = (m > 0) ? xgp[r] : 0.f, v_pm = (m > 0) ? xvp[r] : 0.f;
;             const float g1 = dpp_ror1((fr == 15) ? g_pm : g_cur), g2 = dpp_ror2((fr >= 14) ? g_pm : g_cur);
;             const float v1 = dpp_ror1((fr == 15) ? v_pm : v_cur), v2 = dpp_ror2((fr >= 14) ? v_pm : v_cur);
	s_nop 1
	v_mov_b32_dpp v80, v89 row_ror:2 row_mask:0xf bank_mask:0xf

; __device__ __forceinline__ float dpp_ror1(float v) { return __int_as_float(__builtin_amdgcn_update_dpp(0, __float_as_int(v), 0x121, 0xf, 0xf, false)); }
; __device__ __forceinline__ float dpp_ror2(float v) { return __int_as_float(__builtin_amdgcn_update_dpp(0, __float_as_int(v), 0x122, 0xf, 0xf, false)); }
;   __device__ __forceinline__ void operator()(const AccT& acc, const Unit& u, int wr, int wc, int fr, int fq) const {
;     ...
;         for (int m = 0; m < 4; ++m) {
;           f32x4 res;
; #pragma unroll
;           for (int r = 0; r < 4; ++r) {
;             const float g_cur = xg[m][r], v_cur = xv[m][r];
;             const f32x4 xgp = xg[m > 0 ? m - 1 : 0], xvp = xv[m > 0 ? m - 1 : 0];
;             const float g_pm = (m > 0) ? xgp[r] : 0.f, v_pm = (m > 0) ? xvp[r] : 0.f;
;             const float g1 = dpp_ror1((fr == 15) ? g_pm : g_cur), g2 = dpp_ror2((fr >= 14) ? g_pm : g_cur);
;             const float v1 = dpp_ror1((fr == 15) ? v_pm : v_cur), v2 = dpp_ror2((fr >= 14) ? v_pm : v_cur);
	s_nop 1
	v_mov_b32_dpp v89, v91 row_ror:1 row_mask:0xf bank_mask:0xf
	v_cndmask_b32_e64 v91, v101, v87, s[6:7]

; __device__ __forceinline__ float dpp_ror1(float v) { return __int_as_float(__builtin_amdgcn_update_dpp(0, __float_as_int(v), 0x121, 0xf, 0xf, false)); }
; __device__ __forceinline__ float dpp_ror2(float v) { return __int_as_float(__builtin_amdgcn_update_dpp(0, __float_as_int(v), 0x122, 0xf, 0xf, false)); }
;   __device__ __forceinline__ void operator()(const AccT& acc, const Unit& u, int wr, int wc, int fr, int fq) const {
;     ...
;         for (int m = 0; m < 4; ++m) {
;           f32x4 res;
; #pragma unroll
;           for (int r = 0; r < 4; ++r) {
;             const float g_cur = xg[m][r], v_cur = xv[m][r];
;             const f32x4 xgp = xg[m > 0 ? m - 1 : 0], xvp = xv[m > 0 ? m - 1 : 0];
;             const float g_pm = (m > 0) ? xgp[r] : 0.f, v_pm = (m > 0) ? xvp[r] : 0.f;
;             const float g1 = dpp_ror1((fr == 15) ? g_pm : g_cur), g2 = dpp_ror2((fr >= 14) ? g_pm : g_cur);
;             const float v1 = dpp_ror1((fr == 15) ? v_pm : v_cur), v2 = dpp_ror2((fr >= 14) ? v_pm : v_cur);
;             const float cg_ = bg[r] + g2 * wg0[r] + g1 * wg1[r] + g_cur * wg2[r];
	s_nop 1
	v_mov_b32_dpp v87, v91 row_ror:2 row_mask:0xf bank_mask:0xf
	v_pk_fma_f32 v[86:87], v[112:113], v[86:87], v[140:141]

; __device__ __forceinline__ float dpp_ror1(float v) { return __int_as_float(__builtin_amdgcn_update_dpp(0, __float_as_int(v), 0x121, 0xf, 0xf, false)); }
; __device__ __forceinline__ float dpp_ror2(float v) { return __int_as_float(__builtin_amdgcn_update_dpp(0, __float_as_int(v), 0x122, 0xf, 0xf, false)); }
;   __device__ __forceinline__ void operator()(const AccT& acc, const Unit& u, int wr, int wc, int fr, int fq) const {
;     ...
;         for (int m = 0; m < 4; ++m) {
;           f32x4 res;
; #pragma unroll
;           for (int r = 0; r < 4; ++r) {
;             const float g_cur = xg[m][r], v_cur = xv[m][r];
;             const f32x4 xgp = xg[m > 0 ? m - 1 : 0], xvp = xv[m > 0 ? m - 1 : 0];
;             const float g_pm = (m > 0) ? xgp[r] : 0.f, v_pm = (m > 0) ? xvp[r] : 0.f;
;             const float g1 = dpp_ror1((fr == 15) ? g_pm : g_cur), g2 = dpp_ror2((fr >= 14) ? g_pm : g_cur);
;             const float v1 = dpp_ror1((fr == 15) ? v_pm : v_cur), v2 = dpp_ror2((fr >= 14) ? v_pm : v_cur);
;             const float cg_ = bg[r] + g2 * wg0[r] + g1 * wg1[r] + g_cur * wg2[r];
;             const float cv_ = bv[r] + v2 * wv0[r] + v1 * wv1[r] + v_cur * wv2[r];
;             res[r] = cg_ * __builtin_amdgcn_rcpf(1.f + __builtin_amdgcn_exp2f(-1.4426950408889634f * cg_)) * cv_;
	v_pk_fma_f32 v[86:87], v[116:117], v[88:89], v[86:87]
	v_add_u32_e32 v112, 0x80, v198
	v_pk_fma_f32 v[86:87], v[100:101], v[124:125], v[86:87]
	v_mov_b32_dpp v91, v92 row_ror:1 row_mask:0xf bank_mask:0xf
	v_cndmask_b32_e64 v92, v97, v81, s[6:7]

; __device__ __forceinline__ float dpp_ror1(float v) { return __int_as_float(__builtin_amdgcn_update_dpp(0, __float_as_int(v), 0x121, 0xf, 0xf, false)); }
; __device__ __forceinline__ float dpp_ror2(float v) { return __int_as_float(__builtin_amdgcn_update_dpp(0, __float_as_int(v), 0x122, 0xf, 0xf, false)); }
;   __device__ __forceinline__ void operator()(const AccT& acc, const Unit& u, int wr, int wc, int fr, int fq) const {
;     ...
;         for (int m = 0; m < 4; ++m) {
;           f32x4 res;
; #pragma unroll
;           for (int r = 0; r < 4; ++r) {
;             const float g_cur = xg[m][r], v_cur = xv[m][r];
;             const f32x4 xgp = xg[m > 0 ? m - 1 : 0], xvp = xv[m > 0 ? m - 1 : 0];
;             const float g_pm = (m > 0) ? xgp[r] : 0.f, v_pm = (m > 0) ? xvp[r] : 0.f;
;             const float g1 = dpp_ror1((fr == 15) ? g_pm : g_cur), g2 = dpp_ror2((fr >= 14) ? g_pm : g_cur);
;             const float v1 = dpp_ror1((fr == 15) ? v_pm : v_cur), v2 = dpp_ror2((fr >= 14) ? v_pm : v_cur);
;             const float cg_ = bg[r] + g2 * wg0[r] + g1 * wg1[r] + g_cur * wg2[r];
;             const float cv_ = bv[r] + v2 * wv0[r] + v1 * wv1[r] + v_cur * wv2[r];
;             res[r] = cg_ * __builtin_amdgcn_rcpf(1.f + __builtin_amdgcn_exp2f(-1.4426950408889634f * cg_)) * cv_;
	v_mul_f32_e32 v88, 0xbfb8aa3b, v86
	v_mul_f32_e32 v89, 0xbfb8aa3b, v87
	v_mov_b32_dpp v81, v92 row_ror:2 row_mask:0xf bank_mask:0xf

; __device__ __forceinline__ float dpp_ror1(float v) { return __int_as_float(__builtin_amdgcn_update_dpp(0, __float_as_int(v), 0x121, 0xf, 0xf, false)); }
; __device__ __forceinline__ float dpp_ror2(float v) { return __int_as_float(__builtin_amdgcn_update_dpp(0, __float_as_int(v), 0x122, 0xf, 0xf, false)); }
;   __device__ __forceinline__ void operator()(const AccT& acc, const Unit& u, int wr, int wc, int fr, int fq) const {
;     ...
;         for (int m = 0; m < 4; ++m) {
;           f32x4 res;
; #pragma unroll
;           for (int r = 0; r < 4; ++r) {
;             const float g_cur = xg[m][r], v_cur = xv[m][r];
;             const f32x4 xgp = xg[m > 0 ? m - 1 : 0], xvp = xv[m > 0 ? m - 1 : 0];
;             const float g_pm = (m > 0) ? xgp[r] : 0.f, v_pm = (m > 0) ? xvp[r] : 0.f;
;             const float g1 = dpp_ror1((fr == 15) ? g_pm : g_cur), g2 = dpp_ror2((fr >= 14) ? g_pm : g_cur);
;             const float v1 = dpp_ror1((fr == 15) ? v_pm : v_cur), v2 = dpp_ror2((fr >= 14) ? v_pm : v_cur);
;             const float cg_ = bg[r] + g2 * wg0[r] + g1 * wg1[r] + g_cur * wg2[r];
;             const float cv_ = bv[r] + v2 * wv0[r] + v1 * wv1[r] + v_cur * wv2[r];
;             res[r] = cg_ * __builtin_amdgcn_rcpf(1.f + __builtin_amdgcn_exp2f(-1.4426950408889634f * cg_)) * cv_;
	v_exp_f32_e32 v88, v88
	v_exp_f32_e32 v89, v89
	v_mov_b32_dpp v92, v93 row_ror:1 row_mask:0xf bank_mask:0xf
	v_cndmask_b32_e64 v93, v102, v84, s[6:7]

; __device__ __forceinline__ float dpp_ror1(float v) { return __int_as_float(__builtin_amdgcn_update_dpp(0, __float_as_int(v), 0x121, 0xf, 0xf, false)); }
; __device__ __forceinline__ float dpp_ror2(float v) { return __int_as_float(__builtin_amdgcn_update_dpp(0, __float_as_int(v), 0x122, 0xf, 0xf, false)); }
;   __device__ __forceinline__ void operator()(const AccT& acc, const Unit& u, int wr, int wc, int fr, int fq) const {
;     ...
;         for (int m = 0; m < 4; ++m) {
;           f32x4 res;
; #pragma unroll
;           for (int r = 0; r < 4; ++r) {
;             const float g_cur = xg[m][r], v_cur = xv[m][r];
;             const f32x4 xgp = xg[m > 0 ? m - 1 : 0], xvp = xv[m > 0 ? m - 1 : 0];
;             const float g_pm = (m > 0) ? xgp[r] : 0.f, v_pm = (m > 0) ? xvp[r] : 0.f;
;             const float g1 = dpp_ror1((fr == 15) ? g_pm : g_cur), g2 = dpp_ror2((fr >= 14) ? g_pm : g_cur);
;             const float v1 = dpp_ror1((fr == 15) ? v_pm : v_cur), v2 = dpp_ror2((fr >= 14) ? v_pm : v_cur);
;             const float cg_ = bg[r] + g2 * wg0[r] + g1 * wg1[r] + g_cur * wg2[r];
;             const float cv_ = bv[r] + v2 * wv0[r] + v1 * wv1[r] + v_cur * wv2[r];
;             res[r] = cg_ * __builtin_amdgcn_rcpf(1.f + __builtin_amdgcn_exp2f(-1.4426950408889634f * cg_)) * cv_;
	v_add_f32_e32 v88, 1.0, v88
	v_add_f32_e32 v89, 1.0, v89
	v_mov_b32_dpp v84, v93 row_ror:2 row_mask:0xf bank_mask:0xf
	v_cndmask_b32_e64 v93, v98, v82, s[8:9]
	v_rcp_f32_e32 v88, v88
	v_rcp_f32_e32 v89, v89
	v_mov_b32_dpp v94, v93 row_ror:1 row_mask:0xf bank_mask:0xf
	v_cndmask_b32_e64 v93, v98, v82, s[6:7]

; __device__ __forceinline__ float dpp_ror1(float v) { return __int_as_float(__builtin_amdgcn_update_dpp(0, __float_as_int(v), 0x121, 0xf, 0xf, false)); }
; __device__ __forceinline__ float dpp_ror2(float v) { return __int_as_float(__builtin_amdgcn_update_dpp(0, __float_as_int(v), 0x122, 0xf, 0xf, false)); }
;   __device__ __forceinline__ void operator()(const AccT& acc, const Unit& u, int wr, int wc, int fr, int fq) const {
;     ...
;         for (int m = 0; m < 4; ++m) {
;           f32x4 res;
; #pragma unroll
;           for (int r = 0; r < 4; ++r) {
;             const float g_cur = xg[m][r], v_cur = xv[m][r];
;             const f32x4 xgp = xg[m > 0 ? m - 1 : 0], xvp = xv[m > 0 ? m - 1 : 0];
;             const float g_pm = (m > 0) ? xgp[r] : 0.f, v_pm = (m > 0) ? xvp[r] : 0.f;
;             const float g1 = dpp_ror1((fr == 15) ? g_pm : g_cur), g2 = dpp_ror2((fr >= 14) ? g_pm : g_cur);
;             const float v1 = dpp_ror1((fr == 15) ? v_pm : v_cur), v2 = dpp_ror2((fr >= 14) ? v_pm : v_cur);
;             const float cg_ = bg[r] + g2 * wg0[r] + g1 * wg1[r] + g_cur * wg2[r];
;             const float cv_ = bv[r] + v2 * wv0[r] + v1 * wv1[r] + v_cur * wv2[r];
;             res[r] = cg_ * __builtin_amdgcn_rcpf(1.f + __builtin_amdgcn_exp2f(-1.4426950408889634f * cg_)) * cv_;
	v_pk_fma_f32 v[80:81], v[120:121], v[80:81], v[136:137]
	v_pk_mul_f32 v[86:87], v[86:87], v[88:89]
	v_mov_b32_dpp v82, v93 row_ror:2 row_mask:0xf bank_mask:0xf

; __device__ __forceinline__ float dpp_ror1(float v) { return __int_as_float(__builtin_amdgcn_update_dpp(0, __float_as_int(v), 0x121, 0xf, 0xf, false)); }
; __device__ __forceinline__ float dpp_ror2(float v) { return __int_as_float(__builtin_amdgcn_update_dpp(0, __float_as_int(v), 0x122, 0xf, 0xf, false)); }
;   __device__ __forceinline__ void operator()(const AccT& acc, const Unit& u, int wr, int wc, int fr, int fq) const {
;     ...
;         for (int m = 0; m < 4; ++m) {
;           f32x4 res;
; #pragma unroll
;           for (int r = 0; r < 4; ++r) {
;             const float g_cur = xg[m][r], v_cur = xv[m][r];
;             const f32x4 xgp = xg[m > 0 ? m - 1 : 0], xvp = xv[m > 0 ? m - 1 : 0];
;             const float g_pm = (m > 0) ? xgp[r] : 0.f, v_pm = (m > 0) ? xvp[r] : 0.f;
;             const float g1 = dpp_ror1((fr == 15) ? g_pm : g_cur), g2 = dpp_ror2((fr >= 14) ? g_pm : g_cur);
;             const float v1 = dpp_ror1((fr == 15) ? v_pm : v_cur), v2 = dpp_ror2((fr >= 14) ? v_pm : v_cur);
;             const float cg_ = bg[r] + g2 * wg0[r] + g1 * wg1[r] + g_cur * wg2[r];
;             const float cv_ = bv[r] + v2 * wv0[r] + v1 * wv1[r] + v_cur * wv2[r];
;             res[r] = cg_ * __builtin_amdgcn_rcpf(1.f + __builtin_amdgcn_exp2f(-1.4426950408889634f * cg_)) * cv_;
	v_pk_fma_f32 v[80:81], v[128:129], v[90:91], v[80:81]
	v_ashrrev_i32_e32 v113, 31, v112
	v_mov_b32_dpp v93, v95 row_ror:1 row_mask:0xf bank_mask:0xf
	v_cndmask_b32_e64 v95, v103, v85, s[6:7]

; __device__ __forceinline__ float dpp_ror1(float v) { return __int_as_float(__builtin_amdgcn_update_dpp(0, __float_as_int(v), 0x121, 0xf, 0xf, false)); }
; __device__ __forceinline__ float dpp_ror2(float v) { return __int_as_float(__builtin_amdgcn_update_dpp(0, __float_as_int(v), 0x122, 0xf, 0xf, false)); }
;   __device__ __forceinline__ void operator()(const AccT& acc, const Unit& u, int wr, int wc, int fr, int fq) const {
;     ...
;         for (int m = 0; m < 4; ++m) {
;           f32x4 res;
; #pragma unroll
;           for (int r = 0; r < 4; ++r) {
;             const float g_cur = xg[m][r], v_cur = xv[m][r];
;             const f32x4 xgp = xg[m > 0 ? m - 1 : 0], xvp = xv[m > 0 ? m - 1 : 0];
;             const float g_pm = (m > 0) ? xgp[r] : 0.f, v_pm = (m > 0) ? xvp[r] : 0.f;
;             const float g1 = dpp_ror1((fr == 15) ? g_pm : g_cur), g2 = dpp_ror2((fr >= 14) ? g_pm : g_cur);
;             const float v1 = dpp_ror1((fr == 15) ? v_pm : v_cur), v2 = dpp_ror2((fr >= 14) ? v_pm : v_cur);
;             const float cg_ = bg[r] + g2 * wg0[r] + g1 * wg1[r] + g_cur * wg2[r];
;             const float cv_ = bv[r] + v2 * wv0[r] + v1 * wv1[r] + v_cur * wv2[r];
;             res[r] = cg_ * __builtin_amdgcn_rcpf(1.f + __builtin_amdgcn_exp2f(-1.4426950408889634f * cg_)) * cv_;
	v_pk_fma_f32 v[80:81], v[96:97], v[132:133], v[80:81]
	v_add_u32_e32 v128, 0xa0, v198
	v_mov_b32_dpp v85, v95 row_ror:2 row_mask:0xf bank_mask:0xf
	v_pk_fma_f32 v[84:85], v[114:115], v[84:85], v[142:143]
	v_pk_mul_f32 v[80:81], v[80:81], v[86:87]
	v_pk_fma_f32 v[84:85], v[118:119], v[92:93], v[84:85]

; __device__ __forceinline__ float dpp_ror1(float v) { return __int_as_float(__builtin_amdgcn_update_dpp(0, __float_as_int(v), 0x121, 0xf, 0xf, false)); }
; __device__ __forceinline__ float dpp_ror2(float v) { return __int_as_float(__builtin_amdgcn_update_dpp(0, __float_as_int(v), 0x122, 0xf, 0xf, false)); }
;   __device__ __forceinline__ void operator()(const AccT& acc, const Unit& u, int wr, int wc, int fr, int fq) const {
;     ...
;         for (int m = 0; m < 4; ++m) {
;           f32x4 res;
; #pragma unroll
;           for (int r = 0; r < 4; ++r) {
;             const float g_cur = xg[m][r], v_cur = xv[m][r];
;             const f32x4 xgp = xg[m > 0 ? m - 1 : 0], xvp = xv[m > 0 ? m - 1 : 0];
;             const float g_pm = (m > 0) ? xgp[r] : 0.f, v_pm = (m > 0) ? xvp[r] : 0.f;
;             const float g1 = dpp_ror1((fr == 15) ? g_pm : g_cur), g2 = dpp_ror2((fr >= 14) ? g_pm : g_cur);
;             const float v1 = dpp_ror1((fr == 15) ? v_pm : v_cur), v2 = dpp_ror2((fr >= 14) ? v_pm : v_cur);
;             const float cg_ = bg[r] + g2 * wg0[r] + g1 * wg1[r] + g_cur * wg2[r];
;             const float cv_ = bv[r] + v2 * wv0[r] + v1 * wv1[r] + v_cur * wv2[r];
;             res[r] = cg_ * __builtin_amdgcn_rcpf(1.f + __builtin_amdgcn_exp2f(-1.4426950408889634f * cg_)) * cv_;
	v_pk_fma_f32 v[84:85], v[102:103], v[126:127], v[84:85]
	v_cvt_pk_bf16_f32 v80, v80, v81
	v_mul_f32_e32 v86, 0xbfb8aa3b, v84
	v_mul_f32_e32 v87, 0xbfb8aa3b, v85
	v_exp_f32_e32 v86, v86
	v_exp_f32_e32 v87, v87
	v_mov_b32_dpp v95, v104 row_ror:1 row_mask:0xf bank_mask:0xf
	v_cndmask_b32_e64 v104, v99, v83, s[6:7]
	v_add_f32_e32 v86, 1.0, v86
	v_add_f32_e32 v87, 1.0, v87

; __device__ __forceinline__ float rstd_of(const unsigned long long* rowss, int row) {
;   return rsqrtf((float)rowss[row] * (1.f / (SS_FIX * DM)) + 1e-6f);
; }
;   __device__ __forceinline__ void operator()(const AccT& acc, const Unit& u, int wr, int wc, int fr, int fq) const {
;     ...
;     for (int ai = 0; ai < 2; ++ai) {
;       float rs[4];
; #pragma unroll
;       for (int m = 0; m < 4; ++m) rs[m] = rstd_of(rowss, EPI_ROW(u, ai, m));
;       const int chunk = 4 * u.pm + 2 * ai + wr;
; #pragma unroll
;       for (int n = 0; n < 2; ++n) {
;         const int f0 = 128 * u.pn + 32 * wc + 16 * n + 4 * fq;
;         const int gc = u.pn * 256 + 32 * wc + 16 * n + 4 * fq;
;         const f32x4 wg0 = *(const f32x4*)(cw + f0), wg1 = *(const f32x4*)(cw + NUP + f0), wg2 = *(const f32x4*)(cw + 2 * NUP + f0);
;         const f32x4 wv0 = *(const f32x4*)(cw + DFF + f0), wv1 = *(const f32x4*)(cw + NUP + DFF + f0), wv2 = *(const f32x4*)(cw + 2 * NUP + DFF + f0);
;         const f32x4 bg = *(const f32x4*)(cb + f0), bv = *(const f32x4*)(cb + DFF + f0);
;         f32x4 xg[4], xv[4];
; #pragma unroll
;         for (int m = 0; m < 4; ++m) { xg[m] = acc[ai][0][m][n] * rs[m]; xv[m] = acc[ai][1][m][n] * rs[m]; }
;         if (fr < 2) {
;           float* d = ub + ((size_t)(chunk * 4 + fr) * NUP + gc);
;           *(float4*)d = make_float4(xg[0][0], xg[0][1], xg[0][2], xg[0][3]);
;           *(float4*)(d + 128) = make_float4(xv[0][0], xv[0][1], xv[0][2], xv[0][3]);
;         }
	v_rcp_f32_e32 v86, v86
	v_rcp_f32_e32 v87, v87
	v_mov_b32_dpp v83, v104 row_ror:2 row_mask:0xf bank_mask:0xf
	v_pk_fma_f32 v[82:83], v[122:123], v[82:83], v[138:139]
	v_ashrrev_i32_e32 v129, 31, v128
	v_pk_fma_f32 v[82:83], v[130:131], v[94:95], v[82:83]
	v_pk_mul_f32 v[84:85], v[84:85], v[86:87]
	v_pk_fma_f32 v[82:83], v[98:99], v[134:135], v[82:83]
	v_add_u32_e32 v130, 0x90, v198
	v_pk_mul_f32 v[82:83], v[82:83], v[84:85]
	v_ashrrev_i32_e32 v131, 31, v130
	v_cvt_pk_bf16_f32 v81, v82, v83
	global_store_dwordx2 v[156:157], v[80:81], off offset:32
	v_lshl_add_u64 v[80:81], v[112:113], 3, s[86:87]
	global_load_dwordx2 v[80:81], v[80:81], off
	v_add_u32_e32 v116, 0xb0, v198
	v_ashrrev_i32_e32 v117, 31, v116
	s_waitcnt vmcnt(0)
	v_ffbh_u32_e32 v82, v81
	v_min_u32_e32 v82, 32, v82
	v_lshlrev_b64 v[80:81], v82, v[80:81]
	v_min_u32_e32 v80, 1, v80
	v_or_b32_e32 v80, v81, v80
	v_cvt_f32_u32_e32 v80, v80
	v_sub_u32_e32 v81, 32, v82
	v_ldexp_f32 v80, v80, v81
	v_fmamk_f32 v80, v80, 0x2e800000, v252
	v_cmp_gt_f32_e32 vcc, s96, v80
	v_mul_f32_e32 v81, 0x4b800000, v80
	s_nop 0
	v_cndmask_b32_e32 v80, v80, v81, vcc
	v_rsq_f32_e32 v80, v80
	s_nop 0
	v_mul_f32_e32 v81, 0x45800000, v80
	v_cndmask_b32_e32 v114, v80, v81, vcc
	v_lshl_add_u64 v[80:81], v[130:131], 3, s[86:87]
	global_load_dwordx2 v[122:123], v[80:81], off
	v_lshl_add_u64 v[80:81], v[128:129], 3, s[86:87]
	global_load_dwordx2 v[126:127], v[80:81], off
	v_lshl_add_u64 v[80:81], v[116:117], 3, s[86:87]
	global_load_dwordx2 v[120:121], v[80:81], off
	v_add_u32_e32 v80, s40, v246
	v_mad_i64_i32 v[118:119], s[34:35], v80, s97, 0
	global_load_dwordx4 v[96:99], v[194:195], off
	global_load_dwordx4 v[100:103], v[200:201], off
	global_load_dwordx4 v[92:95], v[202:203], off
	global_load_dwordx4 v[84:87], v[204:205], off
	global_load_dwordx4 v[88:91], v[206:207], off
	global_load_dwordx4 v[80:83], v[208:209], off
	global_load_dwordx4 v[108:111], v[196:197], off
	global_load_dwordx4 v[104:107], v[210:211], off
	v_pk_mul_f32 v[78:79], v[78:79], v[114:115] op_sel_hi:[1,0]
	v_pk_mul_f32 v[76:77], v[76:77], v[114:115] op_sel_hi:[1,0]
	v_pk_mul_f32 v[74:75], v[74:75], v[114:115] op_sel_hi:[1,0]
	v_pk_mul_f32 v[72:73], v[72:73], v[114:115] op_sel_hi:[1,0]
	v_lshl_add_u64 v[118:119], s[56:57], 0, v[118:119]
	s_and_saveexec_b64 s[38:39], s[4:5]
	s_cbranch_execz .LBB0_500
	v_lshl_add_u64 v[124:125], v[190:191], 2, v[118:119]
	global_store_dwordx4 v[124:125], v[76:79], off
	global_store_dwordx4 v[124:125], v[72:75], off offset:512

; __device__ __forceinline__ float dpp_ror1(float v) { return __int_as_float(__builtin_amdgcn_update_dpp(0, __float_as_int(v), 0x121, 0xf, 0xf, false)); }
; __device__ __forceinline__ float dpp_ror2(float v) { return __int_as_float(__builtin_amdgcn_update_dpp(0, __float_as_int(v), 0x122, 0xf, 0xf, false)); }
;   __device__ __forceinline__ void operator()(const AccT& acc, const Unit& u, int wr, int wc, int fr, int fq) const {
;     ...
;             const float g_cur = xg[m][r], v_cur = xv[m][r];
;             const f32x4 xgp = xg[m > 0 ? m - 1 : 0], xvp = xv[m > 0 ? m - 1 : 0];
;             const float g_pm = (m > 0) ? xgp[r] : 0.f, v_pm = (m > 0) ? xvp[r] : 0.f;
;             const float g1 = dpp_ror1((fr == 15) ? g_pm : g_cur), g2 = dpp_ror2((fr >= 14) ? g_pm : g_cur);
;             const float v1 = dpp_ror1((fr == 15) ? v_pm : v_cur), v2 = dpp_ror2((fr >= 14) ? v_pm : v_cur);
.LBB0_502:
	s_or_b64 exec, exec, s[38:39]
	v_cndmask_b32_e64 v134, v76, 0, s[8:9]
	s_nop 0
	s_nop 0

; __device__ __forceinline__ float dpp_ror1(float v) { return __int_as_float(__builtin_amdgcn_update_dpp(0, __float_as_int(v), 0x121, 0xf, 0xf, false)); }
; __device__ __forceinline__ float dpp_ror2(float v) { return __int_as_float(__builtin_amdgcn_update_dpp(0, __float_as_int(v), 0x122, 0xf, 0xf, false)); }
;   __device__ __forceinline__ void operator()(const AccT& acc, const Unit& u, int wr, int wc, int fr, int fq) const {
;     ...
;             const float g_cur = xg[m][r], v_cur = xv[m][r];
;             const f32x4 xgp = xg[m > 0 ? m - 1 : 0], xvp = xv[m > 0 ? m - 1 : 0];
;             const float g_pm = (m > 0) ? xgp[r] : 0.f, v_pm = (m > 0) ? xvp[r] : 0.f;
;             const float g1 = dpp_ror1((fr == 15) ? g_pm : g_cur), g2 = dpp_ror2((fr >= 14) ? g_pm : g_cur);
;             const float v1 = dpp_ror1((fr == 15) ? v_pm : v_cur), v2 = dpp_ror2((fr >= 14) ? v_pm : v_cur);
	v_mov_b32_dpp v156, v134 row_ror:1 row_mask:0xf bank_mask:0xf
	v_mov_b32_dpp v158, v133 row_ror:2 row_mask:0xf bank_mask:0xf
	v_cndmask_b32_e64 v133, v72, 0, s[8:9]

; __device__ __forceinline__ float dpp_ror1(float v) { return __int_as_float(__builtin_amdgcn_update_dpp(0, __float_as_int(v), 0x121, 0xf, 0xf, false)); }
; __device__ __forceinline__ float dpp_ror2(float v) { return __int_as_float(__builtin_amdgcn_update_dpp(0, __float_as_int(v), 0x122, 0xf, 0xf, false)); }
;   __device__ __forceinline__ void operator()(const AccT& acc, const Unit& u, int wr, int wc, int fr, int fq) const {
;     ...
;             const float g_cur = xg[m][r], v_cur = xv[m][r];
;             const f32x4 xgp = xg[m > 0 ? m - 1 : 0], xvp = xv[m > 0 ? m - 1 : 0];
;             const float g_pm = (m > 0) ? xgp[r] : 0.f, v_pm = (m > 0) ? xvp[r] : 0.f;
;             const float g1 = dpp_ror1((fr == 15) ? g_pm : g_cur), g2 = dpp_ror2((fr >= 14) ? g_pm : g_cur);
;             const float v1 = dpp_ror1((fr == 15) ? v_pm : v_cur), v2 = dpp_ror2((fr >= 14) ? v_pm : v_cur);
	v_mov_b32_dpp v142, v132 row_ror:2 row_mask:0xf bank_mask:0xf
	v_cndmask_b32_e64 v132, v77, 0, s[8:9]
	s_nop 0


; __device__ __forceinline__ float dpp_ror1(float v) { return __int_as_float(__builtin_amdgcn_update_dpp(0, __float_as_int(v), 0x121, 0xf, 0xf, false)); }
; __device__ __forceinline__ float dpp_ror2(float v) { return __int_as_float(__builtin_amdgcn_update_dpp(0, __float_as_int(v), 0x122, 0xf, 0xf, false)); }
;   __device__ __forceinline__ void operator()(const AccT& acc, const Unit& u, int wr, int wc, int fr, int fq) const {
;     ...
;             const float g_cur = xg[m][r], v_cur = xv[m][r];
;             const f32x4 xgp = xg[m > 0 ? m - 1 : 0], xvp = xv[m > 0 ? m - 1 : 0];
;             const float g_pm = (m > 0) ? xgp[r] : 0.f, v_pm = (m > 0) ? xvp[r] : 0.f;
;             const float g1 = dpp_ror1((fr == 15) ? g_pm : g_cur), g2 = dpp_ror2((fr >= 14) ? g_pm : g_cur);
;             const float v1 = dpp_ror1((fr == 15) ? v_pm : v_cur), v2 = dpp_ror2((fr >= 14) ? v_pm : v_cur);
	v_mov_b32_dpp v138, v133 row_ror:1 row_mask:0xf bank_mask:0xf
	v_mov_b32_dpp v157, v132 row_ror:1 row_mask:0xf bank_mask:0xf
	v_mov_b32_dpp v159, v131 row_ror:2 row_mask:0xf bank_mask:0xf
	v_cndmask_b32_e64 v131, v73, 0, s[8:9]

; __device__ __forceinline__ float dpp_ror1(float v) { return __int_as_float(__builtin_amdgcn_update_dpp(0, __float_as_int(v), 0x121, 0xf, 0xf, false)); }
; __device__ __forceinline__ float dpp_ror2(float v) { return __int_as_float(__builtin_amdgcn_update_dpp(0, __float_as_int(v), 0x122, 0xf, 0xf, false)); }
;   __device__ __forceinline__ void operator()(const AccT& acc, const Unit& u, int wr, int wc, int fr, int fq) const {
;     ...
;             const float g_cur = xg[m][r], v_cur = xv[m][r];
;             const f32x4 xgp = xg[m > 0 ? m - 1 : 0], xvp = xv[m > 0 ? m - 1 : 0];
;             const float g_pm = (m > 0) ? xgp[r] : 0.f, v_pm = (m > 0) ? xvp[r] : 0.f;
;             const float g1 = dpp_ror1((fr == 15) ? g_pm : g_cur), g2 = dpp_ror2((fr >= 14) ? g_pm : g_cur);
;             const float v1 = dpp_ror1((fr == 15) ? v_pm : v_cur), v2 = dpp_ror2((fr >= 14) ? v_pm : v_cur);
	v_mov_b32_dpp v143, v129 row_ror:2 row_mask:0xf bank_mask:0xf
	v_cndmask_b32_e64 v129, v78, 0, s[8:9]

; __device__ __forceinline__ float dpp_ror1(float v) { return __int_as_float(__builtin_amdgcn_update_dpp(0, __float_as_int(v), 0x121, 0xf, 0xf, false)); }
; __device__ __forceinline__ float dpp_ror2(float v) { return __int_as_float(__builtin_amdgcn_update_dpp(0, __float_as_int(v), 0x122, 0xf, 0xf, false)); }
;   __device__ __forceinline__ void operator()(const AccT& acc, const Unit& u, int wr, int wc, int fr, int fq) const {
;     ...
;             const float g_cur = xg[m][r], v_cur = xv[m][r];
;             const f32x4 xgp = xg[m > 0 ? m - 1 : 0], xvp = xv[m > 0 ? m - 1 : 0];
;             const float g_pm = (m > 0) ? xgp[r] : 0.f, v_pm = (m > 0) ? xvp[r] : 0.f;
;             const float g1 = dpp_ror1((fr == 15) ? g_pm : g_cur), g2 = dpp_ror2((fr >= 14) ? g_pm : g_cur);
;             const float v1 = dpp_ror1((fr == 15) ? v_pm : v_cur), v2 = dpp_ror2((fr >= 14) ? v_pm : v_cur);
	v_mov_b32_dpp v140, v121 row_ror:2 row_mask:0xf bank_mask:0xf
	v_cndmask_b32_e64 v121, v74, 0, s[8:9]

; __device__ __forceinline__ float dpp_ror1(float v) { return __int_as_float(__builtin_amdgcn_update_dpp(0, __float_as_int(v), 0x121, 0xf, 0xf, false)); }
; __device__ __forceinline__ float dpp_ror2(float v) { return __int_as_float(__builtin_amdgcn_update_dpp(0, __float_as_int(v), 0x122, 0xf, 0xf, false)); }
;   __device__ __forceinline__ void operator()(const AccT& acc, const Unit& u, int wr, int wc, int fr, int fq) const {
;     ...
;             const float g_cur = xg[m][r], v_cur = xv[m][r];
;             const f32x4 xgp = xg[m > 0 ? m - 1 : 0], xvp = xv[m > 0 ? m - 1 : 0];
;             const float g_pm = (m > 0) ? xgp[r] : 0.f, v_pm = (m > 0) ? xvp[r] : 0.f;
;             const float g1 = dpp_ror1((fr == 15) ? g_pm : g_cur), g2 = dpp_ror2((fr >= 14) ? g_pm : g_cur);
;             const float v1 = dpp_ror1((fr == 15) ? v_pm : v_cur), v2 = dpp_ror2((fr >= 14) ? v_pm : v_cur);
	v_mov_b32_dpp v134, v117 row_ror:2 row_mask:0xf bank_mask:0xf
	v_cndmask_b32_e64 v117, v79, 0, s[8:9]

; __device__ __forceinline__ float dpp_ror1(float v) { return __int_as_float(__builtin_amdgcn_update_dpp(0, __float_as_int(v), 0x121, 0xf, 0xf, false)); }
; __device__ __forceinline__ float dpp_ror2(float v) { return __int_as_float(__builtin_amdgcn_update_dpp(0, __float_as_int(v), 0x122, 0xf, 0xf, false)); }
;   __device__ __forceinline__ void operator()(const AccT& acc, const Unit& u, int wr, int wc, int fr, int fq) const {
;     ...
;             const float g_cur = xg[m][r], v_cur = xv[m][r];
;             const f32x4 xgp = xg[m > 0 ? m - 1 : 0], xvp = xv[m > 0 ? m - 1 : 0];
;             const float g_pm = (m > 0) ? xgp[r] : 0.f, v_pm = (m > 0) ? xvp[r] : 0.f;
;             const float g1 = dpp_ror1((fr == 15) ? g_pm : g_cur), g2 = dpp_ror2((fr >= 14) ? g_pm : g_cur);
;             const float v1 = dpp_ror1((fr == 15) ? v_pm : v_cur), v2 = dpp_ror2((fr >= 14) ? v_pm : v_cur);
	v_mov_b32_dpp v141, v115 row_ror:2 row_mask:0xf bank_mask:0xf
	v_cndmask_b32_e64 v115, v75, 0, s[8:9]


; __device__ __forceinline__ uint2 pack4(f32x4 v) { return make_uint2(pack2(v[0], v[1]), pack2(v[2], v[3])); }
; __device__ __forceinline__ float dpp_ror1(float v) { return __int_as_float(__builtin_amdgcn_update_dpp(0, __float_as_int(v), 0x121, 0xf, 0xf, false)); }
; __device__ __forceinline__ float dpp_ror2(float v) { return __int_as_float(__builtin_amdgcn_update_dpp(0, __float_as_int(v), 0x122, 0xf, 0xf, false)); }
; __device__ __forceinline__ float rstd_of(const unsigned long long* rowss, int row) {
;   return rsqrtf((float)rowss[row] * (1.f / (SS_FIX * DM)) + 1e-6f);
;   __device__ __forceinline__ void operator()(const AccT& acc, const Unit& u, int wr, int wc, int fr, int fq) const {
;     ...
;         for (int m = 0; m < 4; ++m) {
;           f32x4 res;
; #pragma unroll
;           for (int r = 0; r < 4; ++r) {
;             const float g_cur = xg[m][r], v_cur = xv[m][r];
;             const f32x4 xgp = xg[m > 0 ? m - 1 : 0], xvp = xv[m > 0 ? m - 1 : 0];
;             const float g_pm = (m > 0) ? xgp[r] : 0.f, v_pm = (m > 0) ? xvp[r] : 0.f;
;             const float g1 = dpp_ror1((fr == 15) ? g_pm : g_cur), g2 = dpp_ror2((fr >= 14) ? g_pm : g_cur);
;             const float v1 = dpp_ror1((fr == 15) ? v_pm : v_cur), v2 = dpp_ror2((fr >= 14) ? v_pm : v_cur);
;             const float cg_ = bg[r] + g2 * wg0[r] + g1 * wg1[r] + g_cur * wg2[r];
;             const float cv_ = bv[r] + v2 * wv0[r] + v1 * wv1[r] + v_cur * wv2[r];
;             res[r] = cg_ * __builtin_amdgcn_rcpf(1.f + __builtin_amdgcn_exp2f(-1.4426950408889634f * cg_)) * cv_;
;           }
;           if (m > 0 || fr >= 2)
;             *(uint2*)(act + (size_t)EPI_ROW(u, ai, m) * DFF + f0) = pack4(res);
	v_mov_b32_dpp v139, v131 row_ror:1 row_mask:0xf bank_mask:0xf
	v_mov_b32_dpp v136, v129 row_ror:1 row_mask:0xf bank_mask:0xf
	v_mov_b32_dpp v132, v121 row_ror:1 row_mask:0xf bank_mask:0xf
	v_mov_b32_dpp v137, v117 row_ror:1 row_mask:0xf bank_mask:0xf
	v_mov_b32_dpp v133, v115 row_ror:1 row_mask:0xf bank_mask:0xf
	v_mov_b32_dpp v135, v113 row_ror:2 row_mask:0xf bank_mask:0xf
	s_and_saveexec_b64 s[34:35], s[4:5]
	s_xor_b64 s[38:39], exec, s[34:35]
	s_andn2_saveexec_b64 s[38:39], s[38:39]
	s_cbranch_execz .LBB0_506
	v_pk_fma_f32 v[158:159], v[96:97], v[158:159], v[108:109]
	v_pk_fma_f32 v[140:141], v[98:99], v[140:141], v[110:111]
	v_pk_fma_f32 v[156:157], v[100:101], v[156:157], v[158:159]
	v_pk_fma_f32 v[136:137], v[102:103], v[136:137], v[140:141]
	v_pk_fma_f32 v[156:157], v[92:93], v[76:77], v[156:157]
	v_pk_fma_f32 v[136:137], v[94:95], v[78:79], v[136:137]
	v_mul_f32_e32 v113, 0xbfb8aa3b, v156
	v_exp_f32_e32 v113, v113
	v_mul_f32_e32 v115, 0xbfb8aa3b, v157
	v_exp_f32_e32 v115, v115
	v_pk_fma_f32 v[134:135], v[86:87], v[134:135], v[106:107]
	v_add_f32_e32 v113, 1.0, v113
	v_rcp_f32_e32 v158, v113
	v_add_f32_e32 v115, 1.0, v115
	v_mul_f32_e32 v113, 0xbfb8aa3b, v136
	v_rcp_f32_e32 v159, v115
	v_exp_f32_e32 v113, v113
	v_mul_f32_e32 v115, 0xbfb8aa3b, v137
	v_exp_f32_e32 v115, v115
	v_pk_fma_f32 v[132:133], v[90:91], v[132:133], v[134:135]
	v_add_f32_e32 v113, 1.0, v113
	v_rcp_f32_e32 v140, v113
	v_add_f32_e32 v113, 1.0, v115
	v_rcp_f32_e32 v141, v113
	v_pk_fma_f32 v[142:143], v[84:85], v[142:143], v[104:105]
	v_pk_fma_f32 v[132:133], v[82:83], v[74:75], v[132:133]
	v_pk_fma_f32 v[138:139], v[88:89], v[138:139], v[142:143]
	v_pk_mul_f32 v[134:135], v[136:137], v[140:141]
	v_pk_fma_f32 v[138:139], v[80:81], v[72:73], v[138:139]
	v_pk_mul_f32 v[132:133], v[132:133], v[134:135]
	v_pk_mul_f32 v[142:143], v[156:157], v[158:159]
	v_cvt_pk_bf16_f32 v135, v132, v133
	v_mov_b64_e32 v[132:133], s[52:53]
	v_pk_mul_f32 v[138:139], v[138:139], v[142:143]
	v_mad_i64_i32 v[132:133], s[34:35], v112, s0, v[132:133]
	v_cvt_pk_bf16_f32 v134, v138, v139
	v_lshl_add_u64 v[132:133], v[188:189], 1, v[132:133]
	global_store_dwordx2 v[132:133], v[134:135], off
.LBB0_506:
	s_or_b64 exec, exec, s[38:39]
	v_ffbh_u32_e32 v113, v123
	v_min_u32_e32 v113, 32, v113
	v_lshlrev_b64 v[122:123], v113, v[122:123]
	v_min_u32_e32 v117, 1, v122
	v_or_b32_e32 v117, v123, v117
	v_cvt_f32_u32_e32 v117, v117
	v_sub_u32_e32 v113, 32, v113


; __device__ __forceinline__ float rstd_of(const unsigned long long* rowss, int row) {
;   return rsqrtf((float)rowss[row] * (1.f / (SS_FIX * DM)) + 1e-6f);
; }
	v_ldexp_f32 v113, v117, v113
	v_fmamk_f32 v113, v113, 0x2e800000, v252
	v_cmp_gt_f32_e32 vcc, s96, v113
	v_mul_f32_e32 v117, 0x4b800000, v113
	s_nop 0
	v_cndmask_b32_e32 v113, v113, v117, vcc
	v_rsq_f32_e32 v113, v113

; __device__ __forceinline__ float dpp_ror1(float v) { return __int_as_float(__builtin_amdgcn_update_dpp(0, __float_as_int(v), 0x121, 0xf, 0xf, false)); }
; __device__ __forceinline__ float rstd_of(const unsigned long long* rowss, int row) {
;   return rsqrtf((float)rowss[row] * (1.f / (SS_FIX * DM)) + 1e-6f);
; }
;   __device__ __forceinline__ void operator()(const AccT& acc, const Unit& u, int wr, int wc, int fr, int fq) const {
;     ...
;       for (int m = 0; m < 4; ++m) rs[m] = rstd_of(rowss, EPI_ROW(u, ai, m));
;       const int chunk = 4 * u.pm + 2 * ai + wr;
; #pragma unroll
;       for (int n = 0; n < 2; ++n) {
;         const int f0 = 128 * u.pn + 32 * wc + 16 * n + 4 * fq;
;         const int gc = u.pn * 256 + 32 * wc + 16 * n + 4 * fq;
;         const f32x4 wg0 = *(const f32x4*)(cw + f0), wg1 = *(const f32x4*)(cw + NUP + f0), wg2 = *(const f32x4*)(cw + 2 * NUP + f0);
;         const f32x4 wv0 = *(const f32x4*)(cw + DFF + f0), wv1 = *(const f32x4*)(cw + NUP + DFF + f0), wv2 = *(const f32x4*)(cw + 2 * NUP + DFF + f0);
;         const f32x4 bg = *(const f32x4*)(cb + f0), bv = *(const f32x4*)(cb + DFF + f0);
;         f32x4 xg[4], xv[4];
; #pragma unroll
;         for (int m = 0; m < 4; ++m) { xg[m] = acc[ai][0][m][n] * rs[m]; xv[m] = acc[ai][1][m][n] * rs[m]; }
;         if (fr < 2) {
;           float* d = ub + ((size_t)(chunk * 4 + fr) * NUP + gc);
;           *(float4*)d = make_float4(xg[0][0], xg[0][1], xg[0][2], xg[0][3]);
;           *(float4*)(d + 128) = make_float4(xv[0][0], xv[0][1], xv[0][2], xv[0][3]);
;         }
;         if (fr >= 14) {
;           float* d = ub + ((size_t)(chunk * 4 + 2 + (fr - 14)) * NUP + gc);
;           *(float4*)d = make_float4(xg[3][0], xg[3][1], xg[3][2], xg[3][3]);
;           *(float4*)(d + 128) = make_float4(xv[3][0], xv[3][1], xv[3][2], xv[3][3]);
;         }
; #pragma unroll
;         for (int m = 0; m < 4; ++m) {
;           f32x4 res;
; #pragma unroll
;           for (int r = 0; r < 4; ++r) {
;             const float g_cur = xg[m][r], v_cur = xv[m][r];
;             const f32x4 xgp = xg[m > 0 ? m - 1 : 0], xvp = xv[m > 0 ? m - 1 : 0];
;             const float g_pm = (m > 0) ? xgp[r] : 0.f, v_pm = (m > 0) ? xvp[r] : 0.f;
;             const float g1 = dpp_ror1((fr == 15) ? g_pm : g_cur), g2 = dpp_ror2((fr >= 14) ? g_pm : g_cur);
	v_mov_b32_e32 v115, v114
	v_pk_mul_f32 v[44:45], v[44:45], v[114:115]
	v_mul_f32_e32 v117, 0x45800000, v113
	v_cndmask_b32_e32 v122, v113, v117, vcc
	v_ffbh_u32_e32 v113, v127
	v_min_u32_e32 v113, 32, v113
	v_lshlrev_b64 v[126:127], v113, v[126:127]
	v_min_u32_e32 v117, 1, v126
	v_or_b32_e32 v117, v127, v117
	v_cvt_f32_u32_e32 v117, v117
	v_sub_u32_e32 v113, 32, v113
	v_pk_mul_f32 v[132:133], v[60:61], v[122:123] op_sel_hi:[1,0]
	v_pk_mul_f32 v[60:61], v[54:55], v[122:123] op_sel_hi:[1,0]
	v_ldexp_f32 v113, v117, v113
	v_fmamk_f32 v113, v113, 0x2e800000, v252
	v_cmp_gt_f32_e32 vcc, s96, v113
	v_mul_f32_e32 v117, 0x4b800000, v113
	v_pk_mul_f32 v[134:135], v[52:53], v[122:123] op_sel_hi:[1,0]
	v_cndmask_b32_e32 v113, v113, v117, vcc
	v_rsq_f32_e32 v113, v113
	v_pk_mul_f32 v[62:63], v[62:63], v[122:123] op_sel_hi:[1,0]
	v_pk_mul_f32 v[40:41], v[40:41], v[114:115]
	v_mul_f32_e32 v117, 0x45800000, v113
	v_cndmask_b32_e32 v126, v113, v117, vcc
	v_pk_mul_f32 v[54:55], v[56:57], v[126:127] op_sel_hi:[1,0]
	v_cndmask_b32_e64 v57, v132, v76, s[8:9]
	s_nop 0
	v_pk_mul_f32 v[52:53], v[58:59], v[126:127] op_sel_hi:[1,0]

; __device__ __forceinline__ float dpp_ror1(float v) { return __int_as_float(__builtin_amdgcn_update_dpp(0, __float_as_int(v), 0x121, 0xf, 0xf, false)); }
; __device__ __forceinline__ float dpp_ror2(float v) { return __int_as_float(__builtin_amdgcn_update_dpp(0, __float_as_int(v), 0x122, 0xf, 0xf, false)); }
;   __device__ __forceinline__ void operator()(const AccT& acc, const Unit& u, int wr, int wc, int fr, int fq) const {
;     ...
;             const float g_cur = xg[m][r], v_cur = xv[m][r];
;             const f32x4 xgp = xg[m > 0 ? m - 1 : 0], xvp = xv[m > 0 ? m - 1 : 0];
;             const float g_pm = (m > 0) ? xgp[r] : 0.f, v_pm = (m > 0) ? xvp[r] : 0.f;
;             const float g1 = dpp_ror1((fr == 15) ? g_pm : g_cur), g2 = dpp_ror2((fr >= 14) ? g_pm : g_cur);
;             const float v1 = dpp_ror1((fr == 15) ? v_pm : v_cur), v2 = dpp_ror2((fr >= 14) ? v_pm : v_cur);
	v_mov_b32_dpp v56, v57 row_ror:1 row_mask:0xf bank_mask:0xf
	v_cndmask_b32_e64 v57, v132, v76, s[6:7]
	s_nop 0
	v_cndmask_b32_e64 v59, v133, v77, s[8:9]
	v_mov_b32_dpp v58, v57 row_ror:2 row_mask:0xf bank_mask:0xf
	v_cndmask_b32_e64 v57, v134, v72, s[8:9]
	v_cndmask_b32_e64 v77, v133, v77, s[6:7]
	v_cndmask_b32_e64 v113, v135, v73, s[8:9]
	v_mov_b32_dpp v76, v57 row_ror:1 row_mask:0xf bank_mask:0xf
	v_cndmask_b32_e64 v57, v134, v72, s[6:7]

; __device__ __forceinline__ float dpp_ror1(float v) { return __int_as_float(__builtin_amdgcn_update_dpp(0, __float_as_int(v), 0x121, 0xf, 0xf, false)); }
; __device__ __forceinline__ float dpp_ror2(float v) { return __int_as_float(__builtin_amdgcn_update_dpp(0, __float_as_int(v), 0x122, 0xf, 0xf, false)); }
;   __device__ __forceinline__ void operator()(const AccT& acc, const Unit& u, int wr, int wc, int fr, int fq) const {
;     ...
;         for (int m = 0; m < 4; ++m) { xg[m] = acc[ai][0][m][n] * rs[m]; xv[m] = acc[ai][1][m][n] * rs[m]; }
;     ...
;             const float g_cur = xg[m][r], v_cur = xv[m][r];
;             const f32x4 xgp = xg[m > 0 ? m - 1 : 0], xvp = xv[m > 0 ? m - 1 : 0];
;             const float g_pm = (m > 0) ? xgp[r] : 0.f, v_pm = (m > 0) ? xvp[r] : 0.f;
;             const float g1 = dpp_ror1((fr == 15) ? g_pm : g_cur), g2 = dpp_ror2((fr >= 14) ? g_pm : g_cur);
;             const float v1 = dpp_ror1((fr == 15) ? v_pm : v_cur), v2 = dpp_ror2((fr >= 14) ? v_pm : v_cur);
	v_pk_mul_f32 v[48:49], v[48:49], v[126:127] op_sel_hi:[1,0]
	v_pk_mul_f32 v[50:51], v[50:51], v[126:127] op_sel_hi:[1,0]
	v_mov_b32_dpp v72, v57 row_ror:2 row_mask:0xf bank_mask:0xf

; __device__ __forceinline__ float dpp_ror1(float v) { return __int_as_float(__builtin_amdgcn_update_dpp(0, __float_as_int(v), 0x121, 0xf, 0xf, false)); }
; __device__ __forceinline__ float dpp_ror2(float v) { return __int_as_float(__builtin_amdgcn_update_dpp(0, __float_as_int(v), 0x122, 0xf, 0xf, false)); }
;   __device__ __forceinline__ void operator()(const AccT& acc, const Unit& u, int wr, int wc, int fr, int fq) const {
;     ...
;             const float g_cur = xg[m][r], v_cur = xv[m][r];
;             const f32x4 xgp = xg[m > 0 ? m - 1 : 0], xvp = xv[m > 0 ? m - 1 : 0];
;             const float g_pm = (m > 0) ? xgp[r] : 0.f, v_pm = (m > 0) ? xvp[r] : 0.f;
;             const float g1 = dpp_ror1((fr == 15) ? g_pm : g_cur), g2 = dpp_ror2((fr >= 14) ? g_pm : g_cur);
;             const float v1 = dpp_ror1((fr == 15) ? v_pm : v_cur), v2 = dpp_ror2((fr >= 14) ? v_pm : v_cur);
	s_nop 1
	v_mov_b32_dpp v57, v59 row_ror:1 row_mask:0xf bank_mask:0xf

; __device__ __forceinline__ float dpp_ror1(float v) { return __int_as_float(__builtin_amdgcn_update_dpp(0, __float_as_int(v), 0x121, 0xf, 0xf, false)); }
; __device__ __forceinline__ float dpp_ror2(float v) { return __int_as_float(__builtin_amdgcn_update_dpp(0, __float_as_int(v), 0x122, 0xf, 0xf, false)); }
;   __device__ __forceinline__ void operator()(const AccT& acc, const Unit& u, int wr, int wc, int fr, int fq) const {
;     ...
;             const float g_cur = xg[m][r], v_cur = xv[m][r];
;             const f32x4 xgp = xg[m > 0 ? m - 1 : 0], xvp = xv[m > 0 ? m - 1 : 0];
;             const float g_pm = (m > 0) ? xgp[r] : 0.f, v_pm = (m > 0) ? xvp[r] : 0.f;
;             const float g1 = dpp_ror1((fr == 15) ? g_pm : g_cur), g2 = dpp_ror2((fr >= 14) ? g_pm : g_cur);
;             const float v1 = dpp_ror1((fr == 15) ? v_pm : v_cur), v2 = dpp_ror2((fr >= 14) ? v_pm : v_cur);
;             const float cg_ = bg[r] + g2 * wg0[r] + g1 * wg1[r] + g_cur * wg2[r];
	s_nop 1
	v_mov_b32_dpp v59, v77 row_ror:2 row_mask:0xf bank_mask:0xf
	v_pk_fma_f32 v[58:59], v[96:97], v[58:59], v[108:109]

; __device__ __forceinline__ float dpp_ror1(float v) { return __int_as_float(__builtin_amdgcn_update_dpp(0, __float_as_int(v), 0x121, 0xf, 0xf, false)); }
; __device__ __forceinline__ float dpp_ror2(float v) { return __int_as_float(__builtin_amdgcn_update_dpp(0, __float_as_int(v), 0x122, 0xf, 0xf, false)); }
;   __device__ __forceinline__ void operator()(const AccT& acc, const Unit& u, int wr, int wc, int fr, int fq) const {
;     ...
;             const float g_cur = xg[m][r], v_cur = xv[m][r];
;             const f32x4 xgp = xg[m > 0 ? m - 1 : 0], xvp = xv[m > 0 ? m - 1 : 0];
;             const float g_pm = (m > 0) ? xgp[r] : 0.f, v_pm = (m > 0) ? xvp[r] : 0.f;
;             const float g1 = dpp_ror1((fr == 15) ? g_pm : g_cur), g2 = dpp_ror2((fr >= 14) ? g_pm : g_cur);
;             const float v1 = dpp_ror1((fr == 15) ? v_pm : v_cur), v2 = dpp_ror2((fr >= 14) ? v_pm : v_cur);
;             const float cg_ = bg[r] + g2 * wg0[r] + g1 * wg1[r] + g_cur * wg2[r];
;             const float cv_ = bv[r] + v2 * wv0[r] + v1 * wv1[r] + v_cur * wv2[r];
;             res[r] = cg_ * __builtin_amdgcn_rcpf(1.f + __builtin_amdgcn_exp2f(-1.4426950408889634f * cg_)) * cv_;
	v_pk_fma_f32 v[56:57], v[100:101], v[56:57], v[58:59]
	s_nop 0
	v_pk_fma_f32 v[56:57], v[92:93], v[132:133], v[56:57]
	v_mov_b32_dpp v77, v113 row_ror:1 row_mask:0xf bank_mask:0xf
	v_mul_f32_e32 v58, 0xbfb8aa3b, v56
	v_mul_f32_e32 v59, 0xbfb8aa3b, v57
	v_exp_f32_e32 v58, v58
	v_exp_f32_e32 v59, v59
	v_cndmask_b32_e64 v113, v135, v73, s[6:7]

; __device__ __forceinline__ float dpp_ror1(float v) { return __int_as_float(__builtin_amdgcn_update_dpp(0, __float_as_int(v), 0x121, 0xf, 0xf, false)); }
; __device__ __forceinline__ float dpp_ror2(float v) { return __int_as_float(__builtin_amdgcn_update_dpp(0, __float_as_int(v), 0x122, 0xf, 0xf, false)); }
;   __device__ __forceinline__ void operator()(const AccT& acc, const Unit& u, int wr, int wc, int fr, int fq) const {
;     ...
;             const float g_cur = xg[m][r], v_cur = xv[m][r];
;             const f32x4 xgp = xg[m > 0 ? m - 1 : 0], xvp = xv[m > 0 ? m - 1 : 0];
;             const float g_pm = (m > 0) ? xgp[r] : 0.f, v_pm = (m > 0) ? xvp[r] : 0.f;
;             const float g1 = dpp_ror1((fr == 15) ? g_pm : g_cur), g2 = dpp_ror2((fr >= 14) ? g_pm : g_cur);
;             const float v1 = dpp_ror1((fr == 15) ? v_pm : v_cur), v2 = dpp_ror2((fr >= 14) ? v_pm : v_cur);
;             const float cg_ = bg[r] + g2 * wg0[r] + g1 * wg1[r] + g_cur * wg2[r];
;             const float cv_ = bv[r] + v2 * wv0[r] + v1 * wv1[r] + v_cur * wv2[r];
;             res[r] = cg_ * __builtin_amdgcn_rcpf(1.f + __builtin_amdgcn_exp2f(-1.4426950408889634f * cg_)) * cv_;
	v_add_f32_e32 v58, 1.0, v58
	v_add_f32_e32 v59, 1.0, v59
	v_mov_b32_dpp v73, v113 row_ror:2 row_mask:0xf bank_mask:0xf
	v_cndmask_b32_e64 v113, v62, v78, s[8:9]
	v_rcp_f32_e32 v58, v58
	v_rcp_f32_e32 v59, v59
	v_mov_b32_dpp v136, v113 row_ror:1 row_mask:0xf bank_mask:0xf
	v_cndmask_b32_e64 v113, v62, v78, s[6:7]

; __device__ __forceinline__ float dpp_ror1(float v) { return __int_as_float(__builtin_amdgcn_update_dpp(0, __float_as_int(v), 0x121, 0xf, 0xf, false)); }
; __device__ __forceinline__ float dpp_ror2(float v) { return __int_as_float(__builtin_amdgcn_update_dpp(0, __float_as_int(v), 0x122, 0xf, 0xf, false)); }
;   __device__ __forceinline__ void operator()(const AccT& acc, const Unit& u, int wr, int wc, int fr, int fq) const {
;     ...
;             const float g_cur = xg[m][r], v_cur = xv[m][r];
;             const f32x4 xgp = xg[m > 0 ? m - 1 : 0], xvp = xv[m > 0 ? m - 1 : 0];
;             const float g_pm = (m > 0) ? xgp[r] : 0.f, v_pm = (m > 0) ? xvp[r] : 0.f;
;             const float g1 = dpp_ror1((fr == 15) ? g_pm : g_cur), g2 = dpp_ror2((fr >= 14) ? g_pm : g_cur);
;             const float v1 = dpp_ror1((fr == 15) ? v_pm : v_cur), v2 = dpp_ror2((fr >= 14) ? v_pm : v_cur);
;             const float cg_ = bg[r] + g2 * wg0[r] + g1 * wg1[r] + g_cur * wg2[r];
;             const float cv_ = bv[r] + v2 * wv0[r] + v1 * wv1[r] + v_cur * wv2[r];
;             res[r] = cg_ * __builtin_amdgcn_rcpf(1.f + __builtin_amdgcn_exp2f(-1.4426950408889634f * cg_)) * cv_;
	v_pk_fma_f32 v[72:73], v[84:85], v[72:73], v[104:105]
	v_pk_mul_f32 v[56:57], v[56:57], v[58:59]
	v_mov_b32_dpp v78, v113 row_ror:2 row_mask:0xf bank_mask:0xf
	v_cndmask_b32_e64 v113, v60, v74, s[8:9]
	v_pk_fma_f32 v[72:73], v[88:89], v[76:77], v[72:73]
	s_nop 0
	v_mov_b32_dpp v138, v113 row_ror:1 row_mask:0xf bank_mask:0xf
	v_cndmask_b32_e64 v113, v60, v74, s[6:7]

; __device__ __forceinline__ float dpp_ror1(float v) { return __int_as_float(__builtin_amdgcn_update_dpp(0, __float_as_int(v), 0x121, 0xf, 0xf, false)); }
; __device__ __forceinline__ float dpp_ror2(float v) { return __int_as_float(__builtin_amdgcn_update_dpp(0, __float_as_int(v), 0x122, 0xf, 0xf, false)); }
;   __device__ __forceinline__ void operator()(const AccT& acc, const Unit& u, int wr, int wc, int fr, int fq) const {
;     ...
;             const float g_cur = xg[m][r], v_cur = xv[m][r];
;             const f32x4 xgp = xg[m > 0 ? m - 1 : 0], xvp = xv[m > 0 ? m - 1 : 0];
;             const float g_pm = (m > 0) ? xgp[r] : 0.f, v_pm = (m > 0) ? xvp[r] : 0.f;
;             const float g1 = dpp_ror1((fr == 15) ? g_pm : g_cur), g2 = dpp_ror2((fr >= 14) ? g_pm : g_cur);
;             const float v1 = dpp_ror1((fr == 15) ? v_pm : v_cur), v2 = dpp_ror2((fr >= 14) ? v_pm : v_cur);
;             const float cg_ = bg[r] + g2 * wg0[r] + g1 * wg1[r] + g_cur * wg2[r];
;             const float cv_ = bv[r] + v2 * wv0[r] + v1 * wv1[r] + v_cur * wv2[r];
;             res[r] = cg_ * __builtin_amdgcn_rcpf(1.f + __builtin_amdgcn_exp2f(-1.4426950408889634f * cg_)) * cv_;
	v_pk_fma_f32 v[72:73], v[80:81], v[134:135], v[72:73]
	v_cndmask_b32_e64 v77, v49, v135, s[8:9]
	v_mov_b32_dpp v74, v113 row_ror:2 row_mask:0xf bank_mask:0xf
	v_cndmask_b32_e64 v113, v63, v79, s[8:9]
	v_pk_mul_f32 v[56:57], v[72:73], v[56:57]
	s_nop 0
	v_mov_b32_dpp v137, v113 row_ror:1 row_mask:0xf bank_mask:0xf
	v_cndmask_b32_e64 v113, v63, v79, s[6:7]

; __device__ __forceinline__ float dpp_ror1(float v) { return __int_as_float(__builtin_amdgcn_update_dpp(0, __float_as_int(v), 0x121, 0xf, 0xf, false)); }
; __device__ __forceinline__ float dpp_ror2(float v) { return __int_as_float(__builtin_amdgcn_update_dpp(0, __float_as_int(v), 0x122, 0xf, 0xf, false)); }
;   __device__ __forceinline__ void operator()(const AccT& acc, const Unit& u, int wr, int wc, int fr, int fq) const {
;     ...
;             const float g_cur = xg[m][r], v_cur = xv[m][r];
;             const f32x4 xgp = xg[m > 0 ? m - 1 : 0], xvp = xv[m > 0 ? m - 1 : 0];
;             const float g_pm = (m > 0) ? xgp[r] : 0.f, v_pm = (m > 0) ? xvp[r] : 0.f;
;             const float g1 = dpp_ror1((fr == 15) ? g_pm : g_cur), g2 = dpp_ror2((fr >= 14) ? g_pm : g_cur);
;             const float v1 = dpp_ror1((fr == 15) ? v_pm : v_cur), v2 = dpp_ror2((fr >= 14) ? v_pm : v_cur);
;             const float cg_ = bg[r] + g2 * wg0[r] + g1 * wg1[r] + g_cur * wg2[r];
;             const float cv_ = bv[r] + v2 * wv0[r] + v1 * wv1[r] + v_cur * wv2[r];
;             res[r] = cg_ * __builtin_amdgcn_rcpf(1.f + __builtin_amdgcn_exp2f(-1.4426950408889634f * cg_)) * cv_;
	s_nop 1
	v_mov_b32_dpp v79, v113 row_ror:2 row_mask:0xf bank_mask:0xf
	v_pk_fma_f32 v[58:59], v[98:99], v[78:79], v[110:111]
	v_cndmask_b32_e64 v113, v61, v75, s[8:9]
	v_pk_fma_f32 v[58:59], v[102:103], v[136:137], v[58:59]
	v_cndmask_b32_e64 v78, v49, v135, s[6:7]
	v_pk_fma_f32 v[58:59], v[94:95], v[62:63], v[58:59]
	v_mov_b32_dpp v139, v113 row_ror:1 row_mask:0xf bank_mask:0xf
	v_mul_f32_e32 v72, 0xbfb8aa3b, v58
	v_mul_f32_e32 v73, 0xbfb8aa3b, v59
	v_exp_f32_e32 v72, v72
	v_exp_f32_e32 v73, v73
	v_cndmask_b32_e64 v113, v61, v75, s[6:7]

; __device__ __forceinline__ uint2 pack4(f32x4 v) { return make_uint2(pack2(v[0], v[1]), pack2(v[2], v[3])); }
;   __device__ __forceinline__ void operator()(const AccT& acc, const Unit& u, int wr, int wc, int fr, int fq) const {
;     ...
;             const float cg_ = bg[r] + g2 * wg0[r] + g1 * wg1[r] + g_cur * wg2[r];
;             const float cv_ = bv[r] + v2 * wv0[r] + v1 * wv1[r] + v_cur * wv2[r];
;             res[r] = cg_ * __builtin_amdgcn_rcpf(1.f + __builtin_amdgcn_exp2f(-1.4426950408889634f * cg_)) * cv_;
;           }
;           if (m > 0 || fr >= 2)
;             *(uint2*)(act + (size_t)EPI_ROW(u, ai, m) * DFF + f0) = pack4(res);
	v_add_f32_e32 v72, 1.0, v72
	v_add_f32_e32 v73, 1.0, v73
	v_rcp_f32_e32 v72, v72
	v_rcp_f32_e32 v73, v73
	v_mov_b32_dpp v75, v113 row_ror:2 row_mask:0xf bank_mask:0xf
	v_pk_fma_f32 v[74:75], v[86:87], v[74:75], v[106:107]
	v_cndmask_b32_e64 v79, v52, v62, s[8:9]
	v_pk_fma_f32 v[74:75], v[90:91], v[138:139], v[74:75]
	v_pk_mul_f32 v[58:59], v[58:59], v[72:73]
	v_pk_fma_f32 v[74:75], v[82:83], v[60:61], v[74:75]
	v_cvt_pk_bf16_f32 v72, v56, v57
	v_pk_mul_f32 v[58:59], v[74:75], v[58:59]
	v_mov_b64_e32 v[56:57], s[52:53]
	v_cvt_pk_bf16_f32 v73, v58, v59
	v_mad_i64_i32 v[58:59], s[34:35], v130, s0, v[56:57]
	v_lshl_add_u64 v[130:131], v[58:59], 0, v[168:169]
	v_cndmask_b32_e64 v59, v54, v132, s[8:9]
	s_nop 0
	global_store_dwordx2 v[130:131], v[72:73], off

; __device__ __forceinline__ float dpp_ror1(float v) { return __int_as_float(__builtin_amdgcn_update_dpp(0, __float_as_int(v), 0x121, 0xf, 0xf, false)); }
; __device__ __forceinline__ float dpp_ror2(float v) { return __int_as_float(__builtin_amdgcn_update_dpp(0, __float_as_int(v), 0x122, 0xf, 0xf, false)); }
;   __device__ __forceinline__ void operator()(const AccT& acc, const Unit& u, int wr, int wc, int fr, int fq) const {
;     ...
;             const float g_cur = xg[m][r], v_cur = xv[m][r];
;             const f32x4 xgp = xg[m > 0 ? m - 1 : 0], xvp = xv[m > 0 ? m - 1 : 0];
;             const float g_pm = (m > 0) ? xgp[r] : 0.f, v_pm = (m > 0) ? xvp[r] : 0.f;
;             const float g1 = dpp_ror1((fr == 15) ? g_pm : g_cur), g2 = dpp_ror2((fr >= 14) ? g_pm : g_cur);
;             const float v1 = dpp_ror1((fr == 15) ? v_pm : v_cur), v2 = dpp_ror2((fr >= 14) ? v_pm : v_cur);
	v_mov_b32_dpp v58, v59 row_ror:1 row_mask:0xf bank_mask:0xf
	v_cndmask_b32_e64 v59, v54, v132, s[6:7]
	s_nop 0
	v_cndmask_b32_e64 v73, v55, v133, s[8:9]
	v_mov_b32_dpp v72, v59 row_ror:2 row_mask:0xf bank_mask:0xf
	v_cndmask_b32_e64 v59, v48, v134, s[8:9]
	v_cndmask_b32_e64 v75, v55, v133, s[6:7]
	s_nop 0
	v_mov_b32_dpp v74, v59 row_ror:1 row_mask:0xf bank_mask:0xf
	v_cndmask_b32_e64 v59, v48, v134, s[6:7]
	v_cndmask_b32_e64 v113, v53, v63, s[8:9]
	s_nop 0
	v_mov_b32_dpp v76, v59 row_ror:2 row_mask:0xf bank_mask:0xf

; __device__ __forceinline__ float dpp_ror1(float v) { return __int_as_float(__builtin_amdgcn_update_dpp(0, __float_as_int(v), 0x121, 0xf, 0xf, false)); }
; __device__ __forceinline__ float dpp_ror2(float v) { return __int_as_float(__builtin_amdgcn_update_dpp(0, __float_as_int(v), 0x122, 0xf, 0xf, false)); }
;   __device__ __forceinline__ void operator()(const AccT& acc, const Unit& u, int wr, int wc, int fr, int fq) const {
;     ...
;             const float g_cur = xg[m][r], v_cur = xv[m][r];
;             const f32x4 xgp = xg[m > 0 ? m - 1 : 0], xvp = xv[m > 0 ? m - 1 : 0];
;             const float g_pm = (m > 0) ? xgp[r] : 0.f, v_pm = (m > 0) ? xvp[r] : 0.f;
;             const float g1 = dpp_ror1((fr == 15) ? g_pm : g_cur), g2 = dpp_ror2((fr >= 14) ? g_pm : g_cur);
;             const float v1 = dpp_ror1((fr == 15) ? v_pm : v_cur), v2 = dpp_ror2((fr >= 14) ? v_pm : v_cur);
	s_nop 1
	v_mov_b32_dpp v59, v73 row_ror:1 row_mask:0xf bank_mask:0xf

; __device__ __forceinline__ float dpp_ror1(float v) { return __int_as_float(__builtin_amdgcn_update_dpp(0, __float_as_int(v), 0x121, 0xf, 0xf, false)); }
; __device__ __forceinline__ float dpp_ror2(float v) { return __int_as_float(__builtin_amdgcn_update_dpp(0, __float_as_int(v), 0x122, 0xf, 0xf, false)); }
;   __device__ __forceinline__ void operator()(const AccT& acc, const Unit& u, int wr, int wc, int fr, int fq) const {
;     ...
;             const float g_cur = xg[m][r], v_cur = xv[m][r];
;             const f32x4 xgp = xg[m > 0 ? m - 1 : 0], xvp = xv[m > 0 ? m - 1 : 0];
;             const float g_pm = (m > 0) ? xgp[r] : 0.f, v_pm = (m > 0) ? xvp[r] : 0.f;
;             const float g1 = dpp_ror1((fr == 15) ? g_pm : g_cur), g2 = dpp_ror2((fr >= 14) ? g_pm : g_cur);
;             const float v1 = dpp_ror1((fr == 15) ? v_pm : v_cur), v2 = dpp_ror2((fr >= 14) ? v_pm : v_cur);
;             const float cg_ = bg[r] + g2 * wg0[r] + g1 * wg1[r] + g_cur * wg2[r];
	s_nop 1
	v_mov_b32_dpp v73, v75 row_ror:2 row_mask:0xf bank_mask:0xf
	v_pk_fma_f32 v[72:73], v[96:97], v[72:73], v[108:109]

; __device__ __forceinline__ float dpp_ror1(float v) { return __int_as_float(__builtin_amdgcn_update_dpp(0, __float_as_int(v), 0x121, 0xf, 0xf, false)); }
; __device__ __forceinline__ float dpp_ror2(float v) { return __int_as_float(__builtin_amdgcn_update_dpp(0, __float_as_int(v), 0x122, 0xf, 0xf, false)); }
;   __device__ __forceinline__ void operator()(const AccT& acc, const Unit& u, int wr, int wc, int fr, int fq) const {
;     ...
;             const float g_cur = xg[m][r], v_cur = xv[m][r];
;             const f32x4 xgp = xg[m > 0 ? m - 1 : 0], xvp = xv[m > 0 ? m - 1 : 0];
;             const float g_pm = (m > 0) ? xgp[r] : 0.f, v_pm = (m > 0) ? xvp[r] : 0.f;
;             const float g1 = dpp_ror1((fr == 15) ? g_pm : g_cur), g2 = dpp_ror2((fr >= 14) ? g_pm : g_cur);
;             const float v1 = dpp_ror1((fr == 15) ? v_pm : v_cur), v2 = dpp_ror2((fr >= 14) ? v_pm : v_cur);
;             const float cg_ = bg[r] + g2 * wg0[r] + g1 * wg1[r] + g_cur * wg2[r];
	v_pk_fma_f32 v[58:59], v[100:101], v[58:59], v[72:73]
	s_nop 0
	v_mov_b32_dpp v75, v77 row_ror:1 row_mask:0xf bank_mask:0xf

; __device__ __forceinline__ float dpp_ror1(float v) { return __int_as_float(__builtin_amdgcn_update_dpp(0, __float_as_int(v), 0x121, 0xf, 0xf, false)); }
; __device__ __forceinline__ float dpp_ror2(float v) { return __int_as_float(__builtin_amdgcn_update_dpp(0, __float_as_int(v), 0x122, 0xf, 0xf, false)); }
;   __device__ __forceinline__ void operator()(const AccT& acc, const Unit& u, int wr, int wc, int fr, int fq) const {
;     ...
;             const float g_cur = xg[m][r], v_cur = xv[m][r];
;             const f32x4 xgp = xg[m > 0 ? m - 1 : 0], xvp = xv[m > 0 ? m - 1 : 0];
;             const float g_pm = (m > 0) ? xgp[r] : 0.f, v_pm = (m > 0) ? xvp[r] : 0.f;
;             const float g1 = dpp_ror1((fr == 15) ? g_pm : g_cur), g2 = dpp_ror2((fr >= 14) ? g_pm : g_cur);
;             const float v1 = dpp_ror1((fr == 15) ? v_pm : v_cur), v2 = dpp_ror2((fr >= 14) ? v_pm : v_cur);
;             const float cg_ = bg[r] + g2 * wg0[r] + g1 * wg1[r] + g_cur * wg2[r];
	v_pk_fma_f32 v[58:59], v[92:93], v[54:55], v[58:59]
	s_nop 0
	v_mov_b32_dpp v77, v78 row_ror:2 row_mask:0xf bank_mask:0xf

; __device__ __forceinline__ float dpp_ror1(float v) { return __int_as_float(__builtin_amdgcn_update_dpp(0, __float_as_int(v), 0x121, 0xf, 0xf, false)); }
; __device__ __forceinline__ float dpp_ror2(float v) { return __int_as_float(__builtin_amdgcn_update_dpp(0, __float_as_int(v), 0x122, 0xf, 0xf, false)); }
;   __device__ __forceinline__ void operator()(const AccT& acc, const Unit& u, int wr, int wc, int fr, int fq) const {
;     ...
;             const float g_cur = xg[m][r], v_cur = xv[m][r];
;             const f32x4 xgp = xg[m > 0 ? m - 1 : 0], xvp = xv[m > 0 ? m - 1 : 0];
;             const float g_pm = (m > 0) ? xgp[r] : 0.f, v_pm = (m > 0) ? xvp[r] : 0.f;
;             const float g1 = dpp_ror1((fr == 15) ? g_pm : g_cur), g2 = dpp_ror2((fr >= 14) ? g_pm : g_cur);
;             const float v1 = dpp_ror1((fr == 15) ? v_pm : v_cur), v2 = dpp_ror2((fr >= 14) ? v_pm : v_cur);
;             const float cg_ = bg[r] + g2 * wg0[r] + g1 * wg1[r] + g_cur * wg2[r];
;             const float cv_ = bv[r] + v2 * wv0[r] + v1 * wv1[r] + v_cur * wv2[r];
;             res[r] = cg_ * __builtin_amdgcn_rcpf(1.f + __builtin_amdgcn_exp2f(-1.4426950408889634f * cg_)) * cv_;
	v_mul_f32_e32 v72, 0xbfb8aa3b, v58
	v_mul_f32_e32 v73, 0xbfb8aa3b, v59
	v_mov_b32_dpp v78, v79 row_ror:1 row_mask:0xf bank_mask:0xf
	v_cndmask_b32_e64 v79, v52, v62, s[6:7]

; __device__ __forceinline__ float dpp_ror1(float v) { return __int_as_float(__builtin_amdgcn_update_dpp(0, __float_as_int(v), 0x121, 0xf, 0xf, false)); }
; __device__ __forceinline__ float dpp_ror2(float v) { return __int_as_float(__builtin_amdgcn_update_dpp(0, __float_as_int(v), 0x122, 0xf, 0xf, false)); }
;   __device__ __forceinline__ void operator()(const AccT& acc, const Unit& u, int wr, int wc, int fr, int fq) const {
;     ...
;             const float g_cur = xg[m][r], v_cur = xv[m][r];
;             const f32x4 xgp = xg[m > 0 ? m - 1 : 0], xvp = xv[m > 0 ? m - 1 : 0];
;             const float g_pm = (m > 0) ? xgp[r] : 0.f, v_pm = (m > 0) ? xvp[r] : 0.f;
;             const float g1 = dpp_ror1((fr == 15) ? g_pm : g_cur), g2 = dpp_ror2((fr >= 14) ? g_pm : g_cur);
;             const float v1 = dpp_ror1((fr == 15) ? v_pm : v_cur), v2 = dpp_ror2((fr >= 14) ? v_pm : v_cur);
;             const float cg_ = bg[r] + g2 * wg0[r] + g1 * wg1[r] + g_cur * wg2[r];
;             const float cv_ = bv[r] + v2 * wv0[r] + v1 * wv1[r] + v_cur * wv2[r];
;             res[r] = cg_ * __builtin_amdgcn_rcpf(1.f + __builtin_amdgcn_exp2f(-1.4426950408889634f * cg_)) * cv_;
	v_exp_f32_e32 v72, v72
	v_exp_f32_e32 v73, v73
	v_mov_b32_dpp v62, v79 row_ror:2 row_mask:0xf bank_mask:0xf
	v_cndmask_b32_e64 v79, v50, v60, s[8:9]
	v_add_f32_e32 v72, 1.0, v72
	v_add_f32_e32 v73, 1.0, v73
	v_mov_b32_dpp v132, v79 row_ror:1 row_mask:0xf bank_mask:0xf
	v_cndmask_b32_e64 v79, v50, v60, s[6:7]

; __device__ __forceinline__ float dpp_ror1(float v) { return __int_as_float(__builtin_amdgcn_update_dpp(0, __float_as_int(v), 0x121, 0xf, 0xf, false)); }
; __device__ __forceinline__ float dpp_ror2(float v) { return __int_as_float(__builtin_amdgcn_update_dpp(0, __float_as_int(v), 0x122, 0xf, 0xf, false)); }
;   __device__ __forceinline__ void operator()(const AccT& acc, const Unit& u, int wr, int wc, int fr, int fq) const {
;     ...
;             const float g_cur = xg[m][r], v_cur = xv[m][r];
;             const f32x4 xgp = xg[m > 0 ? m - 1 : 0], xvp = xv[m > 0 ? m - 1 : 0];
;             const float g_pm = (m > 0) ? xgp[r] : 0.f, v_pm = (m > 0) ? xvp[r] : 0.f;
;             const float g1 = dpp_ror1((fr == 15) ? g_pm : g_cur), g2 = dpp_ror2((fr >= 14) ? g_pm : g_cur);
;             const float v1 = dpp_ror1((fr == 15) ? v_pm : v_cur), v2 = dpp_ror2((fr >= 14) ? v_pm : v_cur);
;             const float cg_ = bg[r] + g2 * wg0[r] + g1 * wg1[r] + g_cur * wg2[r];
;             const float cv_ = bv[r] + v2 * wv0[r] + v1 * wv1[r] + v_cur * wv2[r];
;             res[r] = cg_ * __builtin_amdgcn_rcpf(1.f + __builtin_amdgcn_exp2f(-1.4426950408889634f * cg_)) * cv_;
	v_rcp_f32_e32 v72, v72
	v_rcp_f32_e32 v73, v73
	v_mov_b32_dpp v60, v79 row_ror:2 row_mask:0xf bank_mask:0xf

; __device__ __forceinline__ float dpp_ror1(float v) { return __int_as_float(__builtin_amdgcn_update_dpp(0, __float_as_int(v), 0x121, 0xf, 0xf, false)); }
; __device__ __forceinline__ float dpp_ror2(float v) { return __int_as_float(__builtin_amdgcn_update_dpp(0, __float_as_int(v), 0x122, 0xf, 0xf, false)); }
;   __device__ __forceinline__ void operator()(const AccT& acc, const Unit& u, int wr, int wc, int fr, int fq) const {
;     ...
;             const float g_cur = xg[m][r], v_cur = xv[m][r];
;             const f32x4 xgp = xg[m > 0 ? m - 1 : 0], xvp = xv[m > 0 ? m - 1 : 0];
;             const float g_pm = (m > 0) ? xgp[r] : 0.f, v_pm = (m > 0) ? xvp[r] : 0.f;
;             const float g1 = dpp_ror1((fr == 15) ? g_pm : g_cur), g2 = dpp_ror2((fr >= 14) ? g_pm : g_cur);
;             const float v1 = dpp_ror1((fr == 15) ? v_pm : v_cur), v2 = dpp_ror2((fr >= 14) ? v_pm : v_cur);
;             const float cg_ = bg[r] + g2 * wg0[r] + g1 * wg1[r] + g_cur * wg2[r];
;             const float cv_ = bv[r] + v2 * wv0[r] + v1 * wv1[r] + v_cur * wv2[r];
;             res[r] = cg_ * __builtin_amdgcn_rcpf(1.f + __builtin_amdgcn_exp2f(-1.4426950408889634f * cg_)) * cv_;
	v_pk_fma_f32 v[76:77], v[84:85], v[76:77], v[104:105]
	v_pk_mul_f32 v[58:59], v[58:59], v[72:73]
	v_mov_b32_dpp v79, v113 row_ror:1 row_mask:0xf bank_mask:0xf
	v_cndmask_b32_e64 v113, v53, v63, s[6:7]

; __device__ __forceinline__ float dpp_ror1(float v) { return __int_as_float(__builtin_amdgcn_update_dpp(0, __float_as_int(v), 0x121, 0xf, 0xf, false)); }
; __device__ __forceinline__ float dpp_ror2(float v) { return __int_as_float(__builtin_amdgcn_update_dpp(0, __float_as_int(v), 0x122, 0xf, 0xf, false)); }
;   __device__ __forceinline__ void operator()(const AccT& acc, const Unit& u, int wr, int wc, int fr, int fq) const {
;     ...
;             const float g_cur = xg[m][r], v_cur = xv[m][r];
;             const f32x4 xgp = xg[m > 0 ? m - 1 : 0], xvp = xv[m > 0 ? m - 1 : 0];
;             const float g_pm = (m > 0) ? xgp[r] : 0.f, v_pm = (m > 0) ? xvp[r] : 0.f;
;             const float g1 = dpp_ror1((fr == 15) ? g_pm : g_cur), g2 = dpp_ror2((fr >= 14) ? g_pm : g_cur);
;             const float v1 = dpp_ror1((fr == 15) ? v_pm : v_cur), v2 = dpp_ror2((fr >= 14) ? v_pm : v_cur);
;             const float cg_ = bg[r] + g2 * wg0[r] + g1 * wg1[r] + g_cur * wg2[r];
;             const float cv_ = bv[r] + v2 * wv0[r] + v1 * wv1[r] + v_cur * wv2[r];
;             res[r] = cg_ * __builtin_amdgcn_rcpf(1.f + __builtin_amdgcn_exp2f(-1.4426950408889634f * cg_)) * cv_;
	v_pk_fma_f32 v[74:75], v[88:89], v[74:75], v[76:77]
	s_nop 0
	v_mov_b32_dpp v63, v113 row_ror:2 row_mask:0xf bank_mask:0xf
	v_pk_fma_f32 v[62:63], v[98:99], v[62:63], v[110:111]
	v_cndmask_b32_e64 v113, v51, v61, s[8:9]
	v_pk_fma_f32 v[62:63], v[102:103], v[78:79], v[62:63]
	v_pk_fma_f32 v[74:75], v[80:81], v[48:49], v[74:75]
	v_pk_fma_f32 v[62:63], v[94:95], v[52:53], v[62:63]
	v_mov_b32_dpp v133, v113 row_ror:1 row_mask:0xf bank_mask:0xf
	v_mul_f32_e32 v72, 0xbfb8aa3b, v62
	v_mul_f32_e32 v73, 0xbfb8aa3b, v63
	v_exp_f32_e32 v72, v72
	v_exp_f32_e32 v73, v73
	v_cndmask_b32_e64 v113, v51, v61, s[6:7]

; __device__ __forceinline__ uint2 pack4(f32x4 v) { return make_uint2(pack2(v[0], v[1]), pack2(v[2], v[3])); }
; __device__ __forceinline__ float dpp_ror1(float v) { return __int_as_float(__builtin_amdgcn_update_dpp(0, __float_as_int(v), 0x121, 0xf, 0xf, false)); }
; __device__ __forceinline__ float dpp_ror2(float v) { return __int_as_float(__builtin_amdgcn_update_dpp(0, __float_as_int(v), 0x122, 0xf, 0xf, false)); }
;   __device__ __forceinline__ void operator()(const AccT& acc, const Unit& u, int wr, int wc, int fr, int fq) const {
;     ...
;             const float g_cur = xg[m][r], v_cur = xv[m][r];
;             const f32x4 xgp = xg[m > 0 ? m - 1 : 0], xvp = xv[m > 0 ? m - 1 : 0];
;             const float g_pm = (m > 0) ? xgp[r] : 0.f, v_pm = (m > 0) ? xvp[r] : 0.f;
;             const float g1 = dpp_ror1((fr == 15) ? g_pm : g_cur), g2 = dpp_ror2((fr >= 14) ? g_pm : g_cur);
;             const float v1 = dpp_ror1((fr == 15) ? v_pm : v_cur), v2 = dpp_ror2((fr >= 14) ? v_pm : v_cur);
;             const float cg_ = bg[r] + g2 * wg0[r] + g1 * wg1[r] + g_cur * wg2[r];
;             const float cv_ = bv[r] + v2 * wv0[r] + v1 * wv1[r] + v_cur * wv2[r];
;             res[r] = cg_ * __builtin_amdgcn_rcpf(1.f + __builtin_amdgcn_exp2f(-1.4426950408889634f * cg_)) * cv_;
;           }
;           if (m > 0 || fr >= 2)
;             *(uint2*)(act + (size_t)EPI_ROW(u, ai, m) * DFF + f0) = pack4(res);
	v_add_f32_e32 v72, 1.0, v72
	v_add_f32_e32 v73, 1.0, v73
	v_rcp_f32_e32 v72, v72
	v_rcp_f32_e32 v73, v73
	v_mov_b32_dpp v61, v113 row_ror:2 row_mask:0xf bank_mask:0xf
	v_pk_fma_f32 v[60:61], v[86:87], v[60:61], v[106:107]
	v_pk_mul_f32 v[58:59], v[74:75], v[58:59]
	v_pk_fma_f32 v[60:61], v[90:91], v[132:133], v[60:61]
	v_pk_mul_f32 v[62:63], v[62:63], v[72:73]
	v_pk_fma_f32 v[60:61], v[82:83], v[50:51], v[60:61]
	v_cvt_pk_bf16_f32 v58, v58, v59
	v_pk_mul_f32 v[60:61], v[60:61], v[62:63]
	v_cndmask_b32_e64 v62, v65, v49, s[8:9]
	v_cvt_pk_bf16_f32 v59, v60, v61
	v_mad_i64_i32 v[60:61], s[34:35], v128, s0, v[56:57]
	v_lshl_add_u64 v[128:129], v[60:61], 0, v[168:169]
	global_store_dwordx2 v[128:129], v[58:59], off
	v_cndmask_b32_e64 v59, v68, v54, s[8:9]
	s_nop 0

; __device__ __forceinline__ float dpp_ror1(float v) { return __int_as_float(__builtin_amdgcn_update_dpp(0, __float_as_int(v), 0x121, 0xf, 0xf, false)); }
; __device__ __forceinline__ float dpp_ror2(float v) { return __int_as_float(__builtin_amdgcn_update_dpp(0, __float_as_int(v), 0x122, 0xf, 0xf, false)); }
;   __device__ __forceinline__ void operator()(const AccT& acc, const Unit& u, int wr, int wc, int fr, int fq) const {
;     ...
;             const float g_cur = xg[m][r], v_cur = xv[m][r];
;             const f32x4 xgp = xg[m > 0 ? m - 1 : 0], xvp = xv[m > 0 ? m - 1 : 0];
;             const float g_pm = (m > 0) ? xgp[r] : 0.f, v_pm = (m > 0) ? xvp[r] : 0.f;
;             const float g1 = dpp_ror1((fr == 15) ? g_pm : g_cur), g2 = dpp_ror2((fr >= 14) ? g_pm : g_cur);
;             const float v1 = dpp_ror1((fr == 15) ? v_pm : v_cur), v2 = dpp_ror2((fr >= 14) ? v_pm : v_cur);
	v_cndmask_b32_e64 v61, v69, v55, s[8:9]
	v_mov_b32_dpp v58, v59 row_ror:1 row_mask:0xf bank_mask:0xf
	v_cndmask_b32_e64 v59, v68, v54, s[6:7]
	s_nop 0
	v_cndmask_b32_e64 v63, v70, v52, s[8:9]

; __device__ __forceinline__ float dpp_ror1(float v) { return __int_as_float(__builtin_amdgcn_update_dpp(0, __float_as_int(v), 0x121, 0xf, 0xf, false)); }
; __device__ __forceinline__ float dpp_ror2(float v) { return __int_as_float(__builtin_amdgcn_update_dpp(0, __float_as_int(v), 0x122, 0xf, 0xf, false)); }
;   __device__ __forceinline__ void operator()(const AccT& acc, const Unit& u, int wr, int wc, int fr, int fq) const {
;     ...
;             const float g_cur = xg[m][r], v_cur = xv[m][r];
;             const f32x4 xgp = xg[m > 0 ? m - 1 : 0], xvp = xv[m > 0 ? m - 1 : 0];
;             const float g_pm = (m > 0) ? xgp[r] : 0.f, v_pm = (m > 0) ? xvp[r] : 0.f;
;             const float g1 = dpp_ror1((fr == 15) ? g_pm : g_cur), g2 = dpp_ror2((fr >= 14) ? g_pm : g_cur);
;             const float v1 = dpp_ror1((fr == 15) ? v_pm : v_cur), v2 = dpp_ror2((fr >= 14) ? v_pm : v_cur);
	v_mov_b32_dpp v54, v59 row_ror:2 row_mask:0xf bank_mask:0xf
	v_cndmask_b32_e64 v59, v64, v48, s[8:9]
	v_cndmask_b32_e64 v73, v71, v53, s[8:9]
	v_cndmask_b32_e64 v74, v67, v51, s[8:9]
	v_mov_b32_dpp v60, v59 row_ror:1 row_mask:0xf bank_mask:0xf
	v_cndmask_b32_e64 v59, v64, v48, s[6:7]

; __device__ __forceinline__ float dpp_ror1(float v) { return __int_as_float(__builtin_amdgcn_update_dpp(0, __float_as_int(v), 0x121, 0xf, 0xf, false)); }
; __device__ __forceinline__ float dpp_ror2(float v) { return __int_as_float(__builtin_amdgcn_update_dpp(0, __float_as_int(v), 0x122, 0xf, 0xf, false)); }
;   __device__ __forceinline__ void operator()(const AccT& acc, const Unit& u, int wr, int wc, int fr, int fq) const {
;     ...
;             const float g_cur = xg[m][r], v_cur = xv[m][r];
;             const f32x4 xgp = xg[m > 0 ? m - 1 : 0], xvp = xv[m > 0 ? m - 1 : 0];
;             const float g_pm = (m > 0) ? xgp[r] : 0.f, v_pm = (m > 0) ? xvp[r] : 0.f;
;             const float g1 = dpp_ror1((fr == 15) ? g_pm : g_cur), g2 = dpp_ror2((fr >= 14) ? g_pm : g_cur);
;             const float v1 = dpp_ror1((fr == 15) ? v_pm : v_cur), v2 = dpp_ror2((fr >= 14) ? v_pm : v_cur);
	s_nop 1
	v_mov_b32_dpp v48, v59 row_ror:2 row_mask:0xf bank_mask:0xf

; __device__ __forceinline__ float dpp_ror1(float v) { return __int_as_float(__builtin_amdgcn_update_dpp(0, __float_as_int(v), 0x121, 0xf, 0xf, false)); }
; __device__ __forceinline__ float dpp_ror2(float v) { return __int_as_float(__builtin_amdgcn_update_dpp(0, __float_as_int(v), 0x122, 0xf, 0xf, false)); }
;   __device__ __forceinline__ void operator()(const AccT& acc, const Unit& u, int wr, int wc, int fr, int fq) const {
;     ...
;             const float g_cur = xg[m][r], v_cur = xv[m][r];
;             const f32x4 xgp = xg[m > 0 ? m - 1 : 0], xvp = xv[m > 0 ? m - 1 : 0];
;             const float g_pm = (m > 0) ? xgp[r] : 0.f, v_pm = (m > 0) ? xvp[r] : 0.f;
;             const float g1 = dpp_ror1((fr == 15) ? g_pm : g_cur), g2 = dpp_ror2((fr >= 14) ? g_pm : g_cur);
;             const float v1 = dpp_ror1((fr == 15) ? v_pm : v_cur), v2 = dpp_ror2((fr >= 14) ? v_pm : v_cur);
	s_nop 1
	v_mov_b32_dpp v59, v61 row_ror:1 row_mask:0xf bank_mask:0xf
	v_cndmask_b32_e64 v61, v69, v55, s[6:7]

; __device__ __forceinline__ float dpp_ror1(float v) { return __int_as_float(__builtin_amdgcn_update_dpp(0, __float_as_int(v), 0x121, 0xf, 0xf, false)); }
; __device__ __forceinline__ float dpp_ror2(float v) { return __int_as_float(__builtin_amdgcn_update_dpp(0, __float_as_int(v), 0x122, 0xf, 0xf, false)); }
;   __device__ __forceinline__ void operator()(const AccT& acc, const Unit& u, int wr, int wc, int fr, int fq) const {
;     ...
;             const float g_cur = xg[m][r], v_cur = xv[m][r];
;             const f32x4 xgp = xg[m > 0 ? m - 1 : 0], xvp = xv[m > 0 ? m - 1 : 0];
;             const float g_pm = (m > 0) ? xgp[r] : 0.f, v_pm = (m > 0) ? xvp[r] : 0.f;
;             const float g1 = dpp_ror1((fr == 15) ? g_pm : g_cur), g2 = dpp_ror2((fr >= 14) ? g_pm : g_cur);
;             const float v1 = dpp_ror1((fr == 15) ? v_pm : v_cur), v2 = dpp_ror2((fr >= 14) ? v_pm : v_cur);
;             const float cg_ = bg[r] + g2 * wg0[r] + g1 * wg1[r] + g_cur * wg2[r];
	s_nop 1
	v_mov_b32_dpp v55, v61 row_ror:2 row_mask:0xf bank_mask:0xf
	v_pk_fma_f32 v[54:55], v[96:97], v[54:55], v[108:109]

; __device__ __forceinline__ float dpp_ror1(float v) { return __int_as_float(__builtin_amdgcn_update_dpp(0, __float_as_int(v), 0x121, 0xf, 0xf, false)); }
; __device__ __forceinline__ float dpp_ror2(float v) { return __int_as_float(__builtin_amdgcn_update_dpp(0, __float_as_int(v), 0x122, 0xf, 0xf, false)); }
;   __device__ __forceinline__ void operator()(const AccT& acc, const Unit& u, int wr, int wc, int fr, int fq) const {
;     ...
;             const float g_cur = xg[m][r], v_cur = xv[m][r];
;             const f32x4 xgp = xg[m > 0 ? m - 1 : 0], xvp = xv[m > 0 ? m - 1 : 0];
;             const float g_pm = (m > 0) ? xgp[r] : 0.f, v_pm = (m > 0) ? xvp[r] : 0.f;
;             const float g1 = dpp_ror1((fr == 15) ? g_pm : g_cur), g2 = dpp_ror2((fr >= 14) ? g_pm : g_cur);
;             const float v1 = dpp_ror1((fr == 15) ? v_pm : v_cur), v2 = dpp_ror2((fr >= 14) ? v_pm : v_cur);
;             const float cg_ = bg[r] + g2 * wg0[r] + g1 * wg1[r] + g_cur * wg2[r];
	v_pk_fma_f32 v[54:55], v[100:101], v[58:59], v[54:55]
	s_nop 0
	v_pk_fma_f32 v[54:55], v[92:93], v[68:69], v[54:55]
	v_mov_b32_dpp v61, v62 row_ror:1 row_mask:0xf bank_mask:0xf
	v_cndmask_b32_e64 v62, v65, v49, s[6:7]

; __device__ __forceinline__ float dpp_ror1(float v) { return __int_as_float(__builtin_amdgcn_update_dpp(0, __float_as_int(v), 0x121, 0xf, 0xf, false)); }
; __device__ __forceinline__ float dpp_ror2(float v) { return __int_as_float(__builtin_amdgcn_update_dpp(0, __float_as_int(v), 0x122, 0xf, 0xf, false)); }
;   __device__ __forceinline__ void operator()(const AccT& acc, const Unit& u, int wr, int wc, int fr, int fq) const {
;     ...
;             const float g_cur = xg[m][r], v_cur = xv[m][r];
;             const f32x4 xgp = xg[m > 0 ? m - 1 : 0], xvp = xv[m > 0 ? m - 1 : 0];
;             const float g_pm = (m > 0) ? xgp[r] : 0.f, v_pm = (m > 0) ? xvp[r] : 0.f;
;             const float g1 = dpp_ror1((fr == 15) ? g_pm : g_cur), g2 = dpp_ror2((fr >= 14) ? g_pm : g_cur);
;             const float v1 = dpp_ror1((fr == 15) ? v_pm : v_cur), v2 = dpp_ror2((fr >= 14) ? v_pm : v_cur);
;             const float cg_ = bg[r] + g2 * wg0[r] + g1 * wg1[r] + g_cur * wg2[r];
;             const float cv_ = bv[r] + v2 * wv0[r] + v1 * wv1[r] + v_cur * wv2[r];
;             res[r] = cg_ * __builtin_amdgcn_rcpf(1.f + __builtin_amdgcn_exp2f(-1.4426950408889634f * cg_)) * cv_;
	v_mul_f32_e32 v58, 0xbfb8aa3b, v54
	v_mul_f32_e32 v59, 0xbfb8aa3b, v55
	v_mov_b32_dpp v49, v62 row_ror:2 row_mask:0xf bank_mask:0xf

; __device__ __forceinline__ float dpp_ror1(float v) { return __int_as_float(__builtin_amdgcn_update_dpp(0, __float_as_int(v), 0x121, 0xf, 0xf, false)); }
; __device__ __forceinline__ float dpp_ror2(float v) { return __int_as_float(__builtin_amdgcn_update_dpp(0, __float_as_int(v), 0x122, 0xf, 0xf, false)); }
;   __device__ __forceinline__ void operator()(const AccT& acc, const Unit& u, int wr, int wc, int fr, int fq) const {
;     ...
;             const float g_cur = xg[m][r], v_cur = xv[m][r];
;             const f32x4 xgp = xg[m > 0 ? m - 1 : 0], xvp = xv[m > 0 ? m - 1 : 0];
;             const float g_pm = (m > 0) ? xgp[r] : 0.f, v_pm = (m > 0) ? xvp[r] : 0.f;
;             const float g1 = dpp_ror1((fr == 15) ? g_pm : g_cur), g2 = dpp_ror2((fr >= 14) ? g_pm : g_cur);
;             const float v1 = dpp_ror1((fr == 15) ? v_pm : v_cur), v2 = dpp_ror2((fr >= 14) ? v_pm : v_cur);
;             const float cg_ = bg[r] + g2 * wg0[r] + g1 * wg1[r] + g_cur * wg2[r];
;             const float cv_ = bv[r] + v2 * wv0[r] + v1 * wv1[r] + v_cur * wv2[r];
;             res[r] = cg_ * __builtin_amdgcn_rcpf(1.f + __builtin_amdgcn_exp2f(-1.4426950408889634f * cg_)) * cv_;
	v_exp_f32_e32 v58, v58
	v_exp_f32_e32 v59, v59
	v_mov_b32_dpp v62, v63 row_ror:1 row_mask:0xf bank_mask:0xf
	v_cndmask_b32_e64 v63, v70, v52, s[6:7]

; __device__ __forceinline__ float dpp_ror1(float v) { return __int_as_float(__builtin_amdgcn_update_dpp(0, __float_as_int(v), 0x121, 0xf, 0xf, false)); }
; __device__ __forceinline__ float dpp_ror2(float v) { return __int_as_float(__builtin_amdgcn_update_dpp(0, __float_as_int(v), 0x122, 0xf, 0xf, false)); }
;   __device__ __forceinline__ void operator()(const AccT& acc, const Unit& u, int wr, int wc, int fr, int fq) const {
;     ...
;             const float g_cur = xg[m][r], v_cur = xv[m][r];
;             const f32x4 xgp = xg[m > 0 ? m - 1 : 0], xvp = xv[m > 0 ? m - 1 : 0];
;             const float g_pm = (m > 0) ? xgp[r] : 0.f, v_pm = (m > 0) ? xvp[r] : 0.f;
;             const float g1 = dpp_ror1((fr == 15) ? g_pm : g_cur), g2 = dpp_ror2((fr >= 14) ? g_pm : g_cur);
;             const float v1 = dpp_ror1((fr == 15) ? v_pm : v_cur), v2 = dpp_ror2((fr >= 14) ? v_pm : v_cur);
;             const float cg_ = bg[r] + g2 * wg0[r] + g1 * wg1[r] + g_cur * wg2[r];
;             const float cv_ = bv[r] + v2 * wv0[r] + v1 * wv1[r] + v_cur * wv2[r];
;             res[r] = cg_ * __builtin_amdgcn_rcpf(1.f + __builtin_amdgcn_exp2f(-1.4426950408889634f * cg_)) * cv_;
	v_add_f32_e32 v58, 1.0, v58
	v_add_f32_e32 v59, 1.0, v59
	v_mov_b32_dpp v52, v63 row_ror:2 row_mask:0xf bank_mask:0xf
	v_cndmask_b32_e64 v63, v66, v50, s[8:9]
	v_rcp_f32_e32 v58, v58
	v_rcp_f32_e32 v59, v59
	v_mov_b32_dpp v72, v63 row_ror:1 row_mask:0xf bank_mask:0xf
	v_cndmask_b32_e64 v63, v66, v50, s[6:7]

; __device__ __forceinline__ float dpp_ror1(float v) { return __int_as_float(__builtin_amdgcn_update_dpp(0, __float_as_int(v), 0x121, 0xf, 0xf, false)); }
; __device__ __forceinline__ float dpp_ror2(float v) { return __int_as_float(__builtin_amdgcn_update_dpp(0, __float_as_int(v), 0x122, 0xf, 0xf, false)); }
;   __device__ __forceinline__ void operator()(const AccT& acc, const Unit& u, int wr, int wc, int fr, int fq) const {
;     ...
;             const float g_cur = xg[m][r], v_cur = xv[m][r];
;             const f32x4 xgp = xg[m > 0 ? m - 1 : 0], xvp = xv[m > 0 ? m - 1 : 0];
;             const float g_pm = (m > 0) ? xgp[r] : 0.f, v_pm = (m > 0) ? xvp[r] : 0.f;
;             const float g1 = dpp_ror1((fr == 15) ? g_pm : g_cur), g2 = dpp_ror2((fr >= 14) ? g_pm : g_cur);
;             const float v1 = dpp_ror1((fr == 15) ? v_pm : v_cur), v2 = dpp_ror2((fr >= 14) ? v_pm : v_cur);
;             const float cg_ = bg[r] + g2 * wg0[r] + g1 * wg1[r] + g_cur * wg2[r];
;             const float cv_ = bv[r] + v2 * wv0[r] + v1 * wv1[r] + v_cur * wv2[r];
;             res[r] = cg_ * __builtin_amdgcn_rcpf(1.f + __builtin_amdgcn_exp2f(-1.4426950408889634f * cg_)) * cv_;
	v_pk_fma_f32 v[48:49], v[84:85], v[48:49], v[104:105]
	v_pk_mul_f32 v[54:55], v[54:55], v[58:59]
	v_mov_b32_dpp v50, v63 row_ror:2 row_mask:0xf bank_mask:0xf

; __device__ __forceinline__ float dpp_ror1(float v) { return __int_as_float(__builtin_amdgcn_update_dpp(0, __float_as_int(v), 0x121, 0xf, 0xf, false)); }
; __device__ __forceinline__ float dpp_ror2(float v) { return __int_as_float(__builtin_amdgcn_update_dpp(0, __float_as_int(v), 0x122, 0xf, 0xf, false)); }
;   __device__ __forceinline__ void operator()(const AccT& acc, const Unit& u, int wr, int wc, int fr, int fq) const {
;     ...
;             const float g_cur = xg[m][r], v_cur = xv[m][r];
;             const f32x4 xgp = xg[m > 0 ? m - 1 : 0], xvp = xv[m > 0 ? m - 1 : 0];
;             const float g_pm = (m > 0) ? xgp[r] : 0.f, v_pm = (m > 0) ? xvp[r] : 0.f;
;             const float g1 = dpp_ror1((fr == 15) ? g_pm : g_cur), g2 = dpp_ror2((fr >= 14) ? g_pm : g_cur);
;             const float v1 = dpp_ror1((fr == 15) ? v_pm : v_cur), v2 = dpp_ror2((fr >= 14) ? v_pm : v_cur);
;             const float cg_ = bg[r] + g2 * wg0[r] + g1 * wg1[r] + g_cur * wg2[r];
	v_pk_fma_f32 v[48:49], v[88:89], v[60:61], v[48:49]
	s_nop 0
	v_mov_b32_dpp v63, v73 row_ror:1 row_mask:0xf bank_mask:0xf
	v_cndmask_b32_e64 v73, v71, v53, s[6:7]

; __device__ __forceinline__ float dpp_ror1(float v) { return __int_as_float(__builtin_amdgcn_update_dpp(0, __float_as_int(v), 0x121, 0xf, 0xf, false)); }
; __device__ __forceinline__ float dpp_ror2(float v) { return __int_as_float(__builtin_amdgcn_update_dpp(0, __float_as_int(v), 0x122, 0xf, 0xf, false)); }
;   __device__ __forceinline__ void operator()(const AccT& acc, const Unit& u, int wr, int wc, int fr, int fq) const {
;     ...
;             const float g_cur = xg[m][r], v_cur = xv[m][r];
;             const f32x4 xgp = xg[m > 0 ? m - 1 : 0], xvp = xv[m > 0 ? m - 1 : 0];
;             const float g_pm = (m > 0) ? xgp[r] : 0.f, v_pm = (m > 0) ? xvp[r] : 0.f;
;             const float g1 = dpp_ror1((fr == 15) ? g_pm : g_cur), g2 = dpp_ror2((fr >= 14) ? g_pm : g_cur);
;             const float v1 = dpp_ror1((fr == 15) ? v_pm : v_cur), v2 = dpp_ror2((fr >= 14) ? v_pm : v_cur);
;             const float cg_ = bg[r] + g2 * wg0[r] + g1 * wg1[r] + g_cur * wg2[r];
	v_pk_fma_f32 v[48:49], v[80:81], v[64:65], v[48:49]
	s_nop 0
	v_mov_b32_dpp v53, v73 row_ror:2 row_mask:0xf bank_mask:0xf
	v_pk_fma_f32 v[52:53], v[98:99], v[52:53], v[110:111]
	v_pk_mul_f32 v[48:49], v[48:49], v[54:55]
	v_pk_fma_f32 v[52:53], v[102:103], v[62:63], v[52:53]

; __device__ __forceinline__ float dpp_ror1(float v) { return __int_as_float(__builtin_amdgcn_update_dpp(0, __float_as_int(v), 0x121, 0xf, 0xf, false)); }
; __device__ __forceinline__ float dpp_ror2(float v) { return __int_as_float(__builtin_amdgcn_update_dpp(0, __float_as_int(v), 0x122, 0xf, 0xf, false)); }
;   __device__ __forceinline__ void operator()(const AccT& acc, const Unit& u, int wr, int wc, int fr, int fq) const {
;     ...
;             const float g_cur = xg[m][r], v_cur = xv[m][r];
;             const f32x4 xgp = xg[m > 0 ? m - 1 : 0], xvp = xv[m > 0 ? m - 1 : 0];
;             const float g_pm = (m > 0) ? xgp[r] : 0.f, v_pm = (m > 0) ? xvp[r] : 0.f;
;             const float g1 = dpp_ror1((fr == 15) ? g_pm : g_cur), g2 = dpp_ror2((fr >= 14) ? g_pm : g_cur);
;             const float v1 = dpp_ror1((fr == 15) ? v_pm : v_cur), v2 = dpp_ror2((fr >= 14) ? v_pm : v_cur);
;             const float cg_ = bg[r] + g2 * wg0[r] + g1 * wg1[r] + g_cur * wg2[r];
;             const float cv_ = bv[r] + v2 * wv0[r] + v1 * wv1[r] + v_cur * wv2[r];
;             res[r] = cg_ * __builtin_amdgcn_rcpf(1.f + __builtin_amdgcn_exp2f(-1.4426950408889634f * cg_)) * cv_;
	v_pk_fma_f32 v[52:53], v[94:95], v[70:71], v[52:53]
	v_cvt_pk_bf16_f32 v48, v48, v49
	v_mul_f32_e32 v54, 0xbfb8aa3b, v52
	v_mul_f32_e32 v55, 0xbfb8aa3b, v53
	v_exp_f32_e32 v54, v54
	v_exp_f32_e32 v55, v55
	v_mov_b32_dpp v73, v74 row_ror:1 row_mask:0xf bank_mask:0xf
	v_cndmask_b32_e64 v74, v67, v51, s[6:7]
	v_add_f32_e32 v54, 1.0, v54
	v_add_f32_e32 v55, 1.0, v55

; __device__ __forceinline__ uint2 pack4(f32x4 v) { return make_uint2(pack2(v[0], v[1]), pack2(v[2], v[3])); }
;   __device__ __forceinline__ void operator()(const AccT& acc, const Unit& u, int wr, int wc, int fr, int fq) const {
;     ...
;         const f32x4 wg0 = *(const f32x4*)(cw + f0), wg1 = *(const f32x4*)(cw + NUP + f0), wg2 = *(const f32x4*)(cw + 2 * NUP + f0);
;         const f32x4 wv0 = *(const f32x4*)(cw + DFF + f0), wv1 = *(const f32x4*)(cw + NUP + DFF + f0), wv2 = *(const f32x4*)(cw + 2 * NUP + DFF + f0);
;         const f32x4 bg = *(const f32x4*)(cb + f0), bv = *(const f32x4*)(cb + DFF + f0);
;         f32x4 xg[4], xv[4];
; #pragma unroll
;         for (int m = 0; m < 4; ++m) { xg[m] = acc[ai][0][m][n] * rs[m]; xv[m] = acc[ai][1][m][n] * rs[m]; }
;         if (fr < 2) {
;           float* d = ub + ((size_t)(chunk * 4 + fr) * NUP + gc);
;           *(float4*)d = make_float4(xg[0][0], xg[0][1], xg[0][2], xg[0][3]);
;           *(float4*)(d + 128) = make_float4(xv[0][0], xv[0][1], xv[0][2], xv[0][3]);
;         }
;         if (fr >= 14) {
;           float* d = ub + ((size_t)(chunk * 4 + 2 + (fr - 14)) * NUP + gc);
;           *(float4*)d = make_float4(xg[3][0], xg[3][1], xg[3][2], xg[3][3]);
;           *(float4*)(d + 128) = make_float4(xv[3][0], xv[3][1], xv[3][2], xv[3][3]);
;         }
; #pragma unroll
;         for (int m = 0; m < 4; ++m) {
;           f32x4 res;
; #pragma unroll
;           for (int r = 0; r < 4; ++r) {
;             const float g_cur = xg[m][r], v_cur = xv[m][r];
;             const f32x4 xgp = xg[m > 0 ? m - 1 : 0], xvp = xv[m > 0 ? m - 1 : 0];
;             const float g_pm = (m > 0) ? xgp[r] : 0.f, v_pm = (m > 0) ? xvp[r] : 0.f;
;             const float g1 = dpp_ror1((fr == 15) ? g_pm : g_cur), g2 = dpp_ror2((fr >= 14) ? g_pm : g_cur);
;             const float v1 = dpp_ror1((fr == 15) ? v_pm : v_cur), v2 = dpp_ror2((fr >= 14) ? v_pm : v_cur);
;             const float cg_ = bg[r] + g2 * wg0[r] + g1 * wg1[r] + g_cur * wg2[r];
;             const float cv_ = bv[r] + v2 * wv0[r] + v1 * wv1[r] + v_cur * wv2[r];
;             res[r] = cg_ * __builtin_amdgcn_rcpf(1.f + __builtin_amdgcn_exp2f(-1.4426950408889634f * cg_)) * cv_;
;           }
;           if (m > 0 || fr >= 2)
;             *(uint2*)(act + (size_t)EPI_ROW(u, ai, m) * DFF + f0) = pack4(res);
	v_rcp_f32_e32 v54, v54
	v_rcp_f32_e32 v55, v55
	v_mov_b32_dpp v51, v74 row_ror:2 row_mask:0xf bank_mask:0xf
	v_pk_fma_f32 v[50:51], v[86:87], v[50:51], v[106:107]
	v_pk_mul_f32 v[52:53], v[52:53], v[54:55]
	v_pk_fma_f32 v[50:51], v[90:91], v[72:73], v[50:51]
	s_nop 0
	v_pk_fma_f32 v[50:51], v[82:83], v[66:67], v[50:51]
	v_mov_b32_e32 v82, v114
	v_pk_mul_f32 v[50:51], v[50:51], v[52:53]
	v_mov_b32_e32 v83, v114
	v_cvt_pk_bf16_f32 v49, v50, v51
	v_mad_i64_i32 v[50:51], s[34:35], v116, s0, v[56:57]
	v_lshl_add_u64 v[80:81], v[50:51], 0, v[168:169]
	global_store_dwordx2 v[80:81], v[48:49], off
	global_load_dwordx4 v[64:67], v[194:195], off offset:64
	global_load_dwordx4 v[68:71], v[144:145], off
	global_load_dwordx4 v[60:63], v[146:147], off
	global_load_dwordx4 v[52:55], v[148:149], off
	global_load_dwordx4 v[56:59], v[150:151], off
	global_load_dwordx4 v[48:51], v[152:153], off
	global_load_dwordx4 v[76:79], v[196:197], off offset:64
	global_load_dwordx4 v[72:75], v[154:155], off
	v_pk_mul_f32 v[46:47], v[46:47], v[82:83]
	v_pk_mul_f32 v[42:43], v[42:43], v[82:83]
	s_and_saveexec_b64 s[38:39], s[4:5]
	s_cbranch_execz .LBB0_508
	v_lshl_add_u64 v[82:83], v[190:191], 2, v[118:119]
	global_store_dwordx4 v[82:83], v[44:47], off offset:64
	global_store_dwordx4 v[82:83], v[40:43], off offset:576

; __device__ __forceinline__ float dpp_ror1(float v) { return __int_as_float(__builtin_amdgcn_update_dpp(0, __float_as_int(v), 0x121, 0xf, 0xf, false)); }
; __device__ __forceinline__ float dpp_ror2(float v) { return __int_as_float(__builtin_amdgcn_update_dpp(0, __float_as_int(v), 0x122, 0xf, 0xf, false)); }
;   __device__ __forceinline__ void operator()(const AccT& acc, const Unit& u, int wr, int wc, int fr, int fq) const {
;     ...
;             const float g_cur = xg[m][r], v_cur = xv[m][r];
;             const f32x4 xgp = xg[m > 0 ? m - 1 : 0], xvp = xv[m > 0 ? m - 1 : 0];
;             const float g_pm = (m > 0) ? xgp[r] : 0.f, v_pm = (m > 0) ? xvp[r] : 0.f;
;             const float g1 = dpp_ror1((fr == 15) ? g_pm : g_cur), g2 = dpp_ror2((fr >= 14) ? g_pm : g_cur);
;             const float v1 = dpp_ror1((fr == 15) ? v_pm : v_cur), v2 = dpp_ror2((fr >= 14) ? v_pm : v_cur);
.LBB0_510:
	s_or_b64 exec, exec, s[38:39]
	v_cndmask_b32_e64 v89, v44, 0, s[8:9]
	s_nop 0
	s_nop 0

; __device__ __forceinline__ float dpp_ror1(float v) { return __int_as_float(__builtin_amdgcn_update_dpp(0, __float_as_int(v), 0x121, 0xf, 0xf, false)); }
; __device__ __forceinline__ float dpp_ror2(float v) { return __int_as_float(__builtin_amdgcn_update_dpp(0, __float_as_int(v), 0x122, 0xf, 0xf, false)); }
;   __device__ __forceinline__ void operator()(const AccT& acc, const Unit& u, int wr, int wc, int fr, int fq) const {
;     ...
;             const float g_cur = xg[m][r], v_cur = xv[m][r];
;             const f32x4 xgp = xg[m > 0 ? m - 1 : 0], xvp = xv[m > 0 ? m - 1 : 0];
;             const float g_pm = (m > 0) ? xgp[r] : 0.f, v_pm = (m > 0) ? xvp[r] : 0.f;
;             const float g1 = dpp_ror1((fr == 15) ? g_pm : g_cur), g2 = dpp_ror2((fr >= 14) ? g_pm : g_cur);
;             const float v1 = dpp_ror1((fr == 15) ? v_pm : v_cur), v2 = dpp_ror2((fr >= 14) ? v_pm : v_cur);
	v_mov_b32_dpp v94, v89 row_ror:1 row_mask:0xf bank_mask:0xf
	v_mov_b32_dpp v96, v88 row_ror:2 row_mask:0xf bank_mask:0xf
	v_cndmask_b32_e64 v89, v40, 0, s[8:9]

; __device__ __forceinline__ float dpp_ror1(float v) { return __int_as_float(__builtin_amdgcn_update_dpp(0, __float_as_int(v), 0x121, 0xf, 0xf, false)); }
; __device__ __forceinline__ float dpp_ror2(float v) { return __int_as_float(__builtin_amdgcn_update_dpp(0, __float_as_int(v), 0x122, 0xf, 0xf, false)); }
;   __device__ __forceinline__ void operator()(const AccT& acc, const Unit& u, int wr, int wc, int fr, int fq) const {
;     ...
;             const float g_cur = xg[m][r], v_cur = xv[m][r];
;             const f32x4 xgp = xg[m > 0 ? m - 1 : 0], xvp = xv[m > 0 ? m - 1 : 0];
;             const float g_pm = (m > 0) ? xgp[r] : 0.f, v_pm = (m > 0) ? xvp[r] : 0.f;
;             const float g1 = dpp_ror1((fr == 15) ? g_pm : g_cur), g2 = dpp_ror2((fr >= 14) ? g_pm : g_cur);
;             const float v1 = dpp_ror1((fr == 15) ? v_pm : v_cur), v2 = dpp_ror2((fr >= 14) ? v_pm : v_cur);
	v_mov_b32_dpp v97, v86 row_ror:2 row_mask:0xf bank_mask:0xf
	v_cndmask_b32_e64 v86, v41, 0, s[8:9]
	v_mov_b32_dpp v88, v89 row_ror:1 row_mask:0xf bank_mask:0xf
	s_nop 0


; __device__ __forceinline__ float dpp_ror1(float v) { return __int_as_float(__builtin_amdgcn_update_dpp(0, __float_as_int(v), 0x121, 0xf, 0xf, false)); }
; __device__ __forceinline__ float dpp_ror2(float v) { return __int_as_float(__builtin_amdgcn_update_dpp(0, __float_as_int(v), 0x122, 0xf, 0xf, false)); }
;   __device__ __forceinline__ void operator()(const AccT& acc, const Unit& u, int wr, int wc, int fr, int fq) const {
;     ...
;             const float g_cur = xg[m][r], v_cur = xv[m][r];
;             const f32x4 xgp = xg[m > 0 ? m - 1 : 0], xvp = xv[m > 0 ? m - 1 : 0];
;             const float g_pm = (m > 0) ? xgp[r] : 0.f, v_pm = (m > 0) ? xvp[r] : 0.f;
;             const float g1 = dpp_ror1((fr == 15) ? g_pm : g_cur), g2 = dpp_ror2((fr >= 14) ? g_pm : g_cur);
;             const float v1 = dpp_ror1((fr == 15) ? v_pm : v_cur), v2 = dpp_ror2((fr >= 14) ? v_pm : v_cur);
	v_mov_b32_dpp v89, v86 row_ror:1 row_mask:0xf bank_mask:0xf
	v_mov_b32_dpp v93, v84 row_ror:2 row_mask:0xf bank_mask:0xf
	v_cndmask_b32_e64 v84, v46, 0, s[8:9]
	s_nop 0

; __device__ __forceinline__ float dpp_ror1(float v) { return __int_as_float(__builtin_amdgcn_update_dpp(0, __float_as_int(v), 0x121, 0xf, 0xf, false)); }
; __device__ __forceinline__ float dpp_ror2(float v) { return __int_as_float(__builtin_amdgcn_update_dpp(0, __float_as_int(v), 0x122, 0xf, 0xf, false)); }
;   __device__ __forceinline__ void operator()(const AccT& acc, const Unit& u, int wr, int wc, int fr, int fq) const {
;     ...
;             const float g_cur = xg[m][r], v_cur = xv[m][r];
;             const f32x4 xgp = xg[m > 0 ? m - 1 : 0], xvp = xv[m > 0 ? m - 1 : 0];
;             const float g_pm = (m > 0) ? xgp[r] : 0.f, v_pm = (m > 0) ? xvp[r] : 0.f;
;             const float g1 = dpp_ror1((fr == 15) ? g_pm : g_cur), g2 = dpp_ror2((fr >= 14) ? g_pm : g_cur);
;             const float v1 = dpp_ror1((fr == 15) ? v_pm : v_cur), v2 = dpp_ror2((fr >= 14) ? v_pm : v_cur);
	v_mov_b32_dpp v90, v82 row_ror:2 row_mask:0xf bank_mask:0xf
	v_mov_b32_dpp v86, v84 row_ror:1 row_mask:0xf bank_mask:0xf
	v_cndmask_b32_e64 v84, v42, 0, s[8:9]

; __device__ __forceinline__ float dpp_ror1(float v) { return __int_as_float(__builtin_amdgcn_update_dpp(0, __float_as_int(v), 0x121, 0xf, 0xf, false)); }
; __device__ __forceinline__ float dpp_ror2(float v) { return __int_as_float(__builtin_amdgcn_update_dpp(0, __float_as_int(v), 0x122, 0xf, 0xf, false)); }
;   __device__ __forceinline__ void operator()(const AccT& acc, const Unit& u, int wr, int wc, int fr, int fq) const {
;     ...
;             const float g_cur = xg[m][r], v_cur = xv[m][r];
;             const f32x4 xgp = xg[m > 0 ? m - 1 : 0], xvp = xv[m > 0 ? m - 1 : 0];
;             const float g_pm = (m > 0) ? xgp[r] : 0.f, v_pm = (m > 0) ? xvp[r] : 0.f;
;             const float g1 = dpp_ror1((fr == 15) ? g_pm : g_cur), g2 = dpp_ror2((fr >= 14) ? g_pm : g_cur);
;             const float v1 = dpp_ror1((fr == 15) ? v_pm : v_cur), v2 = dpp_ror2((fr >= 14) ? v_pm : v_cur);
	v_mov_b32_dpp v92, v87 row_ror:2 row_mask:0xf bank_mask:0xf
	v_cndmask_b32_e64 v87, v45, 0, s[8:9]
	s_nop 0
	v_mov_b32_dpp v82, v84 row_ror:1 row_mask:0xf bank_mask:0xf

; __device__ __forceinline__ float dpp_ror1(float v) { return __int_as_float(__builtin_amdgcn_update_dpp(0, __float_as_int(v), 0x121, 0xf, 0xf, false)); }
; __device__ __forceinline__ float dpp_ror2(float v) { return __int_as_float(__builtin_amdgcn_update_dpp(0, __float_as_int(v), 0x122, 0xf, 0xf, false)); }
;   __device__ __forceinline__ void operator()(const AccT& acc, const Unit& u, int wr, int wc, int fr, int fq) const {
;     ...
;             const float g_cur = xg[m][r], v_cur = xv[m][r];
;             const f32x4 xgp = xg[m > 0 ? m - 1 : 0], xvp = xv[m > 0 ? m - 1 : 0];
;             const float g_pm = (m > 0) ? xgp[r] : 0.f, v_pm = (m > 0) ? xvp[r] : 0.f;
;             const float g1 = dpp_ror1((fr == 15) ? g_pm : g_cur), g2 = dpp_ror2((fr >= 14) ? g_pm : g_cur);
;             const float v1 = dpp_ror1((fr == 15) ? v_pm : v_cur), v2 = dpp_ror2((fr >= 14) ? v_pm : v_cur);
	v_mov_b32_dpp v95, v87 row_ror:1 row_mask:0xf bank_mask:0xf

; __device__ __forceinline__ float dpp_ror1(float v) { return __int_as_float(__builtin_amdgcn_update_dpp(0, __float_as_int(v), 0x121, 0xf, 0xf, false)); }
; __device__ __forceinline__ float dpp_ror2(float v) { return __int_as_float(__builtin_amdgcn_update_dpp(0, __float_as_int(v), 0x122, 0xf, 0xf, false)); }
;   __device__ __forceinline__ void operator()(const AccT& acc, const Unit& u, int wr, int wc, int fr, int fq) const {
;     ...
;             const float g_cur = xg[m][r], v_cur = xv[m][r];
;             const f32x4 xgp = xg[m > 0 ? m - 1 : 0], xvp = xv[m > 0 ? m - 1 : 0];
;             const float g_pm = (m > 0) ? xgp[r] : 0.f, v_pm = (m > 0) ? xvp[r] : 0.f;
;             const float g1 = dpp_ror1((fr == 15) ? g_pm : g_cur), g2 = dpp_ror2((fr >= 14) ? g_pm : g_cur);
;             const float v1 = dpp_ror1((fr == 15) ? v_pm : v_cur), v2 = dpp_ror2((fr >= 14) ? v_pm : v_cur);
	v_mov_b32_dpp v84, v85 row_ror:2 row_mask:0xf bank_mask:0xf
	v_cndmask_b32_e64 v85, v47, 0, s[8:9]
	s_nop 0
	s_nop 0
	v_mov_b32_dpp v87, v85 row_ror:1 row_mask:0xf bank_mask:0xf
	v_mov_b32_dpp v91, v83 row_ror:2 row_mask:0xf bank_mask:0xf
	v_cndmask_b32_e64 v85, v43, 0, s[8:9]

; __device__ __forceinline__ float dpp_ror1(float v) { return __int_as_float(__builtin_amdgcn_update_dpp(0, __float_as_int(v), 0x121, 0xf, 0xf, false)); }
; __device__ __forceinline__ float dpp_ror2(float v) { return __int_as_float(__builtin_amdgcn_update_dpp(0, __float_as_int(v), 0x122, 0xf, 0xf, false)); }
;   __device__ __forceinline__ void operator()(const AccT& acc, const Unit& u, int wr, int wc, int fr, int fq) const {
;     ...
;             const float g_cur = xg[m][r], v_cur = xv[m][r];
;             const f32x4 xgp = xg[m > 0 ? m - 1 : 0], xvp = xv[m > 0 ? m - 1 : 0];
;             const float g_pm = (m > 0) ? xgp[r] : 0.f, v_pm = (m > 0) ? xvp[r] : 0.f;
;             const float g1 = dpp_ror1((fr == 15) ? g_pm : g_cur), g2 = dpp_ror2((fr >= 14) ? g_pm : g_cur);
;             const float v1 = dpp_ror1((fr == 15) ? v_pm : v_cur), v2 = dpp_ror2((fr >= 14) ? v_pm : v_cur);
	s_nop 1
	v_mov_b32_dpp v83, v85 row_ror:1 row_mask:0xf bank_mask:0xf

; __device__ __forceinline__ uint2 pack4(f32x4 v) { return make_uint2(pack2(v[0], v[1]), pack2(v[2], v[3])); }
;   __device__ __forceinline__ void operator()(const AccT& acc, const Unit& u, int wr, int wc, int fr, int fq) const {
;     ...
;             const float cg_ = bg[r] + g2 * wg0[r] + g1 * wg1[r] + g_cur * wg2[r];
;             const float cv_ = bv[r] + v2 * wv0[r] + v1 * wv1[r] + v_cur * wv2[r];
;             res[r] = cg_ * __builtin_amdgcn_rcpf(1.f + __builtin_amdgcn_exp2f(-1.4426950408889634f * cg_)) * cv_;
;           }
;           if (m > 0 || fr >= 2)
;             *(uint2*)(act + (size_t)EPI_ROW(u, ai, m) * DFF + f0) = pack4(res);
	s_nop 1
	v_mov_b32_dpp v85, v98 row_ror:2 row_mask:0xf bank_mask:0xf
	s_and_saveexec_b64 s[34:35], s[4:5]
	s_xor_b64 s[38:39], exec, s[34:35]
	s_andn2_saveexec_b64 s[38:39], s[38:39]
	s_cbranch_execz .LBB0_477
	s_waitcnt vmcnt(0)
	v_pk_fma_f32 v[90:91], v[66:67], v[90:91], v[78:79]
	v_pk_fma_f32 v[96:97], v[64:65], v[96:97], v[76:77]
	v_pk_fma_f32 v[86:87], v[70:71], v[86:87], v[90:91]
	v_pk_fma_f32 v[94:95], v[68:69], v[94:95], v[96:97]
	v_pk_fma_f32 v[86:87], v[46:47], v[62:63], v[86:87]
	v_pk_fma_f32 v[94:95], v[44:45], v[60:61], v[94:95]
	v_mul_f32_e32 v90, 0xbfb8aa3b, v86
	v_mul_f32_e32 v91, 0xbfb8aa3b, v87
	v_exp_f32_e32 v90, v90
	v_exp_f32_e32 v91, v91
	v_mul_f32_e32 v96, 0xbfb8aa3b, v94
	v_mul_f32_e32 v97, 0xbfb8aa3b, v95
	v_exp_f32_e32 v96, v96
	v_exp_f32_e32 v97, v97
	v_add_f32_e32 v90, 1.0, v90
	v_add_f32_e32 v91, 1.0, v91
	v_rcp_f32_e32 v90, v90
	v_rcp_f32_e32 v91, v91
	v_add_f32_e32 v96, 1.0, v96
	v_add_f32_e32 v97, 1.0, v97
	v_rcp_f32_e32 v96, v96
	v_rcp_f32_e32 v97, v97
	v_pk_fma_f32 v[84:85], v[54:55], v[84:85], v[74:75]
	v_pk_fma_f32 v[92:93], v[52:53], v[92:93], v[72:73]
	v_pk_fma_f32 v[82:83], v[58:59], v[82:83], v[84:85]
	v_pk_mul_f32 v[84:85], v[86:87], v[90:91]
	v_pk_fma_f32 v[82:83], v[42:43], v[50:51], v[82:83]
	v_pk_fma_f32 v[88:89], v[56:57], v[88:89], v[92:93]
	v_pk_mul_f32 v[82:83], v[82:83], v[84:85]
	v_pk_fma_f32 v[88:89], v[40:41], v[48:49], v[88:89]
	v_pk_mul_f32 v[92:93], v[94:95], v[96:97]
	v_cvt_pk_bf16_f32 v85, v82, v83
	v_mov_b64_e32 v[82:83], s[52:53]
	v_pk_mul_f32 v[88:89], v[88:89], v[92:93]
	v_mad_i64_i32 v[82:83], s[34:35], v112, s0, v[82:83]
	v_cvt_pk_bf16_f32 v84, v88, v89
	v_lshl_add_u64 v[82:83], v[188:189], 1, v[82:83]
	global_store_dwordx2 v[82:83], v[84:85], off offset:32
	s_branch .LBB0_477

; __device__ __forceinline__ float dpp_ror1(float v) { return __int_as_float(__builtin_amdgcn_update_dpp(0, __float_as_int(v), 0x121, 0xf, 0xf, false)); }
; __device__ __forceinline__ float dpp_ror2(float v) { return __int_as_float(__builtin_amdgcn_update_dpp(0, __float_as_int(v), 0x122, 0xf, 0xf, false)); }
;   __device__ __forceinline__ void operator()(const AccT& acc, const Unit& u, int wr, int wc, int fr, int fq) const {
;     ...
;         for (int m = 0; m < 4; ++m) { xg[m] = acc[ai][0][m][n] * rs[m]; xv[m] = acc[ai][1][m][n] * rs[m]; }
;         if (fr < 2) {
;           float* d = ub + ((size_t)(chunk * 4 + fr) * NUP + gc);
;           *(float4*)d = make_float4(xg[0][0], xg[0][1], xg[0][2], xg[0][3]);
;           *(float4*)(d + 128) = make_float4(xv[0][0], xv[0][1], xv[0][2], xv[0][3]);
;         }
;         if (fr >= 14) {
;           float* d = ub + ((size_t)(chunk * 4 + 2 + (fr - 14)) * NUP + gc);
;           *(float4*)d = make_float4(xg[3][0], xg[3][1], xg[3][2], xg[3][3]);
;           *(float4*)(d + 128) = make_float4(xv[3][0], xv[3][1], xv[3][2], xv[3][3]);
;         }
; #pragma unroll
;         for (int m = 0; m < 4; ++m) {
;           f32x4 res;
; #pragma unroll
;           for (int r = 0; r < 4; ++r) {
;             const float g_cur = xg[m][r], v_cur = xv[m][r];
;             const f32x4 xgp = xg[m > 0 ? m - 1 : 0], xvp = xv[m > 0 ? m - 1 : 0];
;             const float g_pm = (m > 0) ? xgp[r] : 0.f, v_pm = (m > 0) ? xvp[r] : 0.f;
;             const float g1 = dpp_ror1((fr == 15) ? g_pm : g_cur), g2 = dpp_ror2((fr >= 14) ? g_pm : g_cur);
.LBB0_1497:
	s_or_b64 exec, exec, s[12:13]
	v_mov_b32_e32 v125, v124
	v_mov_b32_e32 v127, v126
	v_mov_b32_e32 v84, v126
	v_mov_b32_e32 v85, v126
	v_pk_mul_f32 v[82:83], v[20:21], v[126:127]
	v_pk_mul_f32 v[20:21], v[30:31], v[84:85]
	v_mov_b32_e32 v30, v124
	v_mov_b32_e32 v31, v124
	v_pk_mul_f32 v[24:25], v[24:25], v[124:125]
	v_pk_mul_f32 v[18:19], v[18:19], v[30:31]
	v_pk_mul_f32 v[26:27], v[26:27], v[30:31]
	v_cndmask_b32_e64 v31, v24, v44, s[8:9]

; __device__ __forceinline__ float dpp_ror1(float v) { return __int_as_float(__builtin_amdgcn_update_dpp(0, __float_as_int(v), 0x121, 0xf, 0xf, false)); }
; __device__ __forceinline__ float dpp_ror2(float v) { return __int_as_float(__builtin_amdgcn_update_dpp(0, __float_as_int(v), 0x122, 0xf, 0xf, false)); }
;   __device__ __forceinline__ void operator()(const AccT& acc, const Unit& u, int wr, int wc, int fr, int fq) const {
;     ...
;         for (int m = 0; m < 4; ++m) { xg[m] = acc[ai][0][m][n] * rs[m]; xv[m] = acc[ai][1][m][n] * rs[m]; }
;         if (fr < 2) {
;           float* d = ub + ((size_t)(chunk * 4 + fr) * NUP + gc);
;           *(float4*)d = make_float4(xg[0][0], xg[0][1], xg[0][2], xg[0][3]);
;           *(float4*)(d + 128) = make_float4(xv[0][0], xv[0][1], xv[0][2], xv[0][3]);
;         }
;         if (fr >= 14) {
;           float* d = ub + ((size_t)(chunk * 4 + 2 + (fr - 14)) * NUP + gc);
;           *(float4*)d = make_float4(xg[3][0], xg[3][1], xg[3][2], xg[3][3]);
;           *(float4*)(d + 128) = make_float4(xv[3][0], xv[3][1], xv[3][2], xv[3][3]);
;         }
; #pragma unroll
;         for (int m = 0; m < 4; ++m) {
;           f32x4 res;
; #pragma unroll
;           for (int r = 0; r < 4; ++r) {
;             const float g_cur = xg[m][r], v_cur = xv[m][r];
;             const f32x4 xgp = xg[m > 0 ? m - 1 : 0], xvp = xv[m > 0 ? m - 1 : 0];
;             const float g_pm = (m > 0) ? xgp[r] : 0.f, v_pm = (m > 0) ? xvp[r] : 0.f;
;             const float g1 = dpp_ror1((fr == 15) ? g_pm : g_cur), g2 = dpp_ror2((fr >= 14) ? g_pm : g_cur);
;             const float v1 = dpp_ror1((fr == 15) ? v_pm : v_cur), v2 = dpp_ror2((fr >= 14) ? v_pm : v_cur);
	v_pk_mul_f32 v[16:17], v[16:17], v[124:125]
	v_pk_mul_f32 v[22:23], v[22:23], v[84:85]
	v_mov_b32_dpp v30, v31 row_ror:1 row_mask:0xf bank_mask:0xf
	v_cndmask_b32_e64 v31, v24, v44, s[6:7]
	s_nop 0

; __device__ __forceinline__ float dpp_ror1(float v) { return __int_as_float(__builtin_amdgcn_update_dpp(0, __float_as_int(v), 0x121, 0xf, 0xf, false)); }
; __device__ __forceinline__ float dpp_ror2(float v) { return __int_as_float(__builtin_amdgcn_update_dpp(0, __float_as_int(v), 0x122, 0xf, 0xf, false)); }
;   __device__ __forceinline__ void operator()(const AccT& acc, const Unit& u, int wr, int wc, int fr, int fq) const {
;     ...
;             const float g_cur = xg[m][r], v_cur = xv[m][r];
;             const f32x4 xgp = xg[m > 0 ? m - 1 : 0], xvp = xv[m > 0 ? m - 1 : 0];
;             const float g_pm = (m > 0) ? xgp[r] : 0.f, v_pm = (m > 0) ? xvp[r] : 0.f;
;             const float g1 = dpp_ror1((fr == 15) ? g_pm : g_cur), g2 = dpp_ror2((fr >= 14) ? g_pm : g_cur);
;             const float v1 = dpp_ror1((fr == 15) ? v_pm : v_cur), v2 = dpp_ror2((fr >= 14) ? v_pm : v_cur);
	v_cndmask_b32_e64 v85, v25, v45, s[8:9]
	v_mov_b32_dpp v44, v31 row_ror:2 row_mask:0xf bank_mask:0xf
	v_cndmask_b32_e64 v31, v16, v40, s[8:9]
	v_cndmask_b32_e64 v86, v17, v41, s[8:9]
	v_cndmask_b32_e64 v87, v26, v46, s[8:9]
	v_mov_b32_dpp v84, v31 row_ror:1 row_mask:0xf bank_mask:0xf
	v_cndmask_b32_e64 v31, v16, v40, s[6:7]

; __device__ __forceinline__ float dpp_ror1(float v) { return __int_as_float(__builtin_amdgcn_update_dpp(0, __float_as_int(v), 0x121, 0xf, 0xf, false)); }
; __device__ __forceinline__ float dpp_ror2(float v) { return __int_as_float(__builtin_amdgcn_update_dpp(0, __float_as_int(v), 0x122, 0xf, 0xf, false)); }
;   __device__ __forceinline__ void operator()(const AccT& acc, const Unit& u, int wr, int wc, int fr, int fq) const {
;     ...
;             const float g_cur = xg[m][r], v_cur = xv[m][r];
;             const f32x4 xgp = xg[m > 0 ? m - 1 : 0], xvp = xv[m > 0 ? m - 1 : 0];
;             const float g_pm = (m > 0) ? xgp[r] : 0.f, v_pm = (m > 0) ? xvp[r] : 0.f;
;             const float g1 = dpp_ror1((fr == 15) ? g_pm : g_cur), g2 = dpp_ror2((fr >= 14) ? g_pm : g_cur);
;             const float v1 = dpp_ror1((fr == 15) ? v_pm : v_cur), v2 = dpp_ror2((fr >= 14) ? v_pm : v_cur);
	v_mov_b32_e32 v88, 0
	v_cndmask_b32_e64 v89, v27, v47, s[8:9]
	v_mov_b32_dpp v40, v31 row_ror:2 row_mask:0xf bank_mask:0xf

; __device__ __forceinline__ float dpp_ror1(float v) { return __int_as_float(__builtin_amdgcn_update_dpp(0, __float_as_int(v), 0x121, 0xf, 0xf, false)); }
; __device__ __forceinline__ float dpp_ror2(float v) { return __int_as_float(__builtin_amdgcn_update_dpp(0, __float_as_int(v), 0x122, 0xf, 0xf, false)); }
;   __device__ __forceinline__ void operator()(const AccT& acc, const Unit& u, int wr, int wc, int fr, int fq) const {
;     ...
;             const float g_cur = xg[m][r], v_cur = xv[m][r];
;             const f32x4 xgp = xg[m > 0 ? m - 1 : 0], xvp = xv[m > 0 ? m - 1 : 0];
;             const float g_pm = (m > 0) ? xgp[r] : 0.f, v_pm = (m > 0) ? xvp[r] : 0.f;
;             const float g1 = dpp_ror1((fr == 15) ? g_pm : g_cur), g2 = dpp_ror2((fr >= 14) ? g_pm : g_cur);
;             const float v1 = dpp_ror1((fr == 15) ? v_pm : v_cur), v2 = dpp_ror2((fr >= 14) ? v_pm : v_cur);
;             const float cg_ = bg[r] + g2 * wg0[r] + g1 * wg1[r] + g_cur * wg2[r];
;             const float cv_ = bv[r] + v2 * wv0[r] + v1 * wv1[r] + v_cur * wv2[r];
	v_cndmask_b32_e64 v90, v19, v43, s[8:9]
	v_pk_mul_f32 v[28:29], v[28:29], v[126:127]
	v_mov_b32_dpp v31, v85 row_ror:1 row_mask:0xf bank_mask:0xf
	v_cndmask_b32_e64 v85, v25, v45, s[6:7]
	v_mov_b32_e32 v45, 0
	s_and_b64 vcc, exec, s[10:11]
	s_mov_b32 s44, s36
	v_mov_b32_dpp v45, v85 row_ror:2 row_mask:0xf bank_mask:0xf
	s_waitcnt vmcnt(0)
	v_pk_fma_f32 v[44:45], v[68:69], v[44:45], v[76:77]

; __device__ __forceinline__ float dpp_ror1(float v) { return __int_as_float(__builtin_amdgcn_update_dpp(0, __float_as_int(v), 0x121, 0xf, 0xf, false)); }
; __device__ __forceinline__ float dpp_ror2(float v) { return __int_as_float(__builtin_amdgcn_update_dpp(0, __float_as_int(v), 0x122, 0xf, 0xf, false)); }
;   __device__ __forceinline__ void operator()(const AccT& acc, const Unit& u, int wr, int wc, int fr, int fq) const {
;     ...
;             const float g_cur = xg[m][r], v_cur = xv[m][r];
;             const f32x4 xgp = xg[m > 0 ? m - 1 : 0], xvp = xv[m > 0 ? m - 1 : 0];
;             const float g_pm = (m > 0) ? xgp[r] : 0.f, v_pm = (m > 0) ? xvp[r] : 0.f;
;             const float g1 = dpp_ror1((fr == 15) ? g_pm : g_cur), g2 = dpp_ror2((fr >= 14) ? g_pm : g_cur);
;             const float v1 = dpp_ror1((fr == 15) ? v_pm : v_cur), v2 = dpp_ror2((fr >= 14) ? v_pm : v_cur);
;             const float cg_ = bg[r] + g2 * wg0[r] + g1 * wg1[r] + g_cur * wg2[r];
;             const float cv_ = bv[r] + v2 * wv0[r] + v1 * wv1[r] + v_cur * wv2[r];
;             res[r] = cg_ * __builtin_amdgcn_rcpf(1.f + __builtin_amdgcn_exp2f(-1.4426950408889634f * cg_)) * cv_;
	v_pk_fma_f32 v[30:31], v[72:73], v[30:31], v[44:45]
	s_mov_b32 s12, s38
	v_pk_fma_f32 v[30:31], v[24:25], v[64:65], v[30:31]
	v_mov_b32_dpp v85, v86 row_ror:1 row_mask:0xf bank_mask:0xf
	v_mul_f32_e32 v44, 0xbfb8aa3b, v30
	v_mul_f32_e32 v45, 0xbfb8aa3b, v31
	v_exp_f32_e32 v44, v44
	v_exp_f32_e32 v45, v45
	v_cndmask_b32_e64 v86, v17, v41, s[6:7]

; __device__ __forceinline__ float dpp_ror1(float v) { return __int_as_float(__builtin_amdgcn_update_dpp(0, __float_as_int(v), 0x121, 0xf, 0xf, false)); }
; __device__ __forceinline__ float dpp_ror2(float v) { return __int_as_float(__builtin_amdgcn_update_dpp(0, __float_as_int(v), 0x122, 0xf, 0xf, false)); }
;   __device__ __forceinline__ void operator()(const AccT& acc, const Unit& u, int wr, int wc, int fr, int fq) const {
;     ...
;             const float g1 = dpp_ror1((fr == 15) ? g_pm : g_cur), g2 = dpp_ror2((fr >= 14) ? g_pm : g_cur);
;             const float v1 = dpp_ror1((fr == 15) ? v_pm : v_cur), v2 = dpp_ror2((fr >= 14) ? v_pm : v_cur);
;             const float cg_ = bg[r] + g2 * wg0[r] + g1 * wg1[r] + g_cur * wg2[r];
;             const float cv_ = bv[r] + v2 * wv0[r] + v1 * wv1[r] + v_cur * wv2[r];
;             res[r] = cg_ * __builtin_amdgcn_rcpf(1.f + __builtin_amdgcn_exp2f(-1.4426950408889634f * cg_)) * cv_;
	v_add_f32_e32 v44, 1.0, v44
	v_add_f32_e32 v45, 1.0, v45
	v_mov_b32_dpp v41, v86 row_ror:2 row_mask:0xf bank_mask:0xf

; __device__ __forceinline__ float dpp_ror1(float v) { return __int_as_float(__builtin_amdgcn_update_dpp(0, __float_as_int(v), 0x121, 0xf, 0xf, false)); }
; __device__ __forceinline__ float dpp_ror2(float v) { return __int_as_float(__builtin_amdgcn_update_dpp(0, __float_as_int(v), 0x122, 0xf, 0xf, false)); }
;   __device__ __forceinline__ void operator()(const AccT& acc, const Unit& u, int wr, int wc, int fr, int fq) const {
;     ...
;             const f32x4 xgp = xg[m > 0 ? m - 1 : 0], xvp = xv[m > 0 ? m - 1 : 0];
;             const float g_pm = (m > 0) ? xgp[r] : 0.f, v_pm = (m > 0) ? xvp[r] : 0.f;
;             const float g1 = dpp_ror1((fr == 15) ? g_pm : g_cur), g2 = dpp_ror2((fr >= 14) ? g_pm : g_cur);
;             const float v1 = dpp_ror1((fr == 15) ? v_pm : v_cur), v2 = dpp_ror2((fr >= 14) ? v_pm : v_cur);
;             const float cg_ = bg[r] + g2 * wg0[r] + g1 * wg1[r] + g_cur * wg2[r];
;             const float cv_ = bv[r] + v2 * wv0[r] + v1 * wv1[r] + v_cur * wv2[r];
;             res[r] = cg_ * __builtin_amdgcn_rcpf(1.f + __builtin_amdgcn_exp2f(-1.4426950408889634f * cg_)) * cv_;
	v_rcp_f32_e32 v44, v44
	v_rcp_f32_e32 v45, v45
	v_mov_b32_dpp v86, v87 row_ror:1 row_mask:0xf bank_mask:0xf
	v_cndmask_b32_e64 v87, v26, v46, s[6:7]

; __device__ __forceinline__ float dpp_ror1(float v) { return __int_as_float(__builtin_amdgcn_update_dpp(0, __float_as_int(v), 0x121, 0xf, 0xf, false)); }
; __device__ __forceinline__ float dpp_ror2(float v) { return __int_as_float(__builtin_amdgcn_update_dpp(0, __float_as_int(v), 0x122, 0xf, 0xf, false)); }
;   __device__ __forceinline__ void operator()(const AccT& acc, const Unit& u, int wr, int wc, int fr, int fq) const {
;     ...
;             const float g1 = dpp_ror1((fr == 15) ? g_pm : g_cur), g2 = dpp_ror2((fr >= 14) ? g_pm : g_cur);
;             const float v1 = dpp_ror1((fr == 15) ? v_pm : v_cur), v2 = dpp_ror2((fr >= 14) ? v_pm : v_cur);
;             const float cg_ = bg[r] + g2 * wg0[r] + g1 * wg1[r] + g_cur * wg2[r];
;             const float cv_ = bv[r] + v2 * wv0[r] + v1 * wv1[r] + v_cur * wv2[r];
;             res[r] = cg_ * __builtin_amdgcn_rcpf(1.f + __builtin_amdgcn_exp2f(-1.4426950408889634f * cg_)) * cv_;
	v_pk_mul_f32 v[30:31], v[30:31], v[44:45]
	v_pk_fma_f32 v[40:41], v[52:53], v[40:41], v[60:61]
	v_mov_b32_dpp v46, v87 row_ror:2 row_mask:0xf bank_mask:0xf
	v_cndmask_b32_e64 v87, v18, v42, s[8:9]
	v_pk_fma_f32 v[40:41], v[56:57], v[84:85], v[40:41]
	s_mov_b64 s[48:49], s[42:43]
	v_mov_b32_dpp v88, v87 row_ror:1 row_mask:0xf bank_mask:0xf
	v_cndmask_b32_e64 v87, v18, v42, s[6:7]

; __device__ __forceinline__ float dpp_ror1(float v) { return __int_as_float(__builtin_amdgcn_update_dpp(0, __float_as_int(v), 0x121, 0xf, 0xf, false)); }
; __device__ __forceinline__ float dpp_ror2(float v) { return __int_as_float(__builtin_amdgcn_update_dpp(0, __float_as_int(v), 0x122, 0xf, 0xf, false)); }
;   __device__ __forceinline__ void operator()(const AccT& acc, const Unit& u, int wr, int wc, int fr, int fq) const {
;     ...
;             const float g1 = dpp_ror1((fr == 15) ? g_pm : g_cur), g2 = dpp_ror2((fr >= 14) ? g_pm : g_cur);
;             const float v1 = dpp_ror1((fr == 15) ? v_pm : v_cur), v2 = dpp_ror2((fr >= 14) ? v_pm : v_cur);
;             const float cg_ = bg[r] + g2 * wg0[r] + g1 * wg1[r] + g_cur * wg2[r];
;             const float cv_ = bv[r] + v2 * wv0[r] + v1 * wv1[r] + v_cur * wv2[r];
	v_pk_fma_f32 v[40:41], v[16:17], v[48:49], v[40:41]
	s_mov_b64 s[46:47], s[40:41]
	v_mov_b32_dpp v42, v87 row_ror:2 row_mask:0xf bank_mask:0xf

; __device__ __forceinline__ float dpp_ror1(float v) { return __int_as_float(__builtin_amdgcn_update_dpp(0, __float_as_int(v), 0x121, 0xf, 0xf, false)); }
; __device__ __forceinline__ float dpp_ror2(float v) { return __int_as_float(__builtin_amdgcn_update_dpp(0, __float_as_int(v), 0x122, 0xf, 0xf, false)); }
;   __device__ __forceinline__ void operator()(const AccT& acc, const Unit& u, int wr, int wc, int fr, int fq) const {
;     ...
;             const float g1 = dpp_ror1((fr == 15) ? g_pm : g_cur), g2 = dpp_ror2((fr >= 14) ? g_pm : g_cur);
;             const float v1 = dpp_ror1((fr == 15) ? v_pm : v_cur), v2 = dpp_ror2((fr >= 14) ? v_pm : v_cur);
;             const float cg_ = bg[r] + g2 * wg0[r] + g1 * wg1[r] + g_cur * wg2[r];
;             const float cv_ = bv[r] + v2 * wv0[r] + v1 * wv1[r] + v_cur * wv2[r];
;             res[r] = cg_ * __builtin_amdgcn_rcpf(1.f + __builtin_amdgcn_exp2f(-1.4426950408889634f * cg_)) * cv_;
	v_pk_mul_f32 v[30:31], v[40:41], v[30:31]
	s_nop 0
	v_mov_b32_dpp v87, v89 row_ror:1 row_mask:0xf bank_mask:0xf
	v_cndmask_b32_e64 v89, v27, v47, s[6:7]

; __device__ __forceinline__ uint2 pack4(f32x4 v) { return make_uint2(pack2(v[0], v[1]), pack2(v[2], v[3])); }
; __device__ __forceinline__ float dpp_ror1(float v) { return __int_as_float(__builtin_amdgcn_update_dpp(0, __float_as_int(v), 0x121, 0xf, 0xf, false)); }
; __device__ __forceinline__ float dpp_ror2(float v) { return __int_as_float(__builtin_amdgcn_update_dpp(0, __float_as_int(v), 0x122, 0xf, 0xf, false)); }
;   __device__ __forceinline__ void operator()(const AccT& acc, const Unit& u, int wr, int wc, int fr, int fq) const {
;     ...
;             const float g1 = dpp_ror1((fr == 15) ? g_pm : g_cur), g2 = dpp_ror2((fr >= 14) ? g_pm : g_cur);
;             const float v1 = dpp_ror1((fr == 15) ? v_pm : v_cur), v2 = dpp_ror2((fr >= 14) ? v_pm : v_cur);
;             const float cg_ = bg[r] + g2 * wg0[r] + g1 * wg1[r] + g_cur * wg2[r];
;             const float cv_ = bv[r] + v2 * wv0[r] + v1 * wv1[r] + v_cur * wv2[r];
;             res[r] = cg_ * __builtin_amdgcn_rcpf(1.f + __builtin_amdgcn_exp2f(-1.4426950408889634f * cg_)) * cv_;
;           }
;           if (m > 0 || fr >= 2)
;             *(uint2*)(act + (size_t)EPI_ROW(u, ai, m) * DFF + f0) = pack4(res);
	v_cvt_pk_bf16_f32 v30, v30, v31
	s_nop 0
	v_mov_b32_dpp v47, v89 row_ror:2 row_mask:0xf bank_mask:0xf
	v_pk_fma_f32 v[44:45], v[70:71], v[46:47], v[78:79]

; __device__ __forceinline__ float dpp_ror1(float v) { return __int_as_float(__builtin_amdgcn_update_dpp(0, __float_as_int(v), 0x121, 0xf, 0xf, false)); }
; __device__ __forceinline__ float dpp_ror2(float v) { return __int_as_float(__builtin_amdgcn_update_dpp(0, __float_as_int(v), 0x122, 0xf, 0xf, false)); }
;   __device__ __forceinline__ void operator()(const AccT& acc, const Unit& u, int wr, int wc, int fr, int fq) const {
;     ...
;             const float g1 = dpp_ror1((fr == 15) ? g_pm : g_cur), g2 = dpp_ror2((fr >= 14) ? g_pm : g_cur);
;             const float v1 = dpp_ror1((fr == 15) ? v_pm : v_cur), v2 = dpp_ror2((fr >= 14) ? v_pm : v_cur);
;             const float cg_ = bg[r] + g2 * wg0[r] + g1 * wg1[r] + g_cur * wg2[r];
;             const float cv_ = bv[r] + v2 * wv0[r] + v1 * wv1[r] + v_cur * wv2[r];
;             res[r] = cg_ * __builtin_amdgcn_rcpf(1.f + __builtin_amdgcn_exp2f(-1.4426950408889634f * cg_)) * cv_;
	v_pk_fma_f32 v[44:45], v[74:75], v[86:87], v[44:45]
	s_nop 0
	v_pk_fma_f32 v[44:45], v[26:27], v[66:67], v[44:45]
	v_mov_b32_dpp v89, v90 row_ror:1 row_mask:0xf bank_mask:0xf
	v_mul_f32_e32 v46, 0xbfb8aa3b, v44
	v_mul_f32_e32 v47, 0xbfb8aa3b, v45
	v_exp_f32_e32 v46, v46
	v_exp_f32_e32 v47, v47
	v_cndmask_b32_e64 v90, v19, v43, s[6:7]

; __device__ __forceinline__ float dpp_ror1(float v) { return __int_as_float(__builtin_amdgcn_update_dpp(0, __float_as_int(v), 0x121, 0xf, 0xf, false)); }
; __device__ __forceinline__ float dpp_ror2(float v) { return __int_as_float(__builtin_amdgcn_update_dpp(0, __float_as_int(v), 0x122, 0xf, 0xf, false)); }
;   __device__ __forceinline__ void operator()(const AccT& acc, const Unit& u, int wr, int wc, int fr, int fq) const {
;     ...
;             const float g1 = dpp_ror1((fr == 15) ? g_pm : g_cur), g2 = dpp_ror2((fr >= 14) ? g_pm : g_cur);
;             const float v1 = dpp_ror1((fr == 15) ? v_pm : v_cur), v2 = dpp_ror2((fr >= 14) ? v_pm : v_cur);
;             const float cg_ = bg[r] + g2 * wg0[r] + g1 * wg1[r] + g_cur * wg2[r];
;             const float cv_ = bv[r] + v2 * wv0[r] + v1 * wv1[r] + v_cur * wv2[r];
;             res[r] = cg_ * __builtin_amdgcn_rcpf(1.f + __builtin_amdgcn_exp2f(-1.4426950408889634f * cg_)) * cv_;
	v_add_f32_e32 v40, 1.0, v46
	v_add_f32_e32 v41, 1.0, v47
	v_rcp_f32_e32 v40, v40
	v_rcp_f32_e32 v41, v41
	v_mov_b32_dpp v43, v90 row_ror:2 row_mask:0xf bank_mask:0xf
	v_pk_fma_f32 v[42:43], v[54:55], v[42:43], v[62:63]
	v_cndmask_b32_e64 v46, v23, v19, s[8:9]
	v_pk_fma_f32 v[42:43], v[58:59], v[88:89], v[42:43]
	v_pk_mul_f32 v[40:41], v[44:45], v[40:41]
	v_pk_fma_f32 v[42:43], v[18:19], v[50:51], v[42:43]

; __device__ __forceinline__ uint2 pack4(f32x4 v) { return make_uint2(pack2(v[0], v[1]), pack2(v[2], v[3])); }
;   __device__ __forceinline__ void operator()(const AccT& acc, const Unit& u, int wr, int wc, int fr, int fq) const {
;     ...
;             const float cg_ = bg[r] + g2 * wg0[r] + g1 * wg1[r] + g_cur * wg2[r];
;             const float cv_ = bv[r] + v2 * wv0[r] + v1 * wv1[r] + v_cur * wv2[r];
;             res[r] = cg_ * __builtin_amdgcn_rcpf(1.f + __builtin_amdgcn_exp2f(-1.4426950408889634f * cg_)) * cv_;
;           }
;           if (m > 0 || fr >= 2)
;             *(uint2*)(act + (size_t)EPI_ROW(u, ai, m) * DFF + f0) = pack4(res);
	v_pk_mul_f32 v[40:41], v[42:43], v[40:41]
	v_cndmask_b32_e64 v42, v83, v17, s[8:9]
	v_cvt_pk_bf16_f32 v31, v40, v41
	global_store_dwordx2 v[128:129], v[30:31], off offset:32
	v_cndmask_b32_e64 v31, v28, v24, s[8:9]
	s_nop 0

; __device__ __forceinline__ float dpp_ror1(float v) { return __int_as_float(__builtin_amdgcn_update_dpp(0, __float_as_int(v), 0x121, 0xf, 0xf, false)); }
; __device__ __forceinline__ float dpp_ror2(float v) { return __int_as_float(__builtin_amdgcn_update_dpp(0, __float_as_int(v), 0x122, 0xf, 0xf, false)); }
;   __device__ __forceinline__ void operator()(const AccT& acc, const Unit& u, int wr, int wc, int fr, int fq) const {
;     ...
;             const float g_cur = xg[m][r], v_cur = xv[m][r];
;             const f32x4 xgp = xg[m > 0 ? m - 1 : 0], xvp = xv[m > 0 ? m - 1 : 0];
;             const float g_pm = (m > 0) ? xgp[r] : 0.f, v_pm = (m > 0) ? xvp[r] : 0.f;
;             const float g1 = dpp_ror1((fr == 15) ? g_pm : g_cur), g2 = dpp_ror2((fr >= 14) ? g_pm : g_cur);
;             const float v1 = dpp_ror1((fr == 15) ? v_pm : v_cur), v2 = dpp_ror2((fr >= 14) ? v_pm : v_cur);
	v_cndmask_b32_e64 v41, v29, v25, s[8:9]
	v_mov_b32_dpp v30, v31 row_ror:1 row_mask:0xf bank_mask:0xf
	v_cndmask_b32_e64 v31, v28, v24, s[6:7]

; __device__ __forceinline__ float dpp_ror1(float v) { return __int_as_float(__builtin_amdgcn_update_dpp(0, __float_as_int(v), 0x121, 0xf, 0xf, false)); }
; __device__ __forceinline__ float dpp_ror2(float v) { return __int_as_float(__builtin_amdgcn_update_dpp(0, __float_as_int(v), 0x122, 0xf, 0xf, false)); }
;   __device__ __forceinline__ void operator()(const AccT& acc, const Unit& u, int wr, int wc, int fr, int fq) const {
;     ...
;             const float g_cur = xg[m][r], v_cur = xv[m][r];
;             const f32x4 xgp = xg[m > 0 ? m - 1 : 0], xvp = xv[m > 0 ? m - 1 : 0];
;             const float g_pm = (m > 0) ? xgp[r] : 0.f, v_pm = (m > 0) ? xvp[r] : 0.f;
;             const float g1 = dpp_ror1((fr == 15) ? g_pm : g_cur), g2 = dpp_ror2((fr >= 14) ? g_pm : g_cur);
;             const float v1 = dpp_ror1((fr == 15) ? v_pm : v_cur), v2 = dpp_ror2((fr >= 14) ? v_pm : v_cur);
	v_cndmask_b32_e64 v43, v20, v26, s[8:9]
	v_cndmask_b32_e64 v45, v21, v27, s[8:9]
	v_mov_b32_dpp v24, v31 row_ror:2 row_mask:0xf bank_mask:0xf
	v_cndmask_b32_e64 v31, v82, v16, s[8:9]
	s_nop 1
	v_mov_b32_dpp v40, v31 row_ror:1 row_mask:0xf bank_mask:0xf
	v_cndmask_b32_e64 v31, v82, v16, s[6:7]

; __device__ __forceinline__ float dpp_ror1(float v) { return __int_as_float(__builtin_amdgcn_update_dpp(0, __float_as_int(v), 0x121, 0xf, 0xf, false)); }
; __device__ __forceinline__ float dpp_ror2(float v) { return __int_as_float(__builtin_amdgcn_update_dpp(0, __float_as_int(v), 0x122, 0xf, 0xf, false)); }
;   __device__ __forceinline__ void operator()(const AccT& acc, const Unit& u, int wr, int wc, int fr, int fq) const {
;     ...
;             const float g1 = dpp_ror1((fr == 15) ? g_pm : g_cur), g2 = dpp_ror2((fr >= 14) ? g_pm : g_cur);
;             const float v1 = dpp_ror1((fr == 15) ? v_pm : v_cur), v2 = dpp_ror2((fr >= 14) ? v_pm : v_cur);
	s_nop 1
	v_mov_b32_dpp v16, v31 row_ror:2 row_mask:0xf bank_mask:0xf

; __device__ __forceinline__ float dpp_ror1(float v) { return __int_as_float(__builtin_amdgcn_update_dpp(0, __float_as_int(v), 0x121, 0xf, 0xf, false)); }
; __device__ __forceinline__ float dpp_ror2(float v) { return __int_as_float(__builtin_amdgcn_update_dpp(0, __float_as_int(v), 0x122, 0xf, 0xf, false)); }
;   __device__ __forceinline__ void operator()(const AccT& acc, const Unit& u, int wr, int wc, int fr, int fq) const {
;     ...
;             const f32x4 xgp = xg[m > 0 ? m - 1 : 0], xvp = xv[m > 0 ? m - 1 : 0];
;             const float g_pm = (m > 0) ? xgp[r] : 0.f, v_pm = (m > 0) ? xvp[r] : 0.f;
;             const float g1 = dpp_ror1((fr == 15) ? g_pm : g_cur), g2 = dpp_ror2((fr >= 14) ? g_pm : g_cur);
;             const float v1 = dpp_ror1((fr == 15) ? v_pm : v_cur), v2 = dpp_ror2((fr >= 14) ? v_pm : v_cur);
	s_nop 1
	v_mov_b32_dpp v31, v41 row_ror:1 row_mask:0xf bank_mask:0xf
	v_cndmask_b32_e64 v41, v29, v25, s[6:7]

; __device__ __forceinline__ float dpp_ror1(float v) { return __int_as_float(__builtin_amdgcn_update_dpp(0, __float_as_int(v), 0x121, 0xf, 0xf, false)); }
; __device__ __forceinline__ float dpp_ror2(float v) { return __int_as_float(__builtin_amdgcn_update_dpp(0, __float_as_int(v), 0x122, 0xf, 0xf, false)); }
;   __device__ __forceinline__ void operator()(const AccT& acc, const Unit& u, int wr, int wc, int fr, int fq) const {
;     ...
;             const float g1 = dpp_ror1((fr == 15) ? g_pm : g_cur), g2 = dpp_ror2((fr >= 14) ? g_pm : g_cur);
;             const float v1 = dpp_ror1((fr == 15) ? v_pm : v_cur), v2 = dpp_ror2((fr >= 14) ? v_pm : v_cur);
;             const float cg_ = bg[r] + g2 * wg0[r] + g1 * wg1[r] + g_cur * wg2[r];
;             const float cv_ = bv[r] + v2 * wv0[r] + v1 * wv1[r] + v_cur * wv2[r];
	s_nop 1
	v_mov_b32_dpp v25, v41 row_ror:2 row_mask:0xf bank_mask:0xf
	v_pk_fma_f32 v[24:25], v[68:69], v[24:25], v[76:77]

; __device__ __forceinline__ float dpp_ror1(float v) { return __int_as_float(__builtin_amdgcn_update_dpp(0, __float_as_int(v), 0x121, 0xf, 0xf, false)); }
; __device__ __forceinline__ float dpp_ror2(float v) { return __int_as_float(__builtin_amdgcn_update_dpp(0, __float_as_int(v), 0x122, 0xf, 0xf, false)); }
;   __device__ __forceinline__ void operator()(const AccT& acc, const Unit& u, int wr, int wc, int fr, int fq) const {
;     ...
;             const f32x4 xgp = xg[m > 0 ? m - 1 : 0], xvp = xv[m > 0 ? m - 1 : 0];
;             const float g_pm = (m > 0) ? xgp[r] : 0.f, v_pm = (m > 0) ? xvp[r] : 0.f;
;             const float g1 = dpp_ror1((fr == 15) ? g_pm : g_cur), g2 = dpp_ror2((fr >= 14) ? g_pm : g_cur);
;             const float v1 = dpp_ror1((fr == 15) ? v_pm : v_cur), v2 = dpp_ror2((fr >= 14) ? v_pm : v_cur);
;             const float cg_ = bg[r] + g2 * wg0[r] + g1 * wg1[r] + g_cur * wg2[r];
	v_pk_fma_f32 v[24:25], v[72:73], v[30:31], v[24:25]
	s_nop 0
	v_mov_b32_dpp v41, v42 row_ror:1 row_mask:0xf bank_mask:0xf
	v_cndmask_b32_e64 v42, v83, v17, s[6:7]

; __device__ __forceinline__ float dpp_ror1(float v) { return __int_as_float(__builtin_amdgcn_update_dpp(0, __float_as_int(v), 0x121, 0xf, 0xf, false)); }
; __device__ __forceinline__ float dpp_ror2(float v) { return __int_as_float(__builtin_amdgcn_update_dpp(0, __float_as_int(v), 0x122, 0xf, 0xf, false)); }
;   __device__ __forceinline__ void operator()(const AccT& acc, const Unit& u, int wr, int wc, int fr, int fq) const {
;     ...
;             const float g1 = dpp_ror1((fr == 15) ? g_pm : g_cur), g2 = dpp_ror2((fr >= 14) ? g_pm : g_cur);
;             const float v1 = dpp_ror1((fr == 15) ? v_pm : v_cur), v2 = dpp_ror2((fr >= 14) ? v_pm : v_cur);
;             const float cg_ = bg[r] + g2 * wg0[r] + g1 * wg1[r] + g_cur * wg2[r];
	v_pk_fma_f32 v[24:25], v[28:29], v[64:65], v[24:25]
	s_nop 0
	v_mov_b32_dpp v17, v42 row_ror:2 row_mask:0xf bank_mask:0xf

; __device__ __forceinline__ float dpp_ror1(float v) { return __int_as_float(__builtin_amdgcn_update_dpp(0, __float_as_int(v), 0x121, 0xf, 0xf, false)); }
; __device__ __forceinline__ float dpp_ror2(float v) { return __int_as_float(__builtin_amdgcn_update_dpp(0, __float_as_int(v), 0x122, 0xf, 0xf, false)); }
;   __device__ __forceinline__ void operator()(const AccT& acc, const Unit& u, int wr, int wc, int fr, int fq) const {
;     ...
;             const float g1 = dpp_ror1((fr == 15) ? g_pm : g_cur), g2 = dpp_ror2((fr >= 14) ? g_pm : g_cur);
;             const float v1 = dpp_ror1((fr == 15) ? v_pm : v_cur), v2 = dpp_ror2((fr >= 14) ? v_pm : v_cur);
;             const float cg_ = bg[r] + g2 * wg0[r] + g1 * wg1[r] + g_cur * wg2[r];
;             const float cv_ = bv[r] + v2 * wv0[r] + v1 * wv1[r] + v_cur * wv2[r];
;             res[r] = cg_ * __builtin_amdgcn_rcpf(1.f + __builtin_amdgcn_exp2f(-1.4426950408889634f * cg_)) * cv_;
	v_mul_f32_e32 v30, 0xbfb8aa3b, v24
	v_mul_f32_e32 v31, 0xbfb8aa3b, v25
	v_mov_b32_dpp v42, v43 row_ror:1 row_mask:0xf bank_mask:0xf
	v_cndmask_b32_e64 v43, v20, v26, s[6:7]

; __device__ __forceinline__ float dpp_ror1(float v) { return __int_as_float(__builtin_amdgcn_update_dpp(0, __float_as_int(v), 0x121, 0xf, 0xf, false)); }
; __device__ __forceinline__ float dpp_ror2(float v) { return __int_as_float(__builtin_amdgcn_update_dpp(0, __float_as_int(v), 0x122, 0xf, 0xf, false)); }
;   __device__ __forceinline__ void operator()(const AccT& acc, const Unit& u, int wr, int wc, int fr, int fq) const {
;     ...
;             const f32x4 xgp = xg[m > 0 ? m - 1 : 0], xvp = xv[m > 0 ? m - 1 : 0];
;             const float g_pm = (m > 0) ? xgp[r] : 0.f, v_pm = (m > 0) ? xvp[r] : 0.f;
;             const float g1 = dpp_ror1((fr == 15) ? g_pm : g_cur), g2 = dpp_ror2((fr >= 14) ? g_pm : g_cur);
;             const float v1 = dpp_ror1((fr == 15) ? v_pm : v_cur), v2 = dpp_ror2((fr >= 14) ? v_pm : v_cur);
;             const float cg_ = bg[r] + g2 * wg0[r] + g1 * wg1[r] + g_cur * wg2[r];
;             const float cv_ = bv[r] + v2 * wv0[r] + v1 * wv1[r] + v_cur * wv2[r];
;             res[r] = cg_ * __builtin_amdgcn_rcpf(1.f + __builtin_amdgcn_exp2f(-1.4426950408889634f * cg_)) * cv_;
	v_exp_f32_e32 v30, v30
	v_exp_f32_e32 v31, v31
	v_mov_b32_dpp v26, v43 row_ror:2 row_mask:0xf bank_mask:0xf
	v_cndmask_b32_e64 v43, v22, v18, s[8:9]
	v_add_f32_e32 v30, 1.0, v30
	v_add_f32_e32 v31, 1.0, v31
	v_mov_b32_dpp v44, v43 row_ror:1 row_mask:0xf bank_mask:0xf
	v_cndmask_b32_e64 v43, v22, v18, s[6:7]

; __device__ __forceinline__ float dpp_ror1(float v) { return __int_as_float(__builtin_amdgcn_update_dpp(0, __float_as_int(v), 0x121, 0xf, 0xf, false)); }
; __device__ __forceinline__ float dpp_ror2(float v) { return __int_as_float(__builtin_amdgcn_update_dpp(0, __float_as_int(v), 0x122, 0xf, 0xf, false)); }
;   __device__ __forceinline__ void operator()(const AccT& acc, const Unit& u, int wr, int wc, int fr, int fq) const {
;     ...
;             const float g1 = dpp_ror1((fr == 15) ? g_pm : g_cur), g2 = dpp_ror2((fr >= 14) ? g_pm : g_cur);
;             const float v1 = dpp_ror1((fr == 15) ? v_pm : v_cur), v2 = dpp_ror2((fr >= 14) ? v_pm : v_cur);
;             const float cg_ = bg[r] + g2 * wg0[r] + g1 * wg1[r] + g_cur * wg2[r];
;             const float cv_ = bv[r] + v2 * wv0[r] + v1 * wv1[r] + v_cur * wv2[r];
;             res[r] = cg_ * __builtin_amdgcn_rcpf(1.f + __builtin_amdgcn_exp2f(-1.4426950408889634f * cg_)) * cv_;
	v_rcp_f32_e32 v30, v30
	v_rcp_f32_e32 v31, v31
	v_mov_b32_dpp v18, v43 row_ror:2 row_mask:0xf bank_mask:0xf

; __device__ __forceinline__ float dpp_ror1(float v) { return __int_as_float(__builtin_amdgcn_update_dpp(0, __float_as_int(v), 0x121, 0xf, 0xf, false)); }
; __device__ __forceinline__ float dpp_ror2(float v) { return __int_as_float(__builtin_amdgcn_update_dpp(0, __float_as_int(v), 0x122, 0xf, 0xf, false)); }
;   __device__ __forceinline__ void operator()(const AccT& acc, const Unit& u, int wr, int wc, int fr, int fq) const {
;     ...
;             const float g1 = dpp_ror1((fr == 15) ? g_pm : g_cur), g2 = dpp_ror2((fr >= 14) ? g_pm : g_cur);
;             const float v1 = dpp_ror1((fr == 15) ? v_pm : v_cur), v2 = dpp_ror2((fr >= 14) ? v_pm : v_cur);
;             const float cg_ = bg[r] + g2 * wg0[r] + g1 * wg1[r] + g_cur * wg2[r];
;             const float cv_ = bv[r] + v2 * wv0[r] + v1 * wv1[r] + v_cur * wv2[r];
	v_pk_fma_f32 v[16:17], v[52:53], v[16:17], v[60:61]
	v_pk_mul_f32 v[24:25], v[24:25], v[30:31]
	v_mov_b32_dpp v43, v45 row_ror:1 row_mask:0xf bank_mask:0xf
	v_cndmask_b32_e64 v45, v21, v27, s[6:7]

; __device__ __forceinline__ float dpp_ror1(float v) { return __int_as_float(__builtin_amdgcn_update_dpp(0, __float_as_int(v), 0x121, 0xf, 0xf, false)); }
; __device__ __forceinline__ float dpp_ror2(float v) { return __int_as_float(__builtin_amdgcn_update_dpp(0, __float_as_int(v), 0x122, 0xf, 0xf, false)); }
;   __device__ __forceinline__ void operator()(const AccT& acc, const Unit& u, int wr, int wc, int fr, int fq) const {
;     ...
;             const float g1 = dpp_ror1((fr == 15) ? g_pm : g_cur), g2 = dpp_ror2((fr >= 14) ? g_pm : g_cur);
;             const float v1 = dpp_ror1((fr == 15) ? v_pm : v_cur), v2 = dpp_ror2((fr >= 14) ? v_pm : v_cur);
;             const float cg_ = bg[r] + g2 * wg0[r] + g1 * wg1[r] + g_cur * wg2[r];
;             const float cv_ = bv[r] + v2 * wv0[r] + v1 * wv1[r] + v_cur * wv2[r];
	v_pk_fma_f32 v[16:17], v[56:57], v[40:41], v[16:17]
	v_cndmask_b32_e64 v40, v35, v23, s[8:9]
	v_mov_b32_dpp v27, v45 row_ror:2 row_mask:0xf bank_mask:0xf
	v_pk_fma_f32 v[26:27], v[70:71], v[26:27], v[78:79]
	v_pk_fma_f32 v[16:17], v[82:83], v[48:49], v[16:17]
	v_pk_fma_f32 v[26:27], v[74:75], v[42:43], v[26:27]

; __device__ __forceinline__ float dpp_ror1(float v) { return __int_as_float(__builtin_amdgcn_update_dpp(0, __float_as_int(v), 0x121, 0xf, 0xf, false)); }
; __device__ __forceinline__ float dpp_ror2(float v) { return __int_as_float(__builtin_amdgcn_update_dpp(0, __float_as_int(v), 0x122, 0xf, 0xf, false)); }
;   __device__ __forceinline__ void operator()(const AccT& acc, const Unit& u, int wr, int wc, int fr, int fq) const {
;     ...
;             const float g1 = dpp_ror1((fr == 15) ? g_pm : g_cur), g2 = dpp_ror2((fr >= 14) ? g_pm : g_cur);
;             const float v1 = dpp_ror1((fr == 15) ? v_pm : v_cur), v2 = dpp_ror2((fr >= 14) ? v_pm : v_cur);
;             const float cg_ = bg[r] + g2 * wg0[r] + g1 * wg1[r] + g_cur * wg2[r];
;             const float cv_ = bv[r] + v2 * wv0[r] + v1 * wv1[r] + v_cur * wv2[r];
;             res[r] = cg_ * __builtin_amdgcn_rcpf(1.f + __builtin_amdgcn_exp2f(-1.4426950408889634f * cg_)) * cv_;
	v_pk_fma_f32 v[26:27], v[20:21], v[66:67], v[26:27]
	v_pk_mul_f32 v[16:17], v[16:17], v[24:25]
	v_mul_f32_e32 v30, 0xbfb8aa3b, v26
	v_mul_f32_e32 v31, 0xbfb8aa3b, v27
	v_exp_f32_e32 v30, v30
	v_exp_f32_e32 v31, v31
	v_mov_b32_dpp v45, v46 row_ror:1 row_mask:0xf bank_mask:0xf
	v_cndmask_b32_e64 v46, v23, v19, s[6:7]
	v_add_f32_e32 v24, 1.0, v30
	v_add_f32_e32 v25, 1.0, v31

; __device__ __forceinline__ uint2 pack4(f32x4 v) { return make_uint2(pack2(v[0], v[1]), pack2(v[2], v[3])); }
; __device__ __forceinline__ float dpp_ror1(float v) { return __int_as_float(__builtin_amdgcn_update_dpp(0, __float_as_int(v), 0x121, 0xf, 0xf, false)); }
; __device__ __forceinline__ float dpp_ror2(float v) { return __int_as_float(__builtin_amdgcn_update_dpp(0, __float_as_int(v), 0x122, 0xf, 0xf, false)); }
;   __device__ __forceinline__ void operator()(const AccT& acc, const Unit& u, int wr, int wc, int fr, int fq) const {
;     ...
;             const float g1 = dpp_ror1((fr == 15) ? g_pm : g_cur), g2 = dpp_ror2((fr >= 14) ? g_pm : g_cur);
;             const float v1 = dpp_ror1((fr == 15) ? v_pm : v_cur), v2 = dpp_ror2((fr >= 14) ? v_pm : v_cur);
;             const float cg_ = bg[r] + g2 * wg0[r] + g1 * wg1[r] + g_cur * wg2[r];
;             const float cv_ = bv[r] + v2 * wv0[r] + v1 * wv1[r] + v_cur * wv2[r];
;             res[r] = cg_ * __builtin_amdgcn_rcpf(1.f + __builtin_amdgcn_exp2f(-1.4426950408889634f * cg_)) * cv_;
;           }
;           if (m > 0 || fr >= 2)
;             *(uint2*)(act + (size_t)EPI_ROW(u, ai, m) * DFF + f0) = pack4(res);
	v_rcp_f32_e32 v24, v24
	v_rcp_f32_e32 v25, v25
	v_mov_b32_dpp v19, v46 row_ror:2 row_mask:0xf bank_mask:0xf
	v_pk_fma_f32 v[18:19], v[54:55], v[18:19], v[62:63]
	v_cvt_pk_bf16_f32 v16, v16, v17
	v_pk_fma_f32 v[18:19], v[58:59], v[44:45], v[18:19]
	v_pk_mul_f32 v[24:25], v[26:27], v[24:25]
	v_pk_fma_f32 v[18:19], v[22:23], v[50:51], v[18:19]

; __device__ __forceinline__ uint2 pack4(f32x4 v) { return make_uint2(pack2(v[0], v[1]), pack2(v[2], v[3])); }
;   __device__ __forceinline__ void operator()(const AccT& acc, const Unit& u, int wr, int wc, int fr, int fq) const {
;     ...
;             res[r] = cg_ * __builtin_amdgcn_rcpf(1.f + __builtin_amdgcn_exp2f(-1.4426950408889634f * cg_)) * cv_;
;           }
;           if (m > 0 || fr >= 2)
;             *(uint2*)(act + (size_t)EPI_ROW(u, ai, m) * DFF + f0) = pack4(res);
	v_pk_mul_f32 v[18:19], v[18:19], v[24:25]

; __device__ __forceinline__ uint2 pack4(f32x4 v) { return make_uint2(pack2(v[0], v[1]), pack2(v[2], v[3])); }
; __device__ __forceinline__ float dpp_ror1(float v) { return __int_as_float(__builtin_amdgcn_update_dpp(0, __float_as_int(v), 0x121, 0xf, 0xf, false)); }
; __device__ __forceinline__ float dpp_ror2(float v) { return __int_as_float(__builtin_amdgcn_update_dpp(0, __float_as_int(v), 0x122, 0xf, 0xf, false)); }
;   __device__ __forceinline__ void operator()(const AccT& acc, const Unit& u, int wr, int wc, int fr, int fq) const {
;     ...
;             const float g_cur = xg[m][r], v_cur = xv[m][r];
;             const f32x4 xgp = xg[m > 0 ? m - 1 : 0], xvp = xv[m > 0 ? m - 1 : 0];
;             const float g_pm = (m > 0) ? xgp[r] : 0.f, v_pm = (m > 0) ? xvp[r] : 0.f;
;             const float g1 = dpp_ror1((fr == 15) ? g_pm : g_cur), g2 = dpp_ror2((fr >= 14) ? g_pm : g_cur);
;             const float v1 = dpp_ror1((fr == 15) ? v_pm : v_cur), v2 = dpp_ror2((fr >= 14) ? v_pm : v_cur);
;             const float cg_ = bg[r] + g2 * wg0[r] + g1 * wg1[r] + g_cur * wg2[r];
;             const float cv_ = bv[r] + v2 * wv0[r] + v1 * wv1[r] + v_cur * wv2[r];
;             res[r] = cg_ * __builtin_amdgcn_rcpf(1.f + __builtin_amdgcn_exp2f(-1.4426950408889634f * cg_)) * cv_;
;           }
;           if (m > 0 || fr >= 2)
;             *(uint2*)(act + (size_t)EPI_ROW(u, ai, m) * DFF + f0) = pack4(res);
	v_cvt_pk_bf16_f32 v17, v18, v19
	global_store_dwordx2 v[130:131], v[16:17], off offset:32
	v_cndmask_b32_e64 v17, v36, v28, s[8:9]
	s_nop 0

; __device__ __forceinline__ float dpp_ror1(float v) { return __int_as_float(__builtin_amdgcn_update_dpp(0, __float_as_int(v), 0x121, 0xf, 0xf, false)); }
; __device__ __forceinline__ float dpp_ror2(float v) { return __int_as_float(__builtin_amdgcn_update_dpp(0, __float_as_int(v), 0x122, 0xf, 0xf, false)); }
;   __device__ __forceinline__ void operator()(const AccT& acc, const Unit& u, int wr, int wc, int fr, int fq) const {
;     ...
;             const float g_cur = xg[m][r], v_cur = xv[m][r];
;             const f32x4 xgp = xg[m > 0 ? m - 1 : 0], xvp = xv[m > 0 ? m - 1 : 0];
;             const float g_pm = (m > 0) ? xgp[r] : 0.f, v_pm = (m > 0) ? xvp[r] : 0.f;
;             const float g1 = dpp_ror1((fr == 15) ? g_pm : g_cur), g2 = dpp_ror2((fr >= 14) ? g_pm : g_cur);
;             const float v1 = dpp_ror1((fr == 15) ? v_pm : v_cur), v2 = dpp_ror2((fr >= 14) ? v_pm : v_cur);
	v_cndmask_b32_e64 v19, v37, v29, s[8:9]
	v_mov_b32_dpp v16, v17 row_ror:1 row_mask:0xf bank_mask:0xf
	v_cndmask_b32_e64 v17, v36, v28, s[6:7]
	v_cndmask_b32_e64 v25, v37, v29, s[6:7]
	v_cndmask_b32_e64 v27, v33, v83, s[8:9]
	v_mov_b32_dpp v18, v17 row_ror:2 row_mask:0xf bank_mask:0xf
	v_cndmask_b32_e64 v17, v32, v82, s[8:9]
	v_cndmask_b32_e64 v28, v33, v83, s[6:7]
	v_cndmask_b32_e64 v29, v38, v20, s[8:9]
	v_mov_b32_dpp v24, v17 row_ror:1 row_mask:0xf bank_mask:0xf
	v_cndmask_b32_e64 v17, v32, v82, s[6:7]
	s_nop 0
	v_cndmask_b32_e64 v31, v39, v21, s[8:9]
	v_mov_b32_dpp v26, v17 row_ror:2 row_mask:0xf bank_mask:0xf

; __device__ __forceinline__ float dpp_ror1(float v) { return __int_as_float(__builtin_amdgcn_update_dpp(0, __float_as_int(v), 0x121, 0xf, 0xf, false)); }
; __device__ __forceinline__ float dpp_ror2(float v) { return __int_as_float(__builtin_amdgcn_update_dpp(0, __float_as_int(v), 0x122, 0xf, 0xf, false)); }
;   __device__ __forceinline__ void operator()(const AccT& acc, const Unit& u, int wr, int wc, int fr, int fq) const {
;     ...
;             const float g1 = dpp_ror1((fr == 15) ? g_pm : g_cur), g2 = dpp_ror2((fr >= 14) ? g_pm : g_cur);
;             const float v1 = dpp_ror1((fr == 15) ? v_pm : v_cur), v2 = dpp_ror2((fr >= 14) ? v_pm : v_cur);
	s_nop 1
	v_mov_b32_dpp v17, v19 row_ror:1 row_mask:0xf bank_mask:0xf

; __device__ __forceinline__ float dpp_ror1(float v) { return __int_as_float(__builtin_amdgcn_update_dpp(0, __float_as_int(v), 0x121, 0xf, 0xf, false)); }
; __device__ __forceinline__ float dpp_ror2(float v) { return __int_as_float(__builtin_amdgcn_update_dpp(0, __float_as_int(v), 0x122, 0xf, 0xf, false)); }
;   __device__ __forceinline__ void operator()(const AccT& acc, const Unit& u, int wr, int wc, int fr, int fq) const {
;     ...
;             const float g1 = dpp_ror1((fr == 15) ? g_pm : g_cur), g2 = dpp_ror2((fr >= 14) ? g_pm : g_cur);
;             const float v1 = dpp_ror1((fr == 15) ? v_pm : v_cur), v2 = dpp_ror2((fr >= 14) ? v_pm : v_cur);
;             const float cg_ = bg[r] + g2 * wg0[r] + g1 * wg1[r] + g_cur * wg2[r];
;             const float cv_ = bv[r] + v2 * wv0[r] + v1 * wv1[r] + v_cur * wv2[r];
	s_nop 1
	v_mov_b32_dpp v19, v25 row_ror:2 row_mask:0xf bank_mask:0xf
	v_pk_fma_f32 v[18:19], v[68:69], v[18:19], v[76:77]

; __device__ __forceinline__ float dpp_ror1(float v) { return __int_as_float(__builtin_amdgcn_update_dpp(0, __float_as_int(v), 0x121, 0xf, 0xf, false)); }
; __device__ __forceinline__ float dpp_ror2(float v) { return __int_as_float(__builtin_amdgcn_update_dpp(0, __float_as_int(v), 0x122, 0xf, 0xf, false)); }
;   __device__ __forceinline__ void operator()(const AccT& acc, const Unit& u, int wr, int wc, int fr, int fq) const {
;     ...
;             const float g1 = dpp_ror1((fr == 15) ? g_pm : g_cur), g2 = dpp_ror2((fr >= 14) ? g_pm : g_cur);
;             const float v1 = dpp_ror1((fr == 15) ? v_pm : v_cur), v2 = dpp_ror2((fr >= 14) ? v_pm : v_cur);
;             const float cg_ = bg[r] + g2 * wg0[r] + g1 * wg1[r] + g_cur * wg2[r];
;             const float cv_ = bv[r] + v2 * wv0[r] + v1 * wv1[r] + v_cur * wv2[r];
;             res[r] = cg_ * __builtin_amdgcn_rcpf(1.f + __builtin_amdgcn_exp2f(-1.4426950408889634f * cg_)) * cv_;
	v_pk_fma_f32 v[16:17], v[72:73], v[16:17], v[18:19]
	s_nop 0
	v_pk_fma_f32 v[16:17], v[36:37], v[64:65], v[16:17]
	v_mov_b32_dpp v25, v27 row_ror:1 row_mask:0xf bank_mask:0xf
	v_mul_f32_e32 v18, 0xbfb8aa3b, v16
	v_mul_f32_e32 v19, 0xbfb8aa3b, v17
	v_exp_f32_e32 v18, v18
	v_exp_f32_e32 v19, v19

; __device__ __forceinline__ float dpp_ror1(float v) { return __int_as_float(__builtin_amdgcn_update_dpp(0, __float_as_int(v), 0x121, 0xf, 0xf, false)); }
; __device__ __forceinline__ float dpp_ror2(float v) { return __int_as_float(__builtin_amdgcn_update_dpp(0, __float_as_int(v), 0x122, 0xf, 0xf, false)); }
;   __device__ __forceinline__ void operator()(const AccT& acc, const Unit& u, int wr, int wc, int fr, int fq) const {
;     ...
;             const float g1 = dpp_ror1((fr == 15) ? g_pm : g_cur), g2 = dpp_ror2((fr >= 14) ? g_pm : g_cur);
;             const float v1 = dpp_ror1((fr == 15) ? v_pm : v_cur), v2 = dpp_ror2((fr >= 14) ? v_pm : v_cur);
;             const float cg_ = bg[r] + g2 * wg0[r] + g1 * wg1[r] + g_cur * wg2[r];
;             const float cv_ = bv[r] + v2 * wv0[r] + v1 * wv1[r] + v_cur * wv2[r];
;             res[r] = cg_ * __builtin_amdgcn_rcpf(1.f + __builtin_amdgcn_exp2f(-1.4426950408889634f * cg_)) * cv_;
	v_add_f32_e32 v18, 1.0, v18
	s_nop 0
	v_mov_b32_dpp v27, v28 row_ror:2 row_mask:0xf bank_mask:0xf

; __device__ __forceinline__ float dpp_ror1(float v) { return __int_as_float(__builtin_amdgcn_update_dpp(0, __float_as_int(v), 0x121, 0xf, 0xf, false)); }
; __device__ __forceinline__ float dpp_ror2(float v) { return __int_as_float(__builtin_amdgcn_update_dpp(0, __float_as_int(v), 0x122, 0xf, 0xf, false)); }
;   __device__ __forceinline__ void operator()(const AccT& acc, const Unit& u, int wr, int wc, int fr, int fq) const {
;     ...
;             const f32x4 xgp = xg[m > 0 ? m - 1 : 0], xvp = xv[m > 0 ? m - 1 : 0];
;             const float g_pm = (m > 0) ? xgp[r] : 0.f, v_pm = (m > 0) ? xvp[r] : 0.f;
;             const float g1 = dpp_ror1((fr == 15) ? g_pm : g_cur), g2 = dpp_ror2((fr >= 14) ? g_pm : g_cur);
;             const float v1 = dpp_ror1((fr == 15) ? v_pm : v_cur), v2 = dpp_ror2((fr >= 14) ? v_pm : v_cur);
;             const float cg_ = bg[r] + g2 * wg0[r] + g1 * wg1[r] + g_cur * wg2[r];
;             const float cv_ = bv[r] + v2 * wv0[r] + v1 * wv1[r] + v_cur * wv2[r];
;             res[r] = cg_ * __builtin_amdgcn_rcpf(1.f + __builtin_amdgcn_exp2f(-1.4426950408889634f * cg_)) * cv_;
	v_add_f32_e32 v19, 1.0, v19
	v_rcp_f32_e32 v18, v18
	v_mov_b32_dpp v28, v29 row_ror:1 row_mask:0xf bank_mask:0xf
	v_cndmask_b32_e64 v29, v38, v20, s[6:7]

; __device__ __forceinline__ float dpp_ror1(float v) { return __int_as_float(__builtin_amdgcn_update_dpp(0, __float_as_int(v), 0x121, 0xf, 0xf, false)); }
; __device__ __forceinline__ float dpp_ror2(float v) { return __int_as_float(__builtin_amdgcn_update_dpp(0, __float_as_int(v), 0x122, 0xf, 0xf, false)); }
;   __device__ __forceinline__ void operator()(const AccT& acc, const Unit& u, int wr, int wc, int fr, int fq) const {
;     ...
;             const f32x4 xgp = xg[m > 0 ? m - 1 : 0], xvp = xv[m > 0 ? m - 1 : 0];
;             const float g_pm = (m > 0) ? xgp[r] : 0.f, v_pm = (m > 0) ? xvp[r] : 0.f;
;             const float g1 = dpp_ror1((fr == 15) ? g_pm : g_cur), g2 = dpp_ror2((fr >= 14) ? g_pm : g_cur);
;             const float v1 = dpp_ror1((fr == 15) ? v_pm : v_cur), v2 = dpp_ror2((fr >= 14) ? v_pm : v_cur);
;             const float cg_ = bg[r] + g2 * wg0[r] + g1 * wg1[r] + g_cur * wg2[r];
;             const float cv_ = bv[r] + v2 * wv0[r] + v1 * wv1[r] + v_cur * wv2[r];
;             res[r] = cg_ * __builtin_amdgcn_rcpf(1.f + __builtin_amdgcn_exp2f(-1.4426950408889634f * cg_)) * cv_;
	v_rcp_f32_e32 v19, v19
	v_pk_fma_f32 v[26:27], v[52:53], v[26:27], v[60:61]
	v_mov_b32_dpp v20, v29 row_ror:2 row_mask:0xf bank_mask:0xf
	v_cndmask_b32_e64 v29, v34, v22, s[8:9]
	v_pk_mul_f32 v[16:17], v[16:17], v[18:19]
	v_pk_fma_f32 v[24:25], v[56:57], v[24:25], v[26:27]
	v_mov_b32_dpp v30, v29 row_ror:1 row_mask:0xf bank_mask:0xf
	v_cndmask_b32_e64 v29, v34, v22, s[6:7]

; __device__ __forceinline__ float dpp_ror1(float v) { return __int_as_float(__builtin_amdgcn_update_dpp(0, __float_as_int(v), 0x121, 0xf, 0xf, false)); }
; __device__ __forceinline__ float dpp_ror2(float v) { return __int_as_float(__builtin_amdgcn_update_dpp(0, __float_as_int(v), 0x122, 0xf, 0xf, false)); }
;   __device__ __forceinline__ void operator()(const AccT& acc, const Unit& u, int wr, int wc, int fr, int fq) const {
;     ...
;             const float g1 = dpp_ror1((fr == 15) ? g_pm : g_cur), g2 = dpp_ror2((fr >= 14) ? g_pm : g_cur);
;             const float v1 = dpp_ror1((fr == 15) ? v_pm : v_cur), v2 = dpp_ror2((fr >= 14) ? v_pm : v_cur);
;             const float cg_ = bg[r] + g2 * wg0[r] + g1 * wg1[r] + g_cur * wg2[r];
;             const float cv_ = bv[r] + v2 * wv0[r] + v1 * wv1[r] + v_cur * wv2[r];
	v_pk_fma_f32 v[24:25], v[32:33], v[48:49], v[24:25]
	s_nop 0
	v_mov_b32_dpp v22, v29 row_ror:2 row_mask:0xf bank_mask:0xf

; __device__ __forceinline__ float dpp_ror1(float v) { return __int_as_float(__builtin_amdgcn_update_dpp(0, __float_as_int(v), 0x121, 0xf, 0xf, false)); }
; __device__ __forceinline__ float dpp_ror2(float v) { return __int_as_float(__builtin_amdgcn_update_dpp(0, __float_as_int(v), 0x122, 0xf, 0xf, false)); }
;   __device__ __forceinline__ void operator()(const AccT& acc, const Unit& u, int wr, int wc, int fr, int fq) const {
;     ...
;             const f32x4 xgp = xg[m > 0 ? m - 1 : 0], xvp = xv[m > 0 ? m - 1 : 0];
;             const float g_pm = (m > 0) ? xgp[r] : 0.f, v_pm = (m > 0) ? xvp[r] : 0.f;
;             const float g1 = dpp_ror1((fr == 15) ? g_pm : g_cur), g2 = dpp_ror2((fr >= 14) ? g_pm : g_cur);
;             const float v1 = dpp_ror1((fr == 15) ? v_pm : v_cur), v2 = dpp_ror2((fr >= 14) ? v_pm : v_cur);
;             const float cg_ = bg[r] + g2 * wg0[r] + g1 * wg1[r] + g_cur * wg2[r];
;             const float cv_ = bv[r] + v2 * wv0[r] + v1 * wv1[r] + v_cur * wv2[r];
;             res[r] = cg_ * __builtin_amdgcn_rcpf(1.f + __builtin_amdgcn_exp2f(-1.4426950408889634f * cg_)) * cv_;
	v_pk_mul_f32 v[16:17], v[24:25], v[16:17]
	s_nop 0
	v_mov_b32_dpp v29, v31 row_ror:1 row_mask:0xf bank_mask:0xf
	v_cndmask_b32_e64 v31, v39, v21, s[6:7]

; __device__ __forceinline__ uint2 pack4(f32x4 v) { return make_uint2(pack2(v[0], v[1]), pack2(v[2], v[3])); }
; __device__ __forceinline__ float dpp_ror1(float v) { return __int_as_float(__builtin_amdgcn_update_dpp(0, __float_as_int(v), 0x121, 0xf, 0xf, false)); }
; __device__ __forceinline__ float dpp_ror2(float v) { return __int_as_float(__builtin_amdgcn_update_dpp(0, __float_as_int(v), 0x122, 0xf, 0xf, false)); }
;   __device__ __forceinline__ void operator()(const AccT& acc, const Unit& u, int wr, int wc, int fr, int fq) const {
;     ...
;             const float g1 = dpp_ror1((fr == 15) ? g_pm : g_cur), g2 = dpp_ror2((fr >= 14) ? g_pm : g_cur);
;             const float v1 = dpp_ror1((fr == 15) ? v_pm : v_cur), v2 = dpp_ror2((fr >= 14) ? v_pm : v_cur);
;             const float cg_ = bg[r] + g2 * wg0[r] + g1 * wg1[r] + g_cur * wg2[r];
;             const float cv_ = bv[r] + v2 * wv0[r] + v1 * wv1[r] + v_cur * wv2[r];
;             res[r] = cg_ * __builtin_amdgcn_rcpf(1.f + __builtin_amdgcn_exp2f(-1.4426950408889634f * cg_)) * cv_;
;           }
;           if (m > 0 || fr >= 2)
;             *(uint2*)(act + (size_t)EPI_ROW(u, ai, m) * DFF + f0) = pack4(res);
	v_cvt_pk_bf16_f32 v16, v16, v17
	s_nop 0
	v_mov_b32_dpp v21, v31 row_ror:2 row_mask:0xf bank_mask:0xf
	v_pk_fma_f32 v[18:19], v[70:71], v[20:21], v[78:79]

; __device__ __forceinline__ float dpp_ror1(float v) { return __int_as_float(__builtin_amdgcn_update_dpp(0, __float_as_int(v), 0x121, 0xf, 0xf, false)); }
; __device__ __forceinline__ float dpp_ror2(float v) { return __int_as_float(__builtin_amdgcn_update_dpp(0, __float_as_int(v), 0x122, 0xf, 0xf, false)); }
;   __device__ __forceinline__ void operator()(const AccT& acc, const Unit& u, int wr, int wc, int fr, int fq) const {
;     ...
;             const float g1 = dpp_ror1((fr == 15) ? g_pm : g_cur), g2 = dpp_ror2((fr >= 14) ? g_pm : g_cur);
;             const float v1 = dpp_ror1((fr == 15) ? v_pm : v_cur), v2 = dpp_ror2((fr >= 14) ? v_pm : v_cur);
;             const float cg_ = bg[r] + g2 * wg0[r] + g1 * wg1[r] + g_cur * wg2[r];
;             const float cv_ = bv[r] + v2 * wv0[r] + v1 * wv1[r] + v_cur * wv2[r];
;             res[r] = cg_ * __builtin_amdgcn_rcpf(1.f + __builtin_amdgcn_exp2f(-1.4426950408889634f * cg_)) * cv_;
	v_pk_fma_f32 v[18:19], v[74:75], v[28:29], v[18:19]
	s_nop 0
	v_pk_fma_f32 v[18:19], v[38:39], v[66:67], v[18:19]
	v_mov_b32_dpp v31, v40 row_ror:1 row_mask:0xf bank_mask:0xf
	v_mul_f32_e32 v20, 0xbfb8aa3b, v18
	v_mul_f32_e32 v21, 0xbfb8aa3b, v19
	v_exp_f32_e32 v20, v20
	v_exp_f32_e32 v21, v21
	v_cndmask_b32_e64 v40, v35, v23, s[6:7]

; __device__ __forceinline__ uint2 pack4(f32x4 v) { return make_uint2(pack2(v[0], v[1]), pack2(v[2], v[3])); }
;   __device__ __forceinline__ void operator()(const AccT& acc, const Unit& u, int wr, int wc, int fr, int fq) const {
;     ...
;             const float cg_ = bg[r] + g2 * wg0[r] + g1 * wg1[r] + g_cur * wg2[r];
;             const float cv_ = bv[r] + v2 * wv0[r] + v1 * wv1[r] + v_cur * wv2[r];
;             res[r] = cg_ * __builtin_amdgcn_rcpf(1.f + __builtin_amdgcn_exp2f(-1.4426950408889634f * cg_)) * cv_;
;           }
;           if (m > 0 || fr >= 2)
;             *(uint2*)(act + (size_t)EPI_ROW(u, ai, m) * DFF + f0) = pack4(res);
	v_add_f32_e32 v20, 1.0, v20
	v_add_f32_e32 v21, 1.0, v21
	v_rcp_f32_e32 v20, v20
	v_rcp_f32_e32 v21, v21
	v_mov_b32_dpp v23, v40 row_ror:2 row_mask:0xf bank_mask:0xf
	v_pk_fma_f32 v[22:23], v[54:55], v[22:23], v[62:63]
	v_pk_mul_f32 v[18:19], v[18:19], v[20:21]
	v_pk_fma_f32 v[22:23], v[58:59], v[30:31], v[22:23]
	s_nop 0
	v_pk_fma_f32 v[22:23], v[34:35], v[50:51], v[22:23]
	s_nop 0
	v_pk_mul_f32 v[18:19], v[22:23], v[18:19]
	s_nop 0
	v_cvt_pk_bf16_f32 v17, v18, v19
	global_store_dwordx2 v[80:81], v[16:17], off offset:32
	s_cbranch_vccnz .LBB0_1534

; __device__ __forceinline__ float dpp_ror1(float v) { return __int_as_float(__builtin_amdgcn_update_dpp(0, __float_as_int(v), 0x121, 0xf, 0xf, false)); }
; __device__ __forceinline__ float dpp_ror2(float v) { return __int_as_float(__builtin_amdgcn_update_dpp(0, __float_as_int(v), 0x122, 0xf, 0xf, false)); }
;   __device__ __forceinline__ void operator()(const AccT& acc, const Unit& u, int wr, int wc, int fr, int fq) const {
;     ...
;             const float g_cur = xg[m][r], v_cur = xv[m][r];
;             const f32x4 xgp = xg[m > 0 ? m - 1 : 0], xvp = xv[m > 0 ? m - 1 : 0];
;             const float g_pm = (m > 0) ? xgp[r] : 0.f, v_pm = (m > 0) ? xvp[r] : 0.f;
;             const float g1 = dpp_ror1((fr == 15) ? g_pm : g_cur), g2 = dpp_ror2((fr >= 14) ? g_pm : g_cur);
;             const float v1 = dpp_ror1((fr == 15) ? v_pm : v_cur), v2 = dpp_ror2((fr >= 14) ? v_pm : v_cur);
.LBB0_1506:
	s_or_b64 exec, exec, s[12:13]
	v_cndmask_b32_e64 v232, v172, 0, s[8:9]
	s_nop 0
	s_nop 0

; __device__ __forceinline__ float dpp_ror1(float v) { return __int_as_float(__builtin_amdgcn_update_dpp(0, __float_as_int(v), 0x121, 0xf, 0xf, false)); }
; __device__ __forceinline__ float dpp_ror2(float v) { return __int_as_float(__builtin_amdgcn_update_dpp(0, __float_as_int(v), 0x122, 0xf, 0xf, false)); }
;   __device__ __forceinline__ void operator()(const AccT& acc, const Unit& u, int wr, int wc, int fr, int fq) const {
;     ...
;             const f32x4 xgp = xg[m > 0 ? m - 1 : 0], xvp = xv[m > 0 ? m - 1 : 0];
;             const float g_pm = (m > 0) ? xgp[r] : 0.f, v_pm = (m > 0) ? xvp[r] : 0.f;
;             const float g1 = dpp_ror1((fr == 15) ? g_pm : g_cur), g2 = dpp_ror2((fr >= 14) ? g_pm : g_cur);
;             const float v1 = dpp_ror1((fr == 15) ? v_pm : v_cur), v2 = dpp_ror2((fr >= 14) ? v_pm : v_cur);
	v_mov_b32_dpp v242, v232 row_ror:1 row_mask:0xf bank_mask:0xf
	v_mov_b32_dpp v244, v231 row_ror:2 row_mask:0xf bank_mask:0xf
	v_cndmask_b32_e64 v231, v168, 0, s[8:9]

; __device__ __forceinline__ float dpp_ror1(float v) { return __int_as_float(__builtin_amdgcn_update_dpp(0, __float_as_int(v), 0x121, 0xf, 0xf, false)); }
; __device__ __forceinline__ float dpp_ror2(float v) { return __int_as_float(__builtin_amdgcn_update_dpp(0, __float_as_int(v), 0x122, 0xf, 0xf, false)); }
;   __device__ __forceinline__ void operator()(const AccT& acc, const Unit& u, int wr, int wc, int fr, int fq) const {
;     ...
;             const f32x4 xgp = xg[m > 0 ? m - 1 : 0], xvp = xv[m > 0 ? m - 1 : 0];
;             const float g_pm = (m > 0) ? xgp[r] : 0.f, v_pm = (m > 0) ? xvp[r] : 0.f;
;             const float g1 = dpp_ror1((fr == 15) ? g_pm : g_cur), g2 = dpp_ror2((fr >= 14) ? g_pm : g_cur);
;             const float v1 = dpp_ror1((fr == 15) ? v_pm : v_cur), v2 = dpp_ror2((fr >= 14) ? v_pm : v_cur);
	v_mov_b32_dpp v240, v230 row_ror:2 row_mask:0xf bank_mask:0xf
	v_cndmask_b32_e64 v230, v173, 0, s[8:9]
	s_nop 0


; __device__ __forceinline__ float dpp_ror1(float v) { return __int_as_float(__builtin_amdgcn_update_dpp(0, __float_as_int(v), 0x121, 0xf, 0xf, false)); }
; __device__ __forceinline__ float dpp_ror2(float v) { return __int_as_float(__builtin_amdgcn_update_dpp(0, __float_as_int(v), 0x122, 0xf, 0xf, false)); }
;   __device__ __forceinline__ void operator()(const AccT& acc, const Unit& u, int wr, int wc, int fr, int fq) const {
;     ...
;             const float g1 = dpp_ror1((fr == 15) ? g_pm : g_cur), g2 = dpp_ror2((fr >= 14) ? g_pm : g_cur);
;             const float v1 = dpp_ror1((fr == 15) ? v_pm : v_cur), v2 = dpp_ror2((fr >= 14) ? v_pm : v_cur);
	v_mov_b32_dpp v236, v231 row_ror:1 row_mask:0xf bank_mask:0xf
	v_mov_b32_dpp v243, v230 row_ror:1 row_mask:0xf bank_mask:0xf
	v_mov_b32_dpp v245, v229 row_ror:2 row_mask:0xf bank_mask:0xf
	v_cndmask_b32_e64 v229, v169, 0, s[8:9]

; __device__ __forceinline__ float dpp_ror1(float v) { return __int_as_float(__builtin_amdgcn_update_dpp(0, __float_as_int(v), 0x121, 0xf, 0xf, false)); }
; __device__ __forceinline__ float dpp_ror2(float v) { return __int_as_float(__builtin_amdgcn_update_dpp(0, __float_as_int(v), 0x122, 0xf, 0xf, false)); }
;   __device__ __forceinline__ void operator()(const AccT& acc, const Unit& u, int wr, int wc, int fr, int fq) const {
;     ...
;             const f32x4 xgp = xg[m > 0 ? m - 1 : 0], xvp = xv[m > 0 ? m - 1 : 0];
;             const float g_pm = (m > 0) ? xgp[r] : 0.f, v_pm = (m > 0) ? xvp[r] : 0.f;
;             const float g1 = dpp_ror1((fr == 15) ? g_pm : g_cur), g2 = dpp_ror2((fr >= 14) ? g_pm : g_cur);
;             const float v1 = dpp_ror1((fr == 15) ? v_pm : v_cur), v2 = dpp_ror2((fr >= 14) ? v_pm : v_cur);
	v_mov_b32_dpp v241, v227 row_ror:2 row_mask:0xf bank_mask:0xf
	v_cndmask_b32_e64 v227, v174, 0, s[8:9]

; __device__ __forceinline__ float dpp_ror1(float v) { return __int_as_float(__builtin_amdgcn_update_dpp(0, __float_as_int(v), 0x121, 0xf, 0xf, false)); }
; __device__ __forceinline__ float dpp_ror2(float v) { return __int_as_float(__builtin_amdgcn_update_dpp(0, __float_as_int(v), 0x122, 0xf, 0xf, false)); }
;   __device__ __forceinline__ void operator()(const AccT& acc, const Unit& u, int wr, int wc, int fr, int fq) const {
;     ...
;             const f32x4 xgp = xg[m > 0 ? m - 1 : 0], xvp = xv[m > 0 ? m - 1 : 0];
;             const float g_pm = (m > 0) ? xgp[r] : 0.f, v_pm = (m > 0) ? xvp[r] : 0.f;
;             const float g1 = dpp_ror1((fr == 15) ? g_pm : g_cur), g2 = dpp_ror2((fr >= 14) ? g_pm : g_cur);
;             const float v1 = dpp_ror1((fr == 15) ? v_pm : v_cur), v2 = dpp_ror2((fr >= 14) ? v_pm : v_cur);
	v_mov_b32_dpp v238, v219 row_ror:2 row_mask:0xf bank_mask:0xf
	v_cndmask_b32_e64 v219, v170, 0, s[8:9]

; __device__ __forceinline__ float dpp_ror1(float v) { return __int_as_float(__builtin_amdgcn_update_dpp(0, __float_as_int(v), 0x121, 0xf, 0xf, false)); }
; __device__ __forceinline__ float dpp_ror2(float v) { return __int_as_float(__builtin_amdgcn_update_dpp(0, __float_as_int(v), 0x122, 0xf, 0xf, false)); }
;   __device__ __forceinline__ void operator()(const AccT& acc, const Unit& u, int wr, int wc, int fr, int fq) const {
;     ...
;             const f32x4 xgp = xg[m > 0 ? m - 1 : 0], xvp = xv[m > 0 ? m - 1 : 0];
;             const float g_pm = (m > 0) ? xgp[r] : 0.f, v_pm = (m > 0) ? xvp[r] : 0.f;
;             const float g1 = dpp_ror1((fr == 15) ? g_pm : g_cur), g2 = dpp_ror2((fr >= 14) ? g_pm : g_cur);
;             const float v1 = dpp_ror1((fr == 15) ? v_pm : v_cur), v2 = dpp_ror2((fr >= 14) ? v_pm : v_cur);
	v_mov_b32_dpp v232, v217 row_ror:2 row_mask:0xf bank_mask:0xf
	v_cndmask_b32_e64 v217, v175, 0, s[8:9]

; __device__ __forceinline__ float dpp_ror1(float v) { return __int_as_float(__builtin_amdgcn_update_dpp(0, __float_as_int(v), 0x121, 0xf, 0xf, false)); }
; __device__ __forceinline__ float dpp_ror2(float v) { return __int_as_float(__builtin_amdgcn_update_dpp(0, __float_as_int(v), 0x122, 0xf, 0xf, false)); }
;   __device__ __forceinline__ void operator()(const AccT& acc, const Unit& u, int wr, int wc, int fr, int fq) const {
;     ...
;             const f32x4 xgp = xg[m > 0 ? m - 1 : 0], xvp = xv[m > 0 ? m - 1 : 0];
;             const float g_pm = (m > 0) ? xgp[r] : 0.f, v_pm = (m > 0) ? xvp[r] : 0.f;
;             const float g1 = dpp_ror1((fr == 15) ? g_pm : g_cur), g2 = dpp_ror2((fr >= 14) ? g_pm : g_cur);
;             const float v1 = dpp_ror1((fr == 15) ? v_pm : v_cur), v2 = dpp_ror2((fr >= 14) ? v_pm : v_cur);
	v_mov_b32_dpp v239, v213 row_ror:2 row_mask:0xf bank_mask:0xf
	v_cndmask_b32_e64 v213, v171, 0, s[8:9]


; __device__ __forceinline__ uint2 pack4(f32x4 v) { return make_uint2(pack2(v[0], v[1]), pack2(v[2], v[3])); }
; __device__ __forceinline__ float rstd_of(const unsigned long long* rowss, int row) {
;   return rsqrtf((float)rowss[row] * (1.f / (SS_FIX * DM)) + 1e-6f);
; }
; __device__ __forceinline__ float dpp_ror1(float v) { return __int_as_float(__builtin_amdgcn_update_dpp(0, __float_as_int(v), 0x121, 0xf, 0xf, false)); }
; __device__ __forceinline__ float dpp_ror2(float v) { return __int_as_float(__builtin_amdgcn_update_dpp(0, __float_as_int(v), 0x122, 0xf, 0xf, false)); }
;   __device__ __forceinline__ void operator()(const AccT& acc, const Unit& u, int wr, int wc, int fr, int fq) const {
; #pragma unroll
;     for (int ai = 0; ai < 2; ++ai) {
;       float rs[4];
; #pragma unroll
;       for (int m = 0; m < 4; ++m) rs[m] = rstd_of(rowss, EPI_ROW(u, ai, m));
;       const int chunk = 4 * u.pm + 2 * ai + wr;
; #pragma unroll
;       for (int n = 0; n < 2; ++n) {
;         const int f0 = 128 * u.pn + 32 * wc + 16 * n + 4 * fq;
;         const int gc = u.pn * 256 + 32 * wc + 16 * n + 4 * fq;
;         const f32x4 wg0 = *(const f32x4*)(cw + f0), wg1 = *(const f32x4*)(cw + NUP + f0), wg2 = *(const f32x4*)(cw + 2 * NUP + f0);
;         const f32x4 wv0 = *(const f32x4*)(cw + DFF + f0), wv1 = *(const f32x4*)(cw + NUP + DFF + f0), wv2 = *(const f32x4*)(cw + 2 * NUP + DFF + f0);
;         const f32x4 bg = *(const f32x4*)(cb + f0), bv = *(const f32x4*)(cb + DFF + f0);
;         f32x4 xg[4], xv[4];
; #pragma unroll
;         for (int m = 0; m < 4; ++m) { xg[m] = acc[ai][0][m][n] * rs[m]; xv[m] = acc[ai][1][m][n] * rs[m]; }
;     ...
;             const float cg_ = bg[r] + g2 * wg0[r] + g1 * wg1[r] + g_cur * wg2[r];
;             const float cv_ = bv[r] + v2 * wv0[r] + v1 * wv1[r] + v_cur * wv2[r];
;             res[r] = cg_ * __builtin_amdgcn_rcpf(1.f + __builtin_amdgcn_exp2f(-1.4426950408889634f * cg_)) * cv_;
;           }
;           if (m > 0 || fr >= 2)
;             *(uint2*)(act + (size_t)EPI_ROW(u, ai, m) * DFF + f0) = pack4(res);
	v_mov_b32_dpp v237, v229 row_ror:1 row_mask:0xf bank_mask:0xf
	v_mov_b32_dpp v234, v227 row_ror:1 row_mask:0xf bank_mask:0xf
	v_mov_b32_dpp v230, v219 row_ror:1 row_mask:0xf bank_mask:0xf
	v_mov_b32_dpp v235, v217 row_ror:1 row_mask:0xf bank_mask:0xf
	v_mov_b32_dpp v231, v213 row_ror:1 row_mask:0xf bank_mask:0xf
	v_mov_b32_dpp v233, v195 row_ror:2 row_mask:0xf bank_mask:0xf
	s_and_saveexec_b64 s[12:13], s[4:5]
	s_xor_b64 s[12:13], exec, s[12:13]
	s_andn2_saveexec_b64 s[12:13], s[12:13]
	s_cbranch_execz .LBB0_1510
	v_pk_fma_f32 v[244:245], v[148:149], v[244:245], v[160:161]
	v_pk_fma_f32 v[238:239], v[150:151], v[238:239], v[162:163]
	v_pk_fma_f32 v[242:243], v[152:153], v[242:243], v[244:245]
	v_pk_fma_f32 v[234:235], v[154:155], v[234:235], v[238:239]
	v_pk_fma_f32 v[242:243], v[156:157], v[172:173], v[242:243]
	v_pk_fma_f32 v[234:235], v[158:159], v[174:175], v[234:235]
	v_mul_f32_e32 v195, 0xbfb8aa3b, v242
	v_exp_f32_e32 v195, v195
	v_mul_f32_e32 v213, 0xbfb8aa3b, v243
	v_exp_f32_e32 v213, v213
	v_pk_fma_f32 v[232:233], v[130:131], v[232:233], v[146:147]
	v_add_f32_e32 v195, 1.0, v195
	v_rcp_f32_e32 v244, v195
	v_add_f32_e32 v213, 1.0, v213
	v_mul_f32_e32 v195, 0xbfb8aa3b, v234
	v_rcp_f32_e32 v245, v213
	v_exp_f32_e32 v195, v195
	v_mul_f32_e32 v213, 0xbfb8aa3b, v235
	v_exp_f32_e32 v213, v213
	v_pk_fma_f32 v[230:231], v[138:139], v[230:231], v[232:233]
	v_add_f32_e32 v195, 1.0, v195
	v_rcp_f32_e32 v238, v195
	v_add_f32_e32 v195, 1.0, v213
	v_rcp_f32_e32 v239, v195
	v_pk_fma_f32 v[240:241], v[128:129], v[240:241], v[144:145]
	v_pk_fma_f32 v[230:231], v[134:135], v[170:171], v[230:231]
	v_pk_fma_f32 v[236:237], v[136:137], v[236:237], v[240:241]
	v_pk_mul_f32 v[232:233], v[234:235], v[238:239]
	v_pk_fma_f32 v[236:237], v[132:133], v[168:169], v[236:237]
	v_pk_mul_f32 v[230:231], v[230:231], v[232:233]
	v_pk_mul_f32 v[240:241], v[242:243], v[244:245]
	v_cvt_pk_bf16_f32 v233, v230, v231
	v_mov_b64_e32 v[230:231], s[52:53]
	v_pk_mul_f32 v[236:237], v[236:237], v[240:241]
	v_mad_i64_i32 v[230:231], s[46:47], v194, s88, v[230:231]
	v_cvt_pk_bf16_f32 v232, v236, v237
	v_lshl_add_u64 v[230:231], v[188:189], 1, v[230:231]
	global_store_dwordx2 v[230:231], v[232:233], off
.LBB0_1510:
	s_or_b64 exec, exec, s[12:13]
	v_ffbh_u32_e32 v195, v225
	v_min_u32_e32 v195, 32, v195
	v_lshlrev_b64 v[224:225], v195, v[224:225]
	v_min_u32_e32 v213, 1, v224
	v_or_b32_e32 v213, v225, v213
	v_ffbh_u32_e32 v217, v223
	v_cvt_f32_u32_e32 v213, v213
	v_min_u32_e32 v217, 32, v217
	v_lshlrev_b64 v[222:223], v217, v[222:223]
	v_min_u32_e32 v219, 1, v222
	v_sub_u32_e32 v195, 32, v195
	v_or_b32_e32 v219, v223, v219
	v_ldexp_f32 v195, v213, v195
	v_cvt_f32_u32_e32 v219, v219
	v_fmamk_f32 v195, v195, 0x2e800000, v252
	v_mul_f32_e32 v213, 0x4b800000, v195
	v_cmp_gt_f32_e32 vcc, s86, v195
	s_nop 0
	s_nop 0
	v_cndmask_b32_e32 v195, v195, v213, vcc
	v_sub_u32_e32 v213, 32, v217
	v_ldexp_f32 v213, v219, v213
	v_fmamk_f32 v213, v213, 0x2e800000, v252
	v_mul_f32_e32 v217, 0x4b800000, v213
	v_cmp_gt_f32_e64 s[12:13], s86, v213
	v_rsq_f32_e32 v195, v195
	s_nop 0
	v_cndmask_b32_e64 v213, v213, v217, s[12:13]
	v_rsq_f32_e32 v213, v213
	v_mul_f32_e32 v217, 0x45800000, v195
	v_cndmask_b32_e32 v224, v195, v217, vcc
	v_pk_mul_f32 v[124:125], v[124:125], v[224:225] op_sel_hi:[1,0]
	v_mul_f32_e32 v195, 0x45800000, v213
	v_cndmask_b32_e64 v222, v213, v195, s[12:13]
	v_pk_mul_f32 v[230:231], v[118:119], v[224:225] op_sel_hi:[1,0]
	v_pk_mul_f32 v[118:119], v[120:121], v[222:223] op_sel_hi:[1,0]
	v_cndmask_b32_e64 v121, v124, v172, s[8:9]

; __device__ __forceinline__ float dpp_ror1(float v) { return __int_as_float(__builtin_amdgcn_update_dpp(0, __float_as_int(v), 0x121, 0xf, 0xf, false)); }
; __device__ __forceinline__ float dpp_ror2(float v) { return __int_as_float(__builtin_amdgcn_update_dpp(0, __float_as_int(v), 0x122, 0xf, 0xf, false)); }
;   __device__ __forceinline__ void operator()(const AccT& acc, const Unit& u, int wr, int wc, int fr, int fq) const {
;     ...
;         for (int m = 0; m < 4; ++m) { xg[m] = acc[ai][0][m][n] * rs[m]; xv[m] = acc[ai][1][m][n] * rs[m]; }
;         if (fr < 2) {
;           float* d = ub + ((size_t)(chunk * 4 + fr) * NUP + gc);
;           *(float4*)d = make_float4(xg[0][0], xg[0][1], xg[0][2], xg[0][3]);
;           *(float4*)(d + 128) = make_float4(xv[0][0], xv[0][1], xv[0][2], xv[0][3]);
;         }
;         if (fr >= 14) {
;           float* d = ub + ((size_t)(chunk * 4 + 2 + (fr - 14)) * NUP + gc);
;           *(float4*)d = make_float4(xg[3][0], xg[3][1], xg[3][2], xg[3][3]);
;           *(float4*)(d + 128) = make_float4(xv[3][0], xv[3][1], xv[3][2], xv[3][3]);
;         }
; #pragma unroll
;         for (int m = 0; m < 4; ++m) {
;           f32x4 res;
; #pragma unroll
;           for (int r = 0; r < 4; ++r) {
;             const float g_cur = xg[m][r], v_cur = xv[m][r];
;             const f32x4 xgp = xg[m > 0 ? m - 1 : 0], xvp = xv[m > 0 ? m - 1 : 0];
;             const float g_pm = (m > 0) ? xgp[r] : 0.f, v_pm = (m > 0) ? xvp[r] : 0.f;
;             const float g1 = dpp_ror1((fr == 15) ? g_pm : g_cur), g2 = dpp_ror2((fr >= 14) ? g_pm : g_cur);
;             const float v1 = dpp_ror1((fr == 15) ? v_pm : v_cur), v2 = dpp_ror2((fr >= 14) ? v_pm : v_cur);
	v_pk_mul_f32 v[232:233], v[116:117], v[224:225] op_sel_hi:[1,0]
	v_pk_mul_f32 v[116:117], v[122:123], v[222:223] op_sel_hi:[1,0]
	v_mov_b32_dpp v120, v121 row_ror:1 row_mask:0xf bank_mask:0xf
	v_cndmask_b32_e64 v121, v124, v172, s[6:7]
	s_nop 0

; __device__ __forceinline__ float dpp_ror1(float v) { return __int_as_float(__builtin_amdgcn_update_dpp(0, __float_as_int(v), 0x121, 0xf, 0xf, false)); }
; __device__ __forceinline__ float dpp_ror2(float v) { return __int_as_float(__builtin_amdgcn_update_dpp(0, __float_as_int(v), 0x122, 0xf, 0xf, false)); }
;   __device__ __forceinline__ void operator()(const AccT& acc, const Unit& u, int wr, int wc, int fr, int fq) const {
;     ...
;         for (int m = 0; m < 4; ++m) { xg[m] = acc[ai][0][m][n] * rs[m]; xv[m] = acc[ai][1][m][n] * rs[m]; }
;         if (fr < 2) {
;           float* d = ub + ((size_t)(chunk * 4 + fr) * NUP + gc);
;           *(float4*)d = make_float4(xg[0][0], xg[0][1], xg[0][2], xg[0][3]);
;           *(float4*)(d + 128) = make_float4(xv[0][0], xv[0][1], xv[0][2], xv[0][3]);
;         }
;         if (fr >= 14) {
;           float* d = ub + ((size_t)(chunk * 4 + 2 + (fr - 14)) * NUP + gc);
;           *(float4*)d = make_float4(xg[3][0], xg[3][1], xg[3][2], xg[3][3]);
;           *(float4*)(d + 128) = make_float4(xv[3][0], xv[3][1], xv[3][2], xv[3][3]);
;         }
; #pragma unroll
;         for (int m = 0; m < 4; ++m) {
;           f32x4 res;
; #pragma unroll
;           for (int r = 0; r < 4; ++r) {
;             const float g_cur = xg[m][r], v_cur = xv[m][r];
;             const f32x4 xgp = xg[m > 0 ? m - 1 : 0], xvp = xv[m > 0 ? m - 1 : 0];
;             const float g_pm = (m > 0) ? xgp[r] : 0.f, v_pm = (m > 0) ? xvp[r] : 0.f;
;             const float g1 = dpp_ror1((fr == 15) ? g_pm : g_cur), g2 = dpp_ror2((fr >= 14) ? g_pm : g_cur);
;             const float v1 = dpp_ror1((fr == 15) ? v_pm : v_cur), v2 = dpp_ror2((fr >= 14) ? v_pm : v_cur);
	v_cndmask_b32_e64 v123, v125, v173, s[8:9]
	v_mov_b32_dpp v122, v121 row_ror:2 row_mask:0xf bank_mask:0xf
	v_cndmask_b32_e64 v121, v232, v168, s[8:9]
	v_cndmask_b32_e64 v173, v125, v173, s[6:7]
	v_cndmask_b32_e64 v195, v233, v169, s[8:9]
	v_mov_b32_dpp v172, v121 row_ror:1 row_mask:0xf bank_mask:0xf
	v_cndmask_b32_e64 v121, v232, v168, s[6:7]
	s_nop 0
	v_pk_mul_f32 v[126:127], v[126:127], v[224:225] op_sel_hi:[1,0]

; __device__ __forceinline__ float dpp_ror1(float v) { return __int_as_float(__builtin_amdgcn_update_dpp(0, __float_as_int(v), 0x121, 0xf, 0xf, false)); }
; __device__ __forceinline__ float dpp_ror2(float v) { return __int_as_float(__builtin_amdgcn_update_dpp(0, __float_as_int(v), 0x122, 0xf, 0xf, false)); }
;   __device__ __forceinline__ void operator()(const AccT& acc, const Unit& u, int wr, int wc, int fr, int fq) const {
;     ...
;             const float g1 = dpp_ror1((fr == 15) ? g_pm : g_cur), g2 = dpp_ror2((fr >= 14) ? g_pm : g_cur);
;             const float v1 = dpp_ror1((fr == 15) ? v_pm : v_cur), v2 = dpp_ror2((fr >= 14) ? v_pm : v_cur);
	v_mov_b32_dpp v168, v121 row_ror:2 row_mask:0xf bank_mask:0xf

; __device__ __forceinline__ float dpp_ror1(float v) { return __int_as_float(__builtin_amdgcn_update_dpp(0, __float_as_int(v), 0x121, 0xf, 0xf, false)); }
; __device__ __forceinline__ float dpp_ror2(float v) { return __int_as_float(__builtin_amdgcn_update_dpp(0, __float_as_int(v), 0x122, 0xf, 0xf, false)); }
;   __device__ __forceinline__ void operator()(const AccT& acc, const Unit& u, int wr, int wc, int fr, int fq) const {
;     ...
;         for (int m = 0; m < 4; ++m) { xg[m] = acc[ai][0][m][n] * rs[m]; xv[m] = acc[ai][1][m][n] * rs[m]; }
;         if (fr < 2) {
;           float* d = ub + ((size_t)(chunk * 4 + fr) * NUP + gc);
;           *(float4*)d = make_float4(xg[0][0], xg[0][1], xg[0][2], xg[0][3]);
;           *(float4*)(d + 128) = make_float4(xv[0][0], xv[0][1], xv[0][2], xv[0][3]);
;         }
;         if (fr >= 14) {
;           float* d = ub + ((size_t)(chunk * 4 + 2 + (fr - 14)) * NUP + gc);
;           *(float4*)d = make_float4(xg[3][0], xg[3][1], xg[3][2], xg[3][3]);
;           *(float4*)(d + 128) = make_float4(xv[3][0], xv[3][1], xv[3][2], xv[3][3]);
;         }
; #pragma unroll
;         for (int m = 0; m < 4; ++m) {
;           f32x4 res;
; #pragma unroll
;           for (int r = 0; r < 4; ++r) {
;             const float g_cur = xg[m][r], v_cur = xv[m][r];
;             const f32x4 xgp = xg[m > 0 ? m - 1 : 0], xvp = xv[m > 0 ? m - 1 : 0];
;             const float g_pm = (m > 0) ? xgp[r] : 0.f, v_pm = (m > 0) ? xvp[r] : 0.f;
;             const float g1 = dpp_ror1((fr == 15) ? g_pm : g_cur), g2 = dpp_ror2((fr >= 14) ? g_pm : g_cur);
;             const float v1 = dpp_ror1((fr == 15) ? v_pm : v_cur), v2 = dpp_ror2((fr >= 14) ? v_pm : v_cur);
	v_pk_mul_f32 v[112:113], v[112:113], v[222:223] op_sel_hi:[1,0]
	v_pk_mul_f32 v[114:115], v[114:115], v[222:223] op_sel_hi:[1,0]
	v_mov_b32_dpp v121, v123 row_ror:1 row_mask:0xf bank_mask:0xf


; __device__ __forceinline__ float dpp_ror1(float v) { return __int_as_float(__builtin_amdgcn_update_dpp(0, __float_as_int(v), 0x121, 0xf, 0xf, false)); }
; __device__ __forceinline__ float dpp_ror2(float v) { return __int_as_float(__builtin_amdgcn_update_dpp(0, __float_as_int(v), 0x122, 0xf, 0xf, false)); }
;   __device__ __forceinline__ void operator()(const AccT& acc, const Unit& u, int wr, int wc, int fr, int fq) const {
;     ...
;         for (int m = 0; m < 4; ++m) { xg[m] = acc[ai][0][m][n] * rs[m]; xv[m] = acc[ai][1][m][n] * rs[m]; }
;         if (fr < 2) {
;           float* d = ub + ((size_t)(chunk * 4 + fr) * NUP + gc);
;           *(float4*)d = make_float4(xg[0][0], xg[0][1], xg[0][2], xg[0][3]);
;           *(float4*)(d + 128) = make_float4(xv[0][0], xv[0][1], xv[0][2], xv[0][3]);
;         }
;         if (fr >= 14) {
;           float* d = ub + ((size_t)(chunk * 4 + 2 + (fr - 14)) * NUP + gc);
;           *(float4*)d = make_float4(xg[3][0], xg[3][1], xg[3][2], xg[3][3]);
;           *(float4*)(d + 128) = make_float4(xv[3][0], xv[3][1], xv[3][2], xv[3][3]);
;         }
; #pragma unroll
;         for (int m = 0; m < 4; ++m) {
;           f32x4 res;
; #pragma unroll
;           for (int r = 0; r < 4; ++r) {
;             const float g_cur = xg[m][r], v_cur = xv[m][r];
;             const f32x4 xgp = xg[m > 0 ? m - 1 : 0], xvp = xv[m > 0 ? m - 1 : 0];
;             const float g_pm = (m > 0) ? xgp[r] : 0.f, v_pm = (m > 0) ? xvp[r] : 0.f;
;             const float g1 = dpp_ror1((fr == 15) ? g_pm : g_cur), g2 = dpp_ror2((fr >= 14) ? g_pm : g_cur);
;             const float v1 = dpp_ror1((fr == 15) ? v_pm : v_cur), v2 = dpp_ror2((fr >= 14) ? v_pm : v_cur);
;             const float cg_ = bg[r] + g2 * wg0[r] + g1 * wg1[r] + g_cur * wg2[r];
;             const float cv_ = bv[r] + v2 * wv0[r] + v1 * wv1[r] + v_cur * wv2[r];
	v_mov_b32_e32 v219, v218
	v_mov_b32_dpp v123, v173 row_ror:2 row_mask:0xf bank_mask:0xf
	v_pk_fma_f32 v[122:123], v[148:149], v[122:123], v[160:161]

; __device__ __forceinline__ float dpp_ror1(float v) { return __int_as_float(__builtin_amdgcn_update_dpp(0, __float_as_int(v), 0x121, 0xf, 0xf, false)); }
; __device__ __forceinline__ float dpp_ror2(float v) { return __int_as_float(__builtin_amdgcn_update_dpp(0, __float_as_int(v), 0x122, 0xf, 0xf, false)); }
;   __device__ __forceinline__ void operator()(const AccT& acc, const Unit& u, int wr, int wc, int fr, int fq) const {
;     ...
;             const float g1 = dpp_ror1((fr == 15) ? g_pm : g_cur), g2 = dpp_ror2((fr >= 14) ? g_pm : g_cur);
;             const float v1 = dpp_ror1((fr == 15) ? v_pm : v_cur), v2 = dpp_ror2((fr >= 14) ? v_pm : v_cur);
;             const float cg_ = bg[r] + g2 * wg0[r] + g1 * wg1[r] + g_cur * wg2[r];
;             const float cv_ = bv[r] + v2 * wv0[r] + v1 * wv1[r] + v_cur * wv2[r];
;             res[r] = cg_ * __builtin_amdgcn_rcpf(1.f + __builtin_amdgcn_exp2f(-1.4426950408889634f * cg_)) * cv_;
	v_pk_fma_f32 v[120:121], v[152:153], v[120:121], v[122:123]
	v_pk_mul_f32 v[108:109], v[108:109], v[218:219]
	v_pk_fma_f32 v[120:121], v[156:157], v[124:125], v[120:121]
	v_mov_b32_dpp v173, v195 row_ror:1 row_mask:0xf bank_mask:0xf
	v_mul_f32_e32 v122, 0xbfb8aa3b, v120
	v_mul_f32_e32 v123, 0xbfb8aa3b, v121
	v_exp_f32_e32 v122, v122
	v_exp_f32_e32 v123, v123
	v_cndmask_b32_e64 v195, v233, v169, s[6:7]

; __device__ __forceinline__ float dpp_ror1(float v) { return __int_as_float(__builtin_amdgcn_update_dpp(0, __float_as_int(v), 0x121, 0xf, 0xf, false)); }
; __device__ __forceinline__ float dpp_ror2(float v) { return __int_as_float(__builtin_amdgcn_update_dpp(0, __float_as_int(v), 0x122, 0xf, 0xf, false)); }
;   __device__ __forceinline__ void operator()(const AccT& acc, const Unit& u, int wr, int wc, int fr, int fq) const {
;     ...
;             const f32x4 xgp = xg[m > 0 ? m - 1 : 0], xvp = xv[m > 0 ? m - 1 : 0];
;             const float g_pm = (m > 0) ? xgp[r] : 0.f, v_pm = (m > 0) ? xvp[r] : 0.f;
;             const float g1 = dpp_ror1((fr == 15) ? g_pm : g_cur), g2 = dpp_ror2((fr >= 14) ? g_pm : g_cur);
;             const float v1 = dpp_ror1((fr == 15) ? v_pm : v_cur), v2 = dpp_ror2((fr >= 14) ? v_pm : v_cur);
;             const float cg_ = bg[r] + g2 * wg0[r] + g1 * wg1[r] + g_cur * wg2[r];
;             const float cv_ = bv[r] + v2 * wv0[r] + v1 * wv1[r] + v_cur * wv2[r];
;             res[r] = cg_ * __builtin_amdgcn_rcpf(1.f + __builtin_amdgcn_exp2f(-1.4426950408889634f * cg_)) * cv_;
	v_add_f32_e32 v122, 1.0, v122
	v_add_f32_e32 v123, 1.0, v123
	v_mov_b32_dpp v169, v195 row_ror:2 row_mask:0xf bank_mask:0xf
	v_cndmask_b32_e64 v195, v126, v174, s[8:9]
	v_rcp_f32_e32 v122, v122
	v_rcp_f32_e32 v123, v123
	v_mov_b32_dpp v234, v195 row_ror:1 row_mask:0xf bank_mask:0xf
	v_cndmask_b32_e64 v195, v126, v174, s[6:7]

; __device__ __forceinline__ float dpp_ror1(float v) { return __int_as_float(__builtin_amdgcn_update_dpp(0, __float_as_int(v), 0x121, 0xf, 0xf, false)); }
; __device__ __forceinline__ float dpp_ror2(float v) { return __int_as_float(__builtin_amdgcn_update_dpp(0, __float_as_int(v), 0x122, 0xf, 0xf, false)); }
;   __device__ __forceinline__ void operator()(const AccT& acc, const Unit& u, int wr, int wc, int fr, int fq) const {
;     ...
;             const f32x4 xgp = xg[m > 0 ? m - 1 : 0], xvp = xv[m > 0 ? m - 1 : 0];
;             const float g_pm = (m > 0) ? xgp[r] : 0.f, v_pm = (m > 0) ? xvp[r] : 0.f;
;             const float g1 = dpp_ror1((fr == 15) ? g_pm : g_cur), g2 = dpp_ror2((fr >= 14) ? g_pm : g_cur);
;             const float v1 = dpp_ror1((fr == 15) ? v_pm : v_cur), v2 = dpp_ror2((fr >= 14) ? v_pm : v_cur);
;             const float cg_ = bg[r] + g2 * wg0[r] + g1 * wg1[r] + g_cur * wg2[r];
;             const float cv_ = bv[r] + v2 * wv0[r] + v1 * wv1[r] + v_cur * wv2[r];
;             res[r] = cg_ * __builtin_amdgcn_rcpf(1.f + __builtin_amdgcn_exp2f(-1.4426950408889634f * cg_)) * cv_;
	v_pk_mul_f32 v[120:121], v[120:121], v[122:123]
	v_pk_fma_f32 v[168:169], v[128:129], v[168:169], v[144:145]
	v_mov_b32_dpp v174, v195 row_ror:2 row_mask:0xf bank_mask:0xf
	v_cndmask_b32_e64 v195, v230, v170, s[8:9]
	v_pk_fma_f32 v[168:169], v[136:137], v[172:173], v[168:169]
	v_pk_mul_f32 v[104:105], v[104:105], v[218:219]
	v_mov_b32_dpp v236, v195 row_ror:1 row_mask:0xf bank_mask:0xf
	v_cndmask_b32_e64 v195, v230, v170, s[6:7]

; __device__ __forceinline__ float dpp_ror1(float v) { return __int_as_float(__builtin_amdgcn_update_dpp(0, __float_as_int(v), 0x121, 0xf, 0xf, false)); }
; __device__ __forceinline__ float dpp_ror2(float v) { return __int_as_float(__builtin_amdgcn_update_dpp(0, __float_as_int(v), 0x122, 0xf, 0xf, false)); }
;   __device__ __forceinline__ void operator()(const AccT& acc, const Unit& u, int wr, int wc, int fr, int fq) const {
;     ...
;             const f32x4 xgp = xg[m > 0 ? m - 1 : 0], xvp = xv[m > 0 ? m - 1 : 0];
;             const float g_pm = (m > 0) ? xgp[r] : 0.f, v_pm = (m > 0) ? xvp[r] : 0.f;
;             const float g1 = dpp_ror1((fr == 15) ? g_pm : g_cur), g2 = dpp_ror2((fr >= 14) ? g_pm : g_cur);
;             const float v1 = dpp_ror1((fr == 15) ? v_pm : v_cur), v2 = dpp_ror2((fr >= 14) ? v_pm : v_cur);
;             const float cg_ = bg[r] + g2 * wg0[r] + g1 * wg1[r] + g_cur * wg2[r];
;             const float cv_ = bv[r] + v2 * wv0[r] + v1 * wv1[r] + v_cur * wv2[r];
;             res[r] = cg_ * __builtin_amdgcn_rcpf(1.f + __builtin_amdgcn_exp2f(-1.4426950408889634f * cg_)) * cv_;
	v_pk_fma_f32 v[168:169], v[132:133], v[232:233], v[168:169]
	s_nop 0
	v_mov_b32_dpp v170, v195 row_ror:2 row_mask:0xf bank_mask:0xf
	v_cndmask_b32_e64 v195, v127, v175, s[8:9]
	v_pk_mul_f32 v[120:121], v[168:169], v[120:121]
	s_nop 0
	v_mov_b32_dpp v235, v195 row_ror:1 row_mask:0xf bank_mask:0xf
	v_cndmask_b32_e64 v195, v127, v175, s[6:7]

; __device__ __forceinline__ uint2 pack4(f32x4 v) { return make_uint2(pack2(v[0], v[1]), pack2(v[2], v[3])); }
; __device__ __forceinline__ float dpp_ror1(float v) { return __int_as_float(__builtin_amdgcn_update_dpp(0, __float_as_int(v), 0x121, 0xf, 0xf, false)); }
; __device__ __forceinline__ float dpp_ror2(float v) { return __int_as_float(__builtin_amdgcn_update_dpp(0, __float_as_int(v), 0x122, 0xf, 0xf, false)); }
;   __device__ __forceinline__ void operator()(const AccT& acc, const Unit& u, int wr, int wc, int fr, int fq) const {
;     ...
;             const float g1 = dpp_ror1((fr == 15) ? g_pm : g_cur), g2 = dpp_ror2((fr >= 14) ? g_pm : g_cur);
;             const float v1 = dpp_ror1((fr == 15) ? v_pm : v_cur), v2 = dpp_ror2((fr >= 14) ? v_pm : v_cur);
;             const float cg_ = bg[r] + g2 * wg0[r] + g1 * wg1[r] + g_cur * wg2[r];
;             const float cv_ = bv[r] + v2 * wv0[r] + v1 * wv1[r] + v_cur * wv2[r];
;             res[r] = cg_ * __builtin_amdgcn_rcpf(1.f + __builtin_amdgcn_exp2f(-1.4426950408889634f * cg_)) * cv_;
;           }
;           if (m > 0 || fr >= 2)
;             *(uint2*)(act + (size_t)EPI_ROW(u, ai, m) * DFF + f0) = pack4(res);
	v_cvt_pk_bf16_f32 v120, v120, v121
	s_nop 0
	v_mov_b32_dpp v175, v195 row_ror:2 row_mask:0xf bank_mask:0xf
	v_pk_fma_f32 v[122:123], v[150:151], v[174:175], v[162:163]
	v_cndmask_b32_e64 v195, v231, v171, s[8:9]
	v_pk_fma_f32 v[122:123], v[154:155], v[234:235], v[122:123]

; __device__ __forceinline__ float dpp_ror1(float v) { return __int_as_float(__builtin_amdgcn_update_dpp(0, __float_as_int(v), 0x121, 0xf, 0xf, false)); }
; __device__ __forceinline__ float dpp_ror2(float v) { return __int_as_float(__builtin_amdgcn_update_dpp(0, __float_as_int(v), 0x122, 0xf, 0xf, false)); }
;   __device__ __forceinline__ void operator()(const AccT& acc, const Unit& u, int wr, int wc, int fr, int fq) const {
;     ...
;             const float g1 = dpp_ror1((fr == 15) ? g_pm : g_cur), g2 = dpp_ror2((fr >= 14) ? g_pm : g_cur);
;             const float v1 = dpp_ror1((fr == 15) ? v_pm : v_cur), v2 = dpp_ror2((fr >= 14) ? v_pm : v_cur);
;             const float cg_ = bg[r] + g2 * wg0[r] + g1 * wg1[r] + g_cur * wg2[r];
;             const float cv_ = bv[r] + v2 * wv0[r] + v1 * wv1[r] + v_cur * wv2[r];
;             res[r] = cg_ * __builtin_amdgcn_rcpf(1.f + __builtin_amdgcn_exp2f(-1.4426950408889634f * cg_)) * cv_;
	v_pk_fma_f32 v[122:123], v[158:159], v[126:127], v[122:123]
	v_mov_b32_dpp v237, v195 row_ror:1 row_mask:0xf bank_mask:0xf
	v_mul_f32_e32 v172, 0xbfb8aa3b, v122
	v_mul_f32_e32 v173, 0xbfb8aa3b, v123
	v_exp_f32_e32 v172, v172
	v_exp_f32_e32 v173, v173
	v_cndmask_b32_e64 v195, v231, v171, s[6:7]

; __device__ __forceinline__ float dpp_ror1(float v) { return __int_as_float(__builtin_amdgcn_update_dpp(0, __float_as_int(v), 0x121, 0xf, 0xf, false)); }
; __device__ __forceinline__ float dpp_ror2(float v) { return __int_as_float(__builtin_amdgcn_update_dpp(0, __float_as_int(v), 0x122, 0xf, 0xf, false)); }
;   __device__ __forceinline__ void operator()(const AccT& acc, const Unit& u, int wr, int wc, int fr, int fq) const {
;     ...
;             const float g1 = dpp_ror1((fr == 15) ? g_pm : g_cur), g2 = dpp_ror2((fr >= 14) ? g_pm : g_cur);
;             const float v1 = dpp_ror1((fr == 15) ? v_pm : v_cur), v2 = dpp_ror2((fr >= 14) ? v_pm : v_cur);
;             const float cg_ = bg[r] + g2 * wg0[r] + g1 * wg1[r] + g_cur * wg2[r];
;             const float cv_ = bv[r] + v2 * wv0[r] + v1 * wv1[r] + v_cur * wv2[r];
;             res[r] = cg_ * __builtin_amdgcn_rcpf(1.f + __builtin_amdgcn_exp2f(-1.4426950408889634f * cg_)) * cv_;
	v_add_f32_e32 v168, 1.0, v172
	v_add_f32_e32 v169, 1.0, v173
	v_rcp_f32_e32 v168, v168
	v_rcp_f32_e32 v169, v169
	v_mov_b32_dpp v171, v195 row_ror:2 row_mask:0xf bank_mask:0xf
	v_pk_fma_f32 v[170:171], v[130:131], v[170:171], v[146:147]

; __device__ __forceinline__ uint2 pack4(f32x4 v) { return make_uint2(pack2(v[0], v[1]), pack2(v[2], v[3])); }
; __device__ __forceinline__ float dpp_ror1(float v) { return __int_as_float(__builtin_amdgcn_update_dpp(0, __float_as_int(v), 0x121, 0xf, 0xf, false)); }
; __device__ __forceinline__ float dpp_ror2(float v) { return __int_as_float(__builtin_amdgcn_update_dpp(0, __float_as_int(v), 0x122, 0xf, 0xf, false)); }
;   __device__ __forceinline__ void operator()(const AccT& acc, const Unit& u, int wr, int wc, int fr, int fq) const {
;     ...
;             const float g1 = dpp_ror1((fr == 15) ? g_pm : g_cur), g2 = dpp_ror2((fr >= 14) ? g_pm : g_cur);
;             const float v1 = dpp_ror1((fr == 15) ? v_pm : v_cur), v2 = dpp_ror2((fr >= 14) ? v_pm : v_cur);
;             const float cg_ = bg[r] + g2 * wg0[r] + g1 * wg1[r] + g_cur * wg2[r];
;             const float cv_ = bv[r] + v2 * wv0[r] + v1 * wv1[r] + v_cur * wv2[r];
;             res[r] = cg_ * __builtin_amdgcn_rcpf(1.f + __builtin_amdgcn_exp2f(-1.4426950408889634f * cg_)) * cv_;
;           }
;           if (m > 0 || fr >= 2)
;             *(uint2*)(act + (size_t)EPI_ROW(u, ai, m) * DFF + f0) = pack4(res);
	v_pk_fma_f32 v[170:171], v[138:139], v[236:237], v[170:171]
	v_pk_mul_f32 v[122:123], v[122:123], v[168:169]
	v_pk_fma_f32 v[170:171], v[134:135], v[230:231], v[170:171]
	v_lshlrev_b64 v[168:169], 1, v[188:189]
	v_pk_mul_f32 v[122:123], v[170:171], v[122:123]
	v_cndmask_b32_e64 v173, v119, v125, s[8:9]
	v_cvt_pk_bf16_f32 v121, v122, v123
	v_mov_b64_e32 v[122:123], s[52:53]
	v_mad_i64_i32 v[170:171], s[12:13], v228, s88, v[122:123]
	v_lshl_add_u64 v[170:171], v[170:171], 0, v[168:169]
	global_store_dwordx2 v[170:171], v[120:121], off
	v_cndmask_b32_e64 v121, v118, v124, s[8:9]

; __device__ __forceinline__ float dpp_ror1(float v) { return __int_as_float(__builtin_amdgcn_update_dpp(0, __float_as_int(v), 0x121, 0xf, 0xf, false)); }
; __device__ __forceinline__ float dpp_ror2(float v) { return __int_as_float(__builtin_amdgcn_update_dpp(0, __float_as_int(v), 0x122, 0xf, 0xf, false)); }
;   __device__ __forceinline__ void operator()(const AccT& acc, const Unit& u, int wr, int wc, int fr, int fq) const {
;     ...
;             const float g1 = dpp_ror1((fr == 15) ? g_pm : g_cur), g2 = dpp_ror2((fr >= 14) ? g_pm : g_cur);
;             const float v1 = dpp_ror1((fr == 15) ? v_pm : v_cur), v2 = dpp_ror2((fr >= 14) ? v_pm : v_cur);
	v_cndmask_b32_e64 v175, v113, v233, s[8:9]
	v_cndmask_b32_e64 v195, v113, v233, s[6:7]
	v_mov_b32_dpp v120, v121 row_ror:1 row_mask:0xf bank_mask:0xf
	v_cndmask_b32_e64 v121, v118, v124, s[6:7]
	s_nop 0
	s_nop 0

; __device__ __forceinline__ float dpp_ror1(float v) { return __int_as_float(__builtin_amdgcn_update_dpp(0, __float_as_int(v), 0x121, 0xf, 0xf, false)); }
; __device__ __forceinline__ float dpp_ror2(float v) { return __int_as_float(__builtin_amdgcn_update_dpp(0, __float_as_int(v), 0x122, 0xf, 0xf, false)); }
;   __device__ __forceinline__ void operator()(const AccT& acc, const Unit& u, int wr, int wc, int fr, int fq) const {
;     ...
;             const float g1 = dpp_ror1((fr == 15) ? g_pm : g_cur), g2 = dpp_ror2((fr >= 14) ? g_pm : g_cur);
;             const float v1 = dpp_ror1((fr == 15) ? v_pm : v_cur), v2 = dpp_ror2((fr >= 14) ? v_pm : v_cur);
	v_mov_b32_dpp v124, v121 row_ror:2 row_mask:0xf bank_mask:0xf
	v_cndmask_b32_e64 v121, v112, v232, s[8:9]
	s_nop 1
	v_mov_b32_dpp v172, v121 row_ror:1 row_mask:0xf bank_mask:0xf
	v_cndmask_b32_e64 v121, v112, v232, s[6:7]
	s_nop 0
	s_nop 0
	v_mov_b32_dpp v174, v121 row_ror:2 row_mask:0xf bank_mask:0xf

; __device__ __forceinline__ float dpp_ror1(float v) { return __int_as_float(__builtin_amdgcn_update_dpp(0, __float_as_int(v), 0x121, 0xf, 0xf, false)); }
; __device__ __forceinline__ float dpp_ror2(float v) { return __int_as_float(__builtin_amdgcn_update_dpp(0, __float_as_int(v), 0x122, 0xf, 0xf, false)); }
;   __device__ __forceinline__ void operator()(const AccT& acc, const Unit& u, int wr, int wc, int fr, int fq) const {
;     ...
;             const float g1 = dpp_ror1((fr == 15) ? g_pm : g_cur), g2 = dpp_ror2((fr >= 14) ? g_pm : g_cur);
;             const float v1 = dpp_ror1((fr == 15) ? v_pm : v_cur), v2 = dpp_ror2((fr >= 14) ? v_pm : v_cur);
	s_nop 1
	v_mov_b32_dpp v121, v173 row_ror:1 row_mask:0xf bank_mask:0xf
	v_cndmask_b32_e64 v173, v119, v125, s[6:7]

; __device__ __forceinline__ float dpp_ror1(float v) { return __int_as_float(__builtin_amdgcn_update_dpp(0, __float_as_int(v), 0x121, 0xf, 0xf, false)); }
; __device__ __forceinline__ float dpp_ror2(float v) { return __int_as_float(__builtin_amdgcn_update_dpp(0, __float_as_int(v), 0x122, 0xf, 0xf, false)); }
;   __device__ __forceinline__ void operator()(const AccT& acc, const Unit& u, int wr, int wc, int fr, int fq) const {
;     ...
;             const float g1 = dpp_ror1((fr == 15) ? g_pm : g_cur), g2 = dpp_ror2((fr >= 14) ? g_pm : g_cur);
;             const float v1 = dpp_ror1((fr == 15) ? v_pm : v_cur), v2 = dpp_ror2((fr >= 14) ? v_pm : v_cur);
;             const float cg_ = bg[r] + g2 * wg0[r] + g1 * wg1[r] + g_cur * wg2[r];
;             const float cv_ = bv[r] + v2 * wv0[r] + v1 * wv1[r] + v_cur * wv2[r];
	s_nop 1
	v_mov_b32_dpp v125, v173 row_ror:2 row_mask:0xf bank_mask:0xf
	v_pk_fma_f32 v[124:125], v[148:149], v[124:125], v[160:161]

;   __device__ __forceinline__ void operator()(const AccT& acc, const Unit& u, int wr, int wc, int fr, int fq) const {
;     ...
;             const float cg_ = bg[r] + g2 * wg0[r] + g1 * wg1[r] + g_cur * wg2[r];
;             const float cv_ = bv[r] + v2 * wv0[r] + v1 * wv1[r] + v_cur * wv2[r];
;             res[r] = cg_ * __builtin_amdgcn_rcpf(1.f + __builtin_amdgcn_exp2f(-1.4426950408889634f * cg_)) * cv_;
	v_pk_fma_f32 v[120:121], v[152:153], v[120:121], v[124:125]
	s_nop 0
	v_pk_fma_f32 v[120:121], v[156:157], v[118:119], v[120:121]
	v_mov_b32_dpp v173, v175 row_ror:1 row_mask:0xf bank_mask:0xf
	v_mul_f32_e32 v124, 0xbfb8aa3b, v120
	v_mul_f32_e32 v125, 0xbfb8aa3b, v121
	v_exp_f32_e32 v124, v124
	v_exp_f32_e32 v125, v125

; __device__ __forceinline__ float dpp_ror1(float v) { return __int_as_float(__builtin_amdgcn_update_dpp(0, __float_as_int(v), 0x121, 0xf, 0xf, false)); }
; __device__ __forceinline__ float dpp_ror2(float v) { return __int_as_float(__builtin_amdgcn_update_dpp(0, __float_as_int(v), 0x122, 0xf, 0xf, false)); }
;   __device__ __forceinline__ void operator()(const AccT& acc, const Unit& u, int wr, int wc, int fr, int fq) const {
;     ...
;             const float g1 = dpp_ror1((fr == 15) ? g_pm : g_cur), g2 = dpp_ror2((fr >= 14) ? g_pm : g_cur);
;             const float v1 = dpp_ror1((fr == 15) ? v_pm : v_cur), v2 = dpp_ror2((fr >= 14) ? v_pm : v_cur);
;             const float cg_ = bg[r] + g2 * wg0[r] + g1 * wg1[r] + g_cur * wg2[r];
;             const float cv_ = bv[r] + v2 * wv0[r] + v1 * wv1[r] + v_cur * wv2[r];
;             res[r] = cg_ * __builtin_amdgcn_rcpf(1.f + __builtin_amdgcn_exp2f(-1.4426950408889634f * cg_)) * cv_;
	v_add_f32_e32 v124, 1.0, v124
	s_nop 0
	v_mov_b32_dpp v175, v195 row_ror:2 row_mask:0xf bank_mask:0xf
	v_cndmask_b32_e64 v195, v116, v126, s[8:9]
	v_add_f32_e32 v125, 1.0, v125
	v_rcp_f32_e32 v124, v124
	v_mov_b32_dpp v228, v195 row_ror:1 row_mask:0xf bank_mask:0xf
	v_cndmask_b32_e64 v195, v116, v126, s[6:7]

; __device__ __forceinline__ float dpp_ror1(float v) { return __int_as_float(__builtin_amdgcn_update_dpp(0, __float_as_int(v), 0x121, 0xf, 0xf, false)); }
; __device__ __forceinline__ float dpp_ror2(float v) { return __int_as_float(__builtin_amdgcn_update_dpp(0, __float_as_int(v), 0x122, 0xf, 0xf, false)); }
;   __device__ __forceinline__ void operator()(const AccT& acc, const Unit& u, int wr, int wc, int fr, int fq) const {
;     ...
;             const float g1 = dpp_ror1((fr == 15) ? g_pm : g_cur), g2 = dpp_ror2((fr >= 14) ? g_pm : g_cur);
;             const float v1 = dpp_ror1((fr == 15) ? v_pm : v_cur), v2 = dpp_ror2((fr >= 14) ? v_pm : v_cur);
;             const float cg_ = bg[r] + g2 * wg0[r] + g1 * wg1[r] + g_cur * wg2[r];
;             const float cv_ = bv[r] + v2 * wv0[r] + v1 * wv1[r] + v_cur * wv2[r];
	v_rcp_f32_e32 v125, v125
	v_pk_fma_f32 v[174:175], v[128:129], v[174:175], v[144:145]
	v_mov_b32_dpp v126, v195 row_ror:2 row_mask:0xf bank_mask:0xf
	v_cndmask_b32_e64 v195, v114, v230, s[8:9]
	v_pk_mul_f32 v[120:121], v[120:121], v[124:125]
	v_pk_fma_f32 v[172:173], v[136:137], v[172:173], v[174:175]
	v_mov_b32_dpp v232, v195 row_ror:1 row_mask:0xf bank_mask:0xf
	v_cndmask_b32_e64 v195, v114, v230, s[6:7]
	s_nop 0
	v_pk_fma_f32 v[172:173], v[132:133], v[112:113], v[172:173]

; __device__ __forceinline__ float dpp_ror1(float v) { return __int_as_float(__builtin_amdgcn_update_dpp(0, __float_as_int(v), 0x121, 0xf, 0xf, false)); }
; __device__ __forceinline__ float dpp_ror2(float v) { return __int_as_float(__builtin_amdgcn_update_dpp(0, __float_as_int(v), 0x122, 0xf, 0xf, false)); }
;   __device__ __forceinline__ void operator()(const AccT& acc, const Unit& u, int wr, int wc, int fr, int fq) const {
;     ...
;             const float g1 = dpp_ror1((fr == 15) ? g_pm : g_cur), g2 = dpp_ror2((fr >= 14) ? g_pm : g_cur);
;             const float v1 = dpp_ror1((fr == 15) ? v_pm : v_cur), v2 = dpp_ror2((fr >= 14) ? v_pm : v_cur);
;             const float cg_ = bg[r] + g2 * wg0[r] + g1 * wg1[r] + g_cur * wg2[r];
;             const float cv_ = bv[r] + v2 * wv0[r] + v1 * wv1[r] + v_cur * wv2[r];
;             res[r] = cg_ * __builtin_amdgcn_rcpf(1.f + __builtin_amdgcn_exp2f(-1.4426950408889634f * cg_)) * cv_;
	v_mov_b32_dpp v230, v195 row_ror:2 row_mask:0xf bank_mask:0xf
	v_cndmask_b32_e64 v195, v117, v127, s[8:9]
	v_pk_mul_f32 v[120:121], v[172:173], v[120:121]
	v_cndmask_b32_e64 v175, v167, v117, s[8:9]
	v_mov_b32_dpp v229, v195 row_ror:1 row_mask:0xf bank_mask:0xf
	v_cndmask_b32_e64 v195, v117, v127, s[6:7]

; __device__ __forceinline__ float dpp_ror1(float v) { return __int_as_float(__builtin_amdgcn_update_dpp(0, __float_as_int(v), 0x121, 0xf, 0xf, false)); }
; __device__ __forceinline__ float dpp_ror2(float v) { return __int_as_float(__builtin_amdgcn_update_dpp(0, __float_as_int(v), 0x122, 0xf, 0xf, false)); }
;   __device__ __forceinline__ void operator()(const AccT& acc, const Unit& u, int wr, int wc, int fr, int fq) const {
;     ...
;             const float g1 = dpp_ror1((fr == 15) ? g_pm : g_cur), g2 = dpp_ror2((fr >= 14) ? g_pm : g_cur);
;             const float v1 = dpp_ror1((fr == 15) ? v_pm : v_cur), v2 = dpp_ror2((fr >= 14) ? v_pm : v_cur);
;             const float cg_ = bg[r] + g2 * wg0[r] + g1 * wg1[r] + g_cur * wg2[r];
;             const float cv_ = bv[r] + v2 * wv0[r] + v1 * wv1[r] + v_cur * wv2[r];
;             res[r] = cg_ * __builtin_amdgcn_rcpf(1.f + __builtin_amdgcn_exp2f(-1.4426950408889634f * cg_)) * cv_;
	v_cvt_pk_bf16_f32 v120, v120, v121
	s_nop 0
	v_mov_b32_dpp v127, v195 row_ror:2 row_mask:0xf bank_mask:0xf
	v_pk_fma_f32 v[124:125], v[150:151], v[126:127], v[162:163]
	v_cndmask_b32_e64 v195, v115, v231, s[8:9]
	v_pk_fma_f32 v[124:125], v[154:155], v[228:229], v[124:125]
	s_nop 0
	v_pk_fma_f32 v[124:125], v[158:159], v[116:117], v[124:125]
	v_mov_b32_dpp v233, v195 row_ror:1 row_mask:0xf bank_mask:0xf
	v_mul_f32_e32 v126, 0xbfb8aa3b, v124
	v_mul_f32_e32 v127, 0xbfb8aa3b, v125
	v_exp_f32_e32 v126, v126
	v_exp_f32_e32 v127, v127
	v_cndmask_b32_e64 v195, v115, v231, s[6:7]

; __device__ __forceinline__ uint2 pack4(f32x4 v) { return make_uint2(pack2(v[0], v[1]), pack2(v[2], v[3])); }
;   __device__ __forceinline__ void operator()(const AccT& acc, const Unit& u, int wr, int wc, int fr, int fq) const {
;     ...
;             const float cg_ = bg[r] + g2 * wg0[r] + g1 * wg1[r] + g_cur * wg2[r];
;             const float cv_ = bv[r] + v2 * wv0[r] + v1 * wv1[r] + v_cur * wv2[r];
;             res[r] = cg_ * __builtin_amdgcn_rcpf(1.f + __builtin_amdgcn_exp2f(-1.4426950408889634f * cg_)) * cv_;
;           }
;           if (m > 0 || fr >= 2)
;             *(uint2*)(act + (size_t)EPI_ROW(u, ai, m) * DFF + f0) = pack4(res);
	v_add_f32_e32 v126, 1.0, v126
	v_add_f32_e32 v127, 1.0, v127
	v_rcp_f32_e32 v126, v126
	v_rcp_f32_e32 v127, v127
	v_mov_b32_dpp v231, v195 row_ror:2 row_mask:0xf bank_mask:0xf
	v_pk_fma_f32 v[172:173], v[130:131], v[230:231], v[146:147]
	v_cndmask_b32_e64 v195, v143, v115, s[8:9]
	v_pk_fma_f32 v[172:173], v[138:139], v[232:233], v[172:173]
	v_pk_mul_f32 v[124:125], v[124:125], v[126:127]
	v_pk_fma_f32 v[172:173], v[134:135], v[114:115], v[172:173]
	v_cndmask_b32_e64 v126, v141, v113, s[8:9]
	v_pk_mul_f32 v[124:125], v[172:173], v[124:125]
	v_cndmask_b32_e64 v127, v166, v116, s[8:9]
	v_cvt_pk_bf16_f32 v121, v124, v125
	v_mad_i64_i32 v[124:125], s[12:13], v226, s88, v[122:123]
	v_lshl_add_u64 v[172:173], v[124:125], 0, v[168:169]
	global_store_dwordx2 v[172:173], v[120:121], off
	v_cndmask_b32_e64 v121, v164, v118, s[8:9]
	s_nop 0

; __device__ __forceinline__ float dpp_ror1(float v) { return __int_as_float(__builtin_amdgcn_update_dpp(0, __float_as_int(v), 0x121, 0xf, 0xf, false)); }
; __device__ __forceinline__ float dpp_ror2(float v) { return __int_as_float(__builtin_amdgcn_update_dpp(0, __float_as_int(v), 0x122, 0xf, 0xf, false)); }
;   __device__ __forceinline__ void operator()(const AccT& acc, const Unit& u, int wr, int wc, int fr, int fq) const {
;     ...
;             const f32x4 xgp = xg[m > 0 ? m - 1 : 0], xvp = xv[m > 0 ? m - 1 : 0];
;             const float g_pm = (m > 0) ? xgp[r] : 0.f, v_pm = (m > 0) ? xvp[r] : 0.f;
;             const float g1 = dpp_ror1((fr == 15) ? g_pm : g_cur), g2 = dpp_ror2((fr >= 14) ? g_pm : g_cur);
;             const float v1 = dpp_ror1((fr == 15) ? v_pm : v_cur), v2 = dpp_ror2((fr >= 14) ? v_pm : v_cur);
	v_cndmask_b32_e64 v125, v165, v119, s[8:9]
	v_mov_b32_dpp v120, v121 row_ror:1 row_mask:0xf bank_mask:0xf
	v_cndmask_b32_e64 v121, v164, v118, s[6:7]

; __device__ __forceinline__ float dpp_ror1(float v) { return __int_as_float(__builtin_amdgcn_update_dpp(0, __float_as_int(v), 0x121, 0xf, 0xf, false)); }
; __device__ __forceinline__ float dpp_ror2(float v) { return __int_as_float(__builtin_amdgcn_update_dpp(0, __float_as_int(v), 0x122, 0xf, 0xf, false)); }
;   __device__ __forceinline__ void operator()(const AccT& acc, const Unit& u, int wr, int wc, int fr, int fq) const {
;     ...
;             const float g1 = dpp_ror1((fr == 15) ? g_pm : g_cur), g2 = dpp_ror2((fr >= 14) ? g_pm : g_cur);
;             const float v1 = dpp_ror1((fr == 15) ? v_pm : v_cur), v2 = dpp_ror2((fr >= 14) ? v_pm : v_cur);
	s_nop 1
	v_mov_b32_dpp v118, v121 row_ror:2 row_mask:0xf bank_mask:0xf
	v_cndmask_b32_e64 v121, v140, v112, s[8:9]
	s_nop 1
	v_mov_b32_dpp v124, v121 row_ror:1 row_mask:0xf bank_mask:0xf
	v_cndmask_b32_e64 v121, v140, v112, s[6:7]

; __device__ __forceinline__ float dpp_ror1(float v) { return __int_as_float(__builtin_amdgcn_update_dpp(0, __float_as_int(v), 0x121, 0xf, 0xf, false)); }
; __device__ __forceinline__ float dpp_ror2(float v) { return __int_as_float(__builtin_amdgcn_update_dpp(0, __float_as_int(v), 0x122, 0xf, 0xf, false)); }
;   __device__ __forceinline__ void operator()(const AccT& acc, const Unit& u, int wr, int wc, int fr, int fq) const {
;     ...
;             const float g1 = dpp_ror1((fr == 15) ? g_pm : g_cur), g2 = dpp_ror2((fr >= 14) ? g_pm : g_cur);
;             const float v1 = dpp_ror1((fr == 15) ? v_pm : v_cur), v2 = dpp_ror2((fr >= 14) ? v_pm : v_cur);
	s_nop 1
	v_mov_b32_dpp v112, v121 row_ror:2 row_mask:0xf bank_mask:0xf

; __device__ __forceinline__ float dpp_ror1(float v) { return __int_as_float(__builtin_amdgcn_update_dpp(0, __float_as_int(v), 0x121, 0xf, 0xf, false)); }
; __device__ __forceinline__ float dpp_ror2(float v) { return __int_as_float(__builtin_amdgcn_update_dpp(0, __float_as_int(v), 0x122, 0xf, 0xf, false)); }
;   __device__ __forceinline__ void operator()(const AccT& acc, const Unit& u, int wr, int wc, int fr, int fq) const {
;     ...
;             const float v1 = dpp_ror1((fr == 15) ? v_pm : v_cur), v2 = dpp_ror2((fr >= 14) ? v_pm : v_cur);
	s_nop 1
	v_mov_b32_dpp v121, v125 row_ror:1 row_mask:0xf bank_mask:0xf
	v_cndmask_b32_e64 v125, v165, v119, s[6:7]

; __device__ __forceinline__ float dpp_ror1(float v) { return __int_as_float(__builtin_amdgcn_update_dpp(0, __float_as_int(v), 0x121, 0xf, 0xf, false)); }
; __device__ __forceinline__ float dpp_ror2(float v) { return __int_as_float(__builtin_amdgcn_update_dpp(0, __float_as_int(v), 0x122, 0xf, 0xf, false)); }
;   __device__ __forceinline__ void operator()(const AccT& acc, const Unit& u, int wr, int wc, int fr, int fq) const {
;     ...
;             const float v1 = dpp_ror1((fr == 15) ? v_pm : v_cur), v2 = dpp_ror2((fr >= 14) ? v_pm : v_cur);
;             const float cg_ = bg[r] + g2 * wg0[r] + g1 * wg1[r] + g_cur * wg2[r];
;             const float cv_ = bv[r] + v2 * wv0[r] + v1 * wv1[r] + v_cur * wv2[r];
	s_nop 1
	v_mov_b32_dpp v119, v125 row_ror:2 row_mask:0xf bank_mask:0xf
	v_pk_fma_f32 v[118:119], v[148:149], v[118:119], v[160:161]

; __device__ __forceinline__ float dpp_ror1(float v) { return __int_as_float(__builtin_amdgcn_update_dpp(0, __float_as_int(v), 0x121, 0xf, 0xf, false)); }
; __device__ __forceinline__ float dpp_ror2(float v) { return __int_as_float(__builtin_amdgcn_update_dpp(0, __float_as_int(v), 0x122, 0xf, 0xf, false)); }
;   __device__ __forceinline__ void operator()(const AccT& acc, const Unit& u, int wr, int wc, int fr, int fq) const {
;     ...
;             const float g1 = dpp_ror1((fr == 15) ? g_pm : g_cur), g2 = dpp_ror2((fr >= 14) ? g_pm : g_cur);
;             const float v1 = dpp_ror1((fr == 15) ? v_pm : v_cur), v2 = dpp_ror2((fr >= 14) ? v_pm : v_cur);
;             const float cg_ = bg[r] + g2 * wg0[r] + g1 * wg1[r] + g_cur * wg2[r];
	v_pk_fma_f32 v[118:119], v[152:153], v[120:121], v[118:119]
	s_nop 0
	v_mov_b32_dpp v125, v126 row_ror:1 row_mask:0xf bank_mask:0xf
	v_cndmask_b32_e64 v126, v141, v113, s[6:7]

; __device__ __forceinline__ float dpp_ror1(float v) { return __int_as_float(__builtin_amdgcn_update_dpp(0, __float_as_int(v), 0x121, 0xf, 0xf, false)); }
; __device__ __forceinline__ float dpp_ror2(float v) { return __int_as_float(__builtin_amdgcn_update_dpp(0, __float_as_int(v), 0x122, 0xf, 0xf, false)); }
;   __device__ __forceinline__ void operator()(const AccT& acc, const Unit& u, int wr, int wc, int fr, int fq) const {
;     ...
;             const float g1 = dpp_ror1((fr == 15) ? g_pm : g_cur), g2 = dpp_ror2((fr >= 14) ? g_pm : g_cur);
;             const float v1 = dpp_ror1((fr == 15) ? v_pm : v_cur), v2 = dpp_ror2((fr >= 14) ? v_pm : v_cur);
;             const float cg_ = bg[r] + g2 * wg0[r] + g1 * wg1[r] + g_cur * wg2[r];
	v_pk_fma_f32 v[118:119], v[156:157], v[164:165], v[118:119]
	s_nop 0
	v_mov_b32_dpp v113, v126 row_ror:2 row_mask:0xf bank_mask:0xf

; __device__ __forceinline__ float dpp_ror1(float v) { return __int_as_float(__builtin_amdgcn_update_dpp(0, __float_as_int(v), 0x121, 0xf, 0xf, false)); }
; __device__ __forceinline__ float dpp_ror2(float v) { return __int_as_float(__builtin_amdgcn_update_dpp(0, __float_as_int(v), 0x122, 0xf, 0xf, false)); }
;   __device__ __forceinline__ void operator()(const AccT& acc, const Unit& u, int wr, int wc, int fr, int fq) const {
;     ...
;             const float v1 = dpp_ror1((fr == 15) ? v_pm : v_cur), v2 = dpp_ror2((fr >= 14) ? v_pm : v_cur);
;             const float cg_ = bg[r] + g2 * wg0[r] + g1 * wg1[r] + g_cur * wg2[r];
;             const float cv_ = bv[r] + v2 * wv0[r] + v1 * wv1[r] + v_cur * wv2[r];
;             res[r] = cg_ * __builtin_amdgcn_rcpf(1.f + __builtin_amdgcn_exp2f(-1.4426950408889634f * cg_)) * cv_;
	v_mul_f32_e32 v120, 0xbfb8aa3b, v118
	v_mul_f32_e32 v121, 0xbfb8aa3b, v119
	v_mov_b32_dpp v126, v127 row_ror:1 row_mask:0xf bank_mask:0xf
	v_cndmask_b32_e64 v127, v166, v116, s[6:7]

; __device__ __forceinline__ float dpp_ror1(float v) { return __int_as_float(__builtin_amdgcn_update_dpp(0, __float_as_int(v), 0x121, 0xf, 0xf, false)); }
; __device__ __forceinline__ float dpp_ror2(float v) { return __int_as_float(__builtin_amdgcn_update_dpp(0, __float_as_int(v), 0x122, 0xf, 0xf, false)); }
;   __device__ __forceinline__ void operator()(const AccT& acc, const Unit& u, int wr, int wc, int fr, int fq) const {
;     ...
;             const float v1 = dpp_ror1((fr == 15) ? v_pm : v_cur), v2 = dpp_ror2((fr >= 14) ? v_pm : v_cur);
;             const float cg_ = bg[r] + g2 * wg0[r] + g1 * wg1[r] + g_cur * wg2[r];
;             const float cv_ = bv[r] + v2 * wv0[r] + v1 * wv1[r] + v_cur * wv2[r];
;             res[r] = cg_ * __builtin_amdgcn_rcpf(1.f + __builtin_amdgcn_exp2f(-1.4426950408889634f * cg_)) * cv_;
	v_exp_f32_e32 v120, v120
	v_exp_f32_e32 v121, v121
	v_mov_b32_dpp v116, v127 row_ror:2 row_mask:0xf bank_mask:0xf
	v_cndmask_b32_e64 v127, v142, v114, s[8:9]
	v_add_f32_e32 v120, 1.0, v120
	v_add_f32_e32 v121, 1.0, v121
	v_mov_b32_dpp v174, v127 row_ror:1 row_mask:0xf bank_mask:0xf
	v_cndmask_b32_e64 v127, v142, v114, s[6:7]

; __device__ __forceinline__ float dpp_ror1(float v) { return __int_as_float(__builtin_amdgcn_update_dpp(0, __float_as_int(v), 0x121, 0xf, 0xf, false)); }
; __device__ __forceinline__ float dpp_ror2(float v) { return __int_as_float(__builtin_amdgcn_update_dpp(0, __float_as_int(v), 0x122, 0xf, 0xf, false)); }
;   __device__ __forceinline__ void operator()(const AccT& acc, const Unit& u, int wr, int wc, int fr, int fq) const {
;     ...
;             const float v1 = dpp_ror1((fr == 15) ? v_pm : v_cur), v2 = dpp_ror2((fr >= 14) ? v_pm : v_cur);
;             const float cg_ = bg[r] + g2 * wg0[r] + g1 * wg1[r] + g_cur * wg2[r];
;             const float cv_ = bv[r] + v2 * wv0[r] + v1 * wv1[r] + v_cur * wv2[r];
;             res[r] = cg_ * __builtin_amdgcn_rcpf(1.f + __builtin_amdgcn_exp2f(-1.4426950408889634f * cg_)) * cv_;
	v_rcp_f32_e32 v120, v120
	v_rcp_f32_e32 v121, v121
	v_mov_b32_dpp v114, v127 row_ror:2 row_mask:0xf bank_mask:0xf

; __device__ __forceinline__ float dpp_ror1(float v) { return __int_as_float(__builtin_amdgcn_update_dpp(0, __float_as_int(v), 0x121, 0xf, 0xf, false)); }
; __device__ __forceinline__ float dpp_ror2(float v) { return __int_as_float(__builtin_amdgcn_update_dpp(0, __float_as_int(v), 0x122, 0xf, 0xf, false)); }
;   __device__ __forceinline__ void operator()(const AccT& acc, const Unit& u, int wr, int wc, int fr, int fq) const {
;     ...
;             const float v1 = dpp_ror1((fr == 15) ? v_pm : v_cur), v2 = dpp_ror2((fr >= 14) ? v_pm : v_cur);
;             const float cg_ = bg[r] + g2 * wg0[r] + g1 * wg1[r] + g_cur * wg2[r];
;             const float cv_ = bv[r] + v2 * wv0[r] + v1 * wv1[r] + v_cur * wv2[r];
;             res[r] = cg_ * __builtin_amdgcn_rcpf(1.f + __builtin_amdgcn_exp2f(-1.4426950408889634f * cg_)) * cv_;
	v_pk_fma_f32 v[112:113], v[128:129], v[112:113], v[144:145]
	v_pk_mul_f32 v[118:119], v[118:119], v[120:121]
	v_mov_b32_dpp v127, v175 row_ror:1 row_mask:0xf bank_mask:0xf
	v_cndmask_b32_e64 v175, v167, v117, s[6:7]

; __device__ __forceinline__ float dpp_ror1(float v) { return __int_as_float(__builtin_amdgcn_update_dpp(0, __float_as_int(v), 0x121, 0xf, 0xf, false)); }
; __device__ __forceinline__ float dpp_ror2(float v) { return __int_as_float(__builtin_amdgcn_update_dpp(0, __float_as_int(v), 0x122, 0xf, 0xf, false)); }
;   __device__ __forceinline__ void operator()(const AccT& acc, const Unit& u, int wr, int wc, int fr, int fq) const {
;     ...
;             const float v1 = dpp_ror1((fr == 15) ? v_pm : v_cur), v2 = dpp_ror2((fr >= 14) ? v_pm : v_cur);
;             const float cg_ = bg[r] + g2 * wg0[r] + g1 * wg1[r] + g_cur * wg2[r];
;             const float cv_ = bv[r] + v2 * wv0[r] + v1 * wv1[r] + v_cur * wv2[r];
	v_pk_fma_f32 v[112:113], v[136:137], v[124:125], v[112:113]
	s_nop 0
	v_mov_b32_dpp v117, v175 row_ror:2 row_mask:0xf bank_mask:0xf
	v_pk_fma_f32 v[116:117], v[150:151], v[116:117], v[162:163]
	v_pk_fma_f32 v[112:113], v[132:133], v[140:141], v[112:113]
	v_pk_fma_f32 v[116:117], v[154:155], v[126:127], v[116:117]

; __device__ __forceinline__ float dpp_ror1(float v) { return __int_as_float(__builtin_amdgcn_update_dpp(0, __float_as_int(v), 0x121, 0xf, 0xf, false)); }
; __device__ __forceinline__ float dpp_ror2(float v) { return __int_as_float(__builtin_amdgcn_update_dpp(0, __float_as_int(v), 0x122, 0xf, 0xf, false)); }
;   __device__ __forceinline__ void operator()(const AccT& acc, const Unit& u, int wr, int wc, int fr, int fq) const {
;     ...
;             const float v1 = dpp_ror1((fr == 15) ? v_pm : v_cur), v2 = dpp_ror2((fr >= 14) ? v_pm : v_cur);
;             const float cg_ = bg[r] + g2 * wg0[r] + g1 * wg1[r] + g_cur * wg2[r];
;             const float cv_ = bv[r] + v2 * wv0[r] + v1 * wv1[r] + v_cur * wv2[r];
;             res[r] = cg_ * __builtin_amdgcn_rcpf(1.f + __builtin_amdgcn_exp2f(-1.4426950408889634f * cg_)) * cv_;
	v_pk_fma_f32 v[116:117], v[158:159], v[166:167], v[116:117]
	v_pk_mul_f32 v[112:113], v[112:113], v[118:119]
	v_mul_f32_e32 v120, 0xbfb8aa3b, v116
	v_mul_f32_e32 v121, 0xbfb8aa3b, v117
	v_exp_f32_e32 v120, v120
	v_exp_f32_e32 v121, v121
	v_mov_b32_dpp v175, v195 row_ror:1 row_mask:0xf bank_mask:0xf
	v_cndmask_b32_e64 v195, v143, v115, s[6:7]
	v_add_f32_e32 v118, 1.0, v120
	v_add_f32_e32 v119, 1.0, v121

; __device__ __forceinline__ uint2 pack4(f32x4 v) { return make_uint2(pack2(v[0], v[1]), pack2(v[2], v[3])); }
;   __device__ __forceinline__ void operator()(const AccT& acc, const Unit& u, int wr, int wc, int fr, int fq) const {
;     ...
;         const int f0 = 128 * u.pn + 32 * wc + 16 * n + 4 * fq;
;         const int gc = u.pn * 256 + 32 * wc + 16 * n + 4 * fq;
;         const f32x4 wg0 = *(const f32x4*)(cw + f0), wg1 = *(const f32x4*)(cw + NUP + f0), wg2 = *(const f32x4*)(cw + 2 * NUP + f0);
;         const f32x4 wv0 = *(const f32x4*)(cw + DFF + f0), wv1 = *(const f32x4*)(cw + NUP + DFF + f0), wv2 = *(const f32x4*)(cw + 2 * NUP + DFF + f0);
;         const f32x4 bg = *(const f32x4*)(cb + f0), bv = *(const f32x4*)(cb + DFF + f0);
;         f32x4 xg[4], xv[4];
; #pragma unroll
;         for (int m = 0; m < 4; ++m) { xg[m] = acc[ai][0][m][n] * rs[m]; xv[m] = acc[ai][1][m][n] * rs[m]; }
;         if (fr < 2) {
;           float* d = ub + ((size_t)(chunk * 4 + fr) * NUP + gc);
;           *(float4*)d = make_float4(xg[0][0], xg[0][1], xg[0][2], xg[0][3]);
;           *(float4*)(d + 128) = make_float4(xv[0][0], xv[0][1], xv[0][2], xv[0][3]);
;     ...
;             const float cg_ = bg[r] + g2 * wg0[r] + g1 * wg1[r] + g_cur * wg2[r];
;             const float cv_ = bv[r] + v2 * wv0[r] + v1 * wv1[r] + v_cur * wv2[r];
;             res[r] = cg_ * __builtin_amdgcn_rcpf(1.f + __builtin_amdgcn_exp2f(-1.4426950408889634f * cg_)) * cv_;
;           }
;           if (m > 0 || fr >= 2)
;             *(uint2*)(act + (size_t)EPI_ROW(u, ai, m) * DFF + f0) = pack4(res);
	v_rcp_f32_e32 v118, v118
	v_rcp_f32_e32 v119, v119
	v_mov_b32_dpp v115, v195 row_ror:2 row_mask:0xf bank_mask:0xf
	v_pk_fma_f32 v[114:115], v[130:131], v[114:115], v[146:147]
	v_cvt_pk_bf16_f32 v112, v112, v113
	v_pk_fma_f32 v[114:115], v[138:139], v[174:175], v[114:115]
	v_pk_mul_f32 v[116:117], v[116:117], v[118:119]
	v_pk_fma_f32 v[114:115], v[134:135], v[142:143], v[114:115]
	v_mov_b32_e32 v162, v218
	v_pk_mul_f32 v[114:115], v[114:115], v[116:117]
	v_mov_b32_e32 v163, v218
	v_cvt_pk_bf16_f32 v113, v114, v115
	v_mad_i64_i32 v[114:115], s[12:13], v212, s88, v[122:123]
	v_lshl_add_u64 v[160:161], v[114:115], 0, v[168:169]
	global_store_dwordx2 v[160:161], v[112:113], off
	v_or_b32_e32 v112, 16, v188
	v_ashrrev_i32_e32 v113, 31, v112
	v_lshlrev_b64 v[124:125], 2, v[112:113]
	v_lshl_add_u64 v[144:145], s[16:17], 0, v[124:125]
	v_lshl_add_u64 v[148:149], s[24:25], 0, v[124:125]
	v_lshl_add_u64 v[152:153], s[28:29], 0, v[124:125]
	v_lshl_add_u64 v[156:157], s[18:19], 0, v[124:125]
	v_lshl_add_u64 v[146:147], s[22:23], 0, v[124:125]
	global_load_dwordx4 v[128:131], v[144:145], off
	global_load_dwordx4 v[132:135], v[146:147], off
	v_lshl_add_u64 v[150:151], s[26:27], 0, v[124:125]
	global_load_dwordx4 v[136:139], v[148:149], off
	global_load_dwordx4 v[112:115], v[150:151], off
	v_lshl_add_u64 v[154:155], s[30:31], 0, v[124:125]
	global_load_dwordx4 v[120:123], v[152:153], off
	global_load_dwordx4 v[116:119], v[154:155], off
	v_lshl_add_u64 v[158:159], s[34:35], 0, v[124:125]
	global_load_dwordx4 v[140:143], v[156:157], off
	global_load_dwordx4 v[124:127], v[158:159], off
	v_pk_mul_f32 v[110:111], v[110:111], v[162:163]
	v_pk_mul_f32 v[106:107], v[106:107], v[162:163]
	s_and_saveexec_b64 s[12:13], s[4:5]
	s_cbranch_execz .LBB0_1512
	v_lshl_add_u64 v[162:163], v[190:191], 2, v[214:215]
	global_store_dwordx4 v[162:163], v[108:111], off offset:64
	global_store_dwordx4 v[162:163], v[104:107], off offset:576

; __device__ __forceinline__ float dpp_ror1(float v) { return __int_as_float(__builtin_amdgcn_update_dpp(0, __float_as_int(v), 0x121, 0xf, 0xf, false)); }
; __device__ __forceinline__ float dpp_ror2(float v) { return __int_as_float(__builtin_amdgcn_update_dpp(0, __float_as_int(v), 0x122, 0xf, 0xf, false)); }
;   __device__ __forceinline__ void operator()(const AccT& acc, const Unit& u, int wr, int wc, int fr, int fq) const {
;     ...
;         if (fr < 2) {
;           float* d = ub + ((size_t)(chunk * 4 + fr) * NUP + gc);
;           *(float4*)d = make_float4(xg[0][0], xg[0][1], xg[0][2], xg[0][3]);
;           *(float4*)(d + 128) = make_float4(xv[0][0], xv[0][1], xv[0][2], xv[0][3]);
;         }
;         if (fr >= 14) {
;           float* d = ub + ((size_t)(chunk * 4 + 2 + (fr - 14)) * NUP + gc);
;           *(float4*)d = make_float4(xg[3][0], xg[3][1], xg[3][2], xg[3][3]);
;           *(float4*)(d + 128) = make_float4(xv[3][0], xv[3][1], xv[3][2], xv[3][3]);
;         }
; #pragma unroll
;         for (int m = 0; m < 4; ++m) {
;           f32x4 res;
; #pragma unroll
;           for (int r = 0; r < 4; ++r) {
;             const float g_cur = xg[m][r], v_cur = xv[m][r];
;             const f32x4 xgp = xg[m > 0 ? m - 1 : 0], xvp = xv[m > 0 ? m - 1 : 0];
;             const float g_pm = (m > 0) ? xgp[r] : 0.f, v_pm = (m > 0) ? xvp[r] : 0.f;
;             const float g1 = dpp_ror1((fr == 15) ? g_pm : g_cur), g2 = dpp_ror2((fr >= 14) ? g_pm : g_cur);
.LBB0_1514:
	s_or_b64 exec, exec, s[12:13]
	v_cndmask_b32_e64 v175, v108, 0, s[8:9]
	s_nop 0
	s_nop 0

; __device__ __forceinline__ float dpp_ror1(float v) { return __int_as_float(__builtin_amdgcn_update_dpp(0, __float_as_int(v), 0x121, 0xf, 0xf, false)); }
; __device__ __forceinline__ float dpp_ror2(float v) { return __int_as_float(__builtin_amdgcn_update_dpp(0, __float_as_int(v), 0x122, 0xf, 0xf, false)); }
;   __device__ __forceinline__ void operator()(const AccT& acc, const Unit& u, int wr, int wc, int fr, int fq) const {
;     ...
;             const float g1 = dpp_ror1((fr == 15) ? g_pm : g_cur), g2 = dpp_ror2((fr >= 14) ? g_pm : g_cur);
;             const float v1 = dpp_ror1((fr == 15) ? v_pm : v_cur), v2 = dpp_ror2((fr >= 14) ? v_pm : v_cur);
	v_mov_b32_dpp v216, v175 row_ror:1 row_mask:0xf bank_mask:0xf
	v_mov_b32_dpp v218, v174 row_ror:2 row_mask:0xf bank_mask:0xf
	v_cndmask_b32_e64 v175, v104, 0, s[8:9]

; __device__ __forceinline__ float dpp_ror1(float v) { return __int_as_float(__builtin_amdgcn_update_dpp(0, __float_as_int(v), 0x121, 0xf, 0xf, false)); }
; __device__ __forceinline__ float dpp_ror2(float v) { return __int_as_float(__builtin_amdgcn_update_dpp(0, __float_as_int(v), 0x122, 0xf, 0xf, false)); }
;   __device__ __forceinline__ void operator()(const AccT& acc, const Unit& u, int wr, int wc, int fr, int fq) const {
;     ...
;             const float g1 = dpp_ror1((fr == 15) ? g_pm : g_cur), g2 = dpp_ror2((fr >= 14) ? g_pm : g_cur);
;             const float v1 = dpp_ror1((fr == 15) ? v_pm : v_cur), v2 = dpp_ror2((fr >= 14) ? v_pm : v_cur);
	v_mov_b32_dpp v219, v166 row_ror:2 row_mask:0xf bank_mask:0xf
	v_cndmask_b32_e64 v166, v105, 0, s[8:9]
	v_mov_b32_dpp v174, v175 row_ror:1 row_mask:0xf bank_mask:0xf
	s_nop 0


; __device__ __forceinline__ float dpp_ror1(float v) { return __int_as_float(__builtin_amdgcn_update_dpp(0, __float_as_int(v), 0x121, 0xf, 0xf, false)); }
; __device__ __forceinline__ float dpp_ror2(float v) { return __int_as_float(__builtin_amdgcn_update_dpp(0, __float_as_int(v), 0x122, 0xf, 0xf, false)); }
;   __device__ __forceinline__ void operator()(const AccT& acc, const Unit& u, int wr, int wc, int fr, int fq) const {
;     ...
;             const float g1 = dpp_ror1((fr == 15) ? g_pm : g_cur), g2 = dpp_ror2((fr >= 14) ? g_pm : g_cur);
;             const float v1 = dpp_ror1((fr == 15) ? v_pm : v_cur), v2 = dpp_ror2((fr >= 14) ? v_pm : v_cur);
	v_mov_b32_dpp v175, v166 row_ror:1 row_mask:0xf bank_mask:0xf
	v_mov_b32_dpp v215, v164 row_ror:2 row_mask:0xf bank_mask:0xf
	v_cndmask_b32_e64 v164, v110, 0, s[8:9]
	s_nop 0

; __device__ __forceinline__ float dpp_ror1(float v) { return __int_as_float(__builtin_amdgcn_update_dpp(0, __float_as_int(v), 0x121, 0xf, 0xf, false)); }
; __device__ __forceinline__ float dpp_ror2(float v) { return __int_as_float(__builtin_amdgcn_update_dpp(0, __float_as_int(v), 0x122, 0xf, 0xf, false)); }
;   __device__ __forceinline__ void operator()(const AccT& acc, const Unit& u, int wr, int wc, int fr, int fq) const {
;     ...
;             const float g1 = dpp_ror1((fr == 15) ? g_pm : g_cur), g2 = dpp_ror2((fr >= 14) ? g_pm : g_cur);
;             const float v1 = dpp_ror1((fr == 15) ? v_pm : v_cur), v2 = dpp_ror2((fr >= 14) ? v_pm : v_cur);
	v_mov_b32_dpp v212, v162 row_ror:2 row_mask:0xf bank_mask:0xf
	v_mov_b32_dpp v166, v164 row_ror:1 row_mask:0xf bank_mask:0xf
	v_cndmask_b32_e64 v164, v106, 0, s[8:9]

; __device__ __forceinline__ float dpp_ror1(float v) { return __int_as_float(__builtin_amdgcn_update_dpp(0, __float_as_int(v), 0x121, 0xf, 0xf, false)); }
; __device__ __forceinline__ float dpp_ror2(float v) { return __int_as_float(__builtin_amdgcn_update_dpp(0, __float_as_int(v), 0x122, 0xf, 0xf, false)); }
;   __device__ __forceinline__ void operator()(const AccT& acc, const Unit& u, int wr, int wc, int fr, int fq) const {
;     ...
;             const float g1 = dpp_ror1((fr == 15) ? g_pm : g_cur), g2 = dpp_ror2((fr >= 14) ? g_pm : g_cur);
;             const float v1 = dpp_ror1((fr == 15) ? v_pm : v_cur), v2 = dpp_ror2((fr >= 14) ? v_pm : v_cur);
	v_mov_b32_dpp v214, v167 row_ror:2 row_mask:0xf bank_mask:0xf
	v_cndmask_b32_e64 v167, v109, 0, s[8:9]
	s_nop 0
	v_mov_b32_dpp v162, v164 row_ror:1 row_mask:0xf bank_mask:0xf

; __device__ __forceinline__ float dpp_ror1(float v) { return __int_as_float(__builtin_amdgcn_update_dpp(0, __float_as_int(v), 0x121, 0xf, 0xf, false)); }
; __device__ __forceinline__ float dpp_ror2(float v) { return __int_as_float(__builtin_amdgcn_update_dpp(0, __float_as_int(v), 0x122, 0xf, 0xf, false)); }
;   __device__ __forceinline__ void operator()(const AccT& acc, const Unit& u, int wr, int wc, int fr, int fq) const {
;     ...
;             const float g1 = dpp_ror1((fr == 15) ? g_pm : g_cur), g2 = dpp_ror2((fr >= 14) ? g_pm : g_cur);
;             const float v1 = dpp_ror1((fr == 15) ? v_pm : v_cur), v2 = dpp_ror2((fr >= 14) ? v_pm : v_cur);
	v_mov_b32_dpp v217, v167 row_ror:1 row_mask:0xf bank_mask:0xf

; __device__ __forceinline__ float dpp_ror1(float v) { return __int_as_float(__builtin_amdgcn_update_dpp(0, __float_as_int(v), 0x121, 0xf, 0xf, false)); }
; __device__ __forceinline__ float dpp_ror2(float v) { return __int_as_float(__builtin_amdgcn_update_dpp(0, __float_as_int(v), 0x122, 0xf, 0xf, false)); }
;   __device__ __forceinline__ void operator()(const AccT& acc, const Unit& u, int wr, int wc, int fr, int fq) const {
;     ...
;             const float g1 = dpp_ror1((fr == 15) ? g_pm : g_cur), g2 = dpp_ror2((fr >= 14) ? g_pm : g_cur);
;             const float v1 = dpp_ror1((fr == 15) ? v_pm : v_cur), v2 = dpp_ror2((fr >= 14) ? v_pm : v_cur);
	v_mov_b32_dpp v164, v165 row_ror:2 row_mask:0xf bank_mask:0xf
	v_cndmask_b32_e64 v165, v111, 0, s[8:9]
	s_nop 0
	s_nop 0
	v_mov_b32_dpp v167, v165 row_ror:1 row_mask:0xf bank_mask:0xf
	v_mov_b32_dpp v213, v163 row_ror:2 row_mask:0xf bank_mask:0xf
	v_cndmask_b32_e64 v165, v107, 0, s[8:9]

; __device__ __forceinline__ float dpp_ror1(float v) { return __int_as_float(__builtin_amdgcn_update_dpp(0, __float_as_int(v), 0x121, 0xf, 0xf, false)); }
; __device__ __forceinline__ float dpp_ror2(float v) { return __int_as_float(__builtin_amdgcn_update_dpp(0, __float_as_int(v), 0x122, 0xf, 0xf, false)); }
;   __device__ __forceinline__ void operator()(const AccT& acc, const Unit& u, int wr, int wc, int fr, int fq) const {
;     ...
;             const float g1 = dpp_ror1((fr == 15) ? g_pm : g_cur), g2 = dpp_ror2((fr >= 14) ? g_pm : g_cur);
;             const float v1 = dpp_ror1((fr == 15) ? v_pm : v_cur), v2 = dpp_ror2((fr >= 14) ? v_pm : v_cur);
	s_nop 1
	v_mov_b32_dpp v163, v165 row_ror:1 row_mask:0xf bank_mask:0xf

; __device__ __forceinline__ uint2 pack4(f32x4 v) { return make_uint2(pack2(v[0], v[1]), pack2(v[2], v[3])); }
; __device__ __forceinline__ float dpp_ror1(float v) { return __int_as_float(__builtin_amdgcn_update_dpp(0, __float_as_int(v), 0x121, 0xf, 0xf, false)); }
; __device__ __forceinline__ float dpp_ror2(float v) { return __int_as_float(__builtin_amdgcn_update_dpp(0, __float_as_int(v), 0x122, 0xf, 0xf, false)); }
;   __device__ __forceinline__ void operator()(const AccT& acc, const Unit& u, int wr, int wc, int fr, int fq) const {
;     ...
;         for (int m = 0; m < 4; ++m) { xg[m] = acc[ai][0][m][n] * rs[m]; xv[m] = acc[ai][1][m][n] * rs[m]; }
;     ...
; #pragma unroll
;         for (int m = 0; m < 4; ++m) {
;           f32x4 res;
; #pragma unroll
;           for (int r = 0; r < 4; ++r) {
;             const float g_cur = xg[m][r], v_cur = xv[m][r];
;             const f32x4 xgp = xg[m > 0 ? m - 1 : 0], xvp = xv[m > 0 ? m - 1 : 0];
;             const float g_pm = (m > 0) ? xgp[r] : 0.f, v_pm = (m > 0) ? xvp[r] : 0.f;
;             const float g1 = dpp_ror1((fr == 15) ? g_pm : g_cur), g2 = dpp_ror2((fr >= 14) ? g_pm : g_cur);
;             const float v1 = dpp_ror1((fr == 15) ? v_pm : v_cur), v2 = dpp_ror2((fr >= 14) ? v_pm : v_cur);
;             const float cg_ = bg[r] + g2 * wg0[r] + g1 * wg1[r] + g_cur * wg2[r];
;             const float cv_ = bv[r] + v2 * wv0[r] + v1 * wv1[r] + v_cur * wv2[r];
;             res[r] = cg_ * __builtin_amdgcn_rcpf(1.f + __builtin_amdgcn_exp2f(-1.4426950408889634f * cg_)) * cv_;
;           }
;           if (m > 0 || fr >= 2)
;             *(uint2*)(act + (size_t)EPI_ROW(u, ai, m) * DFF + f0) = pack4(res);
	s_nop 1
	v_mov_b32_dpp v165, v195 row_ror:2 row_mask:0xf bank_mask:0xf
	s_and_saveexec_b64 s[12:13], s[4:5]
	s_xor_b64 s[12:13], exec, s[12:13]
	s_andn2_saveexec_b64 s[12:13], s[12:13]
	s_cbranch_execz .LBB0_1518
	s_waitcnt vmcnt(0)
	v_pk_fma_f32 v[218:219], v[128:129], v[218:219], v[140:141]
	v_pk_fma_f32 v[212:213], v[130:131], v[212:213], v[142:143]
	v_pk_fma_f32 v[216:217], v[132:133], v[216:217], v[218:219]
	v_pk_fma_f32 v[166:167], v[134:135], v[166:167], v[212:213]
	v_pk_fma_f32 v[216:217], v[108:109], v[136:137], v[216:217]
	v_pk_fma_f32 v[166:167], v[110:111], v[138:139], v[166:167]
	v_mul_f32_e32 v195, 0xbfb8aa3b, v216
	v_exp_f32_e32 v195, v195
	v_mul_f32_e32 v218, 0xbfb8aa3b, v217
	v_exp_f32_e32 v218, v218
	v_mul_f32_e32 v212, 0xbfb8aa3b, v167
	v_add_f32_e32 v195, 1.0, v195
	v_exp_f32_e32 v213, v212
	v_add_f32_e32 v219, 1.0, v218
	v_rcp_f32_e32 v218, v195
	v_mul_f32_e32 v195, 0xbfb8aa3b, v166
	v_exp_f32_e32 v195, v195
	v_rcp_f32_e32 v219, v219
	v_pk_fma_f32 v[164:165], v[114:115], v[164:165], v[126:127]
	v_pk_fma_f32 v[214:215], v[112:113], v[214:215], v[124:125]
	v_add_f32_e32 v195, 1.0, v195
	v_rcp_f32_e32 v212, v195
	v_add_f32_e32 v195, 1.0, v213
	v_rcp_f32_e32 v213, v195
	v_pk_fma_f32 v[162:163], v[122:123], v[162:163], v[164:165]
	v_pk_fma_f32 v[174:175], v[120:121], v[174:175], v[214:215]
	v_pk_fma_f32 v[162:163], v[106:107], v[118:119], v[162:163]
	v_pk_mul_f32 v[164:165], v[166:167], v[212:213]
	v_pk_fma_f32 v[174:175], v[104:105], v[116:117], v[174:175]
	v_pk_mul_f32 v[162:163], v[162:163], v[164:165]
	v_pk_mul_f32 v[214:215], v[216:217], v[218:219]
	v_cvt_pk_bf16_f32 v165, v162, v163
	v_mov_b64_e32 v[162:163], s[52:53]
	v_pk_mul_f32 v[174:175], v[174:175], v[214:215]
	v_mad_i64_i32 v[162:163], s[46:47], v194, s88, v[162:163]
	v_cvt_pk_bf16_f32 v164, v174, v175
	v_lshl_add_u64 v[162:163], v[188:189], 1, v[162:163]
	global_store_dwordx2 v[162:163], v[164:165], off offset:32
.LBB0_1518:
	s_or_b64 exec, exec, s[12:13]
	v_mov_b32_e32 v225, v224
	v_mov_b32_e32 v223, v222
	v_mov_b32_e32 v162, v224
	v_mov_b32_e32 v163, v224
	v_pk_mul_f32 v[92:93], v[92:93], v[224:225]
	v_pk_mul_f32 v[94:95], v[94:95], v[162:163]
	v_pk_mul_f32 v[162:163], v[86:87], v[162:163]
	v_mov_b32_e32 v166, v222
	v_mov_b32_e32 v167, v222
	v_pk_mul_f32 v[86:87], v[88:89], v[222:223]
	v_cndmask_b32_e64 v89, v92, v108, s[8:9]

; __device__ __forceinline__ float dpp_ror1(float v) { return __int_as_float(__builtin_amdgcn_update_dpp(0, __float_as_int(v), 0x121, 0xf, 0xf, false)); }
; __device__ __forceinline__ float dpp_ror2(float v) { return __int_as_float(__builtin_amdgcn_update_dpp(0, __float_as_int(v), 0x122, 0xf, 0xf, false)); }
;   __device__ __forceinline__ void operator()(const AccT& acc, const Unit& u, int wr, int wc, int fr, int fq) const {
;     ...
;             const float g1 = dpp_ror1((fr == 15) ? g_pm : g_cur), g2 = dpp_ror2((fr >= 14) ? g_pm : g_cur);
;             const float v1 = dpp_ror1((fr == 15) ? v_pm : v_cur), v2 = dpp_ror2((fr >= 14) ? v_pm : v_cur);
	v_pk_mul_f32 v[164:165], v[84:85], v[224:225]
	v_pk_mul_f32 v[84:85], v[90:91], v[166:167]
	v_mov_b32_dpp v88, v89 row_ror:1 row_mask:0xf bank_mask:0xf
	v_cndmask_b32_e64 v89, v92, v108, s[6:7]
	s_nop 0

; __device__ __forceinline__ float dpp_ror1(float v) { return __int_as_float(__builtin_amdgcn_update_dpp(0, __float_as_int(v), 0x121, 0xf, 0xf, false)); }
; __device__ __forceinline__ float dpp_ror2(float v) { return __int_as_float(__builtin_amdgcn_update_dpp(0, __float_as_int(v), 0x122, 0xf, 0xf, false)); }
;   __device__ __forceinline__ void operator()(const AccT& acc, const Unit& u, int wr, int wc, int fr, int fq) const {
;     ...
;             const float g1 = dpp_ror1((fr == 15) ? g_pm : g_cur), g2 = dpp_ror2((fr >= 14) ? g_pm : g_cur);
;             const float v1 = dpp_ror1((fr == 15) ? v_pm : v_cur), v2 = dpp_ror2((fr >= 14) ? v_pm : v_cur);
	v_cndmask_b32_e64 v91, v93, v109, s[8:9]
	v_mov_b32_dpp v90, v89 row_ror:2 row_mask:0xf bank_mask:0xf
	v_cndmask_b32_e64 v89, v164, v104, s[8:9]
	v_cndmask_b32_e64 v109, v93, v109, s[6:7]
	v_pk_mul_f32 v[82:83], v[82:83], v[166:167]
	v_mov_b32_dpp v108, v89 row_ror:1 row_mask:0xf bank_mask:0xf
	v_cndmask_b32_e64 v89, v164, v104, s[6:7]

; __device__ __forceinline__ float dpp_ror1(float v) { return __int_as_float(__builtin_amdgcn_update_dpp(0, __float_as_int(v), 0x121, 0xf, 0xf, false)); }
; __device__ __forceinline__ float dpp_ror2(float v) { return __int_as_float(__builtin_amdgcn_update_dpp(0, __float_as_int(v), 0x122, 0xf, 0xf, false)); }
;   __device__ __forceinline__ void operator()(const AccT& acc, const Unit& u, int wr, int wc, int fr, int fq) const {
;     ...
;             const float g1 = dpp_ror1((fr == 15) ? g_pm : g_cur), g2 = dpp_ror2((fr >= 14) ? g_pm : g_cur);
;             const float v1 = dpp_ror1((fr == 15) ? v_pm : v_cur), v2 = dpp_ror2((fr >= 14) ? v_pm : v_cur);
	v_cndmask_b32_e64 v166, v165, v105, s[8:9]
	v_cndmask_b32_e64 v167, v94, v110, s[8:9]
	v_mov_b32_dpp v104, v89 row_ror:2 row_mask:0xf bank_mask:0xf


; __device__ __forceinline__ float dpp_ror1(float v) { return __int_as_float(__builtin_amdgcn_update_dpp(0, __float_as_int(v), 0x121, 0xf, 0xf, false)); }
; __device__ __forceinline__ float dpp_ror2(float v) { return __int_as_float(__builtin_amdgcn_update_dpp(0, __float_as_int(v), 0x122, 0xf, 0xf, false)); }
;   __device__ __forceinline__ void operator()(const AccT& acc, const Unit& u, int wr, int wc, int fr, int fq) const {
;     ...
;             const float g1 = dpp_ror1((fr == 15) ? g_pm : g_cur), g2 = dpp_ror2((fr >= 14) ? g_pm : g_cur);
;             const float v1 = dpp_ror1((fr == 15) ? v_pm : v_cur), v2 = dpp_ror2((fr >= 14) ? v_pm : v_cur);
	v_cndmask_b32_e64 v175, v95, v111, s[8:9]
	v_mov_b32_dpp v89, v91 row_ror:1 row_mask:0xf bank_mask:0xf

; __device__ __forceinline__ float dpp_ror1(float v) { return __int_as_float(__builtin_amdgcn_update_dpp(0, __float_as_int(v), 0x121, 0xf, 0xf, false)); }
; __device__ __forceinline__ float dpp_ror2(float v) { return __int_as_float(__builtin_amdgcn_update_dpp(0, __float_as_int(v), 0x122, 0xf, 0xf, false)); }
;   __device__ __forceinline__ void operator()(const AccT& acc, const Unit& u, int wr, int wc, int fr, int fq) const {
;     ...
;             const float v1 = dpp_ror1((fr == 15) ? v_pm : v_cur), v2 = dpp_ror2((fr >= 14) ? v_pm : v_cur);
;             const float cg_ = bg[r] + g2 * wg0[r] + g1 * wg1[r] + g_cur * wg2[r];
	v_cndmask_b32_e64 v195, v163, v107, s[8:9]
	v_pk_mul_f32 v[80:81], v[80:81], v[222:223]
	v_mov_b32_dpp v91, v109 row_ror:2 row_mask:0xf bank_mask:0xf
	s_waitcnt vmcnt(0)
	v_pk_fma_f32 v[90:91], v[128:129], v[90:91], v[140:141]

; __device__ __forceinline__ float dpp_ror1(float v) { return __int_as_float(__builtin_amdgcn_update_dpp(0, __float_as_int(v), 0x121, 0xf, 0xf, false)); }
; __device__ __forceinline__ float dpp_ror2(float v) { return __int_as_float(__builtin_amdgcn_update_dpp(0, __float_as_int(v), 0x122, 0xf, 0xf, false)); }
;   __device__ __forceinline__ void operator()(const AccT& acc, const Unit& u, int wr, int wc, int fr, int fq) const {
;     ...
;             const float v1 = dpp_ror1((fr == 15) ? v_pm : v_cur), v2 = dpp_ror2((fr >= 14) ? v_pm : v_cur);
;             const float cg_ = bg[r] + g2 * wg0[r] + g1 * wg1[r] + g_cur * wg2[r];
;             const float cv_ = bv[r] + v2 * wv0[r] + v1 * wv1[r] + v_cur * wv2[r];
;             res[r] = cg_ * __builtin_amdgcn_rcpf(1.f + __builtin_amdgcn_exp2f(-1.4426950408889634f * cg_)) * cv_;
	v_pk_fma_f32 v[88:89], v[132:133], v[88:89], v[90:91]
	s_add_i32 s37, s37, 8
	v_pk_fma_f32 v[88:89], v[92:93], v[136:137], v[88:89]
	v_mov_b32_dpp v109, v166 row_ror:1 row_mask:0xf bank_mask:0xf
	v_mul_f32_e32 v90, 0xbfb8aa3b, v88
	v_mul_f32_e32 v91, 0xbfb8aa3b, v89
	v_exp_f32_e32 v90, v90
	v_exp_f32_e32 v91, v91
	v_cndmask_b32_e64 v166, v165, v105, s[6:7]

; __device__ __forceinline__ float dpp_ror1(float v) { return __int_as_float(__builtin_amdgcn_update_dpp(0, __float_as_int(v), 0x121, 0xf, 0xf, false)); }
; __device__ __forceinline__ float dpp_ror2(float v) { return __int_as_float(__builtin_amdgcn_update_dpp(0, __float_as_int(v), 0x122, 0xf, 0xf, false)); }
;   __device__ __forceinline__ void operator()(const AccT& acc, const Unit& u, int wr, int wc, int fr, int fq) const {
;     ...
;             const float v1 = dpp_ror1((fr == 15) ? v_pm : v_cur), v2 = dpp_ror2((fr >= 14) ? v_pm : v_cur);
;             const float cg_ = bg[r] + g2 * wg0[r] + g1 * wg1[r] + g_cur * wg2[r];
;             const float cv_ = bv[r] + v2 * wv0[r] + v1 * wv1[r] + v_cur * wv2[r];
;             res[r] = cg_ * __builtin_amdgcn_rcpf(1.f + __builtin_amdgcn_exp2f(-1.4426950408889634f * cg_)) * cv_;
	v_add_f32_e32 v90, 1.0, v90
	v_add_f32_e32 v91, 1.0, v91
	v_mov_b32_dpp v105, v166 row_ror:2 row_mask:0xf bank_mask:0xf

; __device__ __forceinline__ float dpp_ror1(float v) { return __int_as_float(__builtin_amdgcn_update_dpp(0, __float_as_int(v), 0x121, 0xf, 0xf, false)); }
; __device__ __forceinline__ float dpp_ror2(float v) { return __int_as_float(__builtin_amdgcn_update_dpp(0, __float_as_int(v), 0x122, 0xf, 0xf, false)); }
;   __device__ __forceinline__ void operator()(const AccT& acc, const Unit& u, int wr, int wc, int fr, int fq) const {
;     ...
;             const float v1 = dpp_ror1((fr == 15) ? v_pm : v_cur), v2 = dpp_ror2((fr >= 14) ? v_pm : v_cur);
;             const float cg_ = bg[r] + g2 * wg0[r] + g1 * wg1[r] + g_cur * wg2[r];
;             const float cv_ = bv[r] + v2 * wv0[r] + v1 * wv1[r] + v_cur * wv2[r];
;             res[r] = cg_ * __builtin_amdgcn_rcpf(1.f + __builtin_amdgcn_exp2f(-1.4426950408889634f * cg_)) * cv_;
	v_rcp_f32_e32 v90, v90
	v_rcp_f32_e32 v91, v91
	v_mov_b32_dpp v166, v167 row_ror:1 row_mask:0xf bank_mask:0xf
	v_cndmask_b32_e64 v167, v94, v110, s[6:7]

; __device__ __forceinline__ float dpp_ror1(float v) { return __int_as_float(__builtin_amdgcn_update_dpp(0, __float_as_int(v), 0x121, 0xf, 0xf, false)); }
; __device__ __forceinline__ float dpp_ror2(float v) { return __int_as_float(__builtin_amdgcn_update_dpp(0, __float_as_int(v), 0x122, 0xf, 0xf, false)); }
;   __device__ __forceinline__ void operator()(const AccT& acc, const Unit& u, int wr, int wc, int fr, int fq) const {
;     ...
;             const float v1 = dpp_ror1((fr == 15) ? v_pm : v_cur), v2 = dpp_ror2((fr >= 14) ? v_pm : v_cur);
;             const float cg_ = bg[r] + g2 * wg0[r] + g1 * wg1[r] + g_cur * wg2[r];
;             const float cv_ = bv[r] + v2 * wv0[r] + v1 * wv1[r] + v_cur * wv2[r];
	v_pk_mul_f32 v[88:89], v[88:89], v[90:91]
	v_pk_fma_f32 v[104:105], v[112:113], v[104:105], v[124:125]
	v_mov_b32_dpp v110, v167 row_ror:2 row_mask:0xf bank_mask:0xf
	v_cndmask_b32_e64 v167, v162, v106, s[8:9]
	v_pk_fma_f32 v[104:105], v[120:121], v[108:109], v[104:105]
	s_nop 0
	v_mov_b32_dpp v174, v167 row_ror:1 row_mask:0xf bank_mask:0xf
	v_cndmask_b32_e64 v167, v162, v106, s[6:7]

; __device__ __forceinline__ float dpp_ror1(float v) { return __int_as_float(__builtin_amdgcn_update_dpp(0, __float_as_int(v), 0x121, 0xf, 0xf, false)); }
; __device__ __forceinline__ float dpp_ror2(float v) { return __int_as_float(__builtin_amdgcn_update_dpp(0, __float_as_int(v), 0x122, 0xf, 0xf, false)); }
;   __device__ __forceinline__ void operator()(const AccT& acc, const Unit& u, int wr, int wc, int fr, int fq) const {
;     ...
;             const float v1 = dpp_ror1((fr == 15) ? v_pm : v_cur), v2 = dpp_ror2((fr >= 14) ? v_pm : v_cur);
;             const float cg_ = bg[r] + g2 * wg0[r] + g1 * wg1[r] + g_cur * wg2[r];
;             const float cv_ = bv[r] + v2 * wv0[r] + v1 * wv1[r] + v_cur * wv2[r];
	v_pk_fma_f32 v[104:105], v[164:165], v[116:117], v[104:105]
	s_nop 0
	v_mov_b32_dpp v106, v167 row_ror:2 row_mask:0xf bank_mask:0xf

; __device__ __forceinline__ float dpp_ror1(float v) { return __int_as_float(__builtin_amdgcn_update_dpp(0, __float_as_int(v), 0x121, 0xf, 0xf, false)); }
; __device__ __forceinline__ float dpp_ror2(float v) { return __int_as_float(__builtin_amdgcn_update_dpp(0, __float_as_int(v), 0x122, 0xf, 0xf, false)); }
;   __device__ __forceinline__ void operator()(const AccT& acc, const Unit& u, int wr, int wc, int fr, int fq) const {
;     ...
;             const float v1 = dpp_ror1((fr == 15) ? v_pm : v_cur), v2 = dpp_ror2((fr >= 14) ? v_pm : v_cur);
;             const float cg_ = bg[r] + g2 * wg0[r] + g1 * wg1[r] + g_cur * wg2[r];
;             const float cv_ = bv[r] + v2 * wv0[r] + v1 * wv1[r] + v_cur * wv2[r];
;             res[r] = cg_ * __builtin_amdgcn_rcpf(1.f + __builtin_amdgcn_exp2f(-1.4426950408889634f * cg_)) * cv_;
	v_pk_mul_f32 v[88:89], v[104:105], v[88:89]
	s_nop 0
	v_mov_b32_dpp v167, v175 row_ror:1 row_mask:0xf bank_mask:0xf
	v_cndmask_b32_e64 v175, v95, v111, s[6:7]

; __device__ __forceinline__ uint2 pack4(f32x4 v) { return make_uint2(pack2(v[0], v[1]), pack2(v[2], v[3])); }
; __device__ __forceinline__ float dpp_ror1(float v) { return __int_as_float(__builtin_amdgcn_update_dpp(0, __float_as_int(v), 0x121, 0xf, 0xf, false)); }
; __device__ __forceinline__ float dpp_ror2(float v) { return __int_as_float(__builtin_amdgcn_update_dpp(0, __float_as_int(v), 0x122, 0xf, 0xf, false)); }
;   __device__ __forceinline__ void operator()(const AccT& acc, const Unit& u, int wr, int wc, int fr, int fq) const {
;     ...
;             const float v1 = dpp_ror1((fr == 15) ? v_pm : v_cur), v2 = dpp_ror2((fr >= 14) ? v_pm : v_cur);
;             const float cg_ = bg[r] + g2 * wg0[r] + g1 * wg1[r] + g_cur * wg2[r];
;             const float cv_ = bv[r] + v2 * wv0[r] + v1 * wv1[r] + v_cur * wv2[r];
;             res[r] = cg_ * __builtin_amdgcn_rcpf(1.f + __builtin_amdgcn_exp2f(-1.4426950408889634f * cg_)) * cv_;
;           }
;           if (m > 0 || fr >= 2)
;             *(uint2*)(act + (size_t)EPI_ROW(u, ai, m) * DFF + f0) = pack4(res);
	v_cvt_pk_bf16_f32 v88, v88, v89
	s_nop 0
	v_mov_b32_dpp v111, v175 row_ror:2 row_mask:0xf bank_mask:0xf
	v_pk_fma_f32 v[90:91], v[130:131], v[110:111], v[142:143]

;   __device__ __forceinline__ void operator()(const AccT& acc, const Unit& u, int wr, int wc, int fr, int fq) const {
;     ...
;             const float cg_ = bg[r] + g2 * wg0[r] + g1 * wg1[r] + g_cur * wg2[r];
	v_pk_fma_f32 v[90:91], v[134:135], v[166:167], v[90:91]

; __device__ __forceinline__ float dpp_ror1(float v) { return __int_as_float(__builtin_amdgcn_update_dpp(0, __float_as_int(v), 0x121, 0xf, 0xf, false)); }
; __device__ __forceinline__ float dpp_ror2(float v) { return __int_as_float(__builtin_amdgcn_update_dpp(0, __float_as_int(v), 0x122, 0xf, 0xf, false)); }
;   __device__ __forceinline__ void operator()(const AccT& acc, const Unit& u, int wr, int wc, int fr, int fq) const {
;     ...
;             const float v1 = dpp_ror1((fr == 15) ? v_pm : v_cur), v2 = dpp_ror2((fr >= 14) ? v_pm : v_cur);
;             const float cg_ = bg[r] + g2 * wg0[r] + g1 * wg1[r] + g_cur * wg2[r];
;             const float cv_ = bv[r] + v2 * wv0[r] + v1 * wv1[r] + v_cur * wv2[r];
;             res[r] = cg_ * __builtin_amdgcn_rcpf(1.f + __builtin_amdgcn_exp2f(-1.4426950408889634f * cg_)) * cv_;
	v_pk_fma_f32 v[90:91], v[94:95], v[138:139], v[90:91]
	v_mov_b32_dpp v175, v195 row_ror:1 row_mask:0xf bank_mask:0xf
	v_mul_f32_e32 v108, 0xbfb8aa3b, v90
	v_mul_f32_e32 v109, 0xbfb8aa3b, v91
	v_exp_f32_e32 v108, v108
	v_exp_f32_e32 v109, v109
	v_cndmask_b32_e64 v195, v163, v107, s[6:7]

; __device__ __forceinline__ float dpp_ror1(float v) { return __int_as_float(__builtin_amdgcn_update_dpp(0, __float_as_int(v), 0x121, 0xf, 0xf, false)); }
; __device__ __forceinline__ float dpp_ror2(float v) { return __int_as_float(__builtin_amdgcn_update_dpp(0, __float_as_int(v), 0x122, 0xf, 0xf, false)); }
;   __device__ __forceinline__ void operator()(const AccT& acc, const Unit& u, int wr, int wc, int fr, int fq) const {
;     ...
;             const float v1 = dpp_ror1((fr == 15) ? v_pm : v_cur), v2 = dpp_ror2((fr >= 14) ? v_pm : v_cur);
;             const float cg_ = bg[r] + g2 * wg0[r] + g1 * wg1[r] + g_cur * wg2[r];
;             const float cv_ = bv[r] + v2 * wv0[r] + v1 * wv1[r] + v_cur * wv2[r];
;             res[r] = cg_ * __builtin_amdgcn_rcpf(1.f + __builtin_amdgcn_exp2f(-1.4426950408889634f * cg_)) * cv_;
	v_add_f32_e32 v104, 1.0, v108
	v_add_f32_e32 v105, 1.0, v109
	v_rcp_f32_e32 v104, v104
	v_rcp_f32_e32 v105, v105
	v_mov_b32_dpp v107, v195 row_ror:2 row_mask:0xf bank_mask:0xf
	v_pk_fma_f32 v[106:107], v[114:115], v[106:107], v[126:127]

;   __device__ __forceinline__ void operator()(const AccT& acc, const Unit& u, int wr, int wc, int fr, int fq) const {
;     ...
;             const float cg_ = bg[r] + g2 * wg0[r] + g1 * wg1[r] + g_cur * wg2[r];
;             const float cv_ = bv[r] + v2 * wv0[r] + v1 * wv1[r] + v_cur * wv2[r];
;             res[r] = cg_ * __builtin_amdgcn_rcpf(1.f + __builtin_amdgcn_exp2f(-1.4426950408889634f * cg_)) * cv_;
	v_pk_fma_f32 v[106:107], v[122:123], v[174:175], v[106:107]
	v_pk_mul_f32 v[90:91], v[90:91], v[104:105]
	v_pk_fma_f32 v[106:107], v[162:163], v[118:119], v[106:107]

; __device__ __forceinline__ uint2 pack4(f32x4 v) { return make_uint2(pack2(v[0], v[1]), pack2(v[2], v[3])); }
;   __device__ __forceinline__ void operator()(const AccT& acc, const Unit& u, int wr, int wc, int fr, int fq) const {
;     ...
;             res[r] = cg_ * __builtin_amdgcn_rcpf(1.f + __builtin_amdgcn_exp2f(-1.4426950408889634f * cg_)) * cv_;
;           }
;           if (m > 0 || fr >= 2)
;             *(uint2*)(act + (size_t)EPI_ROW(u, ai, m) * DFF + f0) = pack4(res);
	v_pk_mul_f32 v[90:91], v[106:107], v[90:91]
	v_cndmask_b32_e64 v105, v81, v165, s[8:9]
	v_cvt_pk_bf16_f32 v89, v90, v91
	global_store_dwordx2 v[170:171], v[88:89], off offset:32
	v_cndmask_b32_e64 v89, v86, v92, s[8:9]
	s_nop 0

; __device__ __forceinline__ float dpp_ror1(float v) { return __int_as_float(__builtin_amdgcn_update_dpp(0, __float_as_int(v), 0x121, 0xf, 0xf, false)); }
; __device__ __forceinline__ float dpp_ror2(float v) { return __int_as_float(__builtin_amdgcn_update_dpp(0, __float_as_int(v), 0x122, 0xf, 0xf, false)); }
;   __device__ __forceinline__ void operator()(const AccT& acc, const Unit& u, int wr, int wc, int fr, int fq) const {
;     ...
;             const float g1 = dpp_ror1((fr == 15) ? g_pm : g_cur), g2 = dpp_ror2((fr >= 14) ? g_pm : g_cur);
;             const float v1 = dpp_ror1((fr == 15) ? v_pm : v_cur), v2 = dpp_ror2((fr >= 14) ? v_pm : v_cur);
	v_cndmask_b32_e64 v91, v87, v93, s[8:9]
	v_mov_b32_dpp v88, v89 row_ror:1 row_mask:0xf bank_mask:0xf
	v_cndmask_b32_e64 v89, v86, v92, s[6:7]
	s_nop 0
	v_cndmask_b32_e64 v93, v87, v93, s[6:7]
	v_mov_b32_dpp v90, v89 row_ror:2 row_mask:0xf bank_mask:0xf
	v_cndmask_b32_e64 v89, v80, v164, s[8:9]
	v_cndmask_b32_e64 v106, v81, v165, s[6:7]
	v_cndmask_b32_e64 v107, v84, v94, s[8:9]
	v_mov_b32_dpp v92, v89 row_ror:1 row_mask:0xf bank_mask:0xf
	v_cndmask_b32_e64 v89, v80, v164, s[6:7]
	v_cndmask_b32_e64 v109, v85, v95, s[8:9]
	v_cndmask_b32_e64 v111, v83, v163, s[8:9]
	v_mov_b32_dpp v104, v89 row_ror:2 row_mask:0xf bank_mask:0xf

; __device__ __forceinline__ float dpp_ror1(float v) { return __int_as_float(__builtin_amdgcn_update_dpp(0, __float_as_int(v), 0x121, 0xf, 0xf, false)); }
; __device__ __forceinline__ float dpp_ror2(float v) { return __int_as_float(__builtin_amdgcn_update_dpp(0, __float_as_int(v), 0x122, 0xf, 0xf, false)); }
;   __device__ __forceinline__ void operator()(const AccT& acc, const Unit& u, int wr, int wc, int fr, int fq) const {
;     ...
;             const float g1 = dpp_ror1((fr == 15) ? g_pm : g_cur), g2 = dpp_ror2((fr >= 14) ? g_pm : g_cur);
;             const float v1 = dpp_ror1((fr == 15) ? v_pm : v_cur), v2 = dpp_ror2((fr >= 14) ? v_pm : v_cur);
	s_nop 1
	v_mov_b32_dpp v89, v91 row_ror:1 row_mask:0xf bank_mask:0xf

; __device__ __forceinline__ float dpp_ror1(float v) { return __int_as_float(__builtin_amdgcn_update_dpp(0, __float_as_int(v), 0x121, 0xf, 0xf, false)); }
; __device__ __forceinline__ float dpp_ror2(float v) { return __int_as_float(__builtin_amdgcn_update_dpp(0, __float_as_int(v), 0x122, 0xf, 0xf, false)); }
;   __device__ __forceinline__ void operator()(const AccT& acc, const Unit& u, int wr, int wc, int fr, int fq) const {
;     ...
;             const float v1 = dpp_ror1((fr == 15) ? v_pm : v_cur), v2 = dpp_ror2((fr >= 14) ? v_pm : v_cur);
;             const float cg_ = bg[r] + g2 * wg0[r] + g1 * wg1[r] + g_cur * wg2[r];
	s_nop 1
	v_mov_b32_dpp v91, v93 row_ror:2 row_mask:0xf bank_mask:0xf
	v_pk_fma_f32 v[90:91], v[128:129], v[90:91], v[140:141]

; __device__ __forceinline__ float dpp_ror1(float v) { return __int_as_float(__builtin_amdgcn_update_dpp(0, __float_as_int(v), 0x121, 0xf, 0xf, false)); }
; __device__ __forceinline__ float dpp_ror2(float v) { return __int_as_float(__builtin_amdgcn_update_dpp(0, __float_as_int(v), 0x122, 0xf, 0xf, false)); }
;   __device__ __forceinline__ void operator()(const AccT& acc, const Unit& u, int wr, int wc, int fr, int fq) const {
;     ...
;             const float v1 = dpp_ror1((fr == 15) ? v_pm : v_cur), v2 = dpp_ror2((fr >= 14) ? v_pm : v_cur);
;             const float cg_ = bg[r] + g2 * wg0[r] + g1 * wg1[r] + g_cur * wg2[r];
;             const float cv_ = bv[r] + v2 * wv0[r] + v1 * wv1[r] + v_cur * wv2[r];
;             res[r] = cg_ * __builtin_amdgcn_rcpf(1.f + __builtin_amdgcn_exp2f(-1.4426950408889634f * cg_)) * cv_;
	v_pk_fma_f32 v[88:89], v[132:133], v[88:89], v[90:91]
	s_nop 0
	v_pk_fma_f32 v[88:89], v[86:87], v[136:137], v[88:89]
	v_mov_b32_dpp v93, v105 row_ror:1 row_mask:0xf bank_mask:0xf
	v_mul_f32_e32 v90, 0xbfb8aa3b, v88
	v_mul_f32_e32 v91, 0xbfb8aa3b, v89
	v_exp_f32_e32 v90, v90
	v_exp_f32_e32 v91, v91

; __device__ __forceinline__ float dpp_ror1(float v) { return __int_as_float(__builtin_amdgcn_update_dpp(0, __float_as_int(v), 0x121, 0xf, 0xf, false)); }
; __device__ __forceinline__ float dpp_ror2(float v) { return __int_as_float(__builtin_amdgcn_update_dpp(0, __float_as_int(v), 0x122, 0xf, 0xf, false)); }
;   __device__ __forceinline__ void operator()(const AccT& acc, const Unit& u, int wr, int wc, int fr, int fq) const {
;     ...
;             const float v1 = dpp_ror1((fr == 15) ? v_pm : v_cur), v2 = dpp_ror2((fr >= 14) ? v_pm : v_cur);
;             const float cg_ = bg[r] + g2 * wg0[r] + g1 * wg1[r] + g_cur * wg2[r];
;             const float cv_ = bv[r] + v2 * wv0[r] + v1 * wv1[r] + v_cur * wv2[r];
;             res[r] = cg_ * __builtin_amdgcn_rcpf(1.f + __builtin_amdgcn_exp2f(-1.4426950408889634f * cg_)) * cv_;
	v_add_f32_e32 v90, 1.0, v90
	s_nop 0
	v_mov_b32_dpp v105, v106 row_ror:2 row_mask:0xf bank_mask:0xf

; __device__ __forceinline__ float dpp_ror1(float v) { return __int_as_float(__builtin_amdgcn_update_dpp(0, __float_as_int(v), 0x121, 0xf, 0xf, false)); }
; __device__ __forceinline__ float dpp_ror2(float v) { return __int_as_float(__builtin_amdgcn_update_dpp(0, __float_as_int(v), 0x122, 0xf, 0xf, false)); }
;   __device__ __forceinline__ void operator()(const AccT& acc, const Unit& u, int wr, int wc, int fr, int fq) const {
;     ...
;             const float v1 = dpp_ror1((fr == 15) ? v_pm : v_cur), v2 = dpp_ror2((fr >= 14) ? v_pm : v_cur);
;             const float cg_ = bg[r] + g2 * wg0[r] + g1 * wg1[r] + g_cur * wg2[r];
;             const float cv_ = bv[r] + v2 * wv0[r] + v1 * wv1[r] + v_cur * wv2[r];
;             res[r] = cg_ * __builtin_amdgcn_rcpf(1.f + __builtin_amdgcn_exp2f(-1.4426950408889634f * cg_)) * cv_;
	v_add_f32_e32 v91, 1.0, v91
	v_rcp_f32_e32 v90, v90
	v_mov_b32_dpp v106, v107 row_ror:1 row_mask:0xf bank_mask:0xf
	v_cndmask_b32_e64 v107, v84, v94, s[6:7]

; __device__ __forceinline__ float dpp_ror1(float v) { return __int_as_float(__builtin_amdgcn_update_dpp(0, __float_as_int(v), 0x121, 0xf, 0xf, false)); }
; __device__ __forceinline__ float dpp_ror2(float v) { return __int_as_float(__builtin_amdgcn_update_dpp(0, __float_as_int(v), 0x122, 0xf, 0xf, false)); }
;   __device__ __forceinline__ void operator()(const AccT& acc, const Unit& u, int wr, int wc, int fr, int fq) const {
;     ...
;             const float v1 = dpp_ror1((fr == 15) ? v_pm : v_cur), v2 = dpp_ror2((fr >= 14) ? v_pm : v_cur);
;             const float cg_ = bg[r] + g2 * wg0[r] + g1 * wg1[r] + g_cur * wg2[r];
;             const float cv_ = bv[r] + v2 * wv0[r] + v1 * wv1[r] + v_cur * wv2[r];
	v_rcp_f32_e32 v91, v91
	v_pk_fma_f32 v[104:105], v[112:113], v[104:105], v[124:125]
	v_mov_b32_dpp v94, v107 row_ror:2 row_mask:0xf bank_mask:0xf
	v_cndmask_b32_e64 v107, v82, v162, s[8:9]
	v_pk_mul_f32 v[88:89], v[88:89], v[90:91]
	v_pk_fma_f32 v[92:93], v[120:121], v[92:93], v[104:105]
	v_mov_b32_dpp v108, v107 row_ror:1 row_mask:0xf bank_mask:0xf
	v_cndmask_b32_e64 v107, v82, v162, s[6:7]
	v_pk_fma_f32 v[92:93], v[80:81], v[116:117], v[92:93]
	v_cndmask_b32_e64 v162, v83, v163, s[6:7]
	v_mov_b32_dpp v110, v107 row_ror:2 row_mask:0xf bank_mask:0xf

; __device__ __forceinline__ float dpp_ror1(float v) { return __int_as_float(__builtin_amdgcn_update_dpp(0, __float_as_int(v), 0x121, 0xf, 0xf, false)); }
; __device__ __forceinline__ float dpp_ror2(float v) { return __int_as_float(__builtin_amdgcn_update_dpp(0, __float_as_int(v), 0x122, 0xf, 0xf, false)); }
;   __device__ __forceinline__ void operator()(const AccT& acc, const Unit& u, int wr, int wc, int fr, int fq) const {
;     ...
;             const float v1 = dpp_ror1((fr == 15) ? v_pm : v_cur), v2 = dpp_ror2((fr >= 14) ? v_pm : v_cur);
;             const float cg_ = bg[r] + g2 * wg0[r] + g1 * wg1[r] + g_cur * wg2[r];
;             const float cv_ = bv[r] + v2 * wv0[r] + v1 * wv1[r] + v_cur * wv2[r];
;             res[r] = cg_ * __builtin_amdgcn_rcpf(1.f + __builtin_amdgcn_exp2f(-1.4426950408889634f * cg_)) * cv_;
	v_pk_mul_f32 v[88:89], v[92:93], v[88:89]
	v_cndmask_b32_e64 v104, v99, v83, s[8:9]
	v_mov_b32_dpp v107, v109 row_ror:1 row_mask:0xf bank_mask:0xf
	v_cndmask_b32_e64 v109, v85, v95, s[6:7]

; __device__ __forceinline__ float dpp_ror1(float v) { return __int_as_float(__builtin_amdgcn_update_dpp(0, __float_as_int(v), 0x121, 0xf, 0xf, false)); }
; __device__ __forceinline__ float dpp_ror2(float v) { return __int_as_float(__builtin_amdgcn_update_dpp(0, __float_as_int(v), 0x122, 0xf, 0xf, false)); }
;   __device__ __forceinline__ void operator()(const AccT& acc, const Unit& u, int wr, int wc, int fr, int fq) const {
;     ...
;             const float g_cur = xg[m][r], v_cur = xv[m][r];
;             const f32x4 xgp = xg[m > 0 ? m - 1 : 0], xvp = xv[m > 0 ? m - 1 : 0];
;             const float g_pm = (m > 0) ? xgp[r] : 0.f, v_pm = (m > 0) ? xvp[r] : 0.f;
;             const float g1 = dpp_ror1((fr == 15) ? g_pm : g_cur), g2 = dpp_ror2((fr >= 14) ? g_pm : g_cur);
;             const float v1 = dpp_ror1((fr == 15) ? v_pm : v_cur), v2 = dpp_ror2((fr >= 14) ? v_pm : v_cur);
;             const float cg_ = bg[r] + g2 * wg0[r] + g1 * wg1[r] + g_cur * wg2[r];
;             const float cv_ = bv[r] + v2 * wv0[r] + v1 * wv1[r] + v_cur * wv2[r];
;             res[r] = cg_ * __builtin_amdgcn_rcpf(1.f + __builtin_amdgcn_exp2f(-1.4426950408889634f * cg_)) * cv_;
	v_cvt_pk_bf16_f32 v88, v88, v89
	s_nop 0
	v_mov_b32_dpp v95, v109 row_ror:2 row_mask:0xf bank_mask:0xf
	v_pk_fma_f32 v[90:91], v[130:131], v[94:95], v[142:143]

; __device__ __forceinline__ float dpp_ror1(float v) { return __int_as_float(__builtin_amdgcn_update_dpp(0, __float_as_int(v), 0x121, 0xf, 0xf, false)); }
; __device__ __forceinline__ float dpp_ror2(float v) { return __int_as_float(__builtin_amdgcn_update_dpp(0, __float_as_int(v), 0x122, 0xf, 0xf, false)); }
;   __device__ __forceinline__ void operator()(const AccT& acc, const Unit& u, int wr, int wc, int fr, int fq) const {
;     ...
;             const float g_cur = xg[m][r], v_cur = xv[m][r];
;             const f32x4 xgp = xg[m > 0 ? m - 1 : 0], xvp = xv[m > 0 ? m - 1 : 0];
;             const float g_pm = (m > 0) ? xgp[r] : 0.f, v_pm = (m > 0) ? xvp[r] : 0.f;
;             const float g1 = dpp_ror1((fr == 15) ? g_pm : g_cur), g2 = dpp_ror2((fr >= 14) ? g_pm : g_cur);
;             const float v1 = dpp_ror1((fr == 15) ? v_pm : v_cur), v2 = dpp_ror2((fr >= 14) ? v_pm : v_cur);
;             const float cg_ = bg[r] + g2 * wg0[r] + g1 * wg1[r] + g_cur * wg2[r];
;             const float cv_ = bv[r] + v2 * wv0[r] + v1 * wv1[r] + v_cur * wv2[r];
;             res[r] = cg_ * __builtin_amdgcn_rcpf(1.f + __builtin_amdgcn_exp2f(-1.4426950408889634f * cg_)) * cv_;
	v_pk_fma_f32 v[90:91], v[134:135], v[106:107], v[90:91]
	s_nop 0
	v_pk_fma_f32 v[90:91], v[84:85], v[138:139], v[90:91]
	v_mov_b32_dpp v109, v111 row_ror:1 row_mask:0xf bank_mask:0xf
	v_mul_f32_e32 v94, 0xbfb8aa3b, v90
	v_mul_f32_e32 v95, 0xbfb8aa3b, v91
	v_exp_f32_e32 v94, v94
	v_exp_f32_e32 v95, v95

; __device__ __forceinline__ float dpp_ror1(float v) { return __int_as_float(__builtin_amdgcn_update_dpp(0, __float_as_int(v), 0x121, 0xf, 0xf, false)); }
; __device__ __forceinline__ float dpp_ror2(float v) { return __int_as_float(__builtin_amdgcn_update_dpp(0, __float_as_int(v), 0x122, 0xf, 0xf, false)); }
;   __device__ __forceinline__ void operator()(const AccT& acc, const Unit& u, int wr, int wc, int fr, int fq) const {
;     ...
;             const float g_cur = xg[m][r], v_cur = xv[m][r];
;             const f32x4 xgp = xg[m > 0 ? m - 1 : 0], xvp = xv[m > 0 ? m - 1 : 0];
;             const float g_pm = (m > 0) ? xgp[r] : 0.f, v_pm = (m > 0) ? xvp[r] : 0.f;
;             const float g1 = dpp_ror1((fr == 15) ? g_pm : g_cur), g2 = dpp_ror2((fr >= 14) ? g_pm : g_cur);
;             const float v1 = dpp_ror1((fr == 15) ? v_pm : v_cur), v2 = dpp_ror2((fr >= 14) ? v_pm : v_cur);
;             const float cg_ = bg[r] + g2 * wg0[r] + g1 * wg1[r] + g_cur * wg2[r];
;             const float cv_ = bv[r] + v2 * wv0[r] + v1 * wv1[r] + v_cur * wv2[r];
;             res[r] = cg_ * __builtin_amdgcn_rcpf(1.f + __builtin_amdgcn_exp2f(-1.4426950408889634f * cg_)) * cv_;
	v_add_f32_e32 v92, 1.0, v94
	v_add_f32_e32 v93, 1.0, v95
	v_rcp_f32_e32 v92, v92
	v_rcp_f32_e32 v93, v93
	v_mov_b32_dpp v111, v162 row_ror:2 row_mask:0xf bank_mask:0xf
	v_pk_fma_f32 v[94:95], v[114:115], v[110:111], v[126:127]
	v_pk_mul_f32 v[90:91], v[90:91], v[92:93]
	v_pk_fma_f32 v[94:95], v[122:123], v[108:109], v[94:95]
	v_cndmask_b32_e64 v92, v97, v81, s[8:9]
	v_pk_fma_f32 v[94:95], v[82:83], v[118:119], v[94:95]
	v_cndmask_b32_e64 v93, v102, v84, s[8:9]
	v_pk_mul_f32 v[90:91], v[94:95], v[90:91]

; __device__ __forceinline__ uint2 pack4(f32x4 v) { return make_uint2(pack2(v[0], v[1]), pack2(v[2], v[3])); }
; __device__ __forceinline__ float dpp_ror1(float v) { return __int_as_float(__builtin_amdgcn_update_dpp(0, __float_as_int(v), 0x121, 0xf, 0xf, false)); }
; __device__ __forceinline__ float dpp_ror2(float v) { return __int_as_float(__builtin_amdgcn_update_dpp(0, __float_as_int(v), 0x122, 0xf, 0xf, false)); }
;   __device__ __forceinline__ void operator()(const AccT& acc, const Unit& u, int wr, int wc, int fr, int fq) const {
;     ...
;             const float g_cur = xg[m][r], v_cur = xv[m][r];
;             const f32x4 xgp = xg[m > 0 ? m - 1 : 0], xvp = xv[m > 0 ? m - 1 : 0];
;             const float g_pm = (m > 0) ? xgp[r] : 0.f, v_pm = (m > 0) ? xvp[r] : 0.f;
;             const float g1 = dpp_ror1((fr == 15) ? g_pm : g_cur), g2 = dpp_ror2((fr >= 14) ? g_pm : g_cur);
;             const float v1 = dpp_ror1((fr == 15) ? v_pm : v_cur), v2 = dpp_ror2((fr >= 14) ? v_pm : v_cur);
;             const float cg_ = bg[r] + g2 * wg0[r] + g1 * wg1[r] + g_cur * wg2[r];
;             const float cv_ = bv[r] + v2 * wv0[r] + v1 * wv1[r] + v_cur * wv2[r];
;             res[r] = cg_ * __builtin_amdgcn_rcpf(1.f + __builtin_amdgcn_exp2f(-1.4426950408889634f * cg_)) * cv_;
;           }
;           if (m > 0 || fr >= 2)
;             *(uint2*)(act + (size_t)EPI_ROW(u, ai, m) * DFF + f0) = pack4(res);
	v_cvt_pk_bf16_f32 v89, v90, v91
	global_store_dwordx2 v[172:173], v[88:89], off offset:32
	v_cndmask_b32_e64 v89, v100, v86, s[8:9]
	s_nop 0

; __device__ __forceinline__ float dpp_ror1(float v) { return __int_as_float(__builtin_amdgcn_update_dpp(0, __float_as_int(v), 0x121, 0xf, 0xf, false)); }
; __device__ __forceinline__ float dpp_ror2(float v) { return __int_as_float(__builtin_amdgcn_update_dpp(0, __float_as_int(v), 0x122, 0xf, 0xf, false)); }
;   __device__ __forceinline__ void operator()(const AccT& acc, const Unit& u, int wr, int wc, int fr, int fq) const {
;     ...
;             const float g_cur = xg[m][r], v_cur = xv[m][r];
;             const f32x4 xgp = xg[m > 0 ? m - 1 : 0], xvp = xv[m > 0 ? m - 1 : 0];
;             const float g_pm = (m > 0) ? xgp[r] : 0.f, v_pm = (m > 0) ? xvp[r] : 0.f;
;             const float g1 = dpp_ror1((fr == 15) ? g_pm : g_cur), g2 = dpp_ror2((fr >= 14) ? g_pm : g_cur);
;             const float v1 = dpp_ror1((fr == 15) ? v_pm : v_cur), v2 = dpp_ror2((fr >= 14) ? v_pm : v_cur);
	v_cndmask_b32_e64 v91, v101, v87, s[8:9]
	v_mov_b32_dpp v88, v89 row_ror:1 row_mask:0xf bank_mask:0xf
	v_cndmask_b32_e64 v89, v100, v86, s[6:7]

; __device__ __forceinline__ float dpp_ror1(float v) { return __int_as_float(__builtin_amdgcn_update_dpp(0, __float_as_int(v), 0x121, 0xf, 0xf, false)); }
; __device__ __forceinline__ float dpp_ror2(float v) { return __int_as_float(__builtin_amdgcn_update_dpp(0, __float_as_int(v), 0x122, 0xf, 0xf, false)); }
;   __device__ __forceinline__ void operator()(const AccT& acc, const Unit& u, int wr, int wc, int fr, int fq) const {
;     ...
;             const float g_cur = xg[m][r], v_cur = xv[m][r];
;             const f32x4 xgp = xg[m > 0 ? m - 1 : 0], xvp = xv[m > 0 ? m - 1 : 0];
;             const float g_pm = (m > 0) ? xgp[r] : 0.f, v_pm = (m > 0) ? xvp[r] : 0.f;
;             const float g1 = dpp_ror1((fr == 15) ? g_pm : g_cur), g2 = dpp_ror2((fr >= 14) ? g_pm : g_cur);
;             const float v1 = dpp_ror1((fr == 15) ? v_pm : v_cur), v2 = dpp_ror2((fr >= 14) ? v_pm : v_cur);
	v_cndmask_b32_e64 v95, v103, v85, s[8:9]
	s_nop 0
	v_mov_b32_dpp v86, v89 row_ror:2 row_mask:0xf bank_mask:0xf
	v_cndmask_b32_e64 v89, v96, v80, s[8:9]
	s_nop 1
	v_mov_b32_dpp v90, v89 row_ror:1 row_mask:0xf bank_mask:0xf
	v_cndmask_b32_e64 v89, v96, v80, s[6:7]

; __device__ __forceinline__ float dpp_ror1(float v) { return __int_as_float(__builtin_amdgcn_update_dpp(0, __float_as_int(v), 0x121, 0xf, 0xf, false)); }
; __device__ __forceinline__ float dpp_ror2(float v) { return __int_as_float(__builtin_amdgcn_update_dpp(0, __float_as_int(v), 0x122, 0xf, 0xf, false)); }
;   __device__ __forceinline__ void operator()(const AccT& acc, const Unit& u, int wr, int wc, int fr, int fq) const {
;     ...
;             const float g_cur = xg[m][r], v_cur = xv[m][r];
;             const f32x4 xgp = xg[m > 0 ? m - 1 : 0], xvp = xv[m > 0 ? m - 1 : 0];
;             const float g_pm = (m > 0) ? xgp[r] : 0.f, v_pm = (m > 0) ? xvp[r] : 0.f;
;             const float g1 = dpp_ror1((fr == 15) ? g_pm : g_cur), g2 = dpp_ror2((fr >= 14) ? g_pm : g_cur);
;             const float v1 = dpp_ror1((fr == 15) ? v_pm : v_cur), v2 = dpp_ror2((fr >= 14) ? v_pm : v_cur);
	s_nop 1
	v_mov_b32_dpp v80, v89 row_ror:2 row_mask:0xf bank_mask:0xf

; __device__ __forceinline__ float dpp_ror1(float v) { return __int_as_float(__builtin_amdgcn_update_dpp(0, __float_as_int(v), 0x121, 0xf, 0xf, false)); }
; __device__ __forceinline__ float dpp_ror2(float v) { return __int_as_float(__builtin_amdgcn_update_dpp(0, __float_as_int(v), 0x122, 0xf, 0xf, false)); }
;   __device__ __forceinline__ void operator()(const AccT& acc, const Unit& u, int wr, int wc, int fr, int fq) const {
;     ...
;             const float g_cur = xg[m][r], v_cur = xv[m][r];
;             const f32x4 xgp = xg[m > 0 ? m - 1 : 0], xvp = xv[m > 0 ? m - 1 : 0];
;             const float g_pm = (m > 0) ? xgp[r] : 0.f, v_pm = (m > 0) ? xvp[r] : 0.f;
;             const float g1 = dpp_ror1((fr == 15) ? g_pm : g_cur), g2 = dpp_ror2((fr >= 14) ? g_pm : g_cur);
;             const float v1 = dpp_ror1((fr == 15) ? v_pm : v_cur), v2 = dpp_ror2((fr >= 14) ? v_pm : v_cur);
	s_nop 1
	v_mov_b32_dpp v89, v91 row_ror:1 row_mask:0xf bank_mask:0xf
	v_cndmask_b32_e64 v91, v101, v87, s[6:7]

; __device__ __forceinline__ float dpp_ror1(float v) { return __int_as_float(__builtin_amdgcn_update_dpp(0, __float_as_int(v), 0x121, 0xf, 0xf, false)); }
; __device__ __forceinline__ float dpp_ror2(float v) { return __int_as_float(__builtin_amdgcn_update_dpp(0, __float_as_int(v), 0x122, 0xf, 0xf, false)); }
;   __device__ __forceinline__ void operator()(const AccT& acc, const Unit& u, int wr, int wc, int fr, int fq) const {
;     ...
;             const float g_cur = xg[m][r], v_cur = xv[m][r];
;             const f32x4 xgp = xg[m > 0 ? m - 1 : 0], xvp = xv[m > 0 ? m - 1 : 0];
;             const float g_pm = (m > 0) ? xgp[r] : 0.f, v_pm = (m > 0) ? xvp[r] : 0.f;
;             const float g1 = dpp_ror1((fr == 15) ? g_pm : g_cur), g2 = dpp_ror2((fr >= 14) ? g_pm : g_cur);
;             const float v1 = dpp_ror1((fr == 15) ? v_pm : v_cur), v2 = dpp_ror2((fr >= 14) ? v_pm : v_cur);
;             const float cg_ = bg[r] + g2 * wg0[r] + g1 * wg1[r] + g_cur * wg2[r];
	s_nop 1
	v_mov_b32_dpp v87, v91 row_ror:2 row_mask:0xf bank_mask:0xf
	v_pk_fma_f32 v[86:87], v[128:129], v[86:87], v[140:141]

; __device__ __forceinline__ float dpp_ror1(float v) { return __int_as_float(__builtin_amdgcn_update_dpp(0, __float_as_int(v), 0x121, 0xf, 0xf, false)); }
; __device__ __forceinline__ float dpp_ror2(float v) { return __int_as_float(__builtin_amdgcn_update_dpp(0, __float_as_int(v), 0x122, 0xf, 0xf, false)); }
;   __device__ __forceinline__ void operator()(const AccT& acc, const Unit& u, int wr, int wc, int fr, int fq) const {
;     ...
;             const float g_cur = xg[m][r], v_cur = xv[m][r];
;             const f32x4 xgp = xg[m > 0 ? m - 1 : 0], xvp = xv[m > 0 ? m - 1 : 0];
;             const float g_pm = (m > 0) ? xgp[r] : 0.f, v_pm = (m > 0) ? xvp[r] : 0.f;
;             const float g1 = dpp_ror1((fr == 15) ? g_pm : g_cur), g2 = dpp_ror2((fr >= 14) ? g_pm : g_cur);
;             const float v1 = dpp_ror1((fr == 15) ? v_pm : v_cur), v2 = dpp_ror2((fr >= 14) ? v_pm : v_cur);
;             const float cg_ = bg[r] + g2 * wg0[r] + g1 * wg1[r] + g_cur * wg2[r];
;             const float cv_ = bv[r] + v2 * wv0[r] + v1 * wv1[r] + v_cur * wv2[r];
;             res[r] = cg_ * __builtin_amdgcn_rcpf(1.f + __builtin_amdgcn_exp2f(-1.4426950408889634f * cg_)) * cv_;
	v_pk_fma_f32 v[86:87], v[132:133], v[88:89], v[86:87]
	v_add_u32_e32 v128, 0x90, v194
	v_mov_b32_dpp v91, v92 row_ror:1 row_mask:0xf bank_mask:0xf
	v_cndmask_b32_e64 v92, v97, v81, s[6:7]

; __device__ __forceinline__ float dpp_ror1(float v) { return __int_as_float(__builtin_amdgcn_update_dpp(0, __float_as_int(v), 0x121, 0xf, 0xf, false)); }
; __device__ __forceinline__ float dpp_ror2(float v) { return __int_as_float(__builtin_amdgcn_update_dpp(0, __float_as_int(v), 0x122, 0xf, 0xf, false)); }
;   __device__ __forceinline__ void operator()(const AccT& acc, const Unit& u, int wr, int wc, int fr, int fq) const {
;     ...
;             const float g_cur = xg[m][r], v_cur = xv[m][r];
;             const f32x4 xgp = xg[m > 0 ? m - 1 : 0], xvp = xv[m > 0 ? m - 1 : 0];
;             const float g_pm = (m > 0) ? xgp[r] : 0.f, v_pm = (m > 0) ? xvp[r] : 0.f;
;             const float g1 = dpp_ror1((fr == 15) ? g_pm : g_cur), g2 = dpp_ror2((fr >= 14) ? g_pm : g_cur);
;             const float v1 = dpp_ror1((fr == 15) ? v_pm : v_cur), v2 = dpp_ror2((fr >= 14) ? v_pm : v_cur);
;             const float cg_ = bg[r] + g2 * wg0[r] + g1 * wg1[r] + g_cur * wg2[r];
;             const float cv_ = bv[r] + v2 * wv0[r] + v1 * wv1[r] + v_cur * wv2[r];
;             res[r] = cg_ * __builtin_amdgcn_rcpf(1.f + __builtin_amdgcn_exp2f(-1.4426950408889634f * cg_)) * cv_;
	v_pk_fma_f32 v[86:87], v[100:101], v[136:137], v[86:87]
	v_ashrrev_i32_e32 v129, 31, v128
	v_mov_b32_dpp v81, v92 row_ror:2 row_mask:0xf bank_mask:0xf

; __device__ __forceinline__ float dpp_ror1(float v) { return __int_as_float(__builtin_amdgcn_update_dpp(0, __float_as_int(v), 0x121, 0xf, 0xf, false)); }
; __device__ __forceinline__ float dpp_ror2(float v) { return __int_as_float(__builtin_amdgcn_update_dpp(0, __float_as_int(v), 0x122, 0xf, 0xf, false)); }
;   __device__ __forceinline__ void operator()(const AccT& acc, const Unit& u, int wr, int wc, int fr, int fq) const {
;     ...
;             const float g_cur = xg[m][r], v_cur = xv[m][r];
;             const f32x4 xgp = xg[m > 0 ? m - 1 : 0], xvp = xv[m > 0 ? m - 1 : 0];
;             const float g_pm = (m > 0) ? xgp[r] : 0.f, v_pm = (m > 0) ? xvp[r] : 0.f;
;             const float g1 = dpp_ror1((fr == 15) ? g_pm : g_cur), g2 = dpp_ror2((fr >= 14) ? g_pm : g_cur);
;             const float v1 = dpp_ror1((fr == 15) ? v_pm : v_cur), v2 = dpp_ror2((fr >= 14) ? v_pm : v_cur);
;             const float cg_ = bg[r] + g2 * wg0[r] + g1 * wg1[r] + g_cur * wg2[r];
;             const float cv_ = bv[r] + v2 * wv0[r] + v1 * wv1[r] + v_cur * wv2[r];
;             res[r] = cg_ * __builtin_amdgcn_rcpf(1.f + __builtin_amdgcn_exp2f(-1.4426950408889634f * cg_)) * cv_;
	v_mul_f32_e32 v88, 0xbfb8aa3b, v86
	v_mul_f32_e32 v89, 0xbfb8aa3b, v87
	v_mov_b32_dpp v92, v93 row_ror:1 row_mask:0xf bank_mask:0xf
	v_cndmask_b32_e64 v93, v102, v84, s[6:7]

; __device__ __forceinline__ float dpp_ror1(float v) { return __int_as_float(__builtin_amdgcn_update_dpp(0, __float_as_int(v), 0x121, 0xf, 0xf, false)); }
; __device__ __forceinline__ float dpp_ror2(float v) { return __int_as_float(__builtin_amdgcn_update_dpp(0, __float_as_int(v), 0x122, 0xf, 0xf, false)); }
;   __device__ __forceinline__ void operator()(const AccT& acc, const Unit& u, int wr, int wc, int fr, int fq) const {
;     ...
;             const float g_cur = xg[m][r], v_cur = xv[m][r];
;             const f32x4 xgp = xg[m > 0 ? m - 1 : 0], xvp = xv[m > 0 ? m - 1 : 0];
;             const float g_pm = (m > 0) ? xgp[r] : 0.f, v_pm = (m > 0) ? xvp[r] : 0.f;
;             const float g1 = dpp_ror1((fr == 15) ? g_pm : g_cur), g2 = dpp_ror2((fr >= 14) ? g_pm : g_cur);
;             const float v1 = dpp_ror1((fr == 15) ? v_pm : v_cur), v2 = dpp_ror2((fr >= 14) ? v_pm : v_cur);
;             const float cg_ = bg[r] + g2 * wg0[r] + g1 * wg1[r] + g_cur * wg2[r];
;             const float cv_ = bv[r] + v2 * wv0[r] + v1 * wv1[r] + v_cur * wv2[r];
;             res[r] = cg_ * __builtin_amdgcn_rcpf(1.f + __builtin_amdgcn_exp2f(-1.4426950408889634f * cg_)) * cv_;
	v_exp_f32_e32 v88, v88
	v_exp_f32_e32 v89, v89
	v_mov_b32_dpp v84, v93 row_ror:2 row_mask:0xf bank_mask:0xf
	v_cndmask_b32_e64 v93, v98, v82, s[8:9]
	v_add_f32_e32 v88, 1.0, v88
	v_add_f32_e32 v89, 1.0, v89
	v_mov_b32_dpp v94, v93 row_ror:1 row_mask:0xf bank_mask:0xf
	v_cndmask_b32_e64 v93, v98, v82, s[6:7]

; __device__ __forceinline__ float dpp_ror1(float v) { return __int_as_float(__builtin_amdgcn_update_dpp(0, __float_as_int(v), 0x121, 0xf, 0xf, false)); }
; __device__ __forceinline__ float dpp_ror2(float v) { return __int_as_float(__builtin_amdgcn_update_dpp(0, __float_as_int(v), 0x122, 0xf, 0xf, false)); }
;   __device__ __forceinline__ void operator()(const AccT& acc, const Unit& u, int wr, int wc, int fr, int fq) const {
;     ...
;             const float g_cur = xg[m][r], v_cur = xv[m][r];
;             const f32x4 xgp = xg[m > 0 ? m - 1 : 0], xvp = xv[m > 0 ? m - 1 : 0];
;             const float g_pm = (m > 0) ? xgp[r] : 0.f, v_pm = (m > 0) ? xvp[r] : 0.f;
;             const float g1 = dpp_ror1((fr == 15) ? g_pm : g_cur), g2 = dpp_ror2((fr >= 14) ? g_pm : g_cur);
;             const float v1 = dpp_ror1((fr == 15) ? v_pm : v_cur), v2 = dpp_ror2((fr >= 14) ? v_pm : v_cur);
;             const float cg_ = bg[r] + g2 * wg0[r] + g1 * wg1[r] + g_cur * wg2[r];
;             const float cv_ = bv[r] + v2 * wv0[r] + v1 * wv1[r] + v_cur * wv2[r];
;             res[r] = cg_ * __builtin_amdgcn_rcpf(1.f + __builtin_amdgcn_exp2f(-1.4426950408889634f * cg_)) * cv_;
	v_rcp_f32_e32 v88, v88
	v_rcp_f32_e32 v89, v89
	v_mov_b32_dpp v82, v93 row_ror:2 row_mask:0xf bank_mask:0xf

; __device__ __forceinline__ float dpp_ror1(float v) { return __int_as_float(__builtin_amdgcn_update_dpp(0, __float_as_int(v), 0x121, 0xf, 0xf, false)); }
; __device__ __forceinline__ float dpp_ror2(float v) { return __int_as_float(__builtin_amdgcn_update_dpp(0, __float_as_int(v), 0x122, 0xf, 0xf, false)); }
;   __device__ __forceinline__ void operator()(const AccT& acc, const Unit& u, int wr, int wc, int fr, int fq) const {
;     ...
;             const float g_cur = xg[m][r], v_cur = xv[m][r];
;             const f32x4 xgp = xg[m > 0 ? m - 1 : 0], xvp = xv[m > 0 ? m - 1 : 0];
;             const float g_pm = (m > 0) ? xgp[r] : 0.f, v_pm = (m > 0) ? xvp[r] : 0.f;
;             const float g1 = dpp_ror1((fr == 15) ? g_pm : g_cur), g2 = dpp_ror2((fr >= 14) ? g_pm : g_cur);
;             const float v1 = dpp_ror1((fr == 15) ? v_pm : v_cur), v2 = dpp_ror2((fr >= 14) ? v_pm : v_cur);
;             const float cg_ = bg[r] + g2 * wg0[r] + g1 * wg1[r] + g_cur * wg2[r];
;             const float cv_ = bv[r] + v2 * wv0[r] + v1 * wv1[r] + v_cur * wv2[r];
;             res[r] = cg_ * __builtin_amdgcn_rcpf(1.f + __builtin_amdgcn_exp2f(-1.4426950408889634f * cg_)) * cv_;
	v_pk_fma_f32 v[80:81], v[112:113], v[80:81], v[124:125]
	v_pk_mul_f32 v[86:87], v[86:87], v[88:89]
	v_mov_b32_dpp v93, v95 row_ror:1 row_mask:0xf bank_mask:0xf
	v_cndmask_b32_e64 v95, v103, v85, s[6:7]

; __device__ __forceinline__ float dpp_ror1(float v) { return __int_as_float(__builtin_amdgcn_update_dpp(0, __float_as_int(v), 0x121, 0xf, 0xf, false)); }
; __device__ __forceinline__ float dpp_ror2(float v) { return __int_as_float(__builtin_amdgcn_update_dpp(0, __float_as_int(v), 0x122, 0xf, 0xf, false)); }
;   __device__ __forceinline__ void operator()(const AccT& acc, const Unit& u, int wr, int wc, int fr, int fq) const {
;     ...
;             const float g_cur = xg[m][r], v_cur = xv[m][r];
;             const f32x4 xgp = xg[m > 0 ? m - 1 : 0], xvp = xv[m > 0 ? m - 1 : 0];
;             const float g_pm = (m > 0) ? xgp[r] : 0.f, v_pm = (m > 0) ? xvp[r] : 0.f;
;             const float g1 = dpp_ror1((fr == 15) ? g_pm : g_cur), g2 = dpp_ror2((fr >= 14) ? g_pm : g_cur);
;             const float v1 = dpp_ror1((fr == 15) ? v_pm : v_cur), v2 = dpp_ror2((fr >= 14) ? v_pm : v_cur);
;             const float cg_ = bg[r] + g2 * wg0[r] + g1 * wg1[r] + g_cur * wg2[r];
;             const float cv_ = bv[r] + v2 * wv0[r] + v1 * wv1[r] + v_cur * wv2[r];
;             res[r] = cg_ * __builtin_amdgcn_rcpf(1.f + __builtin_amdgcn_exp2f(-1.4426950408889634f * cg_)) * cv_;
	v_pk_fma_f32 v[80:81], v[120:121], v[90:91], v[80:81]
	v_add_u32_e32 v112, 0x80, v194
	v_mov_b32_dpp v85, v95 row_ror:2 row_mask:0xf bank_mask:0xf
	v_pk_fma_f32 v[84:85], v[130:131], v[84:85], v[142:143]
	v_pk_fma_f32 v[80:81], v[96:97], v[116:117], v[80:81]
	v_pk_fma_f32 v[84:85], v[134:135], v[92:93], v[84:85]

; __device__ __forceinline__ float dpp_ror1(float v) { return __int_as_float(__builtin_amdgcn_update_dpp(0, __float_as_int(v), 0x121, 0xf, 0xf, false)); }
; __device__ __forceinline__ float dpp_ror2(float v) { return __int_as_float(__builtin_amdgcn_update_dpp(0, __float_as_int(v), 0x122, 0xf, 0xf, false)); }
;   __device__ __forceinline__ void operator()(const AccT& acc, const Unit& u, int wr, int wc, int fr, int fq) const {
;     ...
;             const float g_cur = xg[m][r], v_cur = xv[m][r];
;             const f32x4 xgp = xg[m > 0 ? m - 1 : 0], xvp = xv[m > 0 ? m - 1 : 0];
;             const float g_pm = (m > 0) ? xgp[r] : 0.f, v_pm = (m > 0) ? xvp[r] : 0.f;
;             const float g1 = dpp_ror1((fr == 15) ? g_pm : g_cur), g2 = dpp_ror2((fr >= 14) ? g_pm : g_cur);
;             const float v1 = dpp_ror1((fr == 15) ? v_pm : v_cur), v2 = dpp_ror2((fr >= 14) ? v_pm : v_cur);
;             const float cg_ = bg[r] + g2 * wg0[r] + g1 * wg1[r] + g_cur * wg2[r];
;             const float cv_ = bv[r] + v2 * wv0[r] + v1 * wv1[r] + v_cur * wv2[r];
;             res[r] = cg_ * __builtin_amdgcn_rcpf(1.f + __builtin_amdgcn_exp2f(-1.4426950408889634f * cg_)) * cv_;
	v_pk_fma_f32 v[84:85], v[102:103], v[138:139], v[84:85]
	v_pk_mul_f32 v[80:81], v[80:81], v[86:87]
	v_mul_f32_e32 v88, 0xbfb8aa3b, v84
	v_mul_f32_e32 v89, 0xbfb8aa3b, v85
	v_exp_f32_e32 v88, v88
	v_exp_f32_e32 v89, v89
	v_mov_b32_dpp v95, v104 row_ror:1 row_mask:0xf bank_mask:0xf
	v_cndmask_b32_e64 v104, v99, v83, s[6:7]
	v_add_f32_e32 v86, 1.0, v88
	v_add_f32_e32 v87, 1.0, v89

; __device__ __forceinline__ float rstd_of(const unsigned long long* rowss, int row) {
;   return rsqrtf((float)rowss[row] * (1.f / (SS_FIX * DM)) + 1e-6f);
; }
;   __device__ __forceinline__ void operator()(const AccT& acc, const Unit& u, int wr, int wc, int fr, int fq) const {
;     ...
;       for (int m = 0; m < 4; ++m) rs[m] = rstd_of(rowss, EPI_ROW(u, ai, m));
;       const int chunk = 4 * u.pm + 2 * ai + wr;
; #pragma unroll
;       for (int n = 0; n < 2; ++n) {
;         const int f0 = 128 * u.pn + 32 * wc + 16 * n + 4 * fq;
;         const int gc = u.pn * 256 + 32 * wc + 16 * n + 4 * fq;
;         const f32x4 wg0 = *(const f32x4*)(cw + f0), wg1 = *(const f32x4*)(cw + NUP + f0), wg2 = *(const f32x4*)(cw + 2 * NUP + f0);
;         const f32x4 wv0 = *(const f32x4*)(cw + DFF + f0), wv1 = *(const f32x4*)(cw + NUP + DFF + f0), wv2 = *(const f32x4*)(cw + 2 * NUP + DFF + f0);
;         const f32x4 bg = *(const f32x4*)(cb + f0), bv = *(const f32x4*)(cb + DFF + f0);
;         f32x4 xg[4], xv[4];
; #pragma unroll
;         for (int m = 0; m < 4; ++m) { xg[m] = acc[ai][0][m][n] * rs[m]; xv[m] = acc[ai][1][m][n] * rs[m]; }
;         if (fr < 2) {
;           float* d = ub + ((size_t)(chunk * 4 + fr) * NUP + gc);
;           *(float4*)d = make_float4(xg[0][0], xg[0][1], xg[0][2], xg[0][3]);
;           *(float4*)(d + 128) = make_float4(xv[0][0], xv[0][1], xv[0][2], xv[0][3]);
	v_rcp_f32_e32 v86, v86
	v_rcp_f32_e32 v87, v87
	v_mov_b32_dpp v83, v104 row_ror:2 row_mask:0xf bank_mask:0xf
	v_pk_fma_f32 v[82:83], v[114:115], v[82:83], v[126:127]
	v_cvt_pk_bf16_f32 v80, v80, v81
	v_pk_fma_f32 v[82:83], v[122:123], v[94:95], v[82:83]
	v_pk_mul_f32 v[84:85], v[84:85], v[86:87]
	v_pk_fma_f32 v[82:83], v[98:99], v[118:119], v[82:83]
	v_ashrrev_i32_e32 v113, 31, v112
	v_pk_mul_f32 v[82:83], v[82:83], v[84:85]
	v_add_u32_e32 v130, 0xa0, v194
	v_cvt_pk_bf16_f32 v81, v82, v83
	global_store_dwordx2 v[160:161], v[80:81], off offset:32
	v_lshl_add_u64 v[80:81], v[112:113], 3, s[14:15]
	global_load_dwordx2 v[116:117], v[80:81], off
	v_add_u32_e32 v114, 0xb0, v194
	v_ashrrev_i32_e32 v131, 31, v130
	v_ashrrev_i32_e32 v115, 31, v114
	v_lshl_add_u64 v[80:81], v[128:129], 3, s[14:15]
	v_lshl_add_u64 v[82:83], v[130:131], 3, s[14:15]
	v_lshl_add_u64 v[84:85], v[114:115], 3, s[14:15]
	global_load_dwordx2 v[126:127], v[80:81], off
	global_load_dwordx2 v[124:125], v[82:83], off
	global_load_dwordx2 v[120:121], v[84:85], off
	global_load_dwordx4 v[100:103], v[196:197], off
	global_load_dwordx4 v[104:107], v[198:199], off
	global_load_dwordx4 v[96:99], v[200:201], off
	s_nop 0
	global_load_dwordx4 v[84:87], v[202:203], off
	global_load_dwordx4 v[88:91], v[204:205], off
	global_load_dwordx4 v[80:83], v[206:207], off
	global_load_dwordx4 v[108:111], v[208:209], off
	global_load_dwordx4 v[92:95], v[210:211], off
	s_waitcnt vmcnt(0)
	v_ffbh_u32_e32 v113, v117
	v_min_u32_e32 v113, 32, v113
	v_lshlrev_b64 v[116:117], v113, v[116:117]
	v_min_u32_e32 v115, 1, v116
	v_or_b32_e32 v115, v117, v115
	v_cvt_f32_u32_e32 v115, v115
	v_sub_u32_e32 v113, 32, v113
	v_ldexp_f32 v113, v115, v113
	v_fmamk_f32 v113, v113, 0x2e800000, v252
	v_mul_f32_e32 v115, 0x4b800000, v113
	v_cmp_gt_f32_e32 vcc, s86, v113
	s_nop 1
	v_cndmask_b32_e32 v113, v113, v115, vcc
	v_rsq_f32_e32 v113, v113
	s_nop 0
	v_mul_f32_e32 v115, 0x45800000, v113
	v_cndmask_b32_e32 v116, v113, v115, vcc
	v_add_u32_e32 v113, s37, v246
	v_mad_i64_i32 v[118:119], s[12:13], v113, s87, 0
	v_pk_mul_f32 v[78:79], v[78:79], v[116:117] op_sel_hi:[1,0]
	v_pk_mul_f32 v[76:77], v[76:77], v[116:117] op_sel_hi:[1,0]
	v_pk_mul_f32 v[74:75], v[74:75], v[116:117] op_sel_hi:[1,0]
	v_pk_mul_f32 v[72:73], v[72:73], v[116:117] op_sel_hi:[1,0]
	v_lshl_add_u64 v[118:119], s[56:57], 0, v[118:119]
	s_and_saveexec_b64 s[12:13], s[4:5]
	s_cbranch_execz .LBB0_1520
	v_lshl_add_u64 v[122:123], v[190:191], 2, v[118:119]
	global_store_dwordx4 v[122:123], v[76:79], off
	global_store_dwordx4 v[122:123], v[72:75], off offset:512

; __device__ __forceinline__ float dpp_ror1(float v) { return __int_as_float(__builtin_amdgcn_update_dpp(0, __float_as_int(v), 0x121, 0xf, 0xf, false)); }
; __device__ __forceinline__ float dpp_ror2(float v) { return __int_as_float(__builtin_amdgcn_update_dpp(0, __float_as_int(v), 0x122, 0xf, 0xf, false)); }
;   __device__ __forceinline__ void operator()(const AccT& acc, const Unit& u, int wr, int wc, int fr, int fq) const {
;     ...
;             const float g_cur = xg[m][r], v_cur = xv[m][r];
;             const f32x4 xgp = xg[m > 0 ? m - 1 : 0], xvp = xv[m > 0 ? m - 1 : 0];
;             const float g_pm = (m > 0) ? xgp[r] : 0.f, v_pm = (m > 0) ? xvp[r] : 0.f;
;             const float g1 = dpp_ror1((fr == 15) ? g_pm : g_cur), g2 = dpp_ror2((fr >= 14) ? g_pm : g_cur);
;             const float v1 = dpp_ror1((fr == 15) ? v_pm : v_cur), v2 = dpp_ror2((fr >= 14) ? v_pm : v_cur);
.LBB0_1522:
	s_or_b64 exec, exec, s[12:13]
	v_cndmask_b32_e64 v134, v76, 0, s[8:9]
	s_nop 0
	s_nop 0

; __device__ __forceinline__ float dpp_ror1(float v) { return __int_as_float(__builtin_amdgcn_update_dpp(0, __float_as_int(v), 0x121, 0xf, 0xf, false)); }
; __device__ __forceinline__ float dpp_ror2(float v) { return __int_as_float(__builtin_amdgcn_update_dpp(0, __float_as_int(v), 0x122, 0xf, 0xf, false)); }
;   __device__ __forceinline__ void operator()(const AccT& acc, const Unit& u, int wr, int wc, int fr, int fq) const {
;     ...
;             const float g_cur = xg[m][r], v_cur = xv[m][r];
;             const f32x4 xgp = xg[m > 0 ? m - 1 : 0], xvp = xv[m > 0 ? m - 1 : 0];
;             const float g_pm = (m > 0) ? xgp[r] : 0.f, v_pm = (m > 0) ? xvp[r] : 0.f;
;             const float g1 = dpp_ror1((fr == 15) ? g_pm : g_cur), g2 = dpp_ror2((fr >= 14) ? g_pm : g_cur);
;             const float v1 = dpp_ror1((fr == 15) ? v_pm : v_cur), v2 = dpp_ror2((fr >= 14) ? v_pm : v_cur);
	v_mov_b32_dpp v160, v134 row_ror:1 row_mask:0xf bank_mask:0xf
	v_mov_b32_dpp v162, v133 row_ror:2 row_mask:0xf bank_mask:0xf
	v_cndmask_b32_e64 v133, v72, 0, s[8:9]

; __device__ __forceinline__ float dpp_ror1(float v) { return __int_as_float(__builtin_amdgcn_update_dpp(0, __float_as_int(v), 0x121, 0xf, 0xf, false)); }
; __device__ __forceinline__ float dpp_ror2(float v) { return __int_as_float(__builtin_amdgcn_update_dpp(0, __float_as_int(v), 0x122, 0xf, 0xf, false)); }
;   __device__ __forceinline__ void operator()(const AccT& acc, const Unit& u, int wr, int wc, int fr, int fq) const {
;     ...
;             const float g_cur = xg[m][r], v_cur = xv[m][r];
;             const f32x4 xgp = xg[m > 0 ? m - 1 : 0], xvp = xv[m > 0 ? m - 1 : 0];
;             const float g_pm = (m > 0) ? xgp[r] : 0.f, v_pm = (m > 0) ? xvp[r] : 0.f;
;             const float g1 = dpp_ror1((fr == 15) ? g_pm : g_cur), g2 = dpp_ror2((fr >= 14) ? g_pm : g_cur);
;             const float v1 = dpp_ror1((fr == 15) ? v_pm : v_cur), v2 = dpp_ror2((fr >= 14) ? v_pm : v_cur);
	v_mov_b32_dpp v142, v132 row_ror:2 row_mask:0xf bank_mask:0xf
	v_cndmask_b32_e64 v132, v77, 0, s[8:9]
	s_nop 0


; __device__ __forceinline__ float dpp_ror1(float v) { return __int_as_float(__builtin_amdgcn_update_dpp(0, __float_as_int(v), 0x121, 0xf, 0xf, false)); }
; __device__ __forceinline__ float dpp_ror2(float v) { return __int_as_float(__builtin_amdgcn_update_dpp(0, __float_as_int(v), 0x122, 0xf, 0xf, false)); }
;   __device__ __forceinline__ void operator()(const AccT& acc, const Unit& u, int wr, int wc, int fr, int fq) const {
;     ...
;             const float g_cur = xg[m][r], v_cur = xv[m][r];
;             const f32x4 xgp = xg[m > 0 ? m - 1 : 0], xvp = xv[m > 0 ? m - 1 : 0];
;             const float g_pm = (m > 0) ? xgp[r] : 0.f, v_pm = (m > 0) ? xvp[r] : 0.f;
;             const float g1 = dpp_ror1((fr == 15) ? g_pm : g_cur), g2 = dpp_ror2((fr >= 14) ? g_pm : g_cur);
;             const float v1 = dpp_ror1((fr == 15) ? v_pm : v_cur), v2 = dpp_ror2((fr >= 14) ? v_pm : v_cur);
	v_mov_b32_dpp v138, v133 row_ror:1 row_mask:0xf bank_mask:0xf
	v_mov_b32_dpp v161, v132 row_ror:1 row_mask:0xf bank_mask:0xf
	v_mov_b32_dpp v163, v131 row_ror:2 row_mask:0xf bank_mask:0xf
	v_cndmask_b32_e64 v131, v73, 0, s[8:9]

; __device__ __forceinline__ float dpp_ror1(float v) { return __int_as_float(__builtin_amdgcn_update_dpp(0, __float_as_int(v), 0x121, 0xf, 0xf, false)); }
; __device__ __forceinline__ float dpp_ror2(float v) { return __int_as_float(__builtin_amdgcn_update_dpp(0, __float_as_int(v), 0x122, 0xf, 0xf, false)); }
;   __device__ __forceinline__ void operator()(const AccT& acc, const Unit& u, int wr, int wc, int fr, int fq) const {
;     ...
;             const float g_cur = xg[m][r], v_cur = xv[m][r];
;             const f32x4 xgp = xg[m > 0 ? m - 1 : 0], xvp = xv[m > 0 ? m - 1 : 0];
;             const float g_pm = (m > 0) ? xgp[r] : 0.f, v_pm = (m > 0) ? xvp[r] : 0.f;
;             const float g1 = dpp_ror1((fr == 15) ? g_pm : g_cur), g2 = dpp_ror2((fr >= 14) ? g_pm : g_cur);
;             const float v1 = dpp_ror1((fr == 15) ? v_pm : v_cur), v2 = dpp_ror2((fr >= 14) ? v_pm : v_cur);
	v_mov_b32_dpp v143, v129 row_ror:2 row_mask:0xf bank_mask:0xf
	v_cndmask_b32_e64 v129, v78, 0, s[8:9]

; __device__ __forceinline__ float dpp_ror1(float v) { return __int_as_float(__builtin_amdgcn_update_dpp(0, __float_as_int(v), 0x121, 0xf, 0xf, false)); }
; __device__ __forceinline__ float dpp_ror2(float v) { return __int_as_float(__builtin_amdgcn_update_dpp(0, __float_as_int(v), 0x122, 0xf, 0xf, false)); }
;   __device__ __forceinline__ void operator()(const AccT& acc, const Unit& u, int wr, int wc, int fr, int fq) const {
;     ...
;             const float g_cur = xg[m][r], v_cur = xv[m][r];
;             const f32x4 xgp = xg[m > 0 ? m - 1 : 0], xvp = xv[m > 0 ? m - 1 : 0];
;             const float g_pm = (m > 0) ? xgp[r] : 0.f, v_pm = (m > 0) ? xvp[r] : 0.f;
;             const float g1 = dpp_ror1((fr == 15) ? g_pm : g_cur), g2 = dpp_ror2((fr >= 14) ? g_pm : g_cur);
;             const float v1 = dpp_ror1((fr == 15) ? v_pm : v_cur), v2 = dpp_ror2((fr >= 14) ? v_pm : v_cur);
	v_mov_b32_dpp v140, v121 row_ror:2 row_mask:0xf bank_mask:0xf
	v_cndmask_b32_e64 v121, v74, 0, s[8:9]

; __device__ __forceinline__ float dpp_ror1(float v) { return __int_as_float(__builtin_amdgcn_update_dpp(0, __float_as_int(v), 0x121, 0xf, 0xf, false)); }
; __device__ __forceinline__ float dpp_ror2(float v) { return __int_as_float(__builtin_amdgcn_update_dpp(0, __float_as_int(v), 0x122, 0xf, 0xf, false)); }
;   __device__ __forceinline__ void operator()(const AccT& acc, const Unit& u, int wr, int wc, int fr, int fq) const {
;     ...
;             const float g_cur = xg[m][r], v_cur = xv[m][r];
;             const f32x4 xgp = xg[m > 0 ? m - 1 : 0], xvp = xv[m > 0 ? m - 1 : 0];
;             const float g_pm = (m > 0) ? xgp[r] : 0.f, v_pm = (m > 0) ? xvp[r] : 0.f;
;             const float g1 = dpp_ror1((fr == 15) ? g_pm : g_cur), g2 = dpp_ror2((fr >= 14) ? g_pm : g_cur);
;             const float v1 = dpp_ror1((fr == 15) ? v_pm : v_cur), v2 = dpp_ror2((fr >= 14) ? v_pm : v_cur);
	v_mov_b32_dpp v134, v117 row_ror:2 row_mask:0xf bank_mask:0xf
	v_cndmask_b32_e64 v117, v79, 0, s[8:9]

; __device__ __forceinline__ float dpp_ror1(float v) { return __int_as_float(__builtin_amdgcn_update_dpp(0, __float_as_int(v), 0x121, 0xf, 0xf, false)); }
; __device__ __forceinline__ float dpp_ror2(float v) { return __int_as_float(__builtin_amdgcn_update_dpp(0, __float_as_int(v), 0x122, 0xf, 0xf, false)); }
;   __device__ __forceinline__ void operator()(const AccT& acc, const Unit& u, int wr, int wc, int fr, int fq) const {
;     ...
;             const float g_cur = xg[m][r], v_cur = xv[m][r];
;             const f32x4 xgp = xg[m > 0 ? m - 1 : 0], xvp = xv[m > 0 ? m - 1 : 0];
;             const float g_pm = (m > 0) ? xgp[r] : 0.f, v_pm = (m > 0) ? xvp[r] : 0.f;
;             const float g1 = dpp_ror1((fr == 15) ? g_pm : g_cur), g2 = dpp_ror2((fr >= 14) ? g_pm : g_cur);
;             const float v1 = dpp_ror1((fr == 15) ? v_pm : v_cur), v2 = dpp_ror2((fr >= 14) ? v_pm : v_cur);
	v_mov_b32_dpp v141, v115 row_ror:2 row_mask:0xf bank_mask:0xf
	v_cndmask_b32_e64 v115, v75, 0, s[8:9]


;   __device__ __forceinline__ void operator()(const AccT& acc, const Unit& u, int wr, int wc, int fr, int fq) const {
;     ...
;       for (int m = 0; m < 4; ++m) rs[m] = rstd_of(rowss, EPI_ROW(u, ai, m));
;       const int chunk = 4 * u.pm + 2 * ai + wr;
; #pragma unroll
;       for (int n = 0; n < 2; ++n) {
;         const int f0 = 128 * u.pn + 32 * wc + 16 * n + 4 * fq;
;         const int gc = u.pn * 256 + 32 * wc + 16 * n + 4 * fq;
;         const f32x4 wg0 = *(const f32x4*)(cw + f0), wg1 = *(const f32x4*)(cw + NUP + f0), wg2 = *(const f32x4*)(cw + 2 * NUP + f0);
;         const f32x4 wv0 = *(const f32x4*)(cw + DFF + f0), wv1 = *(const f32x4*)(cw + NUP + DFF + f0), wv2 = *(const f32x4*)(cw + 2 * NUP + DFF + f0);
;         const f32x4 bg = *(const f32x4*)(cb + f0), bv = *(const f32x4*)(cb + DFF + f0);
;         f32x4 xg[4], xv[4];
; #pragma unroll
;         for (int m = 0; m < 4; ++m) { xg[m] = acc[ai][0][m][n] * rs[m]; xv[m] = acc[ai][1][m][n] * rs[m]; }
;         if (fr < 2) {
;           float* d = ub + ((size_t)(chunk * 4 + fr) * NUP + gc);
;           *(float4*)d = make_float4(xg[0][0], xg[0][1], xg[0][2], xg[0][3]);
;           *(float4*)(d + 128) = make_float4(xv[0][0], xv[0][1], xv[0][2], xv[0][3]);
;         }
;         if (fr >= 14) {
;           float* d = ub + ((size_t)(chunk * 4 + 2 + (fr - 14)) * NUP + gc);
;           *(float4*)d = make_float4(xg[3][0], xg[3][1], xg[3][2], xg[3][3]);
;           *(float4*)(d + 128) = make_float4(xv[3][0], xv[3][1], xv[3][2], xv[3][3]);
;         }
; #pragma unroll
;         for (int m = 0; m < 4; ++m) {
;           f32x4 res;
; #pragma unroll
;           for (int r = 0; r < 4; ++r) {
;             const float g_cur = xg[m][r], v_cur = xv[m][r];
;             const f32x4 xgp = xg[m > 0 ? m - 1 : 0], xvp = xv[m > 0 ? m - 1 : 0];
;             const float g_pm = (m > 0) ? xgp[r] : 0.f, v_pm = (m > 0) ? xvp[r] : 0.f;
;             const float g1 = dpp_ror1((fr == 15) ? g_pm : g_cur), g2 = dpp_ror2((fr >= 14) ? g_pm : g_cur);
;             const float v1 = dpp_ror1((fr == 15) ? v_pm : v_cur), v2 = dpp_ror2((fr >= 14) ? v_pm : v_cur);
;             const float cg_ = bg[r] + g2 * wg0[r] + g1 * wg1[r] + g_cur * wg2[r];
;             const float cv_ = bv[r] + v2 * wv0[r] + v1 * wv1[r] + v_cur * wv2[r];
;             res[r] = cg_ * __builtin_amdgcn_rcpf(1.f + __builtin_amdgcn_exp2f(-1.4426950408889634f * cg_)) * cv_;
	v_mov_b32_dpp v139, v131 row_ror:1 row_mask:0xf bank_mask:0xf
	v_mov_b32_dpp v136, v129 row_ror:1 row_mask:0xf bank_mask:0xf
	v_mov_b32_dpp v132, v121 row_ror:1 row_mask:0xf bank_mask:0xf
	v_mov_b32_dpp v137, v117 row_ror:1 row_mask:0xf bank_mask:0xf
	v_mov_b32_dpp v133, v115 row_ror:1 row_mask:0xf bank_mask:0xf
	v_mov_b32_dpp v135, v113 row_ror:2 row_mask:0xf bank_mask:0xf
	s_and_saveexec_b64 s[12:13], s[4:5]
	s_xor_b64 s[12:13], exec, s[12:13]
	s_andn2_saveexec_b64 s[12:13], s[12:13]
	s_cbranch_execz .LBB0_1526
	v_pk_fma_f32 v[162:163], v[100:101], v[162:163], v[108:109]
	v_pk_fma_f32 v[140:141], v[102:103], v[140:141], v[110:111]
	v_pk_fma_f32 v[160:161], v[104:105], v[160:161], v[162:163]
	v_pk_fma_f32 v[136:137], v[106:107], v[136:137], v[140:141]
	v_pk_fma_f32 v[160:161], v[96:97], v[76:77], v[160:161]
	v_pk_fma_f32 v[136:137], v[98:99], v[78:79], v[136:137]
	v_mul_f32_e32 v113, 0xbfb8aa3b, v160
	v_exp_f32_e32 v113, v113
	v_mul_f32_e32 v115, 0xbfb8aa3b, v161
	v_exp_f32_e32 v115, v115
	v_pk_fma_f32 v[134:135], v[86:87], v[134:135], v[94:95]
	v_add_f32_e32 v113, 1.0, v113
	v_rcp_f32_e32 v162, v113
	v_add_f32_e32 v115, 1.0, v115
	v_mul_f32_e32 v113, 0xbfb8aa3b, v136
	v_rcp_f32_e32 v163, v115
	v_exp_f32_e32 v113, v113
	v_mul_f32_e32 v115, 0xbfb8aa3b, v137
	v_exp_f32_e32 v115, v115
	v_pk_fma_f32 v[132:133], v[90:91], v[132:133], v[134:135]
	v_add_f32_e32 v113, 1.0, v113
	v_rcp_f32_e32 v140, v113
	v_add_f32_e32 v113, 1.0, v115
	v_rcp_f32_e32 v141, v113
	v_pk_fma_f32 v[142:143], v[84:85], v[142:143], v[92:93]
	v_pk_fma_f32 v[132:133], v[82:83], v[74:75], v[132:133]
	v_pk_fma_f32 v[138:139], v[88:89], v[138:139], v[142:143]
	v_pk_mul_f32 v[134:135], v[136:137], v[140:141]
	v_pk_fma_f32 v[138:139], v[80:81], v[72:73], v[138:139]
	v_pk_mul_f32 v[132:133], v[132:133], v[134:135]
	v_pk_mul_f32 v[142:143], v[160:161], v[162:163]
	v_cvt_pk_bf16_f32 v135, v132, v133
	v_mov_b64_e32 v[132:133], s[52:53]
	v_pk_mul_f32 v[138:139], v[138:139], v[142:143]
	v_mad_i64_i32 v[132:133], s[46:47], v112, s88, v[132:133]
	v_cvt_pk_bf16_f32 v134, v138, v139
	v_lshl_add_u64 v[132:133], v[188:189], 1, v[132:133]
	global_store_dwordx2 v[132:133], v[134:135], off
.LBB0_1526:
	s_or_b64 exec, exec, s[12:13]
	v_ffbh_u32_e32 v113, v127
	v_min_u32_e32 v113, 32, v113
	v_lshlrev_b64 v[126:127], v113, v[126:127]
	v_min_u32_e32 v115, 1, v126
	v_or_b32_e32 v115, v127, v115
	v_ffbh_u32_e32 v117, v125
	v_cvt_f32_u32_e32 v115, v115
	v_min_u32_e32 v117, 32, v117
	v_lshlrev_b64 v[124:125], v117, v[124:125]
	v_min_u32_e32 v121, 1, v124
	v_sub_u32_e32 v113, 32, v113
	v_or_b32_e32 v121, v125, v121
	v_ldexp_f32 v113, v115, v113
	v_cvt_f32_u32_e32 v121, v121
	v_fmamk_f32 v113, v113, 0x2e800000, v252
	v_mul_f32_e32 v115, 0x4b800000, v113
	v_cmp_gt_f32_e32 vcc, s86, v113
	s_nop 0
	s_nop 0
	v_cndmask_b32_e32 v113, v113, v115, vcc
	v_sub_u32_e32 v115, 32, v117
	v_ldexp_f32 v115, v121, v115
	v_fmamk_f32 v115, v115, 0x2e800000, v252
	v_mul_f32_e32 v117, 0x4b800000, v115
	v_cmp_gt_f32_e64 s[12:13], s86, v115
	v_rsq_f32_e32 v113, v113
	s_nop 0
	v_cndmask_b32_e64 v115, v115, v117, s[12:13]
	v_rsq_f32_e32 v115, v115
	v_mul_f32_e32 v117, 0x45800000, v113
	v_cndmask_b32_e32 v124, v113, v117, vcc
	v_pk_mul_f32 v[60:61], v[60:61], v[124:125] op_sel_hi:[1,0]
	v_mul_f32_e32 v113, 0x45800000, v115
	v_cndmask_b32_e64 v126, v115, v113, s[12:13]
	v_pk_mul_f32 v[132:133], v[54:55], v[124:125] op_sel_hi:[1,0]
	v_pk_mul_f32 v[54:55], v[56:57], v[126:127] op_sel_hi:[1,0]
	v_cndmask_b32_e64 v57, v60, v76, s[8:9]

; __device__ __forceinline__ float dpp_ror1(float v) { return __int_as_float(__builtin_amdgcn_update_dpp(0, __float_as_int(v), 0x121, 0xf, 0xf, false)); }
; __device__ __forceinline__ float dpp_ror2(float v) { return __int_as_float(__builtin_amdgcn_update_dpp(0, __float_as_int(v), 0x122, 0xf, 0xf, false)); }
;   __device__ __forceinline__ void operator()(const AccT& acc, const Unit& u, int wr, int wc, int fr, int fq) const {
;     ...
;         for (int m = 0; m < 4; ++m) { xg[m] = acc[ai][0][m][n] * rs[m]; xv[m] = acc[ai][1][m][n] * rs[m]; }
;     ...
;             const float g_cur = xg[m][r], v_cur = xv[m][r];
;             const f32x4 xgp = xg[m > 0 ? m - 1 : 0], xvp = xv[m > 0 ? m - 1 : 0];
;             const float g_pm = (m > 0) ? xgp[r] : 0.f, v_pm = (m > 0) ? xvp[r] : 0.f;
;             const float g1 = dpp_ror1((fr == 15) ? g_pm : g_cur), g2 = dpp_ror2((fr >= 14) ? g_pm : g_cur);
;             const float v1 = dpp_ror1((fr == 15) ? v_pm : v_cur), v2 = dpp_ror2((fr >= 14) ? v_pm : v_cur);
	v_pk_mul_f32 v[134:135], v[52:53], v[124:125] op_sel_hi:[1,0]
	v_pk_mul_f32 v[52:53], v[58:59], v[126:127] op_sel_hi:[1,0]
	v_mov_b32_dpp v56, v57 row_ror:1 row_mask:0xf bank_mask:0xf
	v_cndmask_b32_e64 v57, v60, v76, s[6:7]
	s_nop 0

; __device__ __forceinline__ float dpp_ror1(float v) { return __int_as_float(__builtin_amdgcn_update_dpp(0, __float_as_int(v), 0x121, 0xf, 0xf, false)); }
; __device__ __forceinline__ float dpp_ror2(float v) { return __int_as_float(__builtin_amdgcn_update_dpp(0, __float_as_int(v), 0x122, 0xf, 0xf, false)); }
;   __device__ __forceinline__ void operator()(const AccT& acc, const Unit& u, int wr, int wc, int fr, int fq) const {
;     ...
;         for (int m = 0; m < 4; ++m) { xg[m] = acc[ai][0][m][n] * rs[m]; xv[m] = acc[ai][1][m][n] * rs[m]; }
;     ...
;             const float g_cur = xg[m][r], v_cur = xv[m][r];
;             const f32x4 xgp = xg[m > 0 ? m - 1 : 0], xvp = xv[m > 0 ? m - 1 : 0];
;             const float g_pm = (m > 0) ? xgp[r] : 0.f, v_pm = (m > 0) ? xvp[r] : 0.f;
;             const float g1 = dpp_ror1((fr == 15) ? g_pm : g_cur), g2 = dpp_ror2((fr >= 14) ? g_pm : g_cur);
;             const float v1 = dpp_ror1((fr == 15) ? v_pm : v_cur), v2 = dpp_ror2((fr >= 14) ? v_pm : v_cur);
	v_cndmask_b32_e64 v59, v61, v77, s[8:9]
	v_mov_b32_dpp v58, v57 row_ror:2 row_mask:0xf bank_mask:0xf
	v_cndmask_b32_e64 v57, v134, v72, s[8:9]
	v_cndmask_b32_e64 v77, v61, v77, s[6:7]
	v_cndmask_b32_e64 v113, v135, v73, s[8:9]
	v_mov_b32_dpp v76, v57 row_ror:1 row_mask:0xf bank_mask:0xf
	v_cndmask_b32_e64 v57, v134, v72, s[6:7]
	s_nop 0
	v_pk_mul_f32 v[62:63], v[62:63], v[124:125] op_sel_hi:[1,0]

; __device__ __forceinline__ float dpp_ror1(float v) { return __int_as_float(__builtin_amdgcn_update_dpp(0, __float_as_int(v), 0x121, 0xf, 0xf, false)); }
; __device__ __forceinline__ float dpp_ror2(float v) { return __int_as_float(__builtin_amdgcn_update_dpp(0, __float_as_int(v), 0x122, 0xf, 0xf, false)); }
;   __device__ __forceinline__ void operator()(const AccT& acc, const Unit& u, int wr, int wc, int fr, int fq) const {
;     ...
;             const float g_cur = xg[m][r], v_cur = xv[m][r];
;             const f32x4 xgp = xg[m > 0 ? m - 1 : 0], xvp = xv[m > 0 ? m - 1 : 0];
;             const float g_pm = (m > 0) ? xgp[r] : 0.f, v_pm = (m > 0) ? xvp[r] : 0.f;
;             const float g1 = dpp_ror1((fr == 15) ? g_pm : g_cur), g2 = dpp_ror2((fr >= 14) ? g_pm : g_cur);
;             const float v1 = dpp_ror1((fr == 15) ? v_pm : v_cur), v2 = dpp_ror2((fr >= 14) ? v_pm : v_cur);
	v_mov_b32_dpp v72, v57 row_ror:2 row_mask:0xf bank_mask:0xf

; __device__ __forceinline__ float dpp_ror1(float v) { return __int_as_float(__builtin_amdgcn_update_dpp(0, __float_as_int(v), 0x121, 0xf, 0xf, false)); }
; __device__ __forceinline__ float dpp_ror2(float v) { return __int_as_float(__builtin_amdgcn_update_dpp(0, __float_as_int(v), 0x122, 0xf, 0xf, false)); }
;   __device__ __forceinline__ void operator()(const AccT& acc, const Unit& u, int wr, int wc, int fr, int fq) const {
;     ...
;         for (int m = 0; m < 4; ++m) { xg[m] = acc[ai][0][m][n] * rs[m]; xv[m] = acc[ai][1][m][n] * rs[m]; }
;     ...
;             const float g_cur = xg[m][r], v_cur = xv[m][r];
;             const f32x4 xgp = xg[m > 0 ? m - 1 : 0], xvp = xv[m > 0 ? m - 1 : 0];
;             const float g_pm = (m > 0) ? xgp[r] : 0.f, v_pm = (m > 0) ? xvp[r] : 0.f;
;             const float g1 = dpp_ror1((fr == 15) ? g_pm : g_cur), g2 = dpp_ror2((fr >= 14) ? g_pm : g_cur);
;             const float v1 = dpp_ror1((fr == 15) ? v_pm : v_cur), v2 = dpp_ror2((fr >= 14) ? v_pm : v_cur);
	v_pk_mul_f32 v[48:49], v[48:49], v[126:127] op_sel_hi:[1,0]
	v_pk_mul_f32 v[50:51], v[50:51], v[126:127] op_sel_hi:[1,0]
	v_mov_b32_dpp v57, v59 row_ror:1 row_mask:0xf bank_mask:0xf

; __device__ __forceinline__ float dpp_ror1(float v) { return __int_as_float(__builtin_amdgcn_update_dpp(0, __float_as_int(v), 0x121, 0xf, 0xf, false)); }
; __device__ __forceinline__ float dpp_ror2(float v) { return __int_as_float(__builtin_amdgcn_update_dpp(0, __float_as_int(v), 0x122, 0xf, 0xf, false)); }
;   __device__ __forceinline__ void operator()(const AccT& acc, const Unit& u, int wr, int wc, int fr, int fq) const {
;     ...
;         for (int m = 0; m < 4; ++m) { xg[m] = acc[ai][0][m][n] * rs[m]; xv[m] = acc[ai][1][m][n] * rs[m]; }
;     ...
;             const float g_cur = xg[m][r], v_cur = xv[m][r];
;             const f32x4 xgp = xg[m > 0 ? m - 1 : 0], xvp = xv[m > 0 ? m - 1 : 0];
;             const float g_pm = (m > 0) ? xgp[r] : 0.f, v_pm = (m > 0) ? xvp[r] : 0.f;
;             const float g1 = dpp_ror1((fr == 15) ? g_pm : g_cur), g2 = dpp_ror2((fr >= 14) ? g_pm : g_cur);
;             const float v1 = dpp_ror1((fr == 15) ? v_pm : v_cur), v2 = dpp_ror2((fr >= 14) ? v_pm : v_cur);
;             const float cg_ = bg[r] + g2 * wg0[r] + g1 * wg1[r] + g_cur * wg2[r];
	v_mov_b32_e32 v117, v116
	v_pk_mul_f32 v[44:45], v[44:45], v[116:117]
	v_mov_b32_dpp v59, v77 row_ror:2 row_mask:0xf bank_mask:0xf
	v_pk_fma_f32 v[58:59], v[100:101], v[58:59], v[108:109]

; __device__ __forceinline__ float dpp_ror1(float v) { return __int_as_float(__builtin_amdgcn_update_dpp(0, __float_as_int(v), 0x121, 0xf, 0xf, false)); }
; __device__ __forceinline__ float dpp_ror2(float v) { return __int_as_float(__builtin_amdgcn_update_dpp(0, __float_as_int(v), 0x122, 0xf, 0xf, false)); }
;   __device__ __forceinline__ void operator()(const AccT& acc, const Unit& u, int wr, int wc, int fr, int fq) const {
;     ...
;             const float g_cur = xg[m][r], v_cur = xv[m][r];
;             const f32x4 xgp = xg[m > 0 ? m - 1 : 0], xvp = xv[m > 0 ? m - 1 : 0];
;             const float g_pm = (m > 0) ? xgp[r] : 0.f, v_pm = (m > 0) ? xvp[r] : 0.f;
;             const float g1 = dpp_ror1((fr == 15) ? g_pm : g_cur), g2 = dpp_ror2((fr >= 14) ? g_pm : g_cur);
;             const float v1 = dpp_ror1((fr == 15) ? v_pm : v_cur), v2 = dpp_ror2((fr >= 14) ? v_pm : v_cur);
;             const float cg_ = bg[r] + g2 * wg0[r] + g1 * wg1[r] + g_cur * wg2[r];
;             const float cv_ = bv[r] + v2 * wv0[r] + v1 * wv1[r] + v_cur * wv2[r];
;             res[r] = cg_ * __builtin_amdgcn_rcpf(1.f + __builtin_amdgcn_exp2f(-1.4426950408889634f * cg_)) * cv_;
	v_pk_fma_f32 v[56:57], v[104:105], v[56:57], v[58:59]
	v_pk_mul_f32 v[40:41], v[40:41], v[116:117]
	v_pk_fma_f32 v[56:57], v[96:97], v[60:61], v[56:57]
	v_mov_b32_dpp v77, v113 row_ror:1 row_mask:0xf bank_mask:0xf
	v_mul_f32_e32 v58, 0xbfb8aa3b, v56
	v_mul_f32_e32 v59, 0xbfb8aa3b, v57
	v_exp_f32_e32 v58, v58
	v_exp_f32_e32 v59, v59
	v_cndmask_b32_e64 v113, v135, v73, s[6:7]

; __device__ __forceinline__ float dpp_ror1(float v) { return __int_as_float(__builtin_amdgcn_update_dpp(0, __float_as_int(v), 0x121, 0xf, 0xf, false)); }
; __device__ __forceinline__ float dpp_ror2(float v) { return __int_as_float(__builtin_amdgcn_update_dpp(0, __float_as_int(v), 0x122, 0xf, 0xf, false)); }
;   __device__ __forceinline__ void operator()(const AccT& acc, const Unit& u, int wr, int wc, int fr, int fq) const {
;     ...
;             const float g_cur = xg[m][r], v_cur = xv[m][r];
;             const f32x4 xgp = xg[m > 0 ? m - 1 : 0], xvp = xv[m > 0 ? m - 1 : 0];
;             const float g_pm = (m > 0) ? xgp[r] : 0.f, v_pm = (m > 0) ? xvp[r] : 0.f;
;             const float g1 = dpp_ror1((fr == 15) ? g_pm : g_cur), g2 = dpp_ror2((fr >= 14) ? g_pm : g_cur);
;             const float v1 = dpp_ror1((fr == 15) ? v_pm : v_cur), v2 = dpp_ror2((fr >= 14) ? v_pm : v_cur);
;             const float cg_ = bg[r] + g2 * wg0[r] + g1 * wg1[r] + g_cur * wg2[r];
;             const float cv_ = bv[r] + v2 * wv0[r] + v1 * wv1[r] + v_cur * wv2[r];
;             res[r] = cg_ * __builtin_amdgcn_rcpf(1.f + __builtin_amdgcn_exp2f(-1.4426950408889634f * cg_)) * cv_;
	v_add_f32_e32 v58, 1.0, v58
	v_add_f32_e32 v59, 1.0, v59
	v_mov_b32_dpp v73, v113 row_ror:2 row_mask:0xf bank_mask:0xf
	v_cndmask_b32_e64 v113, v62, v78, s[8:9]
	v_rcp_f32_e32 v58, v58
	v_rcp_f32_e32 v59, v59
	v_mov_b32_dpp v136, v113 row_ror:1 row_mask:0xf bank_mask:0xf
	v_cndmask_b32_e64 v113, v62, v78, s[6:7]

; __device__ __forceinline__ float dpp_ror1(float v) { return __int_as_float(__builtin_amdgcn_update_dpp(0, __float_as_int(v), 0x121, 0xf, 0xf, false)); }
; __device__ __forceinline__ float dpp_ror2(float v) { return __int_as_float(__builtin_amdgcn_update_dpp(0, __float_as_int(v), 0x122, 0xf, 0xf, false)); }
;   __device__ __forceinline__ void operator()(const AccT& acc, const Unit& u, int wr, int wc, int fr, int fq) const {
;     ...
;             const float g_cur = xg[m][r], v_cur = xv[m][r];
;             const f32x4 xgp = xg[m > 0 ? m - 1 : 0], xvp = xv[m > 0 ? m - 1 : 0];
;             const float g_pm = (m > 0) ? xgp[r] : 0.f, v_pm = (m > 0) ? xvp[r] : 0.f;
;             const float g1 = dpp_ror1((fr == 15) ? g_pm : g_cur), g2 = dpp_ror2((fr >= 14) ? g_pm : g_cur);
;             const float v1 = dpp_ror1((fr == 15) ? v_pm : v_cur), v2 = dpp_ror2((fr >= 14) ? v_pm : v_cur);
;             const float cg_ = bg[r] + g2 * wg0[r] + g1 * wg1[r] + g_cur * wg2[r];
;             const float cv_ = bv[r] + v2 * wv0[r] + v1 * wv1[r] + v_cur * wv2[r];
;             res[r] = cg_ * __builtin_amdgcn_rcpf(1.f + __builtin_amdgcn_exp2f(-1.4426950408889634f * cg_)) * cv_;
	v_pk_mul_f32 v[56:57], v[56:57], v[58:59]
	v_pk_fma_f32 v[72:73], v[84:85], v[72:73], v[92:93]
	v_mov_b32_dpp v78, v113 row_ror:2 row_mask:0xf bank_mask:0xf
	v_cndmask_b32_e64 v113, v132, v74, s[8:9]
	v_pk_fma_f32 v[72:73], v[88:89], v[76:77], v[72:73]
	s_nop 0
	v_mov_b32_dpp v138, v113 row_ror:1 row_mask:0xf bank_mask:0xf
	v_cndmask_b32_e64 v113, v132, v74, s[6:7]

; __device__ __forceinline__ float dpp_ror1(float v) { return __int_as_float(__builtin_amdgcn_update_dpp(0, __float_as_int(v), 0x121, 0xf, 0xf, false)); }
; __device__ __forceinline__ float dpp_ror2(float v) { return __int_as_float(__builtin_amdgcn_update_dpp(0, __float_as_int(v), 0x122, 0xf, 0xf, false)); }
;   __device__ __forceinline__ void operator()(const AccT& acc, const Unit& u, int wr, int wc, int fr, int fq) const {
;     ...
;             const float g_cur = xg[m][r], v_cur = xv[m][r];
;             const f32x4 xgp = xg[m > 0 ? m - 1 : 0], xvp = xv[m > 0 ? m - 1 : 0];
;             const float g_pm = (m > 0) ? xgp[r] : 0.f, v_pm = (m > 0) ? xvp[r] : 0.f;
;             const float g1 = dpp_ror1((fr == 15) ? g_pm : g_cur), g2 = dpp_ror2((fr >= 14) ? g_pm : g_cur);
;             const float v1 = dpp_ror1((fr == 15) ? v_pm : v_cur), v2 = dpp_ror2((fr >= 14) ? v_pm : v_cur);
;             const float cg_ = bg[r] + g2 * wg0[r] + g1 * wg1[r] + g_cur * wg2[r];
;             const float cv_ = bv[r] + v2 * wv0[r] + v1 * wv1[r] + v_cur * wv2[r];
;             res[r] = cg_ * __builtin_amdgcn_rcpf(1.f + __builtin_amdgcn_exp2f(-1.4426950408889634f * cg_)) * cv_;
	v_pk_fma_f32 v[72:73], v[80:81], v[134:135], v[72:73]
	s_nop 0
	v_mov_b32_dpp v74, v113 row_ror:2 row_mask:0xf bank_mask:0xf
	v_cndmask_b32_e64 v113, v63, v79, s[8:9]
	v_pk_mul_f32 v[56:57], v[72:73], v[56:57]
	s_nop 0
	v_mov_b32_dpp v137, v113 row_ror:1 row_mask:0xf bank_mask:0xf
	v_cndmask_b32_e64 v113, v63, v79, s[6:7]

; __device__ __forceinline__ float dpp_ror1(float v) { return __int_as_float(__builtin_amdgcn_update_dpp(0, __float_as_int(v), 0x121, 0xf, 0xf, false)); }
; __device__ __forceinline__ float dpp_ror2(float v) { return __int_as_float(__builtin_amdgcn_update_dpp(0, __float_as_int(v), 0x122, 0xf, 0xf, false)); }
;   __device__ __forceinline__ void operator()(const AccT& acc, const Unit& u, int wr, int wc, int fr, int fq) const {
;     ...
;             const float g_cur = xg[m][r], v_cur = xv[m][r];
;             const f32x4 xgp = xg[m > 0 ? m - 1 : 0], xvp = xv[m > 0 ? m - 1 : 0];
;             const float g_pm = (m > 0) ? xgp[r] : 0.f, v_pm = (m > 0) ? xvp[r] : 0.f;
;             const float g1 = dpp_ror1((fr == 15) ? g_pm : g_cur), g2 = dpp_ror2((fr >= 14) ? g_pm : g_cur);
;             const float v1 = dpp_ror1((fr == 15) ? v_pm : v_cur), v2 = dpp_ror2((fr >= 14) ? v_pm : v_cur);
;             const float cg_ = bg[r] + g2 * wg0[r] + g1 * wg1[r] + g_cur * wg2[r];
;             const float cv_ = bv[r] + v2 * wv0[r] + v1 * wv1[r] + v_cur * wv2[r];
;             res[r] = cg_ * __builtin_amdgcn_rcpf(1.f + __builtin_amdgcn_exp2f(-1.4426950408889634f * cg_)) * cv_;
	v_cvt_pk_bf16_f32 v56, v56, v57
	s_nop 0
	v_mov_b32_dpp v79, v113 row_ror:2 row_mask:0xf bank_mask:0xf
	v_pk_fma_f32 v[58:59], v[102:103], v[78:79], v[110:111]
	v_cndmask_b32_e64 v113, v133, v75, s[8:9]
	v_pk_fma_f32 v[58:59], v[106:107], v[136:137], v[58:59]

; __device__ __forceinline__ float dpp_ror1(float v) { return __int_as_float(__builtin_amdgcn_update_dpp(0, __float_as_int(v), 0x121, 0xf, 0xf, false)); }
; __device__ __forceinline__ float dpp_ror2(float v) { return __int_as_float(__builtin_amdgcn_update_dpp(0, __float_as_int(v), 0x122, 0xf, 0xf, false)); }
;   __device__ __forceinline__ void operator()(const AccT& acc, const Unit& u, int wr, int wc, int fr, int fq) const {
;     ...
;             const float g_cur = xg[m][r], v_cur = xv[m][r];
;             const f32x4 xgp = xg[m > 0 ? m - 1 : 0], xvp = xv[m > 0 ? m - 1 : 0];
;             const float g_pm = (m > 0) ? xgp[r] : 0.f, v_pm = (m > 0) ? xvp[r] : 0.f;
;             const float g1 = dpp_ror1((fr == 15) ? g_pm : g_cur), g2 = dpp_ror2((fr >= 14) ? g_pm : g_cur);
;             const float v1 = dpp_ror1((fr == 15) ? v_pm : v_cur), v2 = dpp_ror2((fr >= 14) ? v_pm : v_cur);
;             const float cg_ = bg[r] + g2 * wg0[r] + g1 * wg1[r] + g_cur * wg2[r];
;             const float cv_ = bv[r] + v2 * wv0[r] + v1 * wv1[r] + v_cur * wv2[r];
;             res[r] = cg_ * __builtin_amdgcn_rcpf(1.f + __builtin_amdgcn_exp2f(-1.4426950408889634f * cg_)) * cv_;
	v_pk_fma_f32 v[58:59], v[98:99], v[62:63], v[58:59]
	v_mov_b32_dpp v139, v113 row_ror:1 row_mask:0xf bank_mask:0xf
	v_mul_f32_e32 v76, 0xbfb8aa3b, v58
	v_mul_f32_e32 v77, 0xbfb8aa3b, v59
	v_exp_f32_e32 v76, v76
	v_exp_f32_e32 v77, v77
	v_cndmask_b32_e64 v113, v133, v75, s[6:7]

; __device__ __forceinline__ float dpp_ror1(float v) { return __int_as_float(__builtin_amdgcn_update_dpp(0, __float_as_int(v), 0x121, 0xf, 0xf, false)); }
; __device__ __forceinline__ float dpp_ror2(float v) { return __int_as_float(__builtin_amdgcn_update_dpp(0, __float_as_int(v), 0x122, 0xf, 0xf, false)); }
;   __device__ __forceinline__ void operator()(const AccT& acc, const Unit& u, int wr, int wc, int fr, int fq) const {
;     ...
;             const float g_cur = xg[m][r], v_cur = xv[m][r];
;             const f32x4 xgp = xg[m > 0 ? m - 1 : 0], xvp = xv[m > 0 ? m - 1 : 0];
;             const float g_pm = (m > 0) ? xgp[r] : 0.f, v_pm = (m > 0) ? xvp[r] : 0.f;
;             const float g1 = dpp_ror1((fr == 15) ? g_pm : g_cur), g2 = dpp_ror2((fr >= 14) ? g_pm : g_cur);
;             const float v1 = dpp_ror1((fr == 15) ? v_pm : v_cur), v2 = dpp_ror2((fr >= 14) ? v_pm : v_cur);
;             const float cg_ = bg[r] + g2 * wg0[r] + g1 * wg1[r] + g_cur * wg2[r];
;             const float cv_ = bv[r] + v2 * wv0[r] + v1 * wv1[r] + v_cur * wv2[r];
;             res[r] = cg_ * __builtin_amdgcn_rcpf(1.f + __builtin_amdgcn_exp2f(-1.4426950408889634f * cg_)) * cv_;
	v_add_f32_e32 v72, 1.0, v76
	v_add_f32_e32 v73, 1.0, v77
	v_rcp_f32_e32 v72, v72
	v_rcp_f32_e32 v73, v73
	v_mov_b32_dpp v75, v113 row_ror:2 row_mask:0xf bank_mask:0xf
	v_pk_fma_f32 v[74:75], v[86:87], v[74:75], v[94:95]
	v_cndmask_b32_e64 v76, v49, v135, s[6:7]
	v_pk_fma_f32 v[74:75], v[90:91], v[138:139], v[74:75]
	v_pk_mul_f32 v[58:59], v[58:59], v[72:73]
	v_pk_fma_f32 v[74:75], v[82:83], v[132:133], v[74:75]
	v_cndmask_b32_e64 v77, v52, v62, s[8:9]
	v_pk_mul_f32 v[58:59], v[74:75], v[58:59]

; __device__ __forceinline__ uint2 pack4(f32x4 v) { return make_uint2(pack2(v[0], v[1]), pack2(v[2], v[3])); }
; __device__ __forceinline__ float dpp_ror1(float v) { return __int_as_float(__builtin_amdgcn_update_dpp(0, __float_as_int(v), 0x121, 0xf, 0xf, false)); }
; __device__ __forceinline__ float dpp_ror2(float v) { return __int_as_float(__builtin_amdgcn_update_dpp(0, __float_as_int(v), 0x122, 0xf, 0xf, false)); }
;   __device__ __forceinline__ void operator()(const AccT& acc, const Unit& u, int wr, int wc, int fr, int fq) const {
;     ...
;             const float g_cur = xg[m][r], v_cur = xv[m][r];
;             const f32x4 xgp = xg[m > 0 ? m - 1 : 0], xvp = xv[m > 0 ? m - 1 : 0];
;             const float g_pm = (m > 0) ? xgp[r] : 0.f, v_pm = (m > 0) ? xvp[r] : 0.f;
;             const float g1 = dpp_ror1((fr == 15) ? g_pm : g_cur), g2 = dpp_ror2((fr >= 14) ? g_pm : g_cur);
;             const float v1 = dpp_ror1((fr == 15) ? v_pm : v_cur), v2 = dpp_ror2((fr >= 14) ? v_pm : v_cur);
;             const float cg_ = bg[r] + g2 * wg0[r] + g1 * wg1[r] + g_cur * wg2[r];
;             const float cv_ = bv[r] + v2 * wv0[r] + v1 * wv1[r] + v_cur * wv2[r];
;             res[r] = cg_ * __builtin_amdgcn_rcpf(1.f + __builtin_amdgcn_exp2f(-1.4426950408889634f * cg_)) * cv_;
;           }
;           if (m > 0 || fr >= 2)
;             *(uint2*)(act + (size_t)EPI_ROW(u, ai, m) * DFF + f0) = pack4(res);
	v_cvt_pk_bf16_f32 v57, v58, v59
	v_mov_b64_e32 v[58:59], s[52:53]
	v_mad_i64_i32 v[72:73], s[12:13], v128, s88, v[58:59]
	v_lshl_add_u64 v[128:129], v[72:73], 0, v[168:169]
	global_store_dwordx2 v[128:129], v[56:57], off
	v_cndmask_b32_e64 v57, v54, v60, s[8:9]
	s_nop 0

; __device__ __forceinline__ float dpp_ror1(float v) { return __int_as_float(__builtin_amdgcn_update_dpp(0, __float_as_int(v), 0x121, 0xf, 0xf, false)); }
; __device__ __forceinline__ float dpp_ror2(float v) { return __int_as_float(__builtin_amdgcn_update_dpp(0, __float_as_int(v), 0x122, 0xf, 0xf, false)); }
;   __device__ __forceinline__ void operator()(const AccT& acc, const Unit& u, int wr, int wc, int fr, int fq) const {
;     ...
;             const float g_cur = xg[m][r], v_cur = xv[m][r];
;             const f32x4 xgp = xg[m > 0 ? m - 1 : 0], xvp = xv[m > 0 ? m - 1 : 0];
;             const float g_pm = (m > 0) ? xgp[r] : 0.f, v_pm = (m > 0) ? xvp[r] : 0.f;
;             const float g1 = dpp_ror1((fr == 15) ? g_pm : g_cur), g2 = dpp_ror2((fr >= 14) ? g_pm : g_cur);
;             const float v1 = dpp_ror1((fr == 15) ? v_pm : v_cur), v2 = dpp_ror2((fr >= 14) ? v_pm : v_cur);
	v_cndmask_b32_e64 v73, v55, v61, s[8:9]
	v_mov_b32_dpp v56, v57 row_ror:1 row_mask:0xf bank_mask:0xf
	v_cndmask_b32_e64 v57, v54, v60, s[6:7]

; __device__ __forceinline__ float dpp_ror1(float v) { return __int_as_float(__builtin_amdgcn_update_dpp(0, __float_as_int(v), 0x121, 0xf, 0xf, false)); }
; __device__ __forceinline__ float dpp_ror2(float v) { return __int_as_float(__builtin_amdgcn_update_dpp(0, __float_as_int(v), 0x122, 0xf, 0xf, false)); }
;   __device__ __forceinline__ void operator()(const AccT& acc, const Unit& u, int wr, int wc, int fr, int fq) const {
;     ...
;             const float g_cur = xg[m][r], v_cur = xv[m][r];
;             const f32x4 xgp = xg[m > 0 ? m - 1 : 0], xvp = xv[m > 0 ? m - 1 : 0];
;             const float g_pm = (m > 0) ? xgp[r] : 0.f, v_pm = (m > 0) ? xvp[r] : 0.f;
;             const float g1 = dpp_ror1((fr == 15) ? g_pm : g_cur), g2 = dpp_ror2((fr >= 14) ? g_pm : g_cur);
;             const float v1 = dpp_ror1((fr == 15) ? v_pm : v_cur), v2 = dpp_ror2((fr >= 14) ? v_pm : v_cur);
	v_cndmask_b32_e64 v75, v49, v135, s[8:9]
	v_cndmask_b32_e64 v79, v53, v63, s[8:9]
	v_mov_b32_dpp v60, v57 row_ror:2 row_mask:0xf bank_mask:0xf
	v_cndmask_b32_e64 v57, v48, v134, s[8:9]
	v_cndmask_b32_e64 v113, v51, v133, s[8:9]
	s_nop 0
	v_mov_b32_dpp v72, v57 row_ror:1 row_mask:0xf bank_mask:0xf
	v_cndmask_b32_e64 v57, v48, v134, s[6:7]
	s_nop 1
	v_mov_b32_dpp v74, v57 row_ror:2 row_mask:0xf bank_mask:0xf

; __device__ __forceinline__ float dpp_ror1(float v) { return __int_as_float(__builtin_amdgcn_update_dpp(0, __float_as_int(v), 0x121, 0xf, 0xf, false)); }
; __device__ __forceinline__ float dpp_ror2(float v) { return __int_as_float(__builtin_amdgcn_update_dpp(0, __float_as_int(v), 0x122, 0xf, 0xf, false)); }
;   __device__ __forceinline__ void operator()(const AccT& acc, const Unit& u, int wr, int wc, int fr, int fq) const {
;     ...
;             const float g_cur = xg[m][r], v_cur = xv[m][r];
;             const f32x4 xgp = xg[m > 0 ? m - 1 : 0], xvp = xv[m > 0 ? m - 1 : 0];
;             const float g_pm = (m > 0) ? xgp[r] : 0.f, v_pm = (m > 0) ? xvp[r] : 0.f;
;             const float g1 = dpp_ror1((fr == 15) ? g_pm : g_cur), g2 = dpp_ror2((fr >= 14) ? g_pm : g_cur);
;             const float v1 = dpp_ror1((fr == 15) ? v_pm : v_cur), v2 = dpp_ror2((fr >= 14) ? v_pm : v_cur);
	s_nop 1
	v_mov_b32_dpp v57, v73 row_ror:1 row_mask:0xf bank_mask:0xf
	v_cndmask_b32_e64 v73, v55, v61, s[6:7]

; __device__ __forceinline__ float dpp_ror1(float v) { return __int_as_float(__builtin_amdgcn_update_dpp(0, __float_as_int(v), 0x121, 0xf, 0xf, false)); }
; __device__ __forceinline__ float dpp_ror2(float v) { return __int_as_float(__builtin_amdgcn_update_dpp(0, __float_as_int(v), 0x122, 0xf, 0xf, false)); }
;   __device__ __forceinline__ void operator()(const AccT& acc, const Unit& u, int wr, int wc, int fr, int fq) const {
;     ...
;             const float g_cur = xg[m][r], v_cur = xv[m][r];
;             const f32x4 xgp = xg[m > 0 ? m - 1 : 0], xvp = xv[m > 0 ? m - 1 : 0];
;             const float g_pm = (m > 0) ? xgp[r] : 0.f, v_pm = (m > 0) ? xvp[r] : 0.f;
;             const float g1 = dpp_ror1((fr == 15) ? g_pm : g_cur), g2 = dpp_ror2((fr >= 14) ? g_pm : g_cur);
;             const float v1 = dpp_ror1((fr == 15) ? v_pm : v_cur), v2 = dpp_ror2((fr >= 14) ? v_pm : v_cur);
;             const float cg_ = bg[r] + g2 * wg0[r] + g1 * wg1[r] + g_cur * wg2[r];
	s_nop 1
	v_mov_b32_dpp v61, v73 row_ror:2 row_mask:0xf bank_mask:0xf
	v_pk_fma_f32 v[60:61], v[100:101], v[60:61], v[108:109]

; __device__ __forceinline__ float dpp_ror1(float v) { return __int_as_float(__builtin_amdgcn_update_dpp(0, __float_as_int(v), 0x121, 0xf, 0xf, false)); }
; __device__ __forceinline__ float dpp_ror2(float v) { return __int_as_float(__builtin_amdgcn_update_dpp(0, __float_as_int(v), 0x122, 0xf, 0xf, false)); }
;   __device__ __forceinline__ void operator()(const AccT& acc, const Unit& u, int wr, int wc, int fr, int fq) const {
;     ...
;             const float g_cur = xg[m][r], v_cur = xv[m][r];
;             const f32x4 xgp = xg[m > 0 ? m - 1 : 0], xvp = xv[m > 0 ? m - 1 : 0];
;             const float g_pm = (m > 0) ? xgp[r] : 0.f, v_pm = (m > 0) ? xvp[r] : 0.f;
;             const float g1 = dpp_ror1((fr == 15) ? g_pm : g_cur), g2 = dpp_ror2((fr >= 14) ? g_pm : g_cur);
;             const float v1 = dpp_ror1((fr == 15) ? v_pm : v_cur), v2 = dpp_ror2((fr >= 14) ? v_pm : v_cur);
;             const float cg_ = bg[r] + g2 * wg0[r] + g1 * wg1[r] + g_cur * wg2[r];
;             const float cv_ = bv[r] + v2 * wv0[r] + v1 * wv1[r] + v_cur * wv2[r];
;             res[r] = cg_ * __builtin_amdgcn_rcpf(1.f + __builtin_amdgcn_exp2f(-1.4426950408889634f * cg_)) * cv_;
	v_pk_fma_f32 v[56:57], v[104:105], v[56:57], v[60:61]
	s_nop 0
	v_pk_fma_f32 v[56:57], v[96:97], v[54:55], v[56:57]
	v_mov_b32_dpp v73, v75 row_ror:1 row_mask:0xf bank_mask:0xf
	v_mul_f32_e32 v60, 0xbfb8aa3b, v56
	v_mul_f32_e32 v61, 0xbfb8aa3b, v57
	v_exp_f32_e32 v60, v60
	v_exp_f32_e32 v61, v61

; __device__ __forceinline__ float dpp_ror1(float v) { return __int_as_float(__builtin_amdgcn_update_dpp(0, __float_as_int(v), 0x121, 0xf, 0xf, false)); }
; __device__ __forceinline__ float dpp_ror2(float v) { return __int_as_float(__builtin_amdgcn_update_dpp(0, __float_as_int(v), 0x122, 0xf, 0xf, false)); }
;   __device__ __forceinline__ void operator()(const AccT& acc, const Unit& u, int wr, int wc, int fr, int fq) const {
;     ...
;             const float g_cur = xg[m][r], v_cur = xv[m][r];
;             const f32x4 xgp = xg[m > 0 ? m - 1 : 0], xvp = xv[m > 0 ? m - 1 : 0];
;             const float g_pm = (m > 0) ? xgp[r] : 0.f, v_pm = (m > 0) ? xvp[r] : 0.f;
;             const float g1 = dpp_ror1((fr == 15) ? g_pm : g_cur), g2 = dpp_ror2((fr >= 14) ? g_pm : g_cur);
;             const float v1 = dpp_ror1((fr == 15) ? v_pm : v_cur), v2 = dpp_ror2((fr >= 14) ? v_pm : v_cur);
;             const float cg_ = bg[r] + g2 * wg0[r] + g1 * wg1[r] + g_cur * wg2[r];
;             const float cv_ = bv[r] + v2 * wv0[r] + v1 * wv1[r] + v_cur * wv2[r];
;             res[r] = cg_ * __builtin_amdgcn_rcpf(1.f + __builtin_amdgcn_exp2f(-1.4426950408889634f * cg_)) * cv_;
	v_add_f32_e32 v60, 1.0, v60
	s_nop 0
	v_mov_b32_dpp v75, v76 row_ror:2 row_mask:0xf bank_mask:0xf

; __device__ __forceinline__ float dpp_ror1(float v) { return __int_as_float(__builtin_amdgcn_update_dpp(0, __float_as_int(v), 0x121, 0xf, 0xf, false)); }
; __device__ __forceinline__ float dpp_ror2(float v) { return __int_as_float(__builtin_amdgcn_update_dpp(0, __float_as_int(v), 0x122, 0xf, 0xf, false)); }
;   __device__ __forceinline__ void operator()(const AccT& acc, const Unit& u, int wr, int wc, int fr, int fq) const {
;     ...
;             const float g_cur = xg[m][r], v_cur = xv[m][r];
;             const f32x4 xgp = xg[m > 0 ? m - 1 : 0], xvp = xv[m > 0 ? m - 1 : 0];
;             const float g_pm = (m > 0) ? xgp[r] : 0.f, v_pm = (m > 0) ? xvp[r] : 0.f;
;             const float g1 = dpp_ror1((fr == 15) ? g_pm : g_cur), g2 = dpp_ror2((fr >= 14) ? g_pm : g_cur);
;             const float v1 = dpp_ror1((fr == 15) ? v_pm : v_cur), v2 = dpp_ror2((fr >= 14) ? v_pm : v_cur);
;             const float cg_ = bg[r] + g2 * wg0[r] + g1 * wg1[r] + g_cur * wg2[r];
;             const float cv_ = bv[r] + v2 * wv0[r] + v1 * wv1[r] + v_cur * wv2[r];
;             res[r] = cg_ * __builtin_amdgcn_rcpf(1.f + __builtin_amdgcn_exp2f(-1.4426950408889634f * cg_)) * cv_;
	v_add_f32_e32 v61, 1.0, v61
	v_rcp_f32_e32 v60, v60
	v_mov_b32_dpp v76, v77 row_ror:1 row_mask:0xf bank_mask:0xf
	v_cndmask_b32_e64 v77, v52, v62, s[6:7]

; __device__ __forceinline__ float dpp_ror1(float v) { return __int_as_float(__builtin_amdgcn_update_dpp(0, __float_as_int(v), 0x121, 0xf, 0xf, false)); }
; __device__ __forceinline__ float dpp_ror2(float v) { return __int_as_float(__builtin_amdgcn_update_dpp(0, __float_as_int(v), 0x122, 0xf, 0xf, false)); }
;   __device__ __forceinline__ void operator()(const AccT& acc, const Unit& u, int wr, int wc, int fr, int fq) const {
;     ...
;             const float g_cur = xg[m][r], v_cur = xv[m][r];
;             const f32x4 xgp = xg[m > 0 ? m - 1 : 0], xvp = xv[m > 0 ? m - 1 : 0];
;             const float g_pm = (m > 0) ? xgp[r] : 0.f, v_pm = (m > 0) ? xvp[r] : 0.f;
;             const float g1 = dpp_ror1((fr == 15) ? g_pm : g_cur), g2 = dpp_ror2((fr >= 14) ? g_pm : g_cur);
;             const float v1 = dpp_ror1((fr == 15) ? v_pm : v_cur), v2 = dpp_ror2((fr >= 14) ? v_pm : v_cur);
;             const float cg_ = bg[r] + g2 * wg0[r] + g1 * wg1[r] + g_cur * wg2[r];
;             const float cv_ = bv[r] + v2 * wv0[r] + v1 * wv1[r] + v_cur * wv2[r];
;             res[r] = cg_ * __builtin_amdgcn_rcpf(1.f + __builtin_amdgcn_exp2f(-1.4426950408889634f * cg_)) * cv_;
	v_rcp_f32_e32 v61, v61
	v_pk_fma_f32 v[74:75], v[84:85], v[74:75], v[92:93]
	v_mov_b32_dpp v62, v77 row_ror:2 row_mask:0xf bank_mask:0xf
	v_cndmask_b32_e64 v77, v50, v132, s[8:9]
	v_pk_mul_f32 v[56:57], v[56:57], v[60:61]
	v_pk_fma_f32 v[72:73], v[88:89], v[72:73], v[74:75]
	v_mov_b32_dpp v78, v77 row_ror:1 row_mask:0xf bank_mask:0xf
	v_cndmask_b32_e64 v77, v50, v132, s[6:7]

; __device__ __forceinline__ float dpp_ror1(float v) { return __int_as_float(__builtin_amdgcn_update_dpp(0, __float_as_int(v), 0x121, 0xf, 0xf, false)); }
; __device__ __forceinline__ float dpp_ror2(float v) { return __int_as_float(__builtin_amdgcn_update_dpp(0, __float_as_int(v), 0x122, 0xf, 0xf, false)); }
;   __device__ __forceinline__ void operator()(const AccT& acc, const Unit& u, int wr, int wc, int fr, int fq) const {
;     ...
;             const float g_cur = xg[m][r], v_cur = xv[m][r];
;             const f32x4 xgp = xg[m > 0 ? m - 1 : 0], xvp = xv[m > 0 ? m - 1 : 0];
;             const float g_pm = (m > 0) ? xgp[r] : 0.f, v_pm = (m > 0) ? xvp[r] : 0.f;
;             const float g1 = dpp_ror1((fr == 15) ? g_pm : g_cur), g2 = dpp_ror2((fr >= 14) ? g_pm : g_cur);
;             const float v1 = dpp_ror1((fr == 15) ? v_pm : v_cur), v2 = dpp_ror2((fr >= 14) ? v_pm : v_cur);
;             const float cg_ = bg[r] + g2 * wg0[r] + g1 * wg1[r] + g_cur * wg2[r];
;             const float cv_ = bv[r] + v2 * wv0[r] + v1 * wv1[r] + v_cur * wv2[r];
;             res[r] = cg_ * __builtin_amdgcn_rcpf(1.f + __builtin_amdgcn_exp2f(-1.4426950408889634f * cg_)) * cv_;
	v_pk_fma_f32 v[72:73], v[80:81], v[48:49], v[72:73]
	v_cndmask_b32_e64 v74, v67, v51, s[8:9]
	v_mov_b32_dpp v132, v77 row_ror:2 row_mask:0xf bank_mask:0xf

; __device__ __forceinline__ float dpp_ror1(float v) { return __int_as_float(__builtin_amdgcn_update_dpp(0, __float_as_int(v), 0x121, 0xf, 0xf, false)); }
; __device__ __forceinline__ float dpp_ror2(float v) { return __int_as_float(__builtin_amdgcn_update_dpp(0, __float_as_int(v), 0x122, 0xf, 0xf, false)); }
;   __device__ __forceinline__ void operator()(const AccT& acc, const Unit& u, int wr, int wc, int fr, int fq) const {
;     ...
;             const float g_cur = xg[m][r], v_cur = xv[m][r];
;             const f32x4 xgp = xg[m > 0 ? m - 1 : 0], xvp = xv[m > 0 ? m - 1 : 0];
;             const float g_pm = (m > 0) ? xgp[r] : 0.f, v_pm = (m > 0) ? xvp[r] : 0.f;
;             const float g1 = dpp_ror1((fr == 15) ? g_pm : g_cur), g2 = dpp_ror2((fr >= 14) ? g_pm : g_cur);
;             const float v1 = dpp_ror1((fr == 15) ? v_pm : v_cur), v2 = dpp_ror2((fr >= 14) ? v_pm : v_cur);
;             const float cg_ = bg[r] + g2 * wg0[r] + g1 * wg1[r] + g_cur * wg2[r];
;             const float cv_ = bv[r] + v2 * wv0[r] + v1 * wv1[r] + v_cur * wv2[r];
;             res[r] = cg_ * __builtin_amdgcn_rcpf(1.f + __builtin_amdgcn_exp2f(-1.4426950408889634f * cg_)) * cv_;
	v_pk_mul_f32 v[56:57], v[72:73], v[56:57]
	s_nop 0
	v_mov_b32_dpp v77, v79 row_ror:1 row_mask:0xf bank_mask:0xf
	v_cndmask_b32_e64 v79, v53, v63, s[6:7]

; __device__ __forceinline__ float dpp_ror1(float v) { return __int_as_float(__builtin_amdgcn_update_dpp(0, __float_as_int(v), 0x121, 0xf, 0xf, false)); }
; __device__ __forceinline__ float dpp_ror2(float v) { return __int_as_float(__builtin_amdgcn_update_dpp(0, __float_as_int(v), 0x122, 0xf, 0xf, false)); }
;   __device__ __forceinline__ void operator()(const AccT& acc, const Unit& u, int wr, int wc, int fr, int fq) const {
;     ...
;             const float g_cur = xg[m][r], v_cur = xv[m][r];
;             const f32x4 xgp = xg[m > 0 ? m - 1 : 0], xvp = xv[m > 0 ? m - 1 : 0];
;             const float g_pm = (m > 0) ? xgp[r] : 0.f, v_pm = (m > 0) ? xvp[r] : 0.f;
;             const float g1 = dpp_ror1((fr == 15) ? g_pm : g_cur), g2 = dpp_ror2((fr >= 14) ? g_pm : g_cur);
;             const float v1 = dpp_ror1((fr == 15) ? v_pm : v_cur), v2 = dpp_ror2((fr >= 14) ? v_pm : v_cur);
;             const float cg_ = bg[r] + g2 * wg0[r] + g1 * wg1[r] + g_cur * wg2[r];
;             const float cv_ = bv[r] + v2 * wv0[r] + v1 * wv1[r] + v_cur * wv2[r];
;             res[r] = cg_ * __builtin_amdgcn_rcpf(1.f + __builtin_amdgcn_exp2f(-1.4426950408889634f * cg_)) * cv_;
	v_cvt_pk_bf16_f32 v56, v56, v57
	s_nop 0
	v_mov_b32_dpp v63, v79 row_ror:2 row_mask:0xf bank_mask:0xf
	v_pk_fma_f32 v[60:61], v[102:103], v[62:63], v[110:111]

; __device__ __forceinline__ float dpp_ror1(float v) { return __int_as_float(__builtin_amdgcn_update_dpp(0, __float_as_int(v), 0x121, 0xf, 0xf, false)); }
; __device__ __forceinline__ float dpp_ror2(float v) { return __int_as_float(__builtin_amdgcn_update_dpp(0, __float_as_int(v), 0x122, 0xf, 0xf, false)); }
;   __device__ __forceinline__ void operator()(const AccT& acc, const Unit& u, int wr, int wc, int fr, int fq) const {
;     ...
;             const float g_cur = xg[m][r], v_cur = xv[m][r];
;             const f32x4 xgp = xg[m > 0 ? m - 1 : 0], xvp = xv[m > 0 ? m - 1 : 0];
;             const float g_pm = (m > 0) ? xgp[r] : 0.f, v_pm = (m > 0) ? xvp[r] : 0.f;
;             const float g1 = dpp_ror1((fr == 15) ? g_pm : g_cur), g2 = dpp_ror2((fr >= 14) ? g_pm : g_cur);
;             const float v1 = dpp_ror1((fr == 15) ? v_pm : v_cur), v2 = dpp_ror2((fr >= 14) ? v_pm : v_cur);
;             const float cg_ = bg[r] + g2 * wg0[r] + g1 * wg1[r] + g_cur * wg2[r];
;             const float cv_ = bv[r] + v2 * wv0[r] + v1 * wv1[r] + v_cur * wv2[r];
;             res[r] = cg_ * __builtin_amdgcn_rcpf(1.f + __builtin_amdgcn_exp2f(-1.4426950408889634f * cg_)) * cv_;
	v_pk_fma_f32 v[60:61], v[106:107], v[76:77], v[60:61]
	s_nop 0
	v_pk_fma_f32 v[60:61], v[98:99], v[52:53], v[60:61]
	v_mov_b32_dpp v79, v113 row_ror:1 row_mask:0xf bank_mask:0xf
	v_mul_f32_e32 v62, 0xbfb8aa3b, v60
	v_mul_f32_e32 v63, 0xbfb8aa3b, v61
	v_exp_f32_e32 v62, v62
	v_exp_f32_e32 v63, v63
	v_cndmask_b32_e64 v113, v51, v133, s[6:7]

; __device__ __forceinline__ float dpp_ror1(float v) { return __int_as_float(__builtin_amdgcn_update_dpp(0, __float_as_int(v), 0x121, 0xf, 0xf, false)); }
; __device__ __forceinline__ float dpp_ror2(float v) { return __int_as_float(__builtin_amdgcn_update_dpp(0, __float_as_int(v), 0x122, 0xf, 0xf, false)); }
;   __device__ __forceinline__ void operator()(const AccT& acc, const Unit& u, int wr, int wc, int fr, int fq) const {
;     ...
;             const float g_cur = xg[m][r], v_cur = xv[m][r];
;             const f32x4 xgp = xg[m > 0 ? m - 1 : 0], xvp = xv[m > 0 ? m - 1 : 0];
;             const float g_pm = (m > 0) ? xgp[r] : 0.f, v_pm = (m > 0) ? xvp[r] : 0.f;
;             const float g1 = dpp_ror1((fr == 15) ? g_pm : g_cur), g2 = dpp_ror2((fr >= 14) ? g_pm : g_cur);
;             const float v1 = dpp_ror1((fr == 15) ? v_pm : v_cur), v2 = dpp_ror2((fr >= 14) ? v_pm : v_cur);
;             const float cg_ = bg[r] + g2 * wg0[r] + g1 * wg1[r] + g_cur * wg2[r];
;             const float cv_ = bv[r] + v2 * wv0[r] + v1 * wv1[r] + v_cur * wv2[r];
;             res[r] = cg_ * __builtin_amdgcn_rcpf(1.f + __builtin_amdgcn_exp2f(-1.4426950408889634f * cg_)) * cv_;
	v_add_f32_e32 v62, 1.0, v62
	v_add_f32_e32 v63, 1.0, v63
	v_rcp_f32_e32 v62, v62
	v_rcp_f32_e32 v63, v63
	v_mov_b32_dpp v133, v113 row_ror:2 row_mask:0xf bank_mask:0xf
	v_pk_fma_f32 v[72:73], v[86:87], v[132:133], v[94:95]
	v_pk_mul_f32 v[60:61], v[60:61], v[62:63]
	v_pk_fma_f32 v[72:73], v[90:91], v[78:79], v[72:73]
	v_cndmask_b32_e64 v62, v65, v49, s[8:9]
	v_pk_fma_f32 v[72:73], v[82:83], v[50:51], v[72:73]
	v_cndmask_b32_e64 v63, v70, v52, s[8:9]
	v_pk_mul_f32 v[60:61], v[72:73], v[60:61]

; __device__ __forceinline__ uint2 pack4(f32x4 v) { return make_uint2(pack2(v[0], v[1]), pack2(v[2], v[3])); }
; __device__ __forceinline__ float dpp_ror1(float v) { return __int_as_float(__builtin_amdgcn_update_dpp(0, __float_as_int(v), 0x121, 0xf, 0xf, false)); }
; __device__ __forceinline__ float dpp_ror2(float v) { return __int_as_float(__builtin_amdgcn_update_dpp(0, __float_as_int(v), 0x122, 0xf, 0xf, false)); }
;   __device__ __forceinline__ void operator()(const AccT& acc, const Unit& u, int wr, int wc, int fr, int fq) const {
;     ...
;             const float g_cur = xg[m][r], v_cur = xv[m][r];
;             const f32x4 xgp = xg[m > 0 ? m - 1 : 0], xvp = xv[m > 0 ? m - 1 : 0];
;             const float g_pm = (m > 0) ? xgp[r] : 0.f, v_pm = (m > 0) ? xvp[r] : 0.f;
;             const float g1 = dpp_ror1((fr == 15) ? g_pm : g_cur), g2 = dpp_ror2((fr >= 14) ? g_pm : g_cur);
;             const float v1 = dpp_ror1((fr == 15) ? v_pm : v_cur), v2 = dpp_ror2((fr >= 14) ? v_pm : v_cur);
;             const float cg_ = bg[r] + g2 * wg0[r] + g1 * wg1[r] + g_cur * wg2[r];
;             const float cv_ = bv[r] + v2 * wv0[r] + v1 * wv1[r] + v_cur * wv2[r];
;             res[r] = cg_ * __builtin_amdgcn_rcpf(1.f + __builtin_amdgcn_exp2f(-1.4426950408889634f * cg_)) * cv_;
;           }
;           if (m > 0 || fr >= 2)
;             *(uint2*)(act + (size_t)EPI_ROW(u, ai, m) * DFF + f0) = pack4(res);
	v_cvt_pk_bf16_f32 v57, v60, v61
	v_mad_i64_i32 v[60:61], s[12:13], v130, s88, v[58:59]
	v_lshl_add_u64 v[130:131], v[60:61], 0, v[168:169]
	global_store_dwordx2 v[130:131], v[56:57], off
	v_cndmask_b32_e64 v57, v68, v54, s[8:9]
	s_nop 0

; __device__ __forceinline__ float dpp_ror1(float v) { return __int_as_float(__builtin_amdgcn_update_dpp(0, __float_as_int(v), 0x121, 0xf, 0xf, false)); }
; __device__ __forceinline__ float dpp_ror2(float v) { return __int_as_float(__builtin_amdgcn_update_dpp(0, __float_as_int(v), 0x122, 0xf, 0xf, false)); }
;   __device__ __forceinline__ void operator()(const AccT& acc, const Unit& u, int wr, int wc, int fr, int fq) const {
;     ...
;             const float g_cur = xg[m][r], v_cur = xv[m][r];
;             const f32x4 xgp = xg[m > 0 ? m - 1 : 0], xvp = xv[m > 0 ? m - 1 : 0];
;             const float g_pm = (m > 0) ? xgp[r] : 0.f, v_pm = (m > 0) ? xvp[r] : 0.f;
;             const float g1 = dpp_ror1((fr == 15) ? g_pm : g_cur), g2 = dpp_ror2((fr >= 14) ? g_pm : g_cur);
;             const float v1 = dpp_ror1((fr == 15) ? v_pm : v_cur), v2 = dpp_ror2((fr >= 14) ? v_pm : v_cur);
	v_cndmask_b32_e64 v61, v69, v55, s[8:9]
	v_mov_b32_dpp v56, v57 row_ror:1 row_mask:0xf bank_mask:0xf
	v_cndmask_b32_e64 v57, v68, v54, s[6:7]

; __device__ __forceinline__ float dpp_ror1(float v) { return __int_as_float(__builtin_amdgcn_update_dpp(0, __float_as_int(v), 0x121, 0xf, 0xf, false)); }
; __device__ __forceinline__ float dpp_ror2(float v) { return __int_as_float(__builtin_amdgcn_update_dpp(0, __float_as_int(v), 0x122, 0xf, 0xf, false)); }
;   __device__ __forceinline__ void operator()(const AccT& acc, const Unit& u, int wr, int wc, int fr, int fq) const {
;     ...
;             const float g_cur = xg[m][r], v_cur = xv[m][r];
;             const f32x4 xgp = xg[m > 0 ? m - 1 : 0], xvp = xv[m > 0 ? m - 1 : 0];
;             const float g_pm = (m > 0) ? xgp[r] : 0.f, v_pm = (m > 0) ? xvp[r] : 0.f;
;             const float g1 = dpp_ror1((fr == 15) ? g_pm : g_cur), g2 = dpp_ror2((fr >= 14) ? g_pm : g_cur);
;             const float v1 = dpp_ror1((fr == 15) ? v_pm : v_cur), v2 = dpp_ror2((fr >= 14) ? v_pm : v_cur);
	v_cndmask_b32_e64 v73, v71, v53, s[8:9]
	s_nop 0
	v_mov_b32_dpp v54, v57 row_ror:2 row_mask:0xf bank_mask:0xf
	v_cndmask_b32_e64 v57, v64, v48, s[8:9]
	s_nop 1
	v_mov_b32_dpp v60, v57 row_ror:1 row_mask:0xf bank_mask:0xf
	v_cndmask_b32_e64 v57, v64, v48, s[6:7]

; __device__ __forceinline__ float dpp_ror1(float v) { return __int_as_float(__builtin_amdgcn_update_dpp(0, __float_as_int(v), 0x121, 0xf, 0xf, false)); }
; __device__ __forceinline__ float dpp_ror2(float v) { return __int_as_float(__builtin_amdgcn_update_dpp(0, __float_as_int(v), 0x122, 0xf, 0xf, false)); }
;   __device__ __forceinline__ void operator()(const AccT& acc, const Unit& u, int wr, int wc, int fr, int fq) const {
;     ...
;             const float g_cur = xg[m][r], v_cur = xv[m][r];
;             const f32x4 xgp = xg[m > 0 ? m - 1 : 0], xvp = xv[m > 0 ? m - 1 : 0];
;             const float g_pm = (m > 0) ? xgp[r] : 0.f, v_pm = (m > 0) ? xvp[r] : 0.f;
;             const float g1 = dpp_ror1((fr == 15) ? g_pm : g_cur), g2 = dpp_ror2((fr >= 14) ? g_pm : g_cur);
;             const float v1 = dpp_ror1((fr == 15) ? v_pm : v_cur), v2 = dpp_ror2((fr >= 14) ? v_pm : v_cur);
	s_nop 1
	v_mov_b32_dpp v48, v57 row_ror:2 row_mask:0xf bank_mask:0xf

; __device__ __forceinline__ float dpp_ror1(float v) { return __int_as_float(__builtin_amdgcn_update_dpp(0, __float_as_int(v), 0x121, 0xf, 0xf, false)); }
; __device__ __forceinline__ float dpp_ror2(float v) { return __int_as_float(__builtin_amdgcn_update_dpp(0, __float_as_int(v), 0x122, 0xf, 0xf, false)); }
;   __device__ __forceinline__ void operator()(const AccT& acc, const Unit& u, int wr, int wc, int fr, int fq) const {
;     ...
;             const float g_cur = xg[m][r], v_cur = xv[m][r];
;             const f32x4 xgp = xg[m > 0 ? m - 1 : 0], xvp = xv[m > 0 ? m - 1 : 0];
;             const float g_pm = (m > 0) ? xgp[r] : 0.f, v_pm = (m > 0) ? xvp[r] : 0.f;
;             const float g1 = dpp_ror1((fr == 15) ? g_pm : g_cur), g2 = dpp_ror2((fr >= 14) ? g_pm : g_cur);
;             const float v1 = dpp_ror1((fr == 15) ? v_pm : v_cur), v2 = dpp_ror2((fr >= 14) ? v_pm : v_cur);
	s_nop 1
	v_mov_b32_dpp v57, v61 row_ror:1 row_mask:0xf bank_mask:0xf
	v_cndmask_b32_e64 v61, v69, v55, s[6:7]

; __device__ __forceinline__ float dpp_ror1(float v) { return __int_as_float(__builtin_amdgcn_update_dpp(0, __float_as_int(v), 0x121, 0xf, 0xf, false)); }
; __device__ __forceinline__ float dpp_ror2(float v) { return __int_as_float(__builtin_amdgcn_update_dpp(0, __float_as_int(v), 0x122, 0xf, 0xf, false)); }
;   __device__ __forceinline__ void operator()(const AccT& acc, const Unit& u, int wr, int wc, int fr, int fq) const {
;     ...
;             const float g_cur = xg[m][r], v_cur = xv[m][r];
;             const f32x4 xgp = xg[m > 0 ? m - 1 : 0], xvp = xv[m > 0 ? m - 1 : 0];
;             const float g_pm = (m > 0) ? xgp[r] : 0.f, v_pm = (m > 0) ? xvp[r] : 0.f;
;             const float g1 = dpp_ror1((fr == 15) ? g_pm : g_cur), g2 = dpp_ror2((fr >= 14) ? g_pm : g_cur);
;             const float v1 = dpp_ror1((fr == 15) ? v_pm : v_cur), v2 = dpp_ror2((fr >= 14) ? v_pm : v_cur);
;             const float cg_ = bg[r] + g2 * wg0[r] + g1 * wg1[r] + g_cur * wg2[r];
	s_nop 1
	v_mov_b32_dpp v55, v61 row_ror:2 row_mask:0xf bank_mask:0xf
	v_pk_fma_f32 v[54:55], v[100:101], v[54:55], v[108:109]

; __device__ __forceinline__ float dpp_ror1(float v) { return __int_as_float(__builtin_amdgcn_update_dpp(0, __float_as_int(v), 0x121, 0xf, 0xf, false)); }
; __device__ __forceinline__ float dpp_ror2(float v) { return __int_as_float(__builtin_amdgcn_update_dpp(0, __float_as_int(v), 0x122, 0xf, 0xf, false)); }
;   __device__ __forceinline__ void operator()(const AccT& acc, const Unit& u, int wr, int wc, int fr, int fq) const {
;     ...
;             const float g_cur = xg[m][r], v_cur = xv[m][r];
;             const f32x4 xgp = xg[m > 0 ? m - 1 : 0], xvp = xv[m > 0 ? m - 1 : 0];
;             const float g_pm = (m > 0) ? xgp[r] : 0.f, v_pm = (m > 0) ? xvp[r] : 0.f;
;             const float g1 = dpp_ror1((fr == 15) ? g_pm : g_cur), g2 = dpp_ror2((fr >= 14) ? g_pm : g_cur);
;             const float v1 = dpp_ror1((fr == 15) ? v_pm : v_cur), v2 = dpp_ror2((fr >= 14) ? v_pm : v_cur);
;             const float cg_ = bg[r] + g2 * wg0[r] + g1 * wg1[r] + g_cur * wg2[r];
	v_pk_fma_f32 v[54:55], v[104:105], v[56:57], v[54:55]
	s_nop 0
	v_mov_b32_dpp v61, v62 row_ror:1 row_mask:0xf bank_mask:0xf
	v_cndmask_b32_e64 v62, v65, v49, s[6:7]

; __device__ __forceinline__ float dpp_ror1(float v) { return __int_as_float(__builtin_amdgcn_update_dpp(0, __float_as_int(v), 0x121, 0xf, 0xf, false)); }
; __device__ __forceinline__ float dpp_ror2(float v) { return __int_as_float(__builtin_amdgcn_update_dpp(0, __float_as_int(v), 0x122, 0xf, 0xf, false)); }
;   __device__ __forceinline__ void operator()(const AccT& acc, const Unit& u, int wr, int wc, int fr, int fq) const {
;     ...
;           for (int r = 0; r < 4; ++r) {
;             const float g_cur = xg[m][r], v_cur = xv[m][r];
;             const f32x4 xgp = xg[m > 0 ? m - 1 : 0], xvp = xv[m > 0 ? m - 1 : 0];
;             const float g_pm = (m > 0) ? xgp[r] : 0.f, v_pm = (m > 0) ? xvp[r] : 0.f;
;             const float g1 = dpp_ror1((fr == 15) ? g_pm : g_cur), g2 = dpp_ror2((fr >= 14) ? g_pm : g_cur);
;             const float v1 = dpp_ror1((fr == 15) ? v_pm : v_cur), v2 = dpp_ror2((fr >= 14) ? v_pm : v_cur);
;             const float cg_ = bg[r] + g2 * wg0[r] + g1 * wg1[r] + g_cur * wg2[r];
;             const float cv_ = bv[r] + v2 * wv0[r] + v1 * wv1[r] + v_cur * wv2[r];
;             res[r] = cg_ * __builtin_amdgcn_rcpf(1.f + __builtin_amdgcn_exp2f(-1.4426950408889634f * cg_)) * cv_;
;           }
	v_pk_fma_f32 v[54:55], v[96:97], v[68:69], v[54:55]
	s_nop 0
	v_mov_b32_dpp v49, v62 row_ror:2 row_mask:0xf bank_mask:0xf

; __device__ __forceinline__ float dpp_ror1(float v) { return __int_as_float(__builtin_amdgcn_update_dpp(0, __float_as_int(v), 0x121, 0xf, 0xf, false)); }
; __device__ __forceinline__ float dpp_ror2(float v) { return __int_as_float(__builtin_amdgcn_update_dpp(0, __float_as_int(v), 0x122, 0xf, 0xf, false)); }
;   __device__ __forceinline__ void operator()(const AccT& acc, const Unit& u, int wr, int wc, int fr, int fq) const {
;     ...
;           for (int r = 0; r < 4; ++r) {
;             const float g_cur = xg[m][r], v_cur = xv[m][r];
;             const f32x4 xgp = xg[m > 0 ? m - 1 : 0], xvp = xv[m > 0 ? m - 1 : 0];
;             const float g_pm = (m > 0) ? xgp[r] : 0.f, v_pm = (m > 0) ? xvp[r] : 0.f;
;             const float g1 = dpp_ror1((fr == 15) ? g_pm : g_cur), g2 = dpp_ror2((fr >= 14) ? g_pm : g_cur);
;             const float v1 = dpp_ror1((fr == 15) ? v_pm : v_cur), v2 = dpp_ror2((fr >= 14) ? v_pm : v_cur);
;             const float cg_ = bg[r] + g2 * wg0[r] + g1 * wg1[r] + g_cur * wg2[r];
;             const float cv_ = bv[r] + v2 * wv0[r] + v1 * wv1[r] + v_cur * wv2[r];
;             res[r] = cg_ * __builtin_amdgcn_rcpf(1.f + __builtin_amdgcn_exp2f(-1.4426950408889634f * cg_)) * cv_;
;           }
	v_mul_f32_e32 v56, 0xbfb8aa3b, v54
	v_mul_f32_e32 v57, 0xbfb8aa3b, v55
	v_mov_b32_dpp v62, v63 row_ror:1 row_mask:0xf bank_mask:0xf
	v_cndmask_b32_e64 v63, v70, v52, s[6:7]

; __device__ __forceinline__ float dpp_ror1(float v) { return __int_as_float(__builtin_amdgcn_update_dpp(0, __float_as_int(v), 0x121, 0xf, 0xf, false)); }
; __device__ __forceinline__ float dpp_ror2(float v) { return __int_as_float(__builtin_amdgcn_update_dpp(0, __float_as_int(v), 0x122, 0xf, 0xf, false)); }
;   __device__ __forceinline__ void operator()(const AccT& acc, const Unit& u, int wr, int wc, int fr, int fq) const {
;     ...
;           for (int r = 0; r < 4; ++r) {
;             const float g_cur = xg[m][r], v_cur = xv[m][r];
;             const f32x4 xgp = xg[m > 0 ? m - 1 : 0], xvp = xv[m > 0 ? m - 1 : 0];
;             const float g_pm = (m > 0) ? xgp[r] : 0.f, v_pm = (m > 0) ? xvp[r] : 0.f;
;             const float g1 = dpp_ror1((fr == 15) ? g_pm : g_cur), g2 = dpp_ror2((fr >= 14) ? g_pm : g_cur);
;             const float v1 = dpp_ror1((fr == 15) ? v_pm : v_cur), v2 = dpp_ror2((fr >= 14) ? v_pm : v_cur);
;             const float cg_ = bg[r] + g2 * wg0[r] + g1 * wg1[r] + g_cur * wg2[r];
;             const float cv_ = bv[r] + v2 * wv0[r] + v1 * wv1[r] + v_cur * wv2[r];
;             res[r] = cg_ * __builtin_amdgcn_rcpf(1.f + __builtin_amdgcn_exp2f(-1.4426950408889634f * cg_)) * cv_;
;           }
	v_exp_f32_e32 v56, v56
	v_exp_f32_e32 v57, v57
	v_mov_b32_dpp v52, v63 row_ror:2 row_mask:0xf bank_mask:0xf
	v_cndmask_b32_e64 v63, v66, v50, s[8:9]
	v_add_f32_e32 v56, 1.0, v56
	v_add_f32_e32 v57, 1.0, v57
	v_mov_b32_dpp v72, v63 row_ror:1 row_mask:0xf bank_mask:0xf
	v_cndmask_b32_e64 v63, v66, v50, s[6:7]

; __device__ __forceinline__ float dpp_ror1(float v) { return __int_as_float(__builtin_amdgcn_update_dpp(0, __float_as_int(v), 0x121, 0xf, 0xf, false)); }
; __device__ __forceinline__ float dpp_ror2(float v) { return __int_as_float(__builtin_amdgcn_update_dpp(0, __float_as_int(v), 0x122, 0xf, 0xf, false)); }
;   __device__ __forceinline__ void operator()(const AccT& acc, const Unit& u, int wr, int wc, int fr, int fq) const {
;     ...
;           for (int r = 0; r < 4; ++r) {
;             const float g_cur = xg[m][r], v_cur = xv[m][r];
;             const f32x4 xgp = xg[m > 0 ? m - 1 : 0], xvp = xv[m > 0 ? m - 1 : 0];
;             const float g_pm = (m > 0) ? xgp[r] : 0.f, v_pm = (m > 0) ? xvp[r] : 0.f;
;             const float g1 = dpp_ror1((fr == 15) ? g_pm : g_cur), g2 = dpp_ror2((fr >= 14) ? g_pm : g_cur);
;             const float v1 = dpp_ror1((fr == 15) ? v_pm : v_cur), v2 = dpp_ror2((fr >= 14) ? v_pm : v_cur);
;             const float cg_ = bg[r] + g2 * wg0[r] + g1 * wg1[r] + g_cur * wg2[r];
;             const float cv_ = bv[r] + v2 * wv0[r] + v1 * wv1[r] + v_cur * wv2[r];
;             res[r] = cg_ * __builtin_amdgcn_rcpf(1.f + __builtin_amdgcn_exp2f(-1.4426950408889634f * cg_)) * cv_;
;           }
	v_rcp_f32_e32 v56, v56
	v_rcp_f32_e32 v57, v57
	v_mov_b32_dpp v50, v63 row_ror:2 row_mask:0xf bank_mask:0xf

; __device__ __forceinline__ float dpp_ror1(float v) { return __int_as_float(__builtin_amdgcn_update_dpp(0, __float_as_int(v), 0x121, 0xf, 0xf, false)); }
; __device__ __forceinline__ float dpp_ror2(float v) { return __int_as_float(__builtin_amdgcn_update_dpp(0, __float_as_int(v), 0x122, 0xf, 0xf, false)); }
;   __device__ __forceinline__ void operator()(const AccT& acc, const Unit& u, int wr, int wc, int fr, int fq) const {
;     ...
;           for (int r = 0; r < 4; ++r) {
;             const float g_cur = xg[m][r], v_cur = xv[m][r];
;             const f32x4 xgp = xg[m > 0 ? m - 1 : 0], xvp = xv[m > 0 ? m - 1 : 0];
;             const float g_pm = (m > 0) ? xgp[r] : 0.f, v_pm = (m > 0) ? xvp[r] : 0.f;
;             const float g1 = dpp_ror1((fr == 15) ? g_pm : g_cur), g2 = dpp_ror2((fr >= 14) ? g_pm : g_cur);
;             const float v1 = dpp_ror1((fr == 15) ? v_pm : v_cur), v2 = dpp_ror2((fr >= 14) ? v_pm : v_cur);
;             const float cg_ = bg[r] + g2 * wg0[r] + g1 * wg1[r] + g_cur * wg2[r];
;             const float cv_ = bv[r] + v2 * wv0[r] + v1 * wv1[r] + v_cur * wv2[r];
;             res[r] = cg_ * __builtin_amdgcn_rcpf(1.f + __builtin_amdgcn_exp2f(-1.4426950408889634f * cg_)) * cv_;
;           }
	v_pk_fma_f32 v[48:49], v[84:85], v[48:49], v[92:93]
	v_pk_mul_f32 v[54:55], v[54:55], v[56:57]
	v_mov_b32_dpp v63, v73 row_ror:1 row_mask:0xf bank_mask:0xf
	v_cndmask_b32_e64 v73, v71, v53, s[6:7]

; __device__ __forceinline__ float dpp_ror1(float v) { return __int_as_float(__builtin_amdgcn_update_dpp(0, __float_as_int(v), 0x121, 0xf, 0xf, false)); }
; __device__ __forceinline__ float dpp_ror2(float v) { return __int_as_float(__builtin_amdgcn_update_dpp(0, __float_as_int(v), 0x122, 0xf, 0xf, false)); }
;   __device__ __forceinline__ void operator()(const AccT& acc, const Unit& u, int wr, int wc, int fr, int fq) const {
;     ...
;           for (int r = 0; r < 4; ++r) {
;             const float g_cur = xg[m][r], v_cur = xv[m][r];
;             const f32x4 xgp = xg[m > 0 ? m - 1 : 0], xvp = xv[m > 0 ? m - 1 : 0];
;             const float g_pm = (m > 0) ? xgp[r] : 0.f, v_pm = (m > 0) ? xvp[r] : 0.f;
;             const float g1 = dpp_ror1((fr == 15) ? g_pm : g_cur), g2 = dpp_ror2((fr >= 14) ? g_pm : g_cur);
;             const float v1 = dpp_ror1((fr == 15) ? v_pm : v_cur), v2 = dpp_ror2((fr >= 14) ? v_pm : v_cur);
;             const float cg_ = bg[r] + g2 * wg0[r] + g1 * wg1[r] + g_cur * wg2[r];
;             const float cv_ = bv[r] + v2 * wv0[r] + v1 * wv1[r] + v_cur * wv2[r];
;             res[r] = cg_ * __builtin_amdgcn_rcpf(1.f + __builtin_amdgcn_exp2f(-1.4426950408889634f * cg_)) * cv_;
;           }
	v_pk_fma_f32 v[48:49], v[88:89], v[60:61], v[48:49]
	s_nop 0
	v_mov_b32_dpp v53, v73 row_ror:2 row_mask:0xf bank_mask:0xf
	v_pk_fma_f32 v[52:53], v[102:103], v[52:53], v[110:111]
	v_pk_fma_f32 v[48:49], v[80:81], v[64:65], v[48:49]
	v_pk_fma_f32 v[52:53], v[106:107], v[62:63], v[52:53]

; __device__ __forceinline__ float dpp_ror1(float v) { return __int_as_float(__builtin_amdgcn_update_dpp(0, __float_as_int(v), 0x121, 0xf, 0xf, false)); }
; __device__ __forceinline__ float dpp_ror2(float v) { return __int_as_float(__builtin_amdgcn_update_dpp(0, __float_as_int(v), 0x122, 0xf, 0xf, false)); }
;   __device__ __forceinline__ void operator()(const AccT& acc, const Unit& u, int wr, int wc, int fr, int fq) const {
;     ...
;           for (int r = 0; r < 4; ++r) {
;             const float g_cur = xg[m][r], v_cur = xv[m][r];
;             const f32x4 xgp = xg[m > 0 ? m - 1 : 0], xvp = xv[m > 0 ? m - 1 : 0];
;             const float g_pm = (m > 0) ? xgp[r] : 0.f, v_pm = (m > 0) ? xvp[r] : 0.f;
;             const float g1 = dpp_ror1((fr == 15) ? g_pm : g_cur), g2 = dpp_ror2((fr >= 14) ? g_pm : g_cur);
;             const float v1 = dpp_ror1((fr == 15) ? v_pm : v_cur), v2 = dpp_ror2((fr >= 14) ? v_pm : v_cur);
;             const float cg_ = bg[r] + g2 * wg0[r] + g1 * wg1[r] + g_cur * wg2[r];
;             const float cv_ = bv[r] + v2 * wv0[r] + v1 * wv1[r] + v_cur * wv2[r];
;             res[r] = cg_ * __builtin_amdgcn_rcpf(1.f + __builtin_amdgcn_exp2f(-1.4426950408889634f * cg_)) * cv_;
;           }
	v_pk_fma_f32 v[52:53], v[98:99], v[70:71], v[52:53]
	v_pk_mul_f32 v[48:49], v[48:49], v[54:55]
	v_mul_f32_e32 v56, 0xbfb8aa3b, v52
	v_mul_f32_e32 v57, 0xbfb8aa3b, v53
	v_exp_f32_e32 v56, v56
	v_exp_f32_e32 v57, v57
	v_mov_b32_dpp v73, v74 row_ror:1 row_mask:0xf bank_mask:0xf
	v_cndmask_b32_e64 v74, v67, v51, s[6:7]
	v_add_f32_e32 v54, 1.0, v56
	v_add_f32_e32 v55, 1.0, v57

;   __device__ __forceinline__ void operator()(const AccT& acc, const Unit& u, int wr, int wc, int fr, int fq) const {
;     ...
;         const int f0 = 128 * u.pn + 32 * wc + 16 * n + 4 * fq;
;         const int gc = u.pn * 256 + 32 * wc + 16 * n + 4 * fq;
;         const f32x4 wg0 = *(const f32x4*)(cw + f0), wg1 = *(const f32x4*)(cw + NUP + f0), wg2 = *(const f32x4*)(cw + 2 * NUP + f0);
;         const f32x4 wv0 = *(const f32x4*)(cw + DFF + f0), wv1 = *(const f32x4*)(cw + NUP + DFF + f0), wv2 = *(const f32x4*)(cw + 2 * NUP + DFF + f0);
;         const f32x4 bg = *(const f32x4*)(cb + f0), bv = *(const f32x4*)(cb + DFF + f0);
;         f32x4 xg[4], xv[4];
; #pragma unroll
;         for (int m = 0; m < 4; ++m) { xg[m] = acc[ai][0][m][n] * rs[m]; xv[m] = acc[ai][1][m][n] * rs[m]; }
;         if (fr < 2) {
;           float* d = ub + ((size_t)(chunk * 4 + fr) * NUP + gc);
;           *(float4*)d = make_float4(xg[0][0], xg[0][1], xg[0][2], xg[0][3]);
;           *(float4*)(d + 128) = make_float4(xv[0][0], xv[0][1], xv[0][2], xv[0][3]);
;         }
;         if (fr >= 14) {
;           float* d = ub + ((size_t)(chunk * 4 + 2 + (fr - 14)) * NUP + gc);
;           *(float4*)d = make_float4(xg[3][0], xg[3][1], xg[3][2], xg[3][3]);
;           *(float4*)(d + 128) = make_float4(xv[3][0], xv[3][1], xv[3][2], xv[3][3]);
;         }
; #pragma unroll
;         for (int m = 0; m < 4; ++m) {
;           f32x4 res;
; #pragma unroll
;           for (int r = 0; r < 4; ++r) {
;             const float g_cur = xg[m][r], v_cur = xv[m][r];
;             const f32x4 xgp = xg[m > 0 ? m - 1 : 0], xvp = xv[m > 0 ? m - 1 : 0];
;             const float g_pm = (m > 0) ? xgp[r] : 0.f, v_pm = (m > 0) ? xvp[r] : 0.f;
;             const float g1 = dpp_ror1((fr == 15) ? g_pm : g_cur), g2 = dpp_ror2((fr >= 14) ? g_pm : g_cur);
;             const float v1 = dpp_ror1((fr == 15) ? v_pm : v_cur), v2 = dpp_ror2((fr >= 14) ? v_pm : v_cur);
;             const float cg_ = bg[r] + g2 * wg0[r] + g1 * wg1[r] + g_cur * wg2[r];
;             const float cv_ = bv[r] + v2 * wv0[r] + v1 * wv1[r] + v_cur * wv2[r];
;             res[r] = cg_ * __builtin_amdgcn_rcpf(1.f + __builtin_amdgcn_exp2f(-1.4426950408889634f * cg_)) * cv_;
;           }
;           if (m > 0 || fr >= 2)
;             *(uint2*)(act + (size_t)EPI_ROW(u, ai, m) * DFF + f0) = pack4(res);
	v_rcp_f32_e32 v54, v54
	v_rcp_f32_e32 v55, v55
	v_mov_b32_dpp v51, v74 row_ror:2 row_mask:0xf bank_mask:0xf
	v_pk_fma_f32 v[50:51], v[86:87], v[50:51], v[94:95]
	v_cvt_pk_bf16_f32 v48, v48, v49
	v_pk_fma_f32 v[50:51], v[90:91], v[72:73], v[50:51]
	v_pk_mul_f32 v[52:53], v[52:53], v[54:55]
	v_pk_fma_f32 v[50:51], v[82:83], v[66:67], v[50:51]
	v_mov_b32_e32 v82, v116
	v_pk_mul_f32 v[50:51], v[50:51], v[52:53]
	v_mov_b32_e32 v83, v116
	v_cvt_pk_bf16_f32 v49, v50, v51
	v_mad_i64_i32 v[50:51], s[12:13], v114, s88, v[58:59]
	v_lshl_add_u64 v[80:81], v[50:51], 0, v[168:169]
	global_store_dwordx2 v[80:81], v[48:49], off
	global_load_dwordx4 v[68:71], v[144:145], off
	global_load_dwordx4 v[72:75], v[146:147], off
	global_load_dwordx4 v[64:67], v[148:149], off
	global_load_dwordx4 v[52:55], v[150:151], off
	global_load_dwordx4 v[56:59], v[152:153], off
	global_load_dwordx4 v[48:51], v[154:155], off
	global_load_dwordx4 v[76:79], v[156:157], off
	global_load_dwordx4 v[60:63], v[158:159], off
	v_pk_mul_f32 v[46:47], v[46:47], v[82:83]
	v_pk_mul_f32 v[42:43], v[42:43], v[82:83]
	s_and_saveexec_b64 s[12:13], s[4:5]
	s_cbranch_execz .LBB0_1528
	v_lshl_add_u64 v[82:83], v[190:191], 2, v[118:119]
	global_store_dwordx4 v[82:83], v[44:47], off offset:64
	global_store_dwordx4 v[82:83], v[40:43], off offset:576

; __device__ __forceinline__ float dpp_ror1(float v) { return __int_as_float(__builtin_amdgcn_update_dpp(0, __float_as_int(v), 0x121, 0xf, 0xf, false)); }
; __device__ __forceinline__ float dpp_ror2(float v) { return __int_as_float(__builtin_amdgcn_update_dpp(0, __float_as_int(v), 0x122, 0xf, 0xf, false)); }
;   __device__ __forceinline__ void operator()(const AccT& acc, const Unit& u, int wr, int wc, int fr, int fq) const {
;     ...
;           for (int r = 0; r < 4; ++r) {
;             const float g_cur = xg[m][r], v_cur = xv[m][r];
;             const f32x4 xgp = xg[m > 0 ? m - 1 : 0], xvp = xv[m > 0 ? m - 1 : 0];
;             const float g_pm = (m > 0) ? xgp[r] : 0.f, v_pm = (m > 0) ? xvp[r] : 0.f;
;             const float g1 = dpp_ror1((fr == 15) ? g_pm : g_cur), g2 = dpp_ror2((fr >= 14) ? g_pm : g_cur);
;             const float v1 = dpp_ror1((fr == 15) ? v_pm : v_cur), v2 = dpp_ror2((fr >= 14) ? v_pm : v_cur);
.LBB0_1530:
	s_or_b64 exec, exec, s[12:13]
	v_cndmask_b32_e64 v89, v44, 0, s[8:9]
	s_nop 0
	s_nop 0

; __device__ __forceinline__ float dpp_ror1(float v) { return __int_as_float(__builtin_amdgcn_update_dpp(0, __float_as_int(v), 0x121, 0xf, 0xf, false)); }
; __device__ __forceinline__ float dpp_ror2(float v) { return __int_as_float(__builtin_amdgcn_update_dpp(0, __float_as_int(v), 0x122, 0xf, 0xf, false)); }
;   __device__ __forceinline__ void operator()(const AccT& acc, const Unit& u, int wr, int wc, int fr, int fq) const {
;     ...
;           for (int r = 0; r < 4; ++r) {
;             const float g_cur = xg[m][r], v_cur = xv[m][r];
;             const f32x4 xgp = xg[m > 0 ? m - 1 : 0], xvp = xv[m > 0 ? m - 1 : 0];
;             const float g_pm = (m > 0) ? xgp[r] : 0.f, v_pm = (m > 0) ? xvp[r] : 0.f;
;             const float g1 = dpp_ror1((fr == 15) ? g_pm : g_cur), g2 = dpp_ror2((fr >= 14) ? g_pm : g_cur);
;             const float v1 = dpp_ror1((fr == 15) ? v_pm : v_cur), v2 = dpp_ror2((fr >= 14) ? v_pm : v_cur);
	v_mov_b32_dpp v94, v89 row_ror:1 row_mask:0xf bank_mask:0xf
	v_mov_b32_dpp v96, v88 row_ror:2 row_mask:0xf bank_mask:0xf
	v_cndmask_b32_e64 v89, v40, 0, s[8:9]

; __device__ __forceinline__ float dpp_ror1(float v) { return __int_as_float(__builtin_amdgcn_update_dpp(0, __float_as_int(v), 0x121, 0xf, 0xf, false)); }
; __device__ __forceinline__ float dpp_ror2(float v) { return __int_as_float(__builtin_amdgcn_update_dpp(0, __float_as_int(v), 0x122, 0xf, 0xf, false)); }
;   __device__ __forceinline__ void operator()(const AccT& acc, const Unit& u, int wr, int wc, int fr, int fq) const {
;     ...
;           for (int r = 0; r < 4; ++r) {
;             const float g_cur = xg[m][r], v_cur = xv[m][r];
;             const f32x4 xgp = xg[m > 0 ? m - 1 : 0], xvp = xv[m > 0 ? m - 1 : 0];
;             const float g_pm = (m > 0) ? xgp[r] : 0.f, v_pm = (m > 0) ? xvp[r] : 0.f;
;             const float g1 = dpp_ror1((fr == 15) ? g_pm : g_cur), g2 = dpp_ror2((fr >= 14) ? g_pm : g_cur);
;             const float v1 = dpp_ror1((fr == 15) ? v_pm : v_cur), v2 = dpp_ror2((fr >= 14) ? v_pm : v_cur);
	v_mov_b32_dpp v97, v86 row_ror:2 row_mask:0xf bank_mask:0xf
	v_cndmask_b32_e64 v86, v41, 0, s[8:9]
	v_mov_b32_dpp v88, v89 row_ror:1 row_mask:0xf bank_mask:0xf
	s_nop 0


; __device__ __forceinline__ float dpp_ror1(float v) { return __int_as_float(__builtin_amdgcn_update_dpp(0, __float_as_int(v), 0x121, 0xf, 0xf, false)); }
; __device__ __forceinline__ float dpp_ror2(float v) { return __int_as_float(__builtin_amdgcn_update_dpp(0, __float_as_int(v), 0x122, 0xf, 0xf, false)); }
;   __device__ __forceinline__ void operator()(const AccT& acc, const Unit& u, int wr, int wc, int fr, int fq) const {
;     ...
;           for (int r = 0; r < 4; ++r) {
;             const float g_cur = xg[m][r], v_cur = xv[m][r];
;             const f32x4 xgp = xg[m > 0 ? m - 1 : 0], xvp = xv[m > 0 ? m - 1 : 0];
;             const float g_pm = (m > 0) ? xgp[r] : 0.f, v_pm = (m > 0) ? xvp[r] : 0.f;
;             const float g1 = dpp_ror1((fr == 15) ? g_pm : g_cur), g2 = dpp_ror2((fr >= 14) ? g_pm : g_cur);
;             const float v1 = dpp_ror1((fr == 15) ? v_pm : v_cur), v2 = dpp_ror2((fr >= 14) ? v_pm : v_cur);
	v_mov_b32_dpp v89, v86 row_ror:1 row_mask:0xf bank_mask:0xf
	v_mov_b32_dpp v93, v84 row_ror:2 row_mask:0xf bank_mask:0xf
	v_cndmask_b32_e64 v84, v46, 0, s[8:9]
	s_nop 0

; __device__ __forceinline__ float dpp_ror1(float v) { return __int_as_float(__builtin_amdgcn_update_dpp(0, __float_as_int(v), 0x121, 0xf, 0xf, false)); }
; __device__ __forceinline__ float dpp_ror2(float v) { return __int_as_float(__builtin_amdgcn_update_dpp(0, __float_as_int(v), 0x122, 0xf, 0xf, false)); }
;   __device__ __forceinline__ void operator()(const AccT& acc, const Unit& u, int wr, int wc, int fr, int fq) const {
;     ...
;           for (int r = 0; r < 4; ++r) {
;             const float g_cur = xg[m][r], v_cur = xv[m][r];
;             const f32x4 xgp = xg[m > 0 ? m - 1 : 0], xvp = xv[m > 0 ? m - 1 : 0];
;             const float g_pm = (m > 0) ? xgp[r] : 0.f, v_pm = (m > 0) ? xvp[r] : 0.f;
;             const float g1 = dpp_ror1((fr == 15) ? g_pm : g_cur), g2 = dpp_ror2((fr >= 14) ? g_pm : g_cur);
;             const float v1 = dpp_ror1((fr == 15) ? v_pm : v_cur), v2 = dpp_ror2((fr >= 14) ? v_pm : v_cur);
	v_mov_b32_dpp v90, v82 row_ror:2 row_mask:0xf bank_mask:0xf
	v_mov_b32_dpp v86, v84 row_ror:1 row_mask:0xf bank_mask:0xf
	v_cndmask_b32_e64 v84, v42, 0, s[8:9]

; __device__ __forceinline__ float dpp_ror1(float v) { return __int_as_float(__builtin_amdgcn_update_dpp(0, __float_as_int(v), 0x121, 0xf, 0xf, false)); }
; __device__ __forceinline__ float dpp_ror2(float v) { return __int_as_float(__builtin_amdgcn_update_dpp(0, __float_as_int(v), 0x122, 0xf, 0xf, false)); }
;   __device__ __forceinline__ void operator()(const AccT& acc, const Unit& u, int wr, int wc, int fr, int fq) const {
;     ...
;           for (int r = 0; r < 4; ++r) {
;             const float g_cur = xg[m][r], v_cur = xv[m][r];
;             const f32x4 xgp = xg[m > 0 ? m - 1 : 0], xvp = xv[m > 0 ? m - 1 : 0];
;             const float g_pm = (m > 0) ? xgp[r] : 0.f, v_pm = (m > 0) ? xvp[r] : 0.f;
;             const float g1 = dpp_ror1((fr == 15) ? g_pm : g_cur), g2 = dpp_ror2((fr >= 14) ? g_pm : g_cur);
;             const float v1 = dpp_ror1((fr == 15) ? v_pm : v_cur), v2 = dpp_ror2((fr >= 14) ? v_pm : v_cur);
	v_mov_b32_dpp v92, v87 row_ror:2 row_mask:0xf bank_mask:0xf
	v_cndmask_b32_e64 v87, v45, 0, s[8:9]
	s_nop 0
	v_mov_b32_dpp v82, v84 row_ror:1 row_mask:0xf bank_mask:0xf

; __device__ __forceinline__ float dpp_ror1(float v) { return __int_as_float(__builtin_amdgcn_update_dpp(0, __float_as_int(v), 0x121, 0xf, 0xf, false)); }
; __device__ __forceinline__ float dpp_ror2(float v) { return __int_as_float(__builtin_amdgcn_update_dpp(0, __float_as_int(v), 0x122, 0xf, 0xf, false)); }
;   __device__ __forceinline__ void operator()(const AccT& acc, const Unit& u, int wr, int wc, int fr, int fq) const {
;     ...
;           for (int r = 0; r < 4; ++r) {
;             const float g_cur = xg[m][r], v_cur = xv[m][r];
;             const f32x4 xgp = xg[m > 0 ? m - 1 : 0], xvp = xv[m > 0 ? m - 1 : 0];
;             const float g_pm = (m > 0) ? xgp[r] : 0.f, v_pm = (m > 0) ? xvp[r] : 0.f;
;             const float g1 = dpp_ror1((fr == 15) ? g_pm : g_cur), g2 = dpp_ror2((fr >= 14) ? g_pm : g_cur);
;             const float v1 = dpp_ror1((fr == 15) ? v_pm : v_cur), v2 = dpp_ror2((fr >= 14) ? v_pm : v_cur);
	v_mov_b32_dpp v95, v87 row_ror:1 row_mask:0xf bank_mask:0xf

; __device__ __forceinline__ float dpp_ror1(float v) { return __int_as_float(__builtin_amdgcn_update_dpp(0, __float_as_int(v), 0x121, 0xf, 0xf, false)); }
; __device__ __forceinline__ float dpp_ror2(float v) { return __int_as_float(__builtin_amdgcn_update_dpp(0, __float_as_int(v), 0x122, 0xf, 0xf, false)); }
;   __device__ __forceinline__ void operator()(const AccT& acc, const Unit& u, int wr, int wc, int fr, int fq) const {
;     ...
;           for (int r = 0; r < 4; ++r) {
;             const float g_cur = xg[m][r], v_cur = xv[m][r];
;             const f32x4 xgp = xg[m > 0 ? m - 1 : 0], xvp = xv[m > 0 ? m - 1 : 0];
;             const float g_pm = (m > 0) ? xgp[r] : 0.f, v_pm = (m > 0) ? xvp[r] : 0.f;
;             const float g1 = dpp_ror1((fr == 15) ? g_pm : g_cur), g2 = dpp_ror2((fr >= 14) ? g_pm : g_cur);
;             const float v1 = dpp_ror1((fr == 15) ? v_pm : v_cur), v2 = dpp_ror2((fr >= 14) ? v_pm : v_cur);
	v_mov_b32_dpp v84, v85 row_ror:2 row_mask:0xf bank_mask:0xf
	v_cndmask_b32_e64 v85, v47, 0, s[8:9]
	s_nop 0
	s_nop 0
	v_mov_b32_dpp v87, v85 row_ror:1 row_mask:0xf bank_mask:0xf
	v_mov_b32_dpp v91, v83 row_ror:2 row_mask:0xf bank_mask:0xf
	v_cndmask_b32_e64 v85, v43, 0, s[8:9]

; __device__ __forceinline__ float dpp_ror1(float v) { return __int_as_float(__builtin_amdgcn_update_dpp(0, __float_as_int(v), 0x121, 0xf, 0xf, false)); }
; __device__ __forceinline__ float dpp_ror2(float v) { return __int_as_float(__builtin_amdgcn_update_dpp(0, __float_as_int(v), 0x122, 0xf, 0xf, false)); }
;   __device__ __forceinline__ void operator()(const AccT& acc, const Unit& u, int wr, int wc, int fr, int fq) const {
;     ...
;           for (int r = 0; r < 4; ++r) {
;             const float g_cur = xg[m][r], v_cur = xv[m][r];
;             const f32x4 xgp = xg[m > 0 ? m - 1 : 0], xvp = xv[m > 0 ? m - 1 : 0];
;             const float g_pm = (m > 0) ? xgp[r] : 0.f, v_pm = (m > 0) ? xvp[r] : 0.f;
;             const float g1 = dpp_ror1((fr == 15) ? g_pm : g_cur), g2 = dpp_ror2((fr >= 14) ? g_pm : g_cur);
;             const float v1 = dpp_ror1((fr == 15) ? v_pm : v_cur), v2 = dpp_ror2((fr >= 14) ? v_pm : v_cur);
	s_nop 1
	v_mov_b32_dpp v83, v85 row_ror:1 row_mask:0xf bank_mask:0xf

; __device__ __forceinline__ uint2 pack4(f32x4 v) { return make_uint2(pack2(v[0], v[1]), pack2(v[2], v[3])); }
;   __device__ __forceinline__ void operator()(const AccT& acc, const Unit& u, int wr, int wc, int fr, int fq) const {
;     ...
;             const float cg_ = bg[r] + g2 * wg0[r] + g1 * wg1[r] + g_cur * wg2[r];
;             const float cv_ = bv[r] + v2 * wv0[r] + v1 * wv1[r] + v_cur * wv2[r];
;             res[r] = cg_ * __builtin_amdgcn_rcpf(1.f + __builtin_amdgcn_exp2f(-1.4426950408889634f * cg_)) * cv_;
;           }
;           if (m > 0 || fr >= 2)
;             *(uint2*)(act + (size_t)EPI_ROW(u, ai, m) * DFF + f0) = pack4(res);
	s_nop 1
	v_mov_b32_dpp v85, v98 row_ror:2 row_mask:0xf bank_mask:0xf
	s_and_saveexec_b64 s[12:13], s[4:5]
	s_xor_b64 s[12:13], exec, s[12:13]
	s_andn2_saveexec_b64 s[12:13], s[12:13]
	s_cbranch_execz .LBB0_1497
	s_waitcnt vmcnt(0)
	v_pk_fma_f32 v[90:91], v[70:71], v[90:91], v[78:79]
	v_pk_fma_f32 v[96:97], v[68:69], v[96:97], v[76:77]
	v_pk_fma_f32 v[86:87], v[74:75], v[86:87], v[90:91]
	v_pk_fma_f32 v[94:95], v[72:73], v[94:95], v[96:97]
	v_pk_fma_f32 v[86:87], v[46:47], v[66:67], v[86:87]
	v_pk_fma_f32 v[94:95], v[44:45], v[64:65], v[94:95]
	v_mul_f32_e32 v90, 0xbfb8aa3b, v86
	v_mul_f32_e32 v91, 0xbfb8aa3b, v87
	v_exp_f32_e32 v90, v90
	v_exp_f32_e32 v91, v91
	v_mul_f32_e32 v96, 0xbfb8aa3b, v94
	v_mul_f32_e32 v97, 0xbfb8aa3b, v95
	v_exp_f32_e32 v96, v96
	v_exp_f32_e32 v97, v97
	v_add_f32_e32 v90, 1.0, v90
	v_add_f32_e32 v91, 1.0, v91
	v_rcp_f32_e32 v90, v90
	v_rcp_f32_e32 v91, v91
	v_add_f32_e32 v96, 1.0, v96
	v_add_f32_e32 v97, 1.0, v97
	v_rcp_f32_e32 v96, v96
	v_rcp_f32_e32 v97, v97
	v_pk_fma_f32 v[84:85], v[54:55], v[84:85], v[62:63]
	v_pk_fma_f32 v[92:93], v[52:53], v[92:93], v[60:61]
	v_pk_fma_f32 v[82:83], v[58:59], v[82:83], v[84:85]
	v_pk_mul_f32 v[84:85], v[86:87], v[90:91]
	v_pk_fma_f32 v[82:83], v[42:43], v[50:51], v[82:83]
	v_pk_fma_f32 v[88:89], v[56:57], v[88:89], v[92:93]
	v_pk_mul_f32 v[82:83], v[82:83], v[84:85]
	v_pk_fma_f32 v[88:89], v[40:41], v[48:49], v[88:89]
	v_pk_mul_f32 v[92:93], v[94:95], v[96:97]
	v_cvt_pk_bf16_f32 v85, v82, v83
	v_mov_b64_e32 v[82:83], s[52:53]
	v_pk_mul_f32 v[88:89], v[88:89], v[92:93]
	v_mad_i64_i32 v[82:83], s[46:47], v112, s88, v[82:83]
	v_cvt_pk_bf16_f32 v84, v88, v89
	v_lshl_add_u64 v[82:83], v[188:189], 1, v[82:83]
	global_store_dwordx2 v[82:83], v[84:85], off offset:32
	s_branch .LBB0_1497
